# gemm_setprio1_issued_before_the_cluster_barrier
# speedup vs baseline: 1.0119x; 1.0036x over previous
.LBB0_150:
	ds_read_b128 v[152:155], v148
	ds_read_b128 v[156:159], v148 offset:1024
	ds_read_b128 v[160:163], v148 offset:2048
	ds_read_b128 v[164:167], v148 offset:3072
	s_add_u32 s40, s38, 0xfffc0080
	s_addc_u32 s41, s39, -1
	s_cmp_eq_u32 s75, 12
	s_cselect_b32 s43, s13, s41
	s_cselect_b32 s42, s37, s40
	s_cselect_b32 s41, s9, s74
	s_cselect_b32 s40, s72, s73
	v_lshl_add_u64 v[200:201], s[38:39], 0, v[136:137]
	s_add_i32 m0, s51, 0xc000
	ds_read_b128 v[168:171], v149
	ds_read_b128 v[172:175], v149 offset:1024
	ds_read_b128 v[176:179], v149 offset:2048
	ds_read_b128 v[180:183], v149 offset:3072
	ds_read_b128 v[184:187], v149 offset:4096
	ds_read_b128 v[188:191], v149 offset:5120
	ds_read_b128 v[192:195], v149 offset:6144
	ds_read_b128 v[196:199], v149 offset:7168
	global_load_lds_dwordx4 v[200:201], off
	v_lshl_add_u64 v[200:201], s[38:39], 0, v[138:139]
	s_add_i32 m0, s51, 0xe000
	s_nop 0
	global_load_lds_dwordx4 v[200:201], off
	s_waitcnt lgkmcnt(8)
	s_setprio 1
	s_barrier
	s_waitcnt lgkmcnt(0)
	v_mfma_f32_16x16x32_bf16 v[124:127], v[152:155], v[168:171], v[124:127]
	v_mfma_f32_16x16x32_bf16 v[120:123], v[160:163], v[168:171], v[120:123]
	v_mfma_f32_16x16x32_bf16 v[116:119], v[152:155], v[176:179], v[116:119]
	v_mfma_f32_16x16x32_bf16 v[112:115], v[160:163], v[176:179], v[112:115]
	v_mfma_f32_16x16x32_bf16 v[108:111], v[152:155], v[184:187], v[108:111]
	v_mfma_f32_16x16x32_bf16 v[104:107], v[160:163], v[184:187], v[104:107]
	v_mfma_f32_16x16x32_bf16 v[100:103], v[152:155], v[192:195], v[100:103]
	v_mfma_f32_16x16x32_bf16 v[96:99], v[160:163], v[192:195], v[96:99]
	v_mfma_f32_16x16x32_bf16 v[124:127], v[156:159], v[172:175], v[124:127]
	v_mfma_f32_16x16x32_bf16 v[120:123], v[164:167], v[172:175], v[120:123]
	v_mfma_f32_16x16x32_bf16 v[116:119], v[156:159], v[180:183], v[116:119]
	v_mfma_f32_16x16x32_bf16 v[112:115], v[164:167], v[180:183], v[112:115]
	v_mfma_f32_16x16x32_bf16 v[108:111], v[156:159], v[188:191], v[108:111]
	v_mfma_f32_16x16x32_bf16 v[104:107], v[164:167], v[188:191], v[104:107]
	v_mfma_f32_16x16x32_bf16 v[100:103], v[156:159], v[196:199], v[100:103]
	v_mfma_f32_16x16x32_bf16 v[96:99], v[164:167], v[196:199], v[96:99]
	s_setprio 0
	s_barrier
	s_add_i32 s76, s69, s48
	v_lshl_add_u64 v[208:209], s[40:41], 0, v[132:133]
	s_mov_b32 m0, s76
	ds_read_b128 v[200:203], v150
	ds_read_b128 v[204:207], v150 offset:1024
	ds_read_b128 v[212:215], v150 offset:2048
	ds_read_b128 v[216:219], v150 offset:3072
	global_load_lds_dwordx4 v[208:209], off
	v_lshl_add_u64 v[220:221], s[40:41], 0, v[128:129]
	s_add_i32 m0, s76, 0x2000
	s_nop 0
	global_load_lds_dwordx4 v[220:221], off
	s_setprio 1
	s_barrier
	s_waitcnt lgkmcnt(0)
	v_mfma_f32_16x16x32_bf16 v[76:79], v[200:203], v[168:171], v[76:79]
	v_mfma_f32_16x16x32_bf16 v[72:75], v[212:215], v[168:171], v[72:75]
	v_mfma_f32_16x16x32_bf16 v[60:63], v[200:203], v[176:179], v[60:63]
	v_mfma_f32_16x16x32_bf16 v[56:59], v[212:215], v[176:179], v[56:59]
	v_mfma_f32_16x16x32_bf16 v[44:47], v[200:203], v[184:187], v[44:47]
	v_mfma_f32_16x16x32_bf16 v[40:43], v[212:215], v[184:187], v[40:43]
	v_mfma_f32_16x16x32_bf16 v[36:39], v[200:203], v[192:195], v[36:39]
	v_mfma_f32_16x16x32_bf16 v[32:35], v[212:215], v[192:195], v[32:35]
	v_mfma_f32_16x16x32_bf16 v[76:79], v[204:207], v[172:175], v[76:79]
	v_mfma_f32_16x16x32_bf16 v[72:75], v[216:219], v[172:175], v[72:75]
	v_mfma_f32_16x16x32_bf16 v[60:63], v[204:207], v[180:183], v[60:63]
	v_mfma_f32_16x16x32_bf16 v[56:59], v[216:219], v[180:183], v[56:59]
	v_mfma_f32_16x16x32_bf16 v[44:47], v[204:207], v[188:191], v[44:47]
	v_mfma_f32_16x16x32_bf16 v[40:43], v[216:219], v[188:191], v[40:43]
	v_mfma_f32_16x16x32_bf16 v[36:39], v[204:207], v[196:199], v[36:39]
	v_mfma_f32_16x16x32_bf16 v[32:35], v[216:219], v[196:199], v[32:35]
	s_setprio 0
	s_mov_b32 m0, s51
	v_lshl_add_u64 v[222:223], s[42:43], 0, v[134:135]
	s_barrier
	ds_read_b128 v[168:171], v149 offset:16384
	ds_read_b128 v[172:175], v149 offset:17408
	ds_read_b128 v[176:179], v149 offset:18432
	ds_read_b128 v[180:183], v149 offset:19456
	ds_read_b128 v[184:187], v149 offset:20480
	ds_read_b128 v[188:191], v149 offset:21504
	ds_read_b128 v[192:195], v149 offset:22528
	ds_read_b128 v[196:199], v149 offset:23552
	global_load_lds_dwordx4 v[222:223], off
	v_lshl_add_u64 v[224:225], s[42:43], 0, v[130:131]
	s_mov_b32 m0, s54
	s_nop 0
	global_load_lds_dwordx4 v[224:225], off
	s_setprio 1
	s_barrier
	s_waitcnt lgkmcnt(0)
	v_mfma_f32_16x16x32_bf16 v[92:95], v[152:155], v[168:171], v[92:95]
	v_mfma_f32_16x16x32_bf16 v[88:91], v[160:163], v[168:171], v[88:91]
	v_mfma_f32_16x16x32_bf16 v[84:87], v[152:155], v[176:179], v[84:87]
	v_mfma_f32_16x16x32_bf16 v[80:83], v[160:163], v[176:179], v[80:83]
	v_mfma_f32_16x16x32_bf16 v[68:71], v[152:155], v[184:187], v[68:71]
	v_mfma_f32_16x16x32_bf16 v[64:67], v[160:163], v[184:187], v[64:67]
	v_mfma_f32_16x16x32_bf16 v[52:55], v[152:155], v[192:195], v[52:55]
	v_mfma_f32_16x16x32_bf16 v[48:51], v[160:163], v[192:195], v[48:51]
	v_mfma_f32_16x16x32_bf16 v[92:95], v[156:159], v[172:175], v[92:95]
	v_mfma_f32_16x16x32_bf16 v[88:91], v[164:167], v[172:175], v[88:91]
	v_mfma_f32_16x16x32_bf16 v[84:87], v[156:159], v[180:183], v[84:87]
	v_mfma_f32_16x16x32_bf16 v[80:83], v[164:167], v[180:183], v[80:83]
	v_mfma_f32_16x16x32_bf16 v[68:71], v[156:159], v[188:191], v[68:71]
	v_mfma_f32_16x16x32_bf16 v[64:67], v[164:167], v[188:191], v[64:67]
	v_mfma_f32_16x16x32_bf16 v[52:55], v[156:159], v[196:199], v[52:55]
	v_mfma_f32_16x16x32_bf16 v[48:51], v[164:167], v[196:199], v[48:51]
	s_setprio 0
	s_barrier
	s_add_u32 s76, s40, 0x40000
	s_addc_u32 s77, s41, 0
	s_add_i32 s78, s70, s48
	v_lshl_add_u64 v[152:153], s[76:77], 0, v[132:133]
	s_mov_b32 m0, s78
	s_nop 0
	global_load_lds_dwordx4 v[152:153], off
	v_lshl_add_u64 v[152:153], s[76:77], 0, v[128:129]
	s_add_i32 m0, s78, 0x2000
	s_nop 0
	global_load_lds_dwordx4 v[152:153], off
	s_waitcnt vmcnt(6)
	s_setprio 1
	s_barrier
	v_mfma_f32_16x16x32_bf16 v[28:31], v[200:203], v[168:171], v[28:31]
	v_mfma_f32_16x16x32_bf16 v[24:27], v[212:215], v[168:171], v[24:27]
	v_mfma_f32_16x16x32_bf16 v[20:23], v[200:203], v[176:179], v[20:23]
	v_mfma_f32_16x16x32_bf16 v[16:19], v[212:215], v[176:179], v[16:19]
	v_mfma_f32_16x16x32_bf16 v[12:15], v[200:203], v[184:187], v[12:15]
	v_mfma_f32_16x16x32_bf16 v[8:11], v[212:215], v[184:187], v[8:11]
	v_mfma_f32_16x16x32_bf16 v[4:7], v[200:203], v[192:195], v[4:7]
	v_mfma_f32_16x16x32_bf16 v[0:3], v[212:215], v[192:195], v[0:3]
	v_mfma_f32_16x16x32_bf16 v[28:31], v[204:207], v[172:175], v[28:31]
	v_mfma_f32_16x16x32_bf16 v[24:27], v[216:219], v[172:175], v[24:27]
	v_mfma_f32_16x16x32_bf16 v[20:23], v[204:207], v[180:183], v[20:23]
	v_mfma_f32_16x16x32_bf16 v[16:19], v[216:219], v[180:183], v[16:19]
	v_mfma_f32_16x16x32_bf16 v[12:15], v[204:207], v[188:191], v[12:15]
	v_mfma_f32_16x16x32_bf16 v[8:11], v[216:219], v[188:191], v[8:11]
	v_mfma_f32_16x16x32_bf16 v[4:7], v[204:207], v[196:199], v[4:7]
	v_mfma_f32_16x16x32_bf16 v[0:3], v[216:219], v[196:199], v[0:3]
	s_setprio 0
	s_add_i32 s76, 0, 0x18000
	v_add_u32_e32 v151, s76, v146
	s_barrier
	ds_read_b128 v[152:155], v151
	ds_read_b128 v[156:159], v151 offset:1024
	ds_read_b128 v[160:163], v151 offset:2048
	ds_read_b128 v[164:167], v151 offset:3072
	s_add_u32 s42, s42, 0x40000
	s_addc_u32 s43, s43, 0
	s_mov_b32 m0, s55
	v_lshl_add_u64 v[200:201], s[42:43], 0, v[134:135]
	ds_read_b128 v[168:171], v149 offset:32768
	ds_read_b128 v[172:175], v149 offset:33792
	ds_read_b128 v[176:179], v149 offset:34816
	ds_read_b128 v[180:183], v149 offset:35840
	ds_read_b128 v[184:187], v149 offset:36864
	ds_read_b128 v[188:191], v149 offset:37888
	ds_read_b128 v[192:195], v149 offset:38912
	ds_read_b128 v[196:199], v149 offset:39936
	global_load_lds_dwordx4 v[200:201], off
	v_lshl_add_u64 v[200:201], s[42:43], 0, v[130:131]
	s_mov_b32 m0, s62
	s_nop 0
	global_load_lds_dwordx4 v[200:201], off
	s_waitcnt lgkmcnt(8)
	s_setprio 1
	s_barrier
	s_waitcnt lgkmcnt(0)
	v_mfma_f32_16x16x32_bf16 v[124:127], v[152:155], v[168:171], v[124:127]
	v_mfma_f32_16x16x32_bf16 v[120:123], v[160:163], v[168:171], v[120:123]
	v_mfma_f32_16x16x32_bf16 v[116:119], v[152:155], v[176:179], v[116:119]
	v_mfma_f32_16x16x32_bf16 v[112:115], v[160:163], v[176:179], v[112:115]
	v_mfma_f32_16x16x32_bf16 v[108:111], v[152:155], v[184:187], v[108:111]
	v_mfma_f32_16x16x32_bf16 v[104:107], v[160:163], v[184:187], v[104:107]
	v_mfma_f32_16x16x32_bf16 v[100:103], v[152:155], v[192:195], v[100:103]
	v_mfma_f32_16x16x32_bf16 v[96:99], v[160:163], v[192:195], v[96:99]
	v_mfma_f32_16x16x32_bf16 v[124:127], v[156:159], v[172:175], v[124:127]
	v_mfma_f32_16x16x32_bf16 v[120:123], v[164:167], v[172:175], v[120:123]
	v_mfma_f32_16x16x32_bf16 v[116:119], v[156:159], v[180:183], v[116:119]
	v_mfma_f32_16x16x32_bf16 v[112:115], v[164:167], v[180:183], v[112:115]
	v_mfma_f32_16x16x32_bf16 v[108:111], v[156:159], v[188:191], v[108:111]
	v_mfma_f32_16x16x32_bf16 v[104:107], v[164:167], v[188:191], v[104:107]
	v_mfma_f32_16x16x32_bf16 v[100:103], v[156:159], v[196:199], v[100:103]
	v_mfma_f32_16x16x32_bf16 v[96:99], v[164:167], v[196:199], v[96:99]
	s_setprio 0
	s_barrier
	s_add_i32 s42, 0, 0x1c000
	s_add_i32 s43, s76, s48
	v_add_u32_e32 v151, s42, v146
	v_lshl_add_u64 v[208:209], v[208:209], 0, s[0:1]
	s_mov_b32 m0, s43
	ds_read_b128 v[200:203], v151
	ds_read_b128 v[204:207], v151 offset:1024
	ds_read_b128 v[212:215], v151 offset:2048
	ds_read_b128 v[216:219], v151 offset:3072
	global_load_lds_dwordx4 v[208:209], off
	v_lshl_add_u64 v[208:209], v[220:221], 0, s[0:1]
	s_add_i32 m0, s43, 0x2000
	s_nop 0
	global_load_lds_dwordx4 v[208:209], off
	s_setprio 1
	s_barrier
	s_waitcnt lgkmcnt(0)
	v_mfma_f32_16x16x32_bf16 v[76:79], v[200:203], v[168:171], v[76:79]
	v_mfma_f32_16x16x32_bf16 v[72:75], v[212:215], v[168:171], v[72:75]
	v_mfma_f32_16x16x32_bf16 v[60:63], v[200:203], v[176:179], v[60:63]
	v_mfma_f32_16x16x32_bf16 v[56:59], v[212:215], v[176:179], v[56:59]
	v_mfma_f32_16x16x32_bf16 v[44:47], v[200:203], v[184:187], v[44:47]
	v_mfma_f32_16x16x32_bf16 v[40:43], v[212:215], v[184:187], v[40:43]
	v_mfma_f32_16x16x32_bf16 v[36:39], v[200:203], v[192:195], v[36:39]
	v_mfma_f32_16x16x32_bf16 v[32:35], v[212:215], v[192:195], v[32:35]
	v_mfma_f32_16x16x32_bf16 v[76:79], v[204:207], v[172:175], v[76:79]
	v_mfma_f32_16x16x32_bf16 v[72:75], v[216:219], v[172:175], v[72:75]
	v_mfma_f32_16x16x32_bf16 v[60:63], v[204:207], v[180:183], v[60:63]
	v_mfma_f32_16x16x32_bf16 v[56:59], v[216:219], v[180:183], v[56:59]
	v_mfma_f32_16x16x32_bf16 v[44:47], v[204:207], v[188:191], v[44:47]
	v_mfma_f32_16x16x32_bf16 v[40:43], v[216:219], v[188:191], v[40:43]
	v_mfma_f32_16x16x32_bf16 v[36:39], v[204:207], v[196:199], v[36:39]
	v_mfma_f32_16x16x32_bf16 v[32:35], v[216:219], v[196:199], v[32:35]
	s_setprio 0
	s_mov_b32 m0, s63
	v_lshl_add_u64 v[208:209], v[222:223], 0, s[0:1]
	s_barrier
	ds_read_b128 v[168:171], v149 offset:49152
	ds_read_b128 v[172:175], v149 offset:50176
	ds_read_b128 v[176:179], v149 offset:51200
	ds_read_b128 v[180:183], v149 offset:52224
	ds_read_b128 v[184:187], v149 offset:53248
	ds_read_b128 v[188:191], v149 offset:54272
	ds_read_b128 v[192:195], v149 offset:55296
	ds_read_b128 v[196:199], v149 offset:56320
	global_load_lds_dwordx4 v[208:209], off
	v_lshl_add_u64 v[208:209], v[224:225], 0, s[0:1]
	s_mov_b32 m0, s64
	s_nop 0
	global_load_lds_dwordx4 v[208:209], off
	s_setprio 1
	s_barrier
	s_waitcnt lgkmcnt(0)
	v_mfma_f32_16x16x32_bf16 v[92:95], v[152:155], v[168:171], v[92:95]
	v_mfma_f32_16x16x32_bf16 v[88:91], v[160:163], v[168:171], v[88:91]
	v_mfma_f32_16x16x32_bf16 v[84:87], v[152:155], v[176:179], v[84:87]
	v_mfma_f32_16x16x32_bf16 v[80:83], v[160:163], v[176:179], v[80:83]
	v_mfma_f32_16x16x32_bf16 v[68:71], v[152:155], v[184:187], v[68:71]
	v_mfma_f32_16x16x32_bf16 v[64:67], v[160:163], v[184:187], v[64:67]
	v_mfma_f32_16x16x32_bf16 v[52:55], v[152:155], v[192:195], v[52:55]
	v_mfma_f32_16x16x32_bf16 v[48:51], v[160:163], v[192:195], v[48:51]
	v_mfma_f32_16x16x32_bf16 v[92:95], v[156:159], v[172:175], v[92:95]
	v_mfma_f32_16x16x32_bf16 v[88:91], v[164:167], v[172:175], v[88:91]
	v_mfma_f32_16x16x32_bf16 v[84:87], v[156:159], v[180:183], v[84:87]
	v_mfma_f32_16x16x32_bf16 v[80:83], v[164:167], v[180:183], v[80:83]
	v_mfma_f32_16x16x32_bf16 v[68:71], v[156:159], v[188:191], v[68:71]
	v_mfma_f32_16x16x32_bf16 v[64:67], v[164:167], v[188:191], v[64:67]
	v_mfma_f32_16x16x32_bf16 v[52:55], v[156:159], v[196:199], v[52:55]
	v_mfma_f32_16x16x32_bf16 v[48:51], v[164:167], v[196:199], v[48:51]
	s_setprio 0
	s_barrier
	s_add_u32 s40, s40, 0x40080
	s_addc_u32 s41, s41, 0
	s_add_i32 s42, s42, s48
	v_lshl_add_u64 v[152:153], s[40:41], 0, v[132:133]
	s_mov_b32 m0, s42
	s_nop 0
	global_load_lds_dwordx4 v[152:153], off
	v_lshl_add_u64 v[152:153], s[40:41], 0, v[128:129]
	s_add_i32 m0, s42, 0x2000
	s_nop 0
	global_load_lds_dwordx4 v[152:153], off
	s_waitcnt vmcnt(6)
	s_setprio 1
	s_barrier
	v_mfma_f32_16x16x32_bf16 v[28:31], v[200:203], v[168:171], v[28:31]
	v_mfma_f32_16x16x32_bf16 v[24:27], v[212:215], v[168:171], v[24:27]
	v_mfma_f32_16x16x32_bf16 v[20:23], v[200:203], v[176:179], v[20:23]
	v_mfma_f32_16x16x32_bf16 v[16:19], v[212:215], v[176:179], v[16:19]
	v_mfma_f32_16x16x32_bf16 v[12:15], v[200:203], v[184:187], v[12:15]
	v_mfma_f32_16x16x32_bf16 v[8:11], v[212:215], v[184:187], v[8:11]
	v_mfma_f32_16x16x32_bf16 v[4:7], v[200:203], v[192:195], v[4:7]
	v_mfma_f32_16x16x32_bf16 v[0:3], v[212:215], v[192:195], v[0:3]
	v_mfma_f32_16x16x32_bf16 v[28:31], v[204:207], v[172:175], v[28:31]
	v_mfma_f32_16x16x32_bf16 v[24:27], v[216:219], v[172:175], v[24:27]
	v_mfma_f32_16x16x32_bf16 v[20:23], v[204:207], v[180:183], v[20:23]
	v_mfma_f32_16x16x32_bf16 v[16:19], v[216:219], v[180:183], v[16:19]
	v_mfma_f32_16x16x32_bf16 v[12:15], v[204:207], v[188:191], v[12:15]
	v_mfma_f32_16x16x32_bf16 v[8:11], v[216:219], v[188:191], v[8:11]
	v_mfma_f32_16x16x32_bf16 v[4:7], v[204:207], v[196:199], v[4:7]
	v_mfma_f32_16x16x32_bf16 v[0:3], v[216:219], v[196:199], v[0:3]
	s_setprio 0
	s_add_i32 s75, s75, 2
	s_add_u32 s38, s38, 0x100
	s_addc_u32 s39, s39, 0
	s_add_u32 s73, s73, 0x100
	s_addc_u32 s74, s74, 0
	s_cmp_gt_u32 s75, 13
	s_barrier
	s_cbranch_scc0 .LBB0_150
	v_lshl_add_u32 v151, s36, 8, v144
	s_cmp_gt_i32 s71, 11
	s_mov_b64 s[36:37], -1
	s_cbranch_scc0 .LBB0_155
	s_and_saveexec_b64 s[36:37], s[2:3]
	s_cbranch_execz .LBB0_154
	v_lshl_or_b32 v152, v151, 8, v147
	v_readlane_b32 s38, v253, 59
	v_readlane_b32 s39, v253, 60
	v_or_b32_e32 v153, 0x1000, v152
	s_nop 3
	global_store_dwordx4 v153, v[116:119], s[38:39] nt
	v_or_b32_e32 v153, 0x2000, v152
	global_store_dwordx4 v153, v[108:111], s[38:39] nt
	v_or_b32_e32 v153, 0x3000, v152
	global_store_dwordx4 v153, v[100:103], s[38:39] nt
	v_add_u32_e32 v153, 0x8000, v152
	global_store_dwordx4 v153, v[92:95], s[38:39] nt
	v_add_u32_e32 v153, 0x9000, v152
	global_store_dwordx4 v153, v[84:87], s[38:39] nt
	v_add_u32_e32 v153, 0xa000, v152
	global_store_dwordx4 v153, v[68:71], s[38:39] nt
	v_add_u32_e32 v153, 0xb000, v152
	global_store_dwordx4 v153, v[52:55], s[38:39] nt
	v_or_b32_e32 v153, 16, v152
	global_store_dwordx4 v153, v[120:123], s[38:39] nt
	v_or_b32_e32 v153, 0x1010, v152
	global_store_dwordx4 v153, v[112:115], s[38:39] nt
	v_or_b32_e32 v153, 0x2010, v152
	global_store_dwordx4 v153, v[104:107], s[38:39] nt
	v_or_b32_e32 v153, 0x3010, v152
	global_store_dwordx4 v153, v[96:99], s[38:39] nt
	v_add_u32_e32 v153, 0x8010, v152
	global_store_dwordx4 v153, v[88:91], s[38:39] nt
	v_add_u32_e32 v153, 0x9010, v152
	global_store_dwordx4 v152, v[124:127], s[38:39] nt
	global_store_dwordx4 v153, v[80:83], s[38:39] nt
	v_add_u32_e32 v153, 0xa010, v152
	v_add_u32_e32 v152, 0xb010, v152
	global_store_dwordx4 v153, v[64:67], s[38:39] nt
	global_store_dwordx4 v152, v[48:51], s[38:39] nt

.LBB0_177:
	ds_read_b128 v[152:155], v149
	ds_read_b128 v[156:159], v149 offset:1024
	ds_read_b128 v[160:163], v149 offset:2048
	ds_read_b128 v[164:167], v149 offset:3072
	s_add_u32 s36, s34, 0xfffc0080
	s_addc_u32 s37, s35, -1
	s_cmp_eq_u32 s68, 12
	s_cselect_b32 s39, s9, s37
	s_cselect_b32 s38, s64, s36
	s_cselect_b32 s37, s3, s67
	s_cselect_b32 s36, s65, s66
	v_lshl_add_u64 v[144:145], s[34:35], 0, v[136:137]
	s_add_i32 m0, s13, 0xc000
	ds_read_b128 v[168:171], v150
	ds_read_b128 v[172:175], v150 offset:1024
	ds_read_b128 v[176:179], v150 offset:2048
	ds_read_b128 v[180:183], v150 offset:3072
	ds_read_b128 v[184:187], v150 offset:4096
	ds_read_b128 v[188:191], v150 offset:5120
	ds_read_b128 v[192:195], v150 offset:6144
	ds_read_b128 v[196:199], v150 offset:7168
	global_load_lds_dwordx4 v[144:145], off
	v_lshl_add_u64 v[144:145], s[34:35], 0, v[138:139]
	s_add_i32 m0, s13, 0xe000
	s_nop 0
	global_load_lds_dwordx4 v[144:145], off
	s_waitcnt lgkmcnt(8)
	s_setprio 1
	s_barrier
	s_waitcnt lgkmcnt(0)
	v_mfma_f32_16x16x32_bf16 v[124:127], v[152:155], v[168:171], v[124:127]
	v_mfma_f32_16x16x32_bf16 v[120:123], v[160:163], v[168:171], v[120:123]
	v_mfma_f32_16x16x32_bf16 v[112:115], v[152:155], v[176:179], v[112:115]
	v_mfma_f32_16x16x32_bf16 v[104:107], v[160:163], v[176:179], v[104:107]
	v_mfma_f32_16x16x32_bf16 v[96:99], v[152:155], v[184:187], v[96:99]
	v_mfma_f32_16x16x32_bf16 v[88:91], v[160:163], v[184:187], v[88:91]
	v_mfma_f32_16x16x32_bf16 v[80:83], v[152:155], v[192:195], v[80:83]
	v_mfma_f32_16x16x32_bf16 v[72:75], v[160:163], v[192:195], v[72:75]
	v_mfma_f32_16x16x32_bf16 v[124:127], v[156:159], v[172:175], v[124:127]
	v_mfma_f32_16x16x32_bf16 v[120:123], v[164:167], v[172:175], v[120:123]
	v_mfma_f32_16x16x32_bf16 v[112:115], v[156:159], v[180:183], v[112:115]
	v_mfma_f32_16x16x32_bf16 v[104:107], v[164:167], v[180:183], v[104:107]
	v_mfma_f32_16x16x32_bf16 v[96:99], v[156:159], v[188:191], v[96:99]
	v_mfma_f32_16x16x32_bf16 v[88:91], v[164:167], v[188:191], v[88:91]
	v_mfma_f32_16x16x32_bf16 v[80:83], v[156:159], v[196:199], v[80:83]
	v_mfma_f32_16x16x32_bf16 v[72:75], v[164:167], v[196:199], v[72:75]
	s_setprio 0
	s_barrier
	s_add_i32 s69, s55, s42
	v_lshl_add_u64 v[144:145], s[36:37], 0, v[130:131]
	s_mov_b32 m0, s69
	ds_read_b128 v[200:203], v151
	ds_read_b128 v[204:207], v151 offset:1024
	ds_read_b128 v[212:215], v151 offset:2048
	ds_read_b128 v[216:219], v151 offset:3072
	global_load_lds_dwordx4 v[144:145], off
	v_lshl_add_u64 v[208:209], s[36:37], 0, v[134:135]
	s_add_i32 m0, s69, 0x2000
	s_nop 0
	global_load_lds_dwordx4 v[208:209], off
	s_setprio 1
	s_barrier
	s_waitcnt lgkmcnt(0)
	v_mfma_f32_16x16x32_bf16 v[116:119], v[200:203], v[168:171], v[116:119]
	v_mfma_f32_16x16x32_bf16 v[108:111], v[212:215], v[168:171], v[108:111]
	v_mfma_f32_16x16x32_bf16 v[100:103], v[200:203], v[176:179], v[100:103]
	v_mfma_f32_16x16x32_bf16 v[92:95], v[212:215], v[176:179], v[92:95]
	v_mfma_f32_16x16x32_bf16 v[84:87], v[200:203], v[184:187], v[84:87]
	v_mfma_f32_16x16x32_bf16 v[76:79], v[212:215], v[184:187], v[76:79]
	v_mfma_f32_16x16x32_bf16 v[68:71], v[200:203], v[192:195], v[68:71]
	v_mfma_f32_16x16x32_bf16 v[64:67], v[212:215], v[192:195], v[64:67]
	v_mfma_f32_16x16x32_bf16 v[116:119], v[204:207], v[172:175], v[116:119]
	v_mfma_f32_16x16x32_bf16 v[108:111], v[216:219], v[172:175], v[108:111]
	v_mfma_f32_16x16x32_bf16 v[100:103], v[204:207], v[180:183], v[100:103]
	v_mfma_f32_16x16x32_bf16 v[92:95], v[216:219], v[180:183], v[92:95]
	v_mfma_f32_16x16x32_bf16 v[84:87], v[204:207], v[188:191], v[84:87]
	v_mfma_f32_16x16x32_bf16 v[76:79], v[216:219], v[188:191], v[76:79]
	v_mfma_f32_16x16x32_bf16 v[68:71], v[204:207], v[196:199], v[68:71]
	v_mfma_f32_16x16x32_bf16 v[64:67], v[216:219], v[196:199], v[64:67]
	s_setprio 0
	s_mov_b32 m0, s13
	v_lshl_add_u64 v[220:221], s[38:39], 0, v[128:129]
	s_barrier
	ds_read_b128 v[168:171], v150 offset:16384
	ds_read_b128 v[172:175], v150 offset:17408
	ds_read_b128 v[176:179], v150 offset:18432
	ds_read_b128 v[180:183], v150 offset:19456
	ds_read_b128 v[184:187], v150 offset:20480
	ds_read_b128 v[188:191], v150 offset:21504
	ds_read_b128 v[192:195], v150 offset:22528
	ds_read_b128 v[196:199], v150 offset:23552
	global_load_lds_dwordx4 v[220:221], off
	v_lshl_add_u64 v[222:223], s[38:39], 0, v[132:133]
	s_mov_b32 m0, s43
	s_nop 0
	global_load_lds_dwordx4 v[222:223], off
	s_setprio 1
	s_barrier
	s_waitcnt lgkmcnt(0)
	v_mfma_f32_16x16x32_bf16 v[60:63], v[152:155], v[168:171], v[60:63]
	v_mfma_f32_16x16x32_bf16 v[56:59], v[160:163], v[168:171], v[56:59]
	v_mfma_f32_16x16x32_bf16 v[52:55], v[152:155], v[176:179], v[52:55]
	v_mfma_f32_16x16x32_bf16 v[44:47], v[160:163], v[176:179], v[44:47]
	v_mfma_f32_16x16x32_bf16 v[36:39], v[152:155], v[184:187], v[36:39]
	v_mfma_f32_16x16x32_bf16 v[28:31], v[160:163], v[184:187], v[28:31]
	v_mfma_f32_16x16x32_bf16 v[20:23], v[152:155], v[192:195], v[20:23]
	v_mfma_f32_16x16x32_bf16 v[12:15], v[160:163], v[192:195], v[12:15]
	v_mfma_f32_16x16x32_bf16 v[60:63], v[156:159], v[172:175], v[60:63]
	v_mfma_f32_16x16x32_bf16 v[56:59], v[164:167], v[172:175], v[56:59]
	v_mfma_f32_16x16x32_bf16 v[52:55], v[156:159], v[180:183], v[52:55]
	v_mfma_f32_16x16x32_bf16 v[44:47], v[164:167], v[180:183], v[44:47]
	v_mfma_f32_16x16x32_bf16 v[36:39], v[156:159], v[188:191], v[36:39]
	v_mfma_f32_16x16x32_bf16 v[28:31], v[164:167], v[188:191], v[28:31]
	v_mfma_f32_16x16x32_bf16 v[20:23], v[156:159], v[196:199], v[20:23]
	v_mfma_f32_16x16x32_bf16 v[12:15], v[164:167], v[196:199], v[12:15]
	s_setprio 0
	s_barrier
	s_add_u32 s70, s36, 0x40000
	s_addc_u32 s71, s37, 0
	s_add_i32 s69, s62, s42
	v_lshl_add_u64 v[152:153], s[70:71], 0, v[130:131]
	s_mov_b32 m0, s69
	s_nop 0
	global_load_lds_dwordx4 v[152:153], off
	v_lshl_add_u64 v[152:153], s[70:71], 0, v[134:135]
	s_add_i32 m0, s69, 0x2000
	s_nop 0
	global_load_lds_dwordx4 v[152:153], off
	s_waitcnt vmcnt(6)
	s_setprio 1
	s_barrier
	v_mfma_f32_16x16x32_bf16 v[48:51], v[200:203], v[168:171], v[48:51]
	v_mfma_f32_16x16x32_bf16 v[40:43], v[212:215], v[168:171], v[40:43]
	v_mfma_f32_16x16x32_bf16 v[32:35], v[200:203], v[176:179], v[32:35]
	v_mfma_f32_16x16x32_bf16 v[24:27], v[212:215], v[176:179], v[24:27]
	v_mfma_f32_16x16x32_bf16 v[16:19], v[200:203], v[184:187], v[16:19]
	v_mfma_f32_16x16x32_bf16 v[8:11], v[212:215], v[184:187], v[8:11]
	v_mfma_f32_16x16x32_bf16 v[4:7], v[200:203], v[192:195], v[4:7]
	v_mfma_f32_16x16x32_bf16 v[0:3], v[212:215], v[192:195], v[0:3]
	v_mfma_f32_16x16x32_bf16 v[48:51], v[204:207], v[172:175], v[48:51]
	v_mfma_f32_16x16x32_bf16 v[40:43], v[216:219], v[172:175], v[40:43]
	v_mfma_f32_16x16x32_bf16 v[32:35], v[204:207], v[180:183], v[32:35]
	v_mfma_f32_16x16x32_bf16 v[24:27], v[216:219], v[180:183], v[24:27]
	v_mfma_f32_16x16x32_bf16 v[16:19], v[204:207], v[188:191], v[16:19]
	v_mfma_f32_16x16x32_bf16 v[8:11], v[216:219], v[188:191], v[8:11]
	v_mfma_f32_16x16x32_bf16 v[4:7], v[204:207], v[196:199], v[4:7]
	v_mfma_f32_16x16x32_bf16 v[0:3], v[216:219], v[196:199], v[0:3]
	s_setprio 0
	s_add_i32 s69, 0, 0x18000
	v_add_u32_e32 v164, s69, v147
	s_barrier
	ds_read_b128 v[152:155], v164
	ds_read_b128 v[156:159], v164 offset:1024
	ds_read_b128 v[160:163], v164 offset:2048
	ds_read_b128 v[164:167], v164 offset:3072
	s_add_u32 s38, s38, 0x40000
	s_addc_u32 s39, s39, 0
	s_mov_b32 m0, s48
	v_lshl_add_u64 v[200:201], s[38:39], 0, v[128:129]
	ds_read_b128 v[168:171], v150 offset:32768
	ds_read_b128 v[172:175], v150 offset:33792
	ds_read_b128 v[176:179], v150 offset:34816
	ds_read_b128 v[180:183], v150 offset:35840
	ds_read_b128 v[184:187], v150 offset:36864
	ds_read_b128 v[188:191], v150 offset:37888
	ds_read_b128 v[192:195], v150 offset:38912
	ds_read_b128 v[196:199], v150 offset:39936
	global_load_lds_dwordx4 v[200:201], off
	v_lshl_add_u64 v[200:201], s[38:39], 0, v[132:133]
	s_mov_b32 m0, s49
	s_nop 0
	global_load_lds_dwordx4 v[200:201], off
	s_waitcnt lgkmcnt(8)
	s_setprio 1
	s_barrier
	s_waitcnt lgkmcnt(0)
	v_mfma_f32_16x16x32_bf16 v[124:127], v[152:155], v[168:171], v[124:127]
	v_mfma_f32_16x16x32_bf16 v[120:123], v[160:163], v[168:171], v[120:123]
	v_mfma_f32_16x16x32_bf16 v[112:115], v[152:155], v[176:179], v[112:115]
	v_mfma_f32_16x16x32_bf16 v[104:107], v[160:163], v[176:179], v[104:107]
	v_mfma_f32_16x16x32_bf16 v[96:99], v[152:155], v[184:187], v[96:99]
	v_mfma_f32_16x16x32_bf16 v[88:91], v[160:163], v[184:187], v[88:91]
	v_mfma_f32_16x16x32_bf16 v[80:83], v[152:155], v[192:195], v[80:83]
	v_mfma_f32_16x16x32_bf16 v[72:75], v[160:163], v[192:195], v[72:75]
	v_mfma_f32_16x16x32_bf16 v[124:127], v[156:159], v[172:175], v[124:127]
	v_mfma_f32_16x16x32_bf16 v[120:123], v[164:167], v[172:175], v[120:123]
	v_mfma_f32_16x16x32_bf16 v[112:115], v[156:159], v[180:183], v[112:115]
	v_mfma_f32_16x16x32_bf16 v[104:107], v[164:167], v[180:183], v[104:107]
	v_mfma_f32_16x16x32_bf16 v[96:99], v[156:159], v[188:191], v[96:99]
	v_mfma_f32_16x16x32_bf16 v[88:91], v[164:167], v[188:191], v[88:91]
	v_mfma_f32_16x16x32_bf16 v[80:83], v[156:159], v[196:199], v[80:83]
	v_mfma_f32_16x16x32_bf16 v[72:75], v[164:167], v[196:199], v[72:75]
	s_setprio 0
	s_barrier
	s_add_i32 s38, 0, 0x1c000
	s_add_i32 s39, s69, s42
	v_add_u32_e32 v211, s38, v147
	v_lshl_add_u64 v[144:145], v[144:145], 0, s[0:1]
	s_mov_b32 m0, s39
	ds_read_b128 v[200:203], v211
	ds_read_b128 v[204:207], v211 offset:1024
	ds_read_b128 v[212:215], v211 offset:2048
	ds_read_b128 v[216:219], v211 offset:3072
	global_load_lds_dwordx4 v[144:145], off
	v_lshl_add_u64 v[144:145], v[208:209], 0, s[0:1]
	s_add_i32 m0, s39, 0x2000
	s_nop 0
	global_load_lds_dwordx4 v[144:145], off
	s_setprio 1
	s_barrier
	s_waitcnt lgkmcnt(0)
	v_mfma_f32_16x16x32_bf16 v[116:119], v[200:203], v[168:171], v[116:119]
	v_mfma_f32_16x16x32_bf16 v[108:111], v[212:215], v[168:171], v[108:111]
	v_mfma_f32_16x16x32_bf16 v[100:103], v[200:203], v[176:179], v[100:103]
	v_mfma_f32_16x16x32_bf16 v[92:95], v[212:215], v[176:179], v[92:95]
	v_mfma_f32_16x16x32_bf16 v[84:87], v[200:203], v[184:187], v[84:87]
	v_mfma_f32_16x16x32_bf16 v[76:79], v[212:215], v[184:187], v[76:79]
	v_mfma_f32_16x16x32_bf16 v[68:71], v[200:203], v[192:195], v[68:71]
	v_mfma_f32_16x16x32_bf16 v[64:67], v[212:215], v[192:195], v[64:67]
	v_mfma_f32_16x16x32_bf16 v[116:119], v[204:207], v[172:175], v[116:119]
	v_mfma_f32_16x16x32_bf16 v[108:111], v[216:219], v[172:175], v[108:111]
	v_mfma_f32_16x16x32_bf16 v[100:103], v[204:207], v[180:183], v[100:103]
	v_mfma_f32_16x16x32_bf16 v[92:95], v[216:219], v[180:183], v[92:95]
	v_mfma_f32_16x16x32_bf16 v[84:87], v[204:207], v[188:191], v[84:87]
	v_mfma_f32_16x16x32_bf16 v[76:79], v[216:219], v[188:191], v[76:79]
	v_mfma_f32_16x16x32_bf16 v[68:71], v[204:207], v[196:199], v[68:71]
	v_mfma_f32_16x16x32_bf16 v[64:67], v[216:219], v[196:199], v[64:67]
	s_setprio 0
	s_mov_b32 m0, s51
	v_lshl_add_u64 v[144:145], v[220:221], 0, s[0:1]
	s_barrier
	ds_read_b128 v[168:171], v150 offset:49152
	ds_read_b128 v[172:175], v150 offset:50176
	ds_read_b128 v[176:179], v150 offset:51200
	ds_read_b128 v[180:183], v150 offset:52224
	ds_read_b128 v[184:187], v150 offset:53248
	ds_read_b128 v[188:191], v150 offset:54272
	ds_read_b128 v[192:195], v150 offset:55296
	ds_read_b128 v[196:199], v150 offset:56320
	global_load_lds_dwordx4 v[144:145], off
	v_lshl_add_u64 v[144:145], v[222:223], 0, s[0:1]
	s_mov_b32 m0, s54
	s_nop 0
	global_load_lds_dwordx4 v[144:145], off
	s_setprio 1
	s_barrier
	s_waitcnt lgkmcnt(0)
	v_mfma_f32_16x16x32_bf16 v[60:63], v[152:155], v[168:171], v[60:63]
	v_mfma_f32_16x16x32_bf16 v[56:59], v[160:163], v[168:171], v[56:59]
	v_mfma_f32_16x16x32_bf16 v[52:55], v[152:155], v[176:179], v[52:55]
	v_mfma_f32_16x16x32_bf16 v[44:47], v[160:163], v[176:179], v[44:47]
	v_mfma_f32_16x16x32_bf16 v[36:39], v[152:155], v[184:187], v[36:39]
	v_mfma_f32_16x16x32_bf16 v[28:31], v[160:163], v[184:187], v[28:31]
	v_mfma_f32_16x16x32_bf16 v[20:23], v[152:155], v[192:195], v[20:23]
	v_mfma_f32_16x16x32_bf16 v[12:15], v[160:163], v[192:195], v[12:15]
	v_mfma_f32_16x16x32_bf16 v[60:63], v[156:159], v[172:175], v[60:63]
	v_mfma_f32_16x16x32_bf16 v[56:59], v[164:167], v[172:175], v[56:59]
	v_mfma_f32_16x16x32_bf16 v[52:55], v[156:159], v[180:183], v[52:55]
	v_mfma_f32_16x16x32_bf16 v[44:47], v[164:167], v[180:183], v[44:47]
	v_mfma_f32_16x16x32_bf16 v[36:39], v[156:159], v[188:191], v[36:39]
	v_mfma_f32_16x16x32_bf16 v[28:31], v[164:167], v[188:191], v[28:31]
	v_mfma_f32_16x16x32_bf16 v[20:23], v[156:159], v[196:199], v[20:23]
	v_mfma_f32_16x16x32_bf16 v[12:15], v[164:167], v[196:199], v[12:15]
	s_setprio 0
	s_barrier
	s_add_u32 s36, s36, 0x40080
	s_addc_u32 s37, s37, 0
	s_add_i32 s38, s38, s42
	v_lshl_add_u64 v[144:145], s[36:37], 0, v[130:131]
	s_mov_b32 m0, s38
	s_nop 0
	global_load_lds_dwordx4 v[144:145], off
	v_lshl_add_u64 v[144:145], s[36:37], 0, v[134:135]
	s_add_i32 m0, s38, 0x2000
	s_nop 0
	global_load_lds_dwordx4 v[144:145], off
	s_waitcnt vmcnt(6)
	s_setprio 1
	s_barrier
	v_mfma_f32_16x16x32_bf16 v[48:51], v[200:203], v[168:171], v[48:51]
	v_mfma_f32_16x16x32_bf16 v[40:43], v[212:215], v[168:171], v[40:43]
	v_mfma_f32_16x16x32_bf16 v[32:35], v[200:203], v[176:179], v[32:35]
	v_mfma_f32_16x16x32_bf16 v[24:27], v[212:215], v[176:179], v[24:27]
	v_mfma_f32_16x16x32_bf16 v[16:19], v[200:203], v[184:187], v[16:19]
	v_mfma_f32_16x16x32_bf16 v[8:11], v[212:215], v[184:187], v[8:11]
	v_mfma_f32_16x16x32_bf16 v[4:7], v[200:203], v[192:195], v[4:7]
	v_mfma_f32_16x16x32_bf16 v[0:3], v[212:215], v[192:195], v[0:3]
	v_mfma_f32_16x16x32_bf16 v[48:51], v[204:207], v[172:175], v[48:51]
	v_mfma_f32_16x16x32_bf16 v[40:43], v[216:219], v[172:175], v[40:43]
	v_mfma_f32_16x16x32_bf16 v[32:35], v[204:207], v[180:183], v[32:35]
	v_mfma_f32_16x16x32_bf16 v[24:27], v[216:219], v[180:183], v[24:27]
	v_mfma_f32_16x16x32_bf16 v[16:19], v[204:207], v[188:191], v[16:19]
	v_mfma_f32_16x16x32_bf16 v[8:11], v[216:219], v[188:191], v[8:11]
	v_mfma_f32_16x16x32_bf16 v[4:7], v[204:207], v[196:199], v[4:7]
	v_mfma_f32_16x16x32_bf16 v[0:3], v[216:219], v[196:199], v[0:3]
	s_setprio 0
	s_add_i32 s68, s68, 2
	s_add_u32 s34, s34, 0x100
	s_addc_u32 s35, s35, 0
	s_add_u32 s66, s66, 0x100
	s_addc_u32 s67, s67, 0
	s_cmp_gt_u32 s68, 13
	s_barrier
	s_cbranch_scc0 .LBB0_177
	v_lshl_add_u32 v152, s12, 8, v146
	v_ashrrev_i32_e32 v153, 31, v152
	v_lshl_or_b32 v144, s63, 8, v148
	v_readlane_b32 s34, v253, 61
	v_ashrrev_i32_e32 v145, 31, v144
	v_lshlrev_b64 v[154:155], 17, v[152:153]
	v_readlane_b32 s35, v253, 62
	v_lshlrev_b64 v[156:157], 1, v[144:145]
	v_cvt_pk_bf16_f32 v124, v124, v125
	v_cvt_pk_bf16_f32 v125, v126, v127
	v_cvt_pk_bf16_f32 v126, v120, v121
	s_nop 0
	v_lshl_add_u64 v[154:155], s[34:35], 0, v[154:155]
	v_lshl_add_u64 v[144:145], v[154:155], 0, v[156:157]
	v_cvt_pk_bf16_f32 v127, v122, v123
	global_store_dwordx4 v[144:145], v[124:127], off nt
	v_cvt_pk_bf16_f32 v116, v116, v117
	v_cvt_pk_bf16_f32 v117, v118, v119
	v_cvt_pk_bf16_f32 v118, v108, v109
	v_or_b32_e32 v108, 16, v152
	v_ashrrev_i32_e32 v109, 31, v108
	v_lshlrev_b64 v[108:109], 17, v[108:109]
	v_lshl_add_u64 v[108:109], s[34:35], 0, v[108:109]
	v_cvt_pk_bf16_f32 v119, v110, v111
	global_store_dwordx4 v[144:145], v[116:119], off offset:256 nt
	s_mov_b32 s3, 0x1000000
	s_mov_b32 s63, s2
	v_lshl_add_u64 v[116:117], v[108:109], 0, v[156:157]
	v_cvt_pk_bf16_f32 v108, v112, v113
	v_cvt_pk_bf16_f32 v109, v114, v115
	v_cvt_pk_bf16_f32 v110, v104, v105
	v_cvt_pk_bf16_f32 v111, v106, v107
	global_store_dwordx4 v[116:117], v[108:111], off nt
	v_cvt_pk_bf16_f32 v100, v100, v101
	v_cvt_pk_bf16_f32 v101, v102, v103
	v_cvt_pk_bf16_f32 v102, v92, v93
	v_or_b32_e32 v92, 32, v152
	v_ashrrev_i32_e32 v93, 31, v92
	v_lshlrev_b64 v[92:93], 17, v[92:93]
	v_lshl_add_u64 v[92:93], s[34:35], 0, v[92:93]
	v_cvt_pk_bf16_f32 v103, v94, v95
	global_store_dwordx4 v[116:117], v[100:103], off offset:256 nt
	s_mov_b32 s12, s8
	s_mov_b64 s[36:37], s[30:31]
	v_lshl_add_u64 v[100:101], v[92:93], 0, v[156:157]
	v_cvt_pk_bf16_f32 v92, v96, v97
	v_cvt_pk_bf16_f32 v93, v98, v99
	v_cvt_pk_bf16_f32 v94, v88, v89
	v_cvt_pk_bf16_f32 v95, v90, v91
	global_store_dwordx4 v[100:101], v[92:95], off nt
	v_cvt_pk_bf16_f32 v84, v84, v85
	v_cvt_pk_bf16_f32 v85, v86, v87
	v_cvt_pk_bf16_f32 v86, v76, v77
	v_or_b32_e32 v76, 48, v152
	v_ashrrev_i32_e32 v77, 31, v76
	v_lshlrev_b64 v[76:77], 17, v[76:77]
	v_lshl_add_u64 v[76:77], s[34:35], 0, v[76:77]
	v_cvt_pk_bf16_f32 v87, v78, v79
	global_store_dwordx4 v[100:101], v[84:87], off offset:256 nt
	s_mov_b64 s[34:35], 0x1000000
	s_nop 0
	v_lshl_add_u64 v[84:85], v[76:77], 0, v[156:157]
	v_cvt_pk_bf16_f32 v76, v80, v81
	v_cvt_pk_bf16_f32 v77, v82, v83
	v_cvt_pk_bf16_f32 v78, v72, v73
	v_cvt_pk_bf16_f32 v79, v74, v75
	global_store_dwordx4 v[84:85], v[76:79], off nt
	v_cvt_pk_bf16_f32 v68, v68, v69
	v_cvt_pk_bf16_f32 v69, v70, v71
	v_cvt_pk_bf16_f32 v70, v64, v65
	v_cvt_pk_bf16_f32 v71, v66, v67
	global_store_dwordx4 v[84:85], v[68:71], off offset:256 nt
	v_cvt_pk_bf16_f32 v60, v60, v61
	v_cvt_pk_bf16_f32 v61, v62, v63
	v_cvt_pk_bf16_f32 v62, v56, v57
	v_add_co_u32_e32 v56, vcc, s3, v144
	v_lshl_add_u64 v[64:65], v[144:145], 0, s[34:35]
	s_nop 0
	v_addc_co_u32_e32 v57, vcc, 0, v145, vcc
	s_mov_b32 s3, 0x1200000
	v_cvt_pk_bf16_f32 v63, v58, v59
	global_store_dwordx4 v[56:57], v[60:63], off nt
	v_cvt_pk_bf16_f32 v48, v48, v49
	v_cvt_pk_bf16_f32 v49, v50, v51
	v_cvt_pk_bf16_f32 v50, v40, v41
	v_cvt_pk_bf16_f32 v51, v42, v43
	global_store_dwordx4 v[64:65], v[48:51], off offset:256 nt
	s_mov_b64 s[34:35], 0x1200000
	v_cvt_pk_bf16_f32 v40, v52, v53
	v_cvt_pk_bf16_f32 v41, v54, v55
	v_cvt_pk_bf16_f32 v42, v44, v45
	v_add_co_u32_e32 v44, vcc, s3, v144
	v_lshl_add_u64 v[48:49], v[144:145], 0, s[34:35]
	s_nop 0
	v_addc_co_u32_e32 v45, vcc, 0, v145, vcc
	s_mov_b32 s3, 0x1400000
	v_cvt_pk_bf16_f32 v43, v46, v47
	global_store_dwordx4 v[44:45], v[40:43], off nt
	v_cvt_pk_bf16_f32 v32, v32, v33
	v_cvt_pk_bf16_f32 v33, v34, v35
	v_cvt_pk_bf16_f32 v34, v24, v25
	v_cvt_pk_bf16_f32 v35, v26, v27
	global_store_dwordx4 v[48:49], v[32:35], off offset:256 nt
	s_mov_b64 s[34:35], 0x1400000
	v_cvt_pk_bf16_f32 v24, v36, v37
	v_cvt_pk_bf16_f32 v25, v38, v39
	v_cvt_pk_bf16_f32 v26, v28, v29
	v_add_co_u32_e32 v28, vcc, s3, v144
	v_lshl_add_u64 v[32:33], v[144:145], 0, s[34:35]
	s_nop 0
	v_addc_co_u32_e32 v29, vcc, 0, v145, vcc
	s_mov_b32 s3, 0x1600000
	v_cvt_pk_bf16_f32 v27, v30, v31
	global_store_dwordx4 v[28:29], v[24:27], off nt
	v_cvt_pk_bf16_f32 v16, v16, v17
	v_cvt_pk_bf16_f32 v17, v18, v19
	v_cvt_pk_bf16_f32 v18, v8, v9
	v_cvt_pk_bf16_f32 v19, v10, v11
	global_store_dwordx4 v[32:33], v[16:19], off offset:256 nt
	v_cvt_pk_bf16_f32 v8, v20, v21
	v_cvt_pk_bf16_f32 v9, v22, v23
	v_cvt_pk_bf16_f32 v10, v12, v13
	v_add_co_u32_e32 v12, vcc, s3, v144
	s_mov_b64 s[34:35], 0x1600000
	s_nop 0
	v_addc_co_u32_e32 v13, vcc, 0, v145, vcc
	v_lshl_add_u64 v[16:17], v[144:145], 0, s[34:35]
	s_and_b64 vcc, exec, s[4:5]
	s_mov_b64 s[34:35], s[14:15]
	v_cvt_pk_bf16_f32 v11, v14, v15
	global_store_dwordx4 v[12:13], v[8:11], off nt
	v_cvt_pk_bf16_f32 v4, v4, v5
	v_cvt_pk_bf16_f32 v5, v6, v7
	v_cvt_pk_bf16_f32 v6, v0, v1
	v_cvt_pk_bf16_f32 v7, v2, v3
	global_store_dwordx4 v[16:17], v[4:7], off offset:256 nt
	s_cbranch_vccz .LBB0_170
	s_waitcnt vmcnt(0)
	s_cmpk_gt_u32 s40, 0xff
	s_cbranch_scc1 .LBB0_181
	s_barrier

.LBB0_200:
	s_add_u32 s48, s42, 0xfffc0080
	s_addc_u32 s49, s43, -1
	s_add_i32 s81, 0, 0x10000
	v_add_u32_e32 v140, s81, v144
	ds_read_b128 v[148:151], v140
	ds_read_b128 v[152:155], v140 offset:1024
	ds_read_b128 v[156:159], v140 offset:2048
	ds_read_b128 v[160:163], v140 offset:3072
	s_cmp_eq_u32 s80, 12
	s_cselect_b32 s51, s35, s49
	s_cselect_b32 s50, s76, s48
	s_cselect_b32 s49, s31, s79
	s_cselect_b32 s48, s77, s78
	v_lshl_add_u64 v[140:141], s[42:43], 0, v[136:137]
	s_add_i32 m0, s37, 0xc000
	ds_read_b128 v[164:167], v146
	ds_read_b128 v[168:171], v146 offset:1024
	ds_read_b128 v[172:175], v146 offset:2048
	ds_read_b128 v[176:179], v146 offset:3072
	ds_read_b128 v[180:183], v146 offset:4096
	ds_read_b128 v[184:187], v146 offset:5120
	ds_read_b128 v[188:191], v146 offset:6144
	ds_read_b128 v[192:195], v146 offset:7168
	global_load_lds_dwordx4 v[140:141], off
	v_lshl_add_u64 v[140:141], s[42:43], 0, v[138:139]
	s_add_i32 m0, s37, 0xe000
	s_nop 0
	global_load_lds_dwordx4 v[140:141], off
	s_waitcnt lgkmcnt(8)
	s_setprio 1
	s_barrier
	s_waitcnt lgkmcnt(0)
	v_mfma_f32_16x16x32_bf16 v[124:127], v[148:151], v[164:167], v[124:127]
	v_mfma_f32_16x16x32_bf16 v[120:123], v[156:159], v[164:167], v[120:123]
	v_mfma_f32_16x16x32_bf16 v[116:119], v[148:151], v[172:175], v[116:119]
	v_mfma_f32_16x16x32_bf16 v[108:111], v[156:159], v[172:175], v[108:111]
	v_mfma_f32_16x16x32_bf16 v[100:103], v[148:151], v[180:183], v[100:103]
	v_mfma_f32_16x16x32_bf16 v[92:95], v[156:159], v[180:183], v[92:95]
	v_mfma_f32_16x16x32_bf16 v[84:87], v[148:151], v[188:191], v[84:87]
	v_mfma_f32_16x16x32_bf16 v[76:79], v[156:159], v[188:191], v[76:79]
	v_mfma_f32_16x16x32_bf16 v[124:127], v[152:155], v[168:171], v[124:127]
	v_mfma_f32_16x16x32_bf16 v[120:123], v[160:163], v[168:171], v[120:123]
	v_mfma_f32_16x16x32_bf16 v[116:119], v[152:155], v[176:179], v[116:119]
	v_mfma_f32_16x16x32_bf16 v[108:111], v[160:163], v[176:179], v[108:111]
	v_mfma_f32_16x16x32_bf16 v[100:103], v[152:155], v[184:187], v[100:103]
	v_mfma_f32_16x16x32_bf16 v[92:95], v[160:163], v[184:187], v[92:95]
	v_mfma_f32_16x16x32_bf16 v[84:87], v[152:155], v[192:195], v[84:87]
	v_mfma_f32_16x16x32_bf16 v[76:79], v[160:163], v[192:195], v[76:79]
	s_setprio 0
	s_barrier
	s_add_i32 s84, 0, 0x14000
	v_add_u32_e32 v140, s84, v144
	s_add_i32 s81, s81, s69
	ds_read_b128 v[196:199], v140
	ds_read_b128 v[200:203], v140 offset:1024
	ds_read_b128 v[204:207], v140 offset:2048
	ds_read_b128 v[212:215], v140 offset:3072
	v_lshl_add_u64 v[140:141], s[48:49], 0, v[128:129]
	s_mov_b32 m0, s81
	v_lshl_add_u64 v[208:209], s[48:49], 0, v[134:135]
	global_load_lds_dwordx4 v[140:141], off
	s_add_i32 m0, s81, 0x2000
	s_nop 0
	global_load_lds_dwordx4 v[208:209], off
	s_setprio 1
	s_barrier
	s_waitcnt lgkmcnt(0)
	v_mfma_f32_16x16x32_bf16 v[112:115], v[196:199], v[164:167], v[112:115]
	v_mfma_f32_16x16x32_bf16 v[104:107], v[204:207], v[164:167], v[104:107]
	v_mfma_f32_16x16x32_bf16 v[96:99], v[196:199], v[172:175], v[96:99]
	v_mfma_f32_16x16x32_bf16 v[88:91], v[204:207], v[172:175], v[88:91]
	v_mfma_f32_16x16x32_bf16 v[80:83], v[196:199], v[180:183], v[80:83]
	v_mfma_f32_16x16x32_bf16 v[72:75], v[204:207], v[180:183], v[72:75]
	v_mfma_f32_16x16x32_bf16 v[68:71], v[196:199], v[188:191], v[68:71]
	v_mfma_f32_16x16x32_bf16 v[64:67], v[204:207], v[188:191], v[64:67]
	v_mfma_f32_16x16x32_bf16 v[112:115], v[200:203], v[168:171], v[112:115]
	v_mfma_f32_16x16x32_bf16 v[104:107], v[212:215], v[168:171], v[104:107]
	v_mfma_f32_16x16x32_bf16 v[96:99], v[200:203], v[176:179], v[96:99]
	v_mfma_f32_16x16x32_bf16 v[88:91], v[212:215], v[176:179], v[88:91]
	v_mfma_f32_16x16x32_bf16 v[80:83], v[200:203], v[184:187], v[80:83]
	v_mfma_f32_16x16x32_bf16 v[72:75], v[212:215], v[184:187], v[72:75]
	v_mfma_f32_16x16x32_bf16 v[68:71], v[200:203], v[192:195], v[68:71]
	v_mfma_f32_16x16x32_bf16 v[64:67], v[212:215], v[192:195], v[64:67]
	s_setprio 0
	s_mov_b32 m0, s37
	v_lshl_add_u64 v[216:217], s[50:51], 0, v[130:131]
	s_barrier
	ds_read_b128 v[164:167], v146 offset:16384
	ds_read_b128 v[168:171], v146 offset:17408
	ds_read_b128 v[172:175], v146 offset:18432
	ds_read_b128 v[176:179], v146 offset:19456
	ds_read_b128 v[180:183], v146 offset:20480
	ds_read_b128 v[184:187], v146 offset:21504
	ds_read_b128 v[188:191], v146 offset:22528
	ds_read_b128 v[192:195], v146 offset:23552
	global_load_lds_dwordx4 v[216:217], off
	v_lshl_add_u64 v[218:219], s[50:51], 0, v[132:133]
	s_mov_b32 m0, s70
	s_nop 0
	global_load_lds_dwordx4 v[218:219], off
	s_setprio 1
	s_barrier
	s_waitcnt lgkmcnt(0)
	v_mfma_f32_16x16x32_bf16 v[60:63], v[148:151], v[164:167], v[60:63]
	v_mfma_f32_16x16x32_bf16 v[56:59], v[156:159], v[164:167], v[56:59]
	v_mfma_f32_16x16x32_bf16 v[52:55], v[148:151], v[172:175], v[52:55]
	v_mfma_f32_16x16x32_bf16 v[44:47], v[156:159], v[172:175], v[44:47]
	v_mfma_f32_16x16x32_bf16 v[36:39], v[148:151], v[180:183], v[36:39]
	v_mfma_f32_16x16x32_bf16 v[28:31], v[156:159], v[180:183], v[28:31]
	v_mfma_f32_16x16x32_bf16 v[20:23], v[148:151], v[188:191], v[20:23]
	v_mfma_f32_16x16x32_bf16 v[12:15], v[156:159], v[188:191], v[12:15]
	v_mfma_f32_16x16x32_bf16 v[60:63], v[152:155], v[168:171], v[60:63]
	v_mfma_f32_16x16x32_bf16 v[56:59], v[160:163], v[168:171], v[56:59]
	v_mfma_f32_16x16x32_bf16 v[52:55], v[152:155], v[176:179], v[52:55]
	v_mfma_f32_16x16x32_bf16 v[44:47], v[160:163], v[176:179], v[44:47]
	v_mfma_f32_16x16x32_bf16 v[36:39], v[152:155], v[184:187], v[36:39]
	v_mfma_f32_16x16x32_bf16 v[28:31], v[160:163], v[184:187], v[28:31]
	v_mfma_f32_16x16x32_bf16 v[20:23], v[152:155], v[192:195], v[20:23]
	v_mfma_f32_16x16x32_bf16 v[12:15], v[160:163], v[192:195], v[12:15]
	s_setprio 0
	s_barrier
	s_add_u32 s82, s48, 0x40000
	s_addc_u32 s83, s49, 0
	s_add_i32 s81, s84, s69
	v_lshl_add_u64 v[148:149], s[82:83], 0, v[128:129]
	s_mov_b32 m0, s81
	s_nop 0
	global_load_lds_dwordx4 v[148:149], off
	v_lshl_add_u64 v[148:149], s[82:83], 0, v[134:135]
	s_add_i32 m0, s81, 0x2000
	s_nop 0
	global_load_lds_dwordx4 v[148:149], off
	s_waitcnt vmcnt(6)
	s_setprio 1
	s_barrier
	v_mfma_f32_16x16x32_bf16 v[48:51], v[196:199], v[164:167], v[48:51]
	v_mfma_f32_16x16x32_bf16 v[40:43], v[204:207], v[164:167], v[40:43]
	v_mfma_f32_16x16x32_bf16 v[32:35], v[196:199], v[172:175], v[32:35]
	v_mfma_f32_16x16x32_bf16 v[24:27], v[204:207], v[172:175], v[24:27]
	v_mfma_f32_16x16x32_bf16 v[16:19], v[196:199], v[180:183], v[16:19]
	v_mfma_f32_16x16x32_bf16 v[8:11], v[204:207], v[180:183], v[8:11]
	v_mfma_f32_16x16x32_bf16 v[4:7], v[196:199], v[188:191], v[4:7]
	v_mfma_f32_16x16x32_bf16 v[0:3], v[204:207], v[188:191], v[0:3]
	v_mfma_f32_16x16x32_bf16 v[48:51], v[200:203], v[168:171], v[48:51]
	v_mfma_f32_16x16x32_bf16 v[40:43], v[212:215], v[168:171], v[40:43]
	v_mfma_f32_16x16x32_bf16 v[32:35], v[200:203], v[176:179], v[32:35]
	v_mfma_f32_16x16x32_bf16 v[24:27], v[212:215], v[176:179], v[24:27]
	v_mfma_f32_16x16x32_bf16 v[16:19], v[200:203], v[184:187], v[16:19]
	v_mfma_f32_16x16x32_bf16 v[8:11], v[212:215], v[184:187], v[8:11]
	v_mfma_f32_16x16x32_bf16 v[4:7], v[200:203], v[192:195], v[4:7]
	v_mfma_f32_16x16x32_bf16 v[0:3], v[212:215], v[192:195], v[0:3]
	s_setprio 0
	s_add_i32 s81, 0, 0x18000
	v_add_u32_e32 v147, s81, v144
	s_barrier
	ds_read_b128 v[148:151], v147
	ds_read_b128 v[152:155], v147 offset:1024
	ds_read_b128 v[156:159], v147 offset:2048
	ds_read_b128 v[160:163], v147 offset:3072
	s_add_u32 s50, s50, 0x40000
	s_addc_u32 s51, s51, 0
	s_mov_b32 m0, s71
	v_lshl_add_u64 v[196:197], s[50:51], 0, v[130:131]
	ds_read_b128 v[164:167], v146 offset:32768
	ds_read_b128 v[168:171], v146 offset:33792
	ds_read_b128 v[172:175], v146 offset:34816
	ds_read_b128 v[176:179], v146 offset:35840
	ds_read_b128 v[180:183], v146 offset:36864
	ds_read_b128 v[184:187], v146 offset:37888
	ds_read_b128 v[188:191], v146 offset:38912
	ds_read_b128 v[192:195], v146 offset:39936
	global_load_lds_dwordx4 v[196:197], off
	v_lshl_add_u64 v[196:197], s[50:51], 0, v[132:133]
	s_mov_b32 m0, s72
	s_nop 0
	global_load_lds_dwordx4 v[196:197], off
	s_waitcnt lgkmcnt(8)
	s_setprio 1
	s_barrier
	s_waitcnt lgkmcnt(0)
	v_mfma_f32_16x16x32_bf16 v[124:127], v[148:151], v[164:167], v[124:127]
	v_mfma_f32_16x16x32_bf16 v[120:123], v[156:159], v[164:167], v[120:123]
	v_mfma_f32_16x16x32_bf16 v[116:119], v[148:151], v[172:175], v[116:119]
	v_mfma_f32_16x16x32_bf16 v[108:111], v[156:159], v[172:175], v[108:111]
	v_mfma_f32_16x16x32_bf16 v[100:103], v[148:151], v[180:183], v[100:103]
	v_mfma_f32_16x16x32_bf16 v[92:95], v[156:159], v[180:183], v[92:95]
	v_mfma_f32_16x16x32_bf16 v[84:87], v[148:151], v[188:191], v[84:87]
	v_mfma_f32_16x16x32_bf16 v[76:79], v[156:159], v[188:191], v[76:79]
	v_mfma_f32_16x16x32_bf16 v[124:127], v[152:155], v[168:171], v[124:127]
	v_mfma_f32_16x16x32_bf16 v[120:123], v[160:163], v[168:171], v[120:123]
	v_mfma_f32_16x16x32_bf16 v[116:119], v[152:155], v[176:179], v[116:119]
	v_mfma_f32_16x16x32_bf16 v[108:111], v[160:163], v[176:179], v[108:111]
	v_mfma_f32_16x16x32_bf16 v[100:103], v[152:155], v[184:187], v[100:103]
	v_mfma_f32_16x16x32_bf16 v[92:95], v[160:163], v[184:187], v[92:95]
	v_mfma_f32_16x16x32_bf16 v[84:87], v[152:155], v[192:195], v[84:87]
	v_mfma_f32_16x16x32_bf16 v[76:79], v[160:163], v[192:195], v[76:79]
	s_setprio 0
	s_barrier
	s_add_i32 s50, 0, 0x1c000
	s_add_i32 s51, s81, s69
	v_add_u32_e32 v147, s50, v144
	v_lshl_add_u64 v[140:141], v[140:141], 0, s[2:3]
	s_mov_b32 m0, s51
	ds_read_b128 v[196:199], v147
	ds_read_b128 v[200:203], v147 offset:1024
	ds_read_b128 v[204:207], v147 offset:2048
	ds_read_b128 v[212:215], v147 offset:3072
	global_load_lds_dwordx4 v[140:141], off
	v_lshl_add_u64 v[140:141], v[208:209], 0, s[2:3]
	s_add_i32 m0, s51, 0x2000
	s_nop 0
	global_load_lds_dwordx4 v[140:141], off
	s_setprio 1
	s_barrier
	s_waitcnt lgkmcnt(0)
	v_mfma_f32_16x16x32_bf16 v[112:115], v[196:199], v[164:167], v[112:115]
	v_mfma_f32_16x16x32_bf16 v[104:107], v[204:207], v[164:167], v[104:107]
	v_mfma_f32_16x16x32_bf16 v[96:99], v[196:199], v[172:175], v[96:99]
	v_mfma_f32_16x16x32_bf16 v[88:91], v[204:207], v[172:175], v[88:91]
	v_mfma_f32_16x16x32_bf16 v[80:83], v[196:199], v[180:183], v[80:83]
	v_mfma_f32_16x16x32_bf16 v[72:75], v[204:207], v[180:183], v[72:75]
	v_mfma_f32_16x16x32_bf16 v[68:71], v[196:199], v[188:191], v[68:71]
	v_mfma_f32_16x16x32_bf16 v[64:67], v[204:207], v[188:191], v[64:67]
	v_mfma_f32_16x16x32_bf16 v[112:115], v[200:203], v[168:171], v[112:115]
	v_mfma_f32_16x16x32_bf16 v[104:107], v[212:215], v[168:171], v[104:107]
	v_mfma_f32_16x16x32_bf16 v[96:99], v[200:203], v[176:179], v[96:99]
	v_mfma_f32_16x16x32_bf16 v[88:91], v[212:215], v[176:179], v[88:91]
	v_mfma_f32_16x16x32_bf16 v[80:83], v[200:203], v[184:187], v[80:83]
	v_mfma_f32_16x16x32_bf16 v[72:75], v[212:215], v[184:187], v[72:75]
	v_mfma_f32_16x16x32_bf16 v[68:71], v[200:203], v[192:195], v[68:71]
	v_mfma_f32_16x16x32_bf16 v[64:67], v[212:215], v[192:195], v[64:67]
	s_setprio 0
	s_mov_b32 m0, s0
	v_lshl_add_u64 v[140:141], v[216:217], 0, s[2:3]
	s_barrier
	ds_read_b128 v[164:167], v146 offset:49152
	ds_read_b128 v[168:171], v146 offset:50176
	ds_read_b128 v[172:175], v146 offset:51200
	ds_read_b128 v[176:179], v146 offset:52224
	ds_read_b128 v[180:183], v146 offset:53248
	ds_read_b128 v[184:187], v146 offset:54272
	ds_read_b128 v[188:191], v146 offset:55296
	ds_read_b128 v[192:195], v146 offset:56320
	global_load_lds_dwordx4 v[140:141], off
	v_lshl_add_u64 v[140:141], v[218:219], 0, s[2:3]
	s_mov_b32 m0, s73
	s_nop 0
	global_load_lds_dwordx4 v[140:141], off
	s_setprio 1
	s_barrier
	s_waitcnt lgkmcnt(0)
	v_mfma_f32_16x16x32_bf16 v[60:63], v[148:151], v[164:167], v[60:63]
	v_mfma_f32_16x16x32_bf16 v[56:59], v[156:159], v[164:167], v[56:59]
	v_mfma_f32_16x16x32_bf16 v[52:55], v[148:151], v[172:175], v[52:55]
	v_mfma_f32_16x16x32_bf16 v[44:47], v[156:159], v[172:175], v[44:47]
	v_mfma_f32_16x16x32_bf16 v[36:39], v[148:151], v[180:183], v[36:39]
	v_mfma_f32_16x16x32_bf16 v[28:31], v[156:159], v[180:183], v[28:31]
	v_mfma_f32_16x16x32_bf16 v[20:23], v[148:151], v[188:191], v[20:23]
	v_mfma_f32_16x16x32_bf16 v[12:15], v[156:159], v[188:191], v[12:15]
	v_mfma_f32_16x16x32_bf16 v[60:63], v[152:155], v[168:171], v[60:63]
	v_mfma_f32_16x16x32_bf16 v[56:59], v[160:163], v[168:171], v[56:59]
	v_mfma_f32_16x16x32_bf16 v[52:55], v[152:155], v[176:179], v[52:55]
	v_mfma_f32_16x16x32_bf16 v[44:47], v[160:163], v[176:179], v[44:47]
	v_mfma_f32_16x16x32_bf16 v[36:39], v[152:155], v[184:187], v[36:39]
	v_mfma_f32_16x16x32_bf16 v[28:31], v[160:163], v[184:187], v[28:31]
	v_mfma_f32_16x16x32_bf16 v[20:23], v[152:155], v[192:195], v[20:23]
	v_mfma_f32_16x16x32_bf16 v[12:15], v[160:163], v[192:195], v[12:15]
	s_setprio 0
	s_barrier
	s_add_u32 s48, s48, 0x40080
	s_addc_u32 s49, s49, 0
	s_add_i32 s50, s50, s69
	v_lshl_add_u64 v[140:141], s[48:49], 0, v[128:129]
	s_mov_b32 m0, s50
	s_nop 0
	global_load_lds_dwordx4 v[140:141], off
	v_lshl_add_u64 v[140:141], s[48:49], 0, v[134:135]
	s_add_i32 m0, s50, 0x2000
	s_nop 0
	global_load_lds_dwordx4 v[140:141], off
	s_waitcnt vmcnt(6)
	s_setprio 1
	s_barrier
	v_mfma_f32_16x16x32_bf16 v[48:51], v[196:199], v[164:167], v[48:51]
	v_mfma_f32_16x16x32_bf16 v[40:43], v[204:207], v[164:167], v[40:43]
	v_mfma_f32_16x16x32_bf16 v[32:35], v[196:199], v[172:175], v[32:35]
	v_mfma_f32_16x16x32_bf16 v[24:27], v[204:207], v[172:175], v[24:27]
	v_mfma_f32_16x16x32_bf16 v[16:19], v[196:199], v[180:183], v[16:19]
	v_mfma_f32_16x16x32_bf16 v[8:11], v[204:207], v[180:183], v[8:11]
	v_mfma_f32_16x16x32_bf16 v[4:7], v[196:199], v[188:191], v[4:7]
	v_mfma_f32_16x16x32_bf16 v[0:3], v[204:207], v[188:191], v[0:3]
	v_mfma_f32_16x16x32_bf16 v[48:51], v[200:203], v[168:171], v[48:51]
	v_mfma_f32_16x16x32_bf16 v[40:43], v[212:215], v[168:171], v[40:43]
	v_mfma_f32_16x16x32_bf16 v[32:35], v[200:203], v[176:179], v[32:35]
	v_mfma_f32_16x16x32_bf16 v[24:27], v[212:215], v[176:179], v[24:27]
	v_mfma_f32_16x16x32_bf16 v[16:19], v[200:203], v[184:187], v[16:19]
	v_mfma_f32_16x16x32_bf16 v[8:11], v[212:215], v[184:187], v[8:11]
	v_mfma_f32_16x16x32_bf16 v[4:7], v[200:203], v[192:195], v[4:7]
	v_mfma_f32_16x16x32_bf16 v[0:3], v[212:215], v[192:195], v[0:3]
	s_setprio 0
	s_add_i32 s80, s80, 2
	s_add_u32 s42, s42, 0x100
	s_addc_u32 s43, s43, 0
	s_add_u32 s78, s78, 0x100
	s_addc_u32 s79, s79, 0
	s_cmp_gt_u32 s80, 13
	s_barrier
	s_cbranch_scc0 .LBB0_200
	v_lshl_add_u32 v148, s36, 8, v143
	v_ashrrev_i32_e32 v149, 31, v148
	v_lshl_or_b32 v140, s75, 8, v145
	v_ashrrev_i32_e32 v141, 31, v140
	v_lshlrev_b64 v[150:151], 10, v[148:149]
	v_lshl_add_u64 v[150:151], s[14:15], 0, v[150:151]
	v_lshlrev_b64 v[152:153], 1, v[140:141]
	v_lshl_add_u64 v[140:141], v[150:151], 0, v[152:153]
	v_cvt_pk_bf16_f32 v124, v124, v125
	v_cvt_pk_bf16_f32 v125, v126, v127
	v_cvt_pk_bf16_f32 v126, v120, v121
	v_cvt_pk_bf16_f32 v127, v122, v123
	global_store_dwordx4 v[140:141], v[124:127], off nt
	v_cvt_pk_bf16_f32 v112, v112, v113
	v_cvt_pk_bf16_f32 v113, v114, v115
	v_cvt_pk_bf16_f32 v114, v104, v105
	v_or_b32_e32 v104, 16, v148
	v_ashrrev_i32_e32 v105, 31, v104
	v_lshlrev_b64 v[104:105], 10, v[104:105]
	v_lshl_add_u64 v[104:105], s[14:15], 0, v[104:105]
	v_cvt_pk_bf16_f32 v115, v106, v107
	global_store_dwordx4 v[140:141], v[112:115], off offset:256 nt
	s_mov_b32 s31, 0x20000
	s_mov_b64 s[42:43], 0x20000
	v_lshl_add_u64 v[112:113], v[104:105], 0, v[152:153]
	v_cvt_pk_bf16_f32 v104, v116, v117
	v_cvt_pk_bf16_f32 v105, v118, v119
	v_cvt_pk_bf16_f32 v106, v108, v109
	v_cvt_pk_bf16_f32 v107, v110, v111
	global_store_dwordx4 v[112:113], v[104:107], off nt
	v_cvt_pk_bf16_f32 v96, v96, v97
	v_cvt_pk_bf16_f32 v97, v98, v99
	v_cvt_pk_bf16_f32 v98, v88, v89
	v_or_b32_e32 v88, 32, v148
	v_ashrrev_i32_e32 v89, 31, v88
	v_lshlrev_b64 v[88:89], 10, v[88:89]
	v_lshl_add_u64 v[88:89], s[14:15], 0, v[88:89]
	v_cvt_pk_bf16_f32 v99, v90, v91
	global_store_dwordx4 v[112:113], v[96:99], off offset:256 nt
	s_mov_b32 s75, s30
	s_mov_b32 s36, s34
	v_lshl_add_u64 v[96:97], v[88:89], 0, v[152:153]
	v_cvt_pk_bf16_f32 v88, v100, v101
	v_cvt_pk_bf16_f32 v89, v102, v103
	v_cvt_pk_bf16_f32 v90, v92, v93
	v_cvt_pk_bf16_f32 v91, v94, v95
	global_store_dwordx4 v[96:97], v[88:91], off nt
	v_cvt_pk_bf16_f32 v80, v80, v81
	v_cvt_pk_bf16_f32 v81, v82, v83
	v_cvt_pk_bf16_f32 v82, v72, v73
	v_or_b32_e32 v72, 48, v148
	v_ashrrev_i32_e32 v73, 31, v72
	v_lshlrev_b64 v[72:73], 10, v[72:73]
	v_lshl_add_u64 v[72:73], s[14:15], 0, v[72:73]
	v_cvt_pk_bf16_f32 v83, v74, v75
	global_store_dwordx4 v[96:97], v[80:83], off offset:256 nt
	s_mov_b64 s[48:49], s[40:41]
	s_nop 0
	v_lshl_add_u64 v[80:81], v[72:73], 0, v[152:153]
	v_cvt_pk_bf16_f32 v72, v84, v85
	v_cvt_pk_bf16_f32 v73, v86, v87
	v_cvt_pk_bf16_f32 v74, v76, v77
	v_cvt_pk_bf16_f32 v75, v78, v79
	global_store_dwordx4 v[80:81], v[72:75], off nt
	v_cvt_pk_bf16_f32 v68, v68, v69
	v_cvt_pk_bf16_f32 v69, v70, v71
	v_cvt_pk_bf16_f32 v70, v64, v65
	v_cvt_pk_bf16_f32 v71, v66, v67
	global_store_dwordx4 v[80:81], v[68:71], off offset:256 nt
	v_cvt_pk_bf16_f32 v60, v60, v61
	v_cvt_pk_bf16_f32 v61, v62, v63
	v_cvt_pk_bf16_f32 v62, v56, v57
	v_add_co_u32_e32 v56, vcc, s31, v140
	v_lshl_add_u64 v[64:65], v[140:141], 0, s[42:43]
	s_nop 0
	v_addc_co_u32_e32 v57, vcc, 0, v141, vcc
	s_mov_b32 s31, 0x24000
	v_cvt_pk_bf16_f32 v63, v58, v59
	global_store_dwordx4 v[56:57], v[60:63], off nt
	v_cvt_pk_bf16_f32 v48, v48, v49
	v_cvt_pk_bf16_f32 v49, v50, v51
	v_cvt_pk_bf16_f32 v50, v40, v41
	v_cvt_pk_bf16_f32 v51, v42, v43
	global_store_dwordx4 v[64:65], v[48:51], off offset:256 nt
	s_mov_b64 s[42:43], 0x24000
	v_cvt_pk_bf16_f32 v40, v52, v53
	v_cvt_pk_bf16_f32 v41, v54, v55
	v_cvt_pk_bf16_f32 v42, v44, v45
	v_add_co_u32_e32 v44, vcc, s31, v140
	v_lshl_add_u64 v[48:49], v[140:141], 0, s[42:43]
	s_nop 0
	v_addc_co_u32_e32 v45, vcc, 0, v141, vcc
	s_mov_b32 s31, 0x28000
	v_cvt_pk_bf16_f32 v43, v46, v47
	global_store_dwordx4 v[44:45], v[40:43], off nt
	v_cvt_pk_bf16_f32 v32, v32, v33
	v_cvt_pk_bf16_f32 v33, v34, v35
	v_cvt_pk_bf16_f32 v34, v24, v25
	v_cvt_pk_bf16_f32 v35, v26, v27
	global_store_dwordx4 v[48:49], v[32:35], off offset:256 nt
	s_mov_b64 s[42:43], 0x28000
	v_cvt_pk_bf16_f32 v24, v36, v37
	v_cvt_pk_bf16_f32 v25, v38, v39
	v_cvt_pk_bf16_f32 v26, v28, v29
	v_add_co_u32_e32 v28, vcc, s31, v140
	v_lshl_add_u64 v[32:33], v[140:141], 0, s[42:43]
	s_nop 0
	v_addc_co_u32_e32 v29, vcc, 0, v141, vcc
	s_mov_b32 s31, 0x2c000
	v_cvt_pk_bf16_f32 v27, v30, v31
	global_store_dwordx4 v[28:29], v[24:27], off nt
	v_cvt_pk_bf16_f32 v16, v16, v17
	v_cvt_pk_bf16_f32 v17, v18, v19
	v_cvt_pk_bf16_f32 v18, v8, v9
	v_cvt_pk_bf16_f32 v19, v10, v11
	global_store_dwordx4 v[32:33], v[16:19], off offset:256 nt
	v_cvt_pk_bf16_f32 v8, v20, v21
	v_cvt_pk_bf16_f32 v9, v22, v23
	v_cvt_pk_bf16_f32 v10, v12, v13
	v_add_co_u32_e32 v12, vcc, s31, v140
	s_mov_b64 s[42:43], 0x2c000
	s_nop 0
	v_addc_co_u32_e32 v13, vcc, 0, v141, vcc
	v_lshl_add_u64 v[16:17], v[140:141], 0, s[42:43]
	s_and_b64 vcc, exec, s[28:29]
	s_mov_b64 s[42:43], s[38:39]
	v_cvt_pk_bf16_f32 v11, v14, v15
	global_store_dwordx4 v[12:13], v[8:11], off nt
	v_cvt_pk_bf16_f32 v4, v4, v5
	v_cvt_pk_bf16_f32 v5, v6, v7
	v_cvt_pk_bf16_f32 v6, v0, v1
	v_cvt_pk_bf16_f32 v7, v2, v3
	global_store_dwordx4 v[16:17], v[4:7], off offset:256 nt
	s_cbranch_vccz .LBB0_193
	s_waitcnt vmcnt(0)
	s_cmpk_gt_u32 s65, 0xff
	s_cbranch_scc1 .LBB0_204
	s_barrier

.LBB0_220:
	s_add_u32 s40, s38, 0xfffc0080
	s_addc_u32 s41, s39, -1
	s_add_i32 s76, 0, 0x10000
	v_add_u32_e32 v140, s76, v144
	ds_read_b128 v[148:151], v140
	ds_read_b128 v[152:155], v140 offset:1024
	ds_read_b128 v[156:159], v140 offset:2048
	ds_read_b128 v[160:163], v140 offset:3072
	s_cmp_eq_u32 s75, 12
	s_cselect_b32 s43, s29, s41
	s_cselect_b32 s42, s71, s40
	s_cselect_b32 s41, s15, s74
	s_cselect_b32 s40, s72, s73
	v_lshl_add_u64 v[140:141], s[38:39], 0, v[136:137]
	s_add_i32 m0, s31, 0xc000
	ds_read_b128 v[164:167], v146
	ds_read_b128 v[168:171], v146 offset:1024
	ds_read_b128 v[172:175], v146 offset:2048
	ds_read_b128 v[176:179], v146 offset:3072
	ds_read_b128 v[180:183], v146 offset:4096
	ds_read_b128 v[184:187], v146 offset:5120
	ds_read_b128 v[188:191], v146 offset:6144
	ds_read_b128 v[192:195], v146 offset:7168
	global_load_lds_dwordx4 v[140:141], off
	v_lshl_add_u64 v[140:141], s[38:39], 0, v[138:139]
	s_add_i32 m0, s31, 0xe000
	s_nop 0
	global_load_lds_dwordx4 v[140:141], off
	s_waitcnt lgkmcnt(8)
	s_setprio 1
	s_barrier
	s_waitcnt lgkmcnt(0)
	v_mfma_f32_16x16x32_bf16 v[124:127], v[148:151], v[164:167], v[124:127]
	v_mfma_f32_16x16x32_bf16 v[120:123], v[156:159], v[164:167], v[120:123]
	v_mfma_f32_16x16x32_bf16 v[116:119], v[148:151], v[172:175], v[116:119]
	v_mfma_f32_16x16x32_bf16 v[108:111], v[156:159], v[172:175], v[108:111]
	v_mfma_f32_16x16x32_bf16 v[100:103], v[148:151], v[180:183], v[100:103]
	v_mfma_f32_16x16x32_bf16 v[92:95], v[156:159], v[180:183], v[92:95]
	v_mfma_f32_16x16x32_bf16 v[84:87], v[148:151], v[188:191], v[84:87]
	v_mfma_f32_16x16x32_bf16 v[76:79], v[156:159], v[188:191], v[76:79]
	v_mfma_f32_16x16x32_bf16 v[124:127], v[152:155], v[168:171], v[124:127]
	v_mfma_f32_16x16x32_bf16 v[120:123], v[160:163], v[168:171], v[120:123]
	v_mfma_f32_16x16x32_bf16 v[116:119], v[152:155], v[176:179], v[116:119]
	v_mfma_f32_16x16x32_bf16 v[108:111], v[160:163], v[176:179], v[108:111]
	v_mfma_f32_16x16x32_bf16 v[100:103], v[152:155], v[184:187], v[100:103]
	v_mfma_f32_16x16x32_bf16 v[92:95], v[160:163], v[184:187], v[92:95]
	v_mfma_f32_16x16x32_bf16 v[84:87], v[152:155], v[192:195], v[84:87]
	v_mfma_f32_16x16x32_bf16 v[76:79], v[160:163], v[192:195], v[76:79]
	s_setprio 0
	s_barrier
	s_add_i32 s78, 0, 0x14000
	v_add_u32_e32 v140, s78, v144
	s_add_i32 s76, s76, s64
	ds_read_b128 v[196:199], v140
	ds_read_b128 v[200:203], v140 offset:1024
	ds_read_b128 v[204:207], v140 offset:2048
	ds_read_b128 v[212:215], v140 offset:3072
	v_lshl_add_u64 v[140:141], s[40:41], 0, v[128:129]
	s_mov_b32 m0, s76
	v_lshl_add_u64 v[208:209], s[40:41], 0, v[134:135]
	global_load_lds_dwordx4 v[140:141], off
	s_add_i32 m0, s76, 0x2000
	s_nop 0
	global_load_lds_dwordx4 v[208:209], off
	s_setprio 1
	s_barrier
	s_waitcnt lgkmcnt(0)
	v_mfma_f32_16x16x32_bf16 v[112:115], v[196:199], v[164:167], v[112:115]
	v_mfma_f32_16x16x32_bf16 v[104:107], v[204:207], v[164:167], v[104:107]
	v_mfma_f32_16x16x32_bf16 v[96:99], v[196:199], v[172:175], v[96:99]
	v_mfma_f32_16x16x32_bf16 v[88:91], v[204:207], v[172:175], v[88:91]
	v_mfma_f32_16x16x32_bf16 v[80:83], v[196:199], v[180:183], v[80:83]
	v_mfma_f32_16x16x32_bf16 v[72:75], v[204:207], v[180:183], v[72:75]
	v_mfma_f32_16x16x32_bf16 v[68:71], v[196:199], v[188:191], v[68:71]
	v_mfma_f32_16x16x32_bf16 v[64:67], v[204:207], v[188:191], v[64:67]
	v_mfma_f32_16x16x32_bf16 v[112:115], v[200:203], v[168:171], v[112:115]
	v_mfma_f32_16x16x32_bf16 v[104:107], v[212:215], v[168:171], v[104:107]
	v_mfma_f32_16x16x32_bf16 v[96:99], v[200:203], v[176:179], v[96:99]
	v_mfma_f32_16x16x32_bf16 v[88:91], v[212:215], v[176:179], v[88:91]
	v_mfma_f32_16x16x32_bf16 v[80:83], v[200:203], v[184:187], v[80:83]
	v_mfma_f32_16x16x32_bf16 v[72:75], v[212:215], v[184:187], v[72:75]
	v_mfma_f32_16x16x32_bf16 v[68:71], v[200:203], v[192:195], v[68:71]
	v_mfma_f32_16x16x32_bf16 v[64:67], v[212:215], v[192:195], v[64:67]
	s_setprio 0
	s_mov_b32 m0, s31
	v_lshl_add_u64 v[216:217], s[42:43], 0, v[130:131]
	s_barrier
	ds_read_b128 v[164:167], v146 offset:16384
	ds_read_b128 v[168:171], v146 offset:17408
	ds_read_b128 v[172:175], v146 offset:18432
	ds_read_b128 v[176:179], v146 offset:19456
	ds_read_b128 v[180:183], v146 offset:20480
	ds_read_b128 v[184:187], v146 offset:21504
	ds_read_b128 v[188:191], v146 offset:22528
	ds_read_b128 v[192:195], v146 offset:23552
	global_load_lds_dwordx4 v[216:217], off
	v_lshl_add_u64 v[218:219], s[42:43], 0, v[132:133]
	s_mov_b32 m0, s65
	s_nop 0
	global_load_lds_dwordx4 v[218:219], off
	s_setprio 1
	s_barrier
	s_waitcnt lgkmcnt(0)
	v_mfma_f32_16x16x32_bf16 v[60:63], v[148:151], v[164:167], v[60:63]
	v_mfma_f32_16x16x32_bf16 v[56:59], v[156:159], v[164:167], v[56:59]
	v_mfma_f32_16x16x32_bf16 v[52:55], v[148:151], v[172:175], v[52:55]
	v_mfma_f32_16x16x32_bf16 v[44:47], v[156:159], v[172:175], v[44:47]
	v_mfma_f32_16x16x32_bf16 v[36:39], v[148:151], v[180:183], v[36:39]
	v_mfma_f32_16x16x32_bf16 v[28:31], v[156:159], v[180:183], v[28:31]
	v_mfma_f32_16x16x32_bf16 v[20:23], v[148:151], v[188:191], v[20:23]
	v_mfma_f32_16x16x32_bf16 v[12:15], v[156:159], v[188:191], v[12:15]
	v_mfma_f32_16x16x32_bf16 v[60:63], v[152:155], v[168:171], v[60:63]
	v_mfma_f32_16x16x32_bf16 v[56:59], v[160:163], v[168:171], v[56:59]
	v_mfma_f32_16x16x32_bf16 v[52:55], v[152:155], v[176:179], v[52:55]
	v_mfma_f32_16x16x32_bf16 v[44:47], v[160:163], v[176:179], v[44:47]
	v_mfma_f32_16x16x32_bf16 v[36:39], v[152:155], v[184:187], v[36:39]
	v_mfma_f32_16x16x32_bf16 v[28:31], v[160:163], v[184:187], v[28:31]
	v_mfma_f32_16x16x32_bf16 v[20:23], v[152:155], v[192:195], v[20:23]
	v_mfma_f32_16x16x32_bf16 v[12:15], v[160:163], v[192:195], v[12:15]
	s_setprio 0
	s_barrier
	s_add_u32 s76, s40, 0x40000
	s_addc_u32 s77, s41, 0
	s_add_i32 s78, s78, s64
	v_lshl_add_u64 v[148:149], s[76:77], 0, v[128:129]
	s_mov_b32 m0, s78
	s_nop 0
	global_load_lds_dwordx4 v[148:149], off
	v_lshl_add_u64 v[148:149], s[76:77], 0, v[134:135]
	s_add_i32 m0, s78, 0x2000
	s_nop 0
	global_load_lds_dwordx4 v[148:149], off
	s_waitcnt vmcnt(6)
	s_setprio 1
	s_barrier
	v_mfma_f32_16x16x32_bf16 v[48:51], v[196:199], v[164:167], v[48:51]
	v_mfma_f32_16x16x32_bf16 v[40:43], v[204:207], v[164:167], v[40:43]
	v_mfma_f32_16x16x32_bf16 v[32:35], v[196:199], v[172:175], v[32:35]
	v_mfma_f32_16x16x32_bf16 v[24:27], v[204:207], v[172:175], v[24:27]
	v_mfma_f32_16x16x32_bf16 v[16:19], v[196:199], v[180:183], v[16:19]
	v_mfma_f32_16x16x32_bf16 v[8:11], v[204:207], v[180:183], v[8:11]
	v_mfma_f32_16x16x32_bf16 v[4:7], v[196:199], v[188:191], v[4:7]
	v_mfma_f32_16x16x32_bf16 v[0:3], v[204:207], v[188:191], v[0:3]
	v_mfma_f32_16x16x32_bf16 v[48:51], v[200:203], v[168:171], v[48:51]
	v_mfma_f32_16x16x32_bf16 v[40:43], v[212:215], v[168:171], v[40:43]
	v_mfma_f32_16x16x32_bf16 v[32:35], v[200:203], v[176:179], v[32:35]
	v_mfma_f32_16x16x32_bf16 v[24:27], v[212:215], v[176:179], v[24:27]
	v_mfma_f32_16x16x32_bf16 v[16:19], v[200:203], v[184:187], v[16:19]
	v_mfma_f32_16x16x32_bf16 v[8:11], v[212:215], v[184:187], v[8:11]
	v_mfma_f32_16x16x32_bf16 v[4:7], v[200:203], v[192:195], v[4:7]
	v_mfma_f32_16x16x32_bf16 v[0:3], v[212:215], v[192:195], v[0:3]
	s_setprio 0
	s_add_i32 s76, 0, 0x18000
	v_add_u32_e32 v147, s76, v144
	s_barrier
	ds_read_b128 v[148:151], v147
	ds_read_b128 v[152:155], v147 offset:1024
	ds_read_b128 v[156:159], v147 offset:2048
	ds_read_b128 v[160:163], v147 offset:3072
	s_add_u32 s42, s42, 0x40000
	s_addc_u32 s43, s43, 0
	s_mov_b32 m0, s66
	v_lshl_add_u64 v[196:197], s[42:43], 0, v[130:131]
	ds_read_b128 v[164:167], v146 offset:32768
	ds_read_b128 v[168:171], v146 offset:33792
	ds_read_b128 v[172:175], v146 offset:34816
	ds_read_b128 v[176:179], v146 offset:35840
	ds_read_b128 v[180:183], v146 offset:36864
	ds_read_b128 v[184:187], v146 offset:37888
	ds_read_b128 v[188:191], v146 offset:38912
	ds_read_b128 v[192:195], v146 offset:39936
	global_load_lds_dwordx4 v[196:197], off
	v_lshl_add_u64 v[196:197], s[42:43], 0, v[132:133]
	s_mov_b32 m0, s67
	s_nop 0
	global_load_lds_dwordx4 v[196:197], off
	s_waitcnt lgkmcnt(8)
	s_setprio 1
	s_barrier
	s_waitcnt lgkmcnt(0)
	v_mfma_f32_16x16x32_bf16 v[124:127], v[148:151], v[164:167], v[124:127]
	v_mfma_f32_16x16x32_bf16 v[120:123], v[156:159], v[164:167], v[120:123]
	v_mfma_f32_16x16x32_bf16 v[116:119], v[148:151], v[172:175], v[116:119]
	v_mfma_f32_16x16x32_bf16 v[108:111], v[156:159], v[172:175], v[108:111]
	v_mfma_f32_16x16x32_bf16 v[100:103], v[148:151], v[180:183], v[100:103]
	v_mfma_f32_16x16x32_bf16 v[92:95], v[156:159], v[180:183], v[92:95]
	v_mfma_f32_16x16x32_bf16 v[84:87], v[148:151], v[188:191], v[84:87]
	v_mfma_f32_16x16x32_bf16 v[76:79], v[156:159], v[188:191], v[76:79]
	v_mfma_f32_16x16x32_bf16 v[124:127], v[152:155], v[168:171], v[124:127]
	v_mfma_f32_16x16x32_bf16 v[120:123], v[160:163], v[168:171], v[120:123]
	v_mfma_f32_16x16x32_bf16 v[116:119], v[152:155], v[176:179], v[116:119]
	v_mfma_f32_16x16x32_bf16 v[108:111], v[160:163], v[176:179], v[108:111]
	v_mfma_f32_16x16x32_bf16 v[100:103], v[152:155], v[184:187], v[100:103]
	v_mfma_f32_16x16x32_bf16 v[92:95], v[160:163], v[184:187], v[92:95]
	v_mfma_f32_16x16x32_bf16 v[84:87], v[152:155], v[192:195], v[84:87]
	v_mfma_f32_16x16x32_bf16 v[76:79], v[160:163], v[192:195], v[76:79]
	s_setprio 0
	s_barrier
	s_add_i32 s42, 0, 0x1c000
	s_add_i32 s43, s76, s64
	v_add_u32_e32 v147, s42, v144
	v_lshl_add_u64 v[140:141], v[140:141], 0, s[2:3]
	s_mov_b32 m0, s43
	ds_read_b128 v[196:199], v147
	ds_read_b128 v[200:203], v147 offset:1024
	ds_read_b128 v[204:207], v147 offset:2048
	ds_read_b128 v[212:215], v147 offset:3072
	global_load_lds_dwordx4 v[140:141], off
	v_lshl_add_u64 v[140:141], v[208:209], 0, s[2:3]
	s_add_i32 m0, s43, 0x2000
	s_nop 0
	global_load_lds_dwordx4 v[140:141], off
	s_setprio 1
	s_barrier
	s_waitcnt lgkmcnt(0)
	v_mfma_f32_16x16x32_bf16 v[112:115], v[196:199], v[164:167], v[112:115]
	v_mfma_f32_16x16x32_bf16 v[104:107], v[204:207], v[164:167], v[104:107]
	v_mfma_f32_16x16x32_bf16 v[96:99], v[196:199], v[172:175], v[96:99]
	v_mfma_f32_16x16x32_bf16 v[88:91], v[204:207], v[172:175], v[88:91]
	v_mfma_f32_16x16x32_bf16 v[80:83], v[196:199], v[180:183], v[80:83]
	v_mfma_f32_16x16x32_bf16 v[72:75], v[204:207], v[180:183], v[72:75]
	v_mfma_f32_16x16x32_bf16 v[68:71], v[196:199], v[188:191], v[68:71]
	v_mfma_f32_16x16x32_bf16 v[64:67], v[204:207], v[188:191], v[64:67]
	v_mfma_f32_16x16x32_bf16 v[112:115], v[200:203], v[168:171], v[112:115]
	v_mfma_f32_16x16x32_bf16 v[104:107], v[212:215], v[168:171], v[104:107]
	v_mfma_f32_16x16x32_bf16 v[96:99], v[200:203], v[176:179], v[96:99]
	v_mfma_f32_16x16x32_bf16 v[88:91], v[212:215], v[176:179], v[88:91]
	v_mfma_f32_16x16x32_bf16 v[80:83], v[200:203], v[184:187], v[80:83]
	v_mfma_f32_16x16x32_bf16 v[72:75], v[212:215], v[184:187], v[72:75]
	v_mfma_f32_16x16x32_bf16 v[68:71], v[200:203], v[192:195], v[68:71]
	v_mfma_f32_16x16x32_bf16 v[64:67], v[212:215], v[192:195], v[64:67]
	s_setprio 0
	s_mov_b32 m0, s0
	v_lshl_add_u64 v[140:141], v[216:217], 0, s[2:3]
	s_barrier
	ds_read_b128 v[164:167], v146 offset:49152
	ds_read_b128 v[168:171], v146 offset:50176
	ds_read_b128 v[172:175], v146 offset:51200
	ds_read_b128 v[176:179], v146 offset:52224
	ds_read_b128 v[180:183], v146 offset:53248
	ds_read_b128 v[184:187], v146 offset:54272
	ds_read_b128 v[188:191], v146 offset:55296
	ds_read_b128 v[192:195], v146 offset:56320
	global_load_lds_dwordx4 v[140:141], off
	v_lshl_add_u64 v[140:141], v[218:219], 0, s[2:3]
	s_mov_b32 m0, s68
	s_nop 0
	global_load_lds_dwordx4 v[140:141], off
	s_setprio 1
	s_barrier
	s_waitcnt lgkmcnt(0)
	v_mfma_f32_16x16x32_bf16 v[60:63], v[148:151], v[164:167], v[60:63]
	v_mfma_f32_16x16x32_bf16 v[56:59], v[156:159], v[164:167], v[56:59]
	v_mfma_f32_16x16x32_bf16 v[52:55], v[148:151], v[172:175], v[52:55]
	v_mfma_f32_16x16x32_bf16 v[44:47], v[156:159], v[172:175], v[44:47]
	v_mfma_f32_16x16x32_bf16 v[36:39], v[148:151], v[180:183], v[36:39]
	v_mfma_f32_16x16x32_bf16 v[28:31], v[156:159], v[180:183], v[28:31]
	v_mfma_f32_16x16x32_bf16 v[20:23], v[148:151], v[188:191], v[20:23]
	v_mfma_f32_16x16x32_bf16 v[12:15], v[156:159], v[188:191], v[12:15]
	v_mfma_f32_16x16x32_bf16 v[60:63], v[152:155], v[168:171], v[60:63]
	v_mfma_f32_16x16x32_bf16 v[56:59], v[160:163], v[168:171], v[56:59]
	v_mfma_f32_16x16x32_bf16 v[52:55], v[152:155], v[176:179], v[52:55]
	v_mfma_f32_16x16x32_bf16 v[44:47], v[160:163], v[176:179], v[44:47]
	v_mfma_f32_16x16x32_bf16 v[36:39], v[152:155], v[184:187], v[36:39]
	v_mfma_f32_16x16x32_bf16 v[28:31], v[160:163], v[184:187], v[28:31]
	v_mfma_f32_16x16x32_bf16 v[20:23], v[152:155], v[192:195], v[20:23]
	v_mfma_f32_16x16x32_bf16 v[12:15], v[160:163], v[192:195], v[12:15]
	s_setprio 0
	s_barrier
	s_add_u32 s40, s40, 0x40080
	s_addc_u32 s41, s41, 0
	s_add_i32 s42, s42, s64
	v_lshl_add_u64 v[140:141], s[40:41], 0, v[128:129]
	s_mov_b32 m0, s42
	s_nop 0
	global_load_lds_dwordx4 v[140:141], off
	v_lshl_add_u64 v[140:141], s[40:41], 0, v[134:135]
	s_add_i32 m0, s42, 0x2000
	s_nop 0
	global_load_lds_dwordx4 v[140:141], off
	s_waitcnt vmcnt(6)
	s_setprio 1
	s_barrier
	v_mfma_f32_16x16x32_bf16 v[48:51], v[196:199], v[164:167], v[48:51]
	v_mfma_f32_16x16x32_bf16 v[40:43], v[204:207], v[164:167], v[40:43]
	v_mfma_f32_16x16x32_bf16 v[32:35], v[196:199], v[172:175], v[32:35]
	v_mfma_f32_16x16x32_bf16 v[24:27], v[204:207], v[172:175], v[24:27]
	v_mfma_f32_16x16x32_bf16 v[16:19], v[196:199], v[180:183], v[16:19]
	v_mfma_f32_16x16x32_bf16 v[8:11], v[204:207], v[180:183], v[8:11]
	v_mfma_f32_16x16x32_bf16 v[4:7], v[196:199], v[188:191], v[4:7]
	v_mfma_f32_16x16x32_bf16 v[0:3], v[204:207], v[188:191], v[0:3]
	v_mfma_f32_16x16x32_bf16 v[48:51], v[200:203], v[168:171], v[48:51]
	v_mfma_f32_16x16x32_bf16 v[40:43], v[212:215], v[168:171], v[40:43]
	v_mfma_f32_16x16x32_bf16 v[32:35], v[200:203], v[176:179], v[32:35]
	v_mfma_f32_16x16x32_bf16 v[24:27], v[212:215], v[176:179], v[24:27]
	v_mfma_f32_16x16x32_bf16 v[16:19], v[200:203], v[184:187], v[16:19]
	v_mfma_f32_16x16x32_bf16 v[8:11], v[212:215], v[184:187], v[8:11]
	v_mfma_f32_16x16x32_bf16 v[4:7], v[200:203], v[192:195], v[4:7]
	v_mfma_f32_16x16x32_bf16 v[0:3], v[212:215], v[192:195], v[0:3]
	s_setprio 0
	s_add_i32 s75, s75, 2
	s_add_u32 s38, s38, 0x100
	s_addc_u32 s39, s39, 0
	s_add_u32 s73, s73, 0x100
	s_addc_u32 s74, s74, 0
	s_cmp_gt_u32 s75, 13
	s_barrier
	s_cbranch_scc0 .LBB0_220
	v_lshl_add_u32 v148, s30, 8, v143
	v_ashrrev_i32_e32 v149, 31, v148
	v_lshl_or_b32 v140, s70, 8, v145
	v_ashrrev_i32_e32 v141, 31, v140
	v_lshlrev_b64 v[150:151], 13, v[148:149]
	v_lshl_add_u64 v[150:151], s[8:9], 0, v[150:151]
	v_lshlrev_b64 v[152:153], 1, v[140:141]
	v_lshl_add_u64 v[140:141], v[150:151], 0, v[152:153]
	v_cvt_pk_bf16_f32 v124, v124, v125
	v_cvt_pk_bf16_f32 v125, v126, v127
	v_cvt_pk_bf16_f32 v126, v120, v121
	v_cvt_pk_bf16_f32 v127, v122, v123
	global_store_dwordx4 v[140:141], v[124:127], off nt
	v_cvt_pk_bf16_f32 v112, v112, v113
	v_cvt_pk_bf16_f32 v113, v114, v115
	v_cvt_pk_bf16_f32 v114, v104, v105
	v_or_b32_e32 v104, 16, v148
	v_ashrrev_i32_e32 v105, 31, v104
	v_lshlrev_b64 v[104:105], 13, v[104:105]
	v_lshl_add_u64 v[104:105], s[8:9], 0, v[104:105]
	v_cvt_pk_bf16_f32 v115, v106, v107
	global_store_dwordx4 v[140:141], v[112:115], off offset:256 nt
	s_mov_b32 s15, 0x100000
	s_mov_b64 s[38:39], 0x100000
	v_lshl_add_u64 v[112:113], v[104:105], 0, v[152:153]
	v_cvt_pk_bf16_f32 v104, v116, v117
	v_cvt_pk_bf16_f32 v105, v118, v119
	v_cvt_pk_bf16_f32 v106, v108, v109
	v_cvt_pk_bf16_f32 v107, v110, v111
	global_store_dwordx4 v[112:113], v[104:107], off nt
	v_cvt_pk_bf16_f32 v96, v96, v97
	v_cvt_pk_bf16_f32 v97, v98, v99
	v_cvt_pk_bf16_f32 v98, v88, v89
	v_or_b32_e32 v88, 32, v148
	v_ashrrev_i32_e32 v89, 31, v88
	v_lshlrev_b64 v[88:89], 13, v[88:89]
	v_lshl_add_u64 v[88:89], s[8:9], 0, v[88:89]
	v_cvt_pk_bf16_f32 v99, v90, v91
	global_store_dwordx4 v[112:113], v[96:99], off offset:256 nt
	s_mov_b32 s70, s14
	s_mov_b32 s30, s28
	v_lshl_add_u64 v[96:97], v[88:89], 0, v[152:153]
	v_cvt_pk_bf16_f32 v88, v100, v101
	v_cvt_pk_bf16_f32 v89, v102, v103
	v_cvt_pk_bf16_f32 v90, v92, v93
	v_cvt_pk_bf16_f32 v91, v94, v95
	global_store_dwordx4 v[96:97], v[88:91], off nt
	v_cvt_pk_bf16_f32 v80, v80, v81
	v_cvt_pk_bf16_f32 v81, v82, v83
	v_cvt_pk_bf16_f32 v82, v72, v73
	v_or_b32_e32 v72, 48, v148
	v_ashrrev_i32_e32 v73, 31, v72
	v_lshlrev_b64 v[72:73], 13, v[72:73]
	v_lshl_add_u64 v[72:73], s[8:9], 0, v[72:73]
	v_cvt_pk_bf16_f32 v83, v74, v75
	global_store_dwordx4 v[96:97], v[80:83], off offset:256 nt
	s_mov_b64 s[40:41], s[36:37]
	s_nop 0
	v_lshl_add_u64 v[80:81], v[72:73], 0, v[152:153]
	v_cvt_pk_bf16_f32 v72, v84, v85
	v_cvt_pk_bf16_f32 v73, v86, v87
	v_cvt_pk_bf16_f32 v74, v76, v77
	v_cvt_pk_bf16_f32 v75, v78, v79
	global_store_dwordx4 v[80:81], v[72:75], off nt
	v_cvt_pk_bf16_f32 v68, v68, v69
	v_cvt_pk_bf16_f32 v69, v70, v71
	v_cvt_pk_bf16_f32 v70, v64, v65
	v_cvt_pk_bf16_f32 v71, v66, v67
	global_store_dwordx4 v[80:81], v[68:71], off offset:256 nt
	v_cvt_pk_bf16_f32 v60, v60, v61
	v_cvt_pk_bf16_f32 v61, v62, v63
	v_cvt_pk_bf16_f32 v62, v56, v57
	v_add_co_u32_e32 v56, vcc, s15, v140
	v_lshl_add_u64 v[64:65], v[140:141], 0, s[38:39]
	s_nop 0
	v_addc_co_u32_e32 v57, vcc, 0, v141, vcc
	s_mov_b32 s15, 0x120000
	v_cvt_pk_bf16_f32 v63, v58, v59
	global_store_dwordx4 v[56:57], v[60:63], off nt
	v_cvt_pk_bf16_f32 v48, v48, v49
	v_cvt_pk_bf16_f32 v49, v50, v51
	v_cvt_pk_bf16_f32 v50, v40, v41
	v_cvt_pk_bf16_f32 v51, v42, v43
	global_store_dwordx4 v[64:65], v[48:51], off offset:256 nt
	s_mov_b64 s[38:39], 0x120000
	v_cvt_pk_bf16_f32 v40, v52, v53
	v_cvt_pk_bf16_f32 v41, v54, v55
	v_cvt_pk_bf16_f32 v42, v44, v45
	v_add_co_u32_e32 v44, vcc, s15, v140
	v_lshl_add_u64 v[48:49], v[140:141], 0, s[38:39]
	s_nop 0
	v_addc_co_u32_e32 v45, vcc, 0, v141, vcc
	s_mov_b32 s15, 0x140000
	v_cvt_pk_bf16_f32 v43, v46, v47
	global_store_dwordx4 v[44:45], v[40:43], off nt
	v_cvt_pk_bf16_f32 v32, v32, v33
	v_cvt_pk_bf16_f32 v33, v34, v35
	v_cvt_pk_bf16_f32 v34, v24, v25
	v_cvt_pk_bf16_f32 v35, v26, v27
	global_store_dwordx4 v[48:49], v[32:35], off offset:256 nt
	s_mov_b64 s[38:39], 0x140000
	v_cvt_pk_bf16_f32 v24, v36, v37
	v_cvt_pk_bf16_f32 v25, v38, v39
	v_cvt_pk_bf16_f32 v26, v28, v29
	v_add_co_u32_e32 v28, vcc, s15, v140
	v_lshl_add_u64 v[32:33], v[140:141], 0, s[38:39]
	s_nop 0
	v_addc_co_u32_e32 v29, vcc, 0, v141, vcc
	s_mov_b32 s15, 0x160000
	v_cvt_pk_bf16_f32 v27, v30, v31
	global_store_dwordx4 v[28:29], v[24:27], off nt
	v_cvt_pk_bf16_f32 v16, v16, v17
	v_cvt_pk_bf16_f32 v17, v18, v19
	v_cvt_pk_bf16_f32 v18, v8, v9
	v_cvt_pk_bf16_f32 v19, v10, v11
	global_store_dwordx4 v[32:33], v[16:19], off offset:256 nt
	v_cvt_pk_bf16_f32 v8, v20, v21
	v_cvt_pk_bf16_f32 v9, v22, v23
	v_cvt_pk_bf16_f32 v10, v12, v13
	v_add_co_u32_e32 v12, vcc, s15, v140
	s_mov_b64 s[38:39], 0x160000
	s_nop 0
	v_addc_co_u32_e32 v13, vcc, 0, v141, vcc
	v_lshl_add_u64 v[16:17], v[140:141], 0, s[38:39]
	s_and_b64 vcc, exec, s[12:13]
	s_mov_b64 s[38:39], s[34:35]
	v_cvt_pk_bf16_f32 v11, v14, v15
	global_store_dwordx4 v[12:13], v[8:11], off nt
	v_cvt_pk_bf16_f32 v4, v4, v5
	v_cvt_pk_bf16_f32 v5, v6, v7
	v_cvt_pk_bf16_f32 v6, v0, v1
	v_cvt_pk_bf16_f32 v7, v2, v3
	global_store_dwordx4 v[16:17], v[4:7], off offset:256 nt
	s_cbranch_vccz .LBB0_213
	s_waitcnt vmcnt(0)
	s_cmpk_gt_u32 s49, 0xff
	s_cbranch_scc1 .LBB0_183
	s_barrier
	s_branch .LBB0_183

.LBB0_262:
	ds_read_b128 v[128:131], v157
	ds_read_b128 v[132:135], v157 offset:1024
	ds_read_b128 v[160:163], v157 offset:2048
	ds_read_b128 v[164:167], v157 offset:3072
	s_add_u32 s34, s30, 0xfffc0080
	s_addc_u32 s35, s31, -1
	s_cmp_eq_u32 s59, 28
	s_cselect_b32 s37, s1, s35
	s_cselect_b32 s36, s2, s34
	s_cselect_b32 s35, s13, s58
	s_cselect_b32 s34, s15, s55
	v_lshl_add_u64 v[152:153], s[30:31], 0, v[148:149]
	s_add_i32 m0, s40, 0xc000
	ds_read_b128 v[168:171], v158
	ds_read_b128 v[172:175], v158 offset:1024
	ds_read_b128 v[176:179], v158 offset:2048
	ds_read_b128 v[180:183], v158 offset:3072
	ds_read_b128 v[184:187], v158 offset:4096
	ds_read_b128 v[188:191], v158 offset:5120
	ds_read_b128 v[192:195], v158 offset:6144
	ds_read_b128 v[196:199], v158 offset:7168
	global_load_lds_dwordx4 v[152:153], off
	v_lshl_add_u64 v[152:153], s[30:31], 0, v[150:151]
	s_add_i32 m0, s40, 0xe000
	s_nop 0
	global_load_lds_dwordx4 v[152:153], off
	s_waitcnt lgkmcnt(8)
	s_setprio 1
	s_barrier
	s_waitcnt lgkmcnt(0)
	v_mfma_f32_16x16x32_bf16 v[124:127], v[128:131], v[168:171], v[124:127]
	v_mfma_f32_16x16x32_bf16 v[100:103], v[160:163], v[168:171], v[100:103]
	v_mfma_f32_16x16x32_bf16 v[116:119], v[128:131], v[176:179], v[116:119]
	v_mfma_f32_16x16x32_bf16 v[96:99], v[160:163], v[176:179], v[96:99]
	v_mfma_f32_16x16x32_bf16 v[92:95], v[128:131], v[184:187], v[92:95]
	v_mfma_f32_16x16x32_bf16 v[72:75], v[160:163], v[184:187], v[72:75]
	v_mfma_f32_16x16x32_bf16 v[84:87], v[128:131], v[192:195], v[84:87]
	v_mfma_f32_16x16x32_bf16 v[60:63], v[160:163], v[192:195], v[60:63]
	v_mfma_f32_16x16x32_bf16 v[124:127], v[132:135], v[172:175], v[124:127]
	v_mfma_f32_16x16x32_bf16 v[100:103], v[164:167], v[172:175], v[100:103]
	v_mfma_f32_16x16x32_bf16 v[116:119], v[132:135], v[180:183], v[116:119]
	v_mfma_f32_16x16x32_bf16 v[96:99], v[164:167], v[180:183], v[96:99]
	v_mfma_f32_16x16x32_bf16 v[92:95], v[132:135], v[188:191], v[92:95]
	v_mfma_f32_16x16x32_bf16 v[72:75], v[164:167], v[188:191], v[72:75]
	v_mfma_f32_16x16x32_bf16 v[84:87], v[132:135], v[196:199], v[84:87]
	v_mfma_f32_16x16x32_bf16 v[60:63], v[164:167], v[196:199], v[60:63]
	s_setprio 0
	s_barrier
	s_add_i32 s60, s51, s39
	v_lshl_add_u64 v[152:153], s[34:35], 0, v[138:139]
	s_mov_b32 m0, s60
	ds_read_b128 v[200:203], v159
	ds_read_b128 v[204:207], v159 offset:1024
	ds_read_b128 v[212:215], v159 offset:2048
	ds_read_b128 v[216:219], v159 offset:3072
	global_load_lds_dwordx4 v[152:153], off
	v_lshl_add_u64 v[208:209], s[34:35], 0, v[142:143]
	s_add_i32 m0, s60, 0x2000
	s_nop 0
	global_load_lds_dwordx4 v[208:209], off
	s_setprio 1
	s_barrier
	s_waitcnt lgkmcnt(0)
	v_mfma_f32_16x16x32_bf16 v[120:123], v[200:203], v[168:171], v[120:123]
	v_mfma_f32_16x16x32_bf16 v[108:111], v[212:215], v[168:171], v[108:111]
	v_mfma_f32_16x16x32_bf16 v[112:115], v[200:203], v[176:179], v[112:115]
	v_mfma_f32_16x16x32_bf16 v[104:107], v[212:215], v[176:179], v[104:107]
	v_mfma_f32_16x16x32_bf16 v[88:91], v[200:203], v[184:187], v[88:91]
	v_mfma_f32_16x16x32_bf16 v[80:83], v[212:215], v[184:187], v[80:83]
	v_mfma_f32_16x16x32_bf16 v[76:79], v[200:203], v[192:195], v[76:79]
	v_mfma_f32_16x16x32_bf16 v[68:71], v[212:215], v[192:195], v[68:71]
	v_mfma_f32_16x16x32_bf16 v[120:123], v[204:207], v[172:175], v[120:123]
	v_mfma_f32_16x16x32_bf16 v[108:111], v[216:219], v[172:175], v[108:111]
	v_mfma_f32_16x16x32_bf16 v[112:115], v[204:207], v[180:183], v[112:115]
	v_mfma_f32_16x16x32_bf16 v[104:107], v[216:219], v[180:183], v[104:107]
	v_mfma_f32_16x16x32_bf16 v[88:91], v[204:207], v[188:191], v[88:91]
	v_mfma_f32_16x16x32_bf16 v[80:83], v[216:219], v[188:191], v[80:83]
	v_mfma_f32_16x16x32_bf16 v[76:79], v[204:207], v[196:199], v[76:79]
	v_mfma_f32_16x16x32_bf16 v[68:71], v[216:219], v[196:199], v[68:71]
	s_setprio 0
	s_mov_b32 m0, s40
	v_lshl_add_u64 v[220:221], s[36:37], 0, v[136:137]
	s_barrier
	ds_read_b128 v[168:171], v158 offset:16384
	ds_read_b128 v[172:175], v158 offset:17408
	ds_read_b128 v[176:179], v158 offset:18432
	ds_read_b128 v[180:183], v158 offset:19456
	ds_read_b128 v[184:187], v158 offset:20480
	ds_read_b128 v[188:191], v158 offset:21504
	ds_read_b128 v[192:195], v158 offset:22528
	ds_read_b128 v[196:199], v158 offset:23552
	global_load_lds_dwordx4 v[220:221], off
	v_lshl_add_u64 v[222:223], s[36:37], 0, v[140:141]
	s_mov_b32 m0, s41
	s_nop 0
	global_load_lds_dwordx4 v[222:223], off
	s_setprio 1
	s_barrier
	s_waitcnt lgkmcnt(0)
	v_mfma_f32_16x16x32_bf16 v[64:67], v[128:131], v[168:171], v[64:67]
	v_mfma_f32_16x16x32_bf16 v[48:51], v[160:163], v[168:171], v[48:51]
	v_mfma_f32_16x16x32_bf16 v[44:47], v[128:131], v[176:179], v[44:47]
	v_mfma_f32_16x16x32_bf16 v[32:35], v[160:163], v[176:179], v[32:35]
	v_mfma_f32_16x16x32_bf16 v[28:31], v[128:131], v[184:187], v[28:31]
	v_mfma_f32_16x16x32_bf16 v[16:19], v[160:163], v[184:187], v[16:19]
	v_mfma_f32_16x16x32_bf16 v[12:15], v[128:131], v[192:195], v[12:15]
	v_mfma_f32_16x16x32_bf16 v[0:3], v[160:163], v[192:195], v[0:3]
	v_mfma_f32_16x16x32_bf16 v[64:67], v[132:135], v[172:175], v[64:67]
	v_mfma_f32_16x16x32_bf16 v[48:51], v[164:167], v[172:175], v[48:51]
	v_mfma_f32_16x16x32_bf16 v[44:47], v[132:135], v[180:183], v[44:47]
	v_mfma_f32_16x16x32_bf16 v[32:35], v[164:167], v[180:183], v[32:35]
	v_mfma_f32_16x16x32_bf16 v[28:31], v[132:135], v[188:191], v[28:31]
	v_mfma_f32_16x16x32_bf16 v[16:19], v[164:167], v[188:191], v[16:19]
	v_mfma_f32_16x16x32_bf16 v[12:15], v[132:135], v[196:199], v[12:15]
	v_mfma_f32_16x16x32_bf16 v[0:3], v[164:167], v[196:199], v[0:3]
	s_setprio 0
	s_barrier
	s_add_u32 s60, s34, 0x80000
	s_addc_u32 s61, s35, 0
	s_add_i32 s62, s53, s39
	v_lshl_add_u64 v[128:129], s[60:61], 0, v[138:139]
	s_mov_b32 m0, s62
	s_nop 0
	global_load_lds_dwordx4 v[128:129], off
	v_lshl_add_u64 v[128:129], s[60:61], 0, v[142:143]
	s_add_i32 m0, s62, 0x2000
	s_nop 0
	global_load_lds_dwordx4 v[128:129], off
	s_waitcnt vmcnt(6)
	s_setprio 1
	s_barrier
	v_mfma_f32_16x16x32_bf16 v[56:59], v[200:203], v[168:171], v[56:59]
	v_mfma_f32_16x16x32_bf16 v[52:55], v[212:215], v[168:171], v[52:55]
	v_mfma_f32_16x16x32_bf16 v[40:43], v[200:203], v[176:179], v[40:43]
	v_mfma_f32_16x16x32_bf16 v[36:39], v[212:215], v[176:179], v[36:39]
	v_mfma_f32_16x16x32_bf16 v[24:27], v[200:203], v[184:187], v[24:27]
	v_mfma_f32_16x16x32_bf16 v[20:23], v[212:215], v[184:187], v[20:23]
	v_mfma_f32_16x16x32_bf16 v[8:11], v[200:203], v[192:195], v[8:11]
	v_mfma_f32_16x16x32_bf16 v[4:7], v[212:215], v[192:195], v[4:7]
	v_mfma_f32_16x16x32_bf16 v[56:59], v[204:207], v[172:175], v[56:59]
	v_mfma_f32_16x16x32_bf16 v[52:55], v[216:219], v[172:175], v[52:55]
	v_mfma_f32_16x16x32_bf16 v[40:43], v[204:207], v[180:183], v[40:43]
	v_mfma_f32_16x16x32_bf16 v[36:39], v[216:219], v[180:183], v[36:39]
	v_mfma_f32_16x16x32_bf16 v[24:27], v[204:207], v[188:191], v[24:27]
	v_mfma_f32_16x16x32_bf16 v[20:23], v[216:219], v[188:191], v[20:23]
	v_mfma_f32_16x16x32_bf16 v[8:11], v[204:207], v[196:199], v[8:11]
	v_mfma_f32_16x16x32_bf16 v[4:7], v[216:219], v[196:199], v[4:7]
	s_setprio 0
	s_add_i32 s60, 0, 0x18000
	v_add_u32_e32 v164, s60, v156
	s_barrier
	ds_read_b128 v[128:131], v164
	ds_read_b128 v[132:135], v164 offset:1024
	ds_read_b128 v[160:163], v164 offset:2048
	ds_read_b128 v[164:167], v164 offset:3072
	s_add_u32 s36, s36, 0x40000
	s_addc_u32 s37, s37, 0
	s_mov_b32 m0, s42
	v_lshl_add_u64 v[200:201], s[36:37], 0, v[136:137]
	ds_read_b128 v[168:171], v158 offset:32768
	ds_read_b128 v[172:175], v158 offset:33792
	ds_read_b128 v[176:179], v158 offset:34816
	ds_read_b128 v[180:183], v158 offset:35840
	ds_read_b128 v[184:187], v158 offset:36864
	ds_read_b128 v[188:191], v158 offset:37888
	ds_read_b128 v[192:195], v158 offset:38912
	ds_read_b128 v[196:199], v158 offset:39936
	global_load_lds_dwordx4 v[200:201], off
	v_lshl_add_u64 v[200:201], s[36:37], 0, v[140:141]
	s_mov_b32 m0, s43
	s_nop 0
	global_load_lds_dwordx4 v[200:201], off
	s_waitcnt lgkmcnt(8)
	s_setprio 1
	s_barrier
	s_waitcnt lgkmcnt(0)
	v_mfma_f32_16x16x32_bf16 v[124:127], v[128:131], v[168:171], v[124:127]
	v_mfma_f32_16x16x32_bf16 v[100:103], v[160:163], v[168:171], v[100:103]
	v_mfma_f32_16x16x32_bf16 v[116:119], v[128:131], v[176:179], v[116:119]
	v_mfma_f32_16x16x32_bf16 v[96:99], v[160:163], v[176:179], v[96:99]
	v_mfma_f32_16x16x32_bf16 v[92:95], v[128:131], v[184:187], v[92:95]
	v_mfma_f32_16x16x32_bf16 v[72:75], v[160:163], v[184:187], v[72:75]
	v_mfma_f32_16x16x32_bf16 v[84:87], v[128:131], v[192:195], v[84:87]
	v_mfma_f32_16x16x32_bf16 v[60:63], v[160:163], v[192:195], v[60:63]
	v_mfma_f32_16x16x32_bf16 v[124:127], v[132:135], v[172:175], v[124:127]
	v_mfma_f32_16x16x32_bf16 v[100:103], v[164:167], v[172:175], v[100:103]
	v_mfma_f32_16x16x32_bf16 v[116:119], v[132:135], v[180:183], v[116:119]
	v_mfma_f32_16x16x32_bf16 v[96:99], v[164:167], v[180:183], v[96:99]
	v_mfma_f32_16x16x32_bf16 v[92:95], v[132:135], v[188:191], v[92:95]
	v_mfma_f32_16x16x32_bf16 v[72:75], v[164:167], v[188:191], v[72:75]
	v_mfma_f32_16x16x32_bf16 v[84:87], v[132:135], v[196:199], v[84:87]
	v_mfma_f32_16x16x32_bf16 v[60:63], v[164:167], v[196:199], v[60:63]
	s_setprio 0
	s_barrier
	s_add_i32 s36, 0, 0x1c000
	s_add_i32 s37, s60, s39
	v_add_u32_e32 v211, s36, v156
	v_lshl_add_u64 v[152:153], v[152:153], 0, s[4:5]
	s_mov_b32 m0, s37
	ds_read_b128 v[200:203], v211
	ds_read_b128 v[204:207], v211 offset:1024
	ds_read_b128 v[212:215], v211 offset:2048
	ds_read_b128 v[216:219], v211 offset:3072
	global_load_lds_dwordx4 v[152:153], off
	v_lshl_add_u64 v[152:153], v[208:209], 0, s[4:5]
	s_add_i32 m0, s37, 0x2000
	s_nop 0
	global_load_lds_dwordx4 v[152:153], off
	s_setprio 1
	s_barrier
	s_waitcnt lgkmcnt(0)
	v_mfma_f32_16x16x32_bf16 v[120:123], v[200:203], v[168:171], v[120:123]
	v_mfma_f32_16x16x32_bf16 v[108:111], v[212:215], v[168:171], v[108:111]
	v_mfma_f32_16x16x32_bf16 v[112:115], v[200:203], v[176:179], v[112:115]
	v_mfma_f32_16x16x32_bf16 v[104:107], v[212:215], v[176:179], v[104:107]
	v_mfma_f32_16x16x32_bf16 v[88:91], v[200:203], v[184:187], v[88:91]
	v_mfma_f32_16x16x32_bf16 v[80:83], v[212:215], v[184:187], v[80:83]
	v_mfma_f32_16x16x32_bf16 v[76:79], v[200:203], v[192:195], v[76:79]
	v_mfma_f32_16x16x32_bf16 v[68:71], v[212:215], v[192:195], v[68:71]
	v_mfma_f32_16x16x32_bf16 v[120:123], v[204:207], v[172:175], v[120:123]
	v_mfma_f32_16x16x32_bf16 v[108:111], v[216:219], v[172:175], v[108:111]
	v_mfma_f32_16x16x32_bf16 v[112:115], v[204:207], v[180:183], v[112:115]
	v_mfma_f32_16x16x32_bf16 v[104:107], v[216:219], v[180:183], v[104:107]
	v_mfma_f32_16x16x32_bf16 v[88:91], v[204:207], v[188:191], v[88:91]
	v_mfma_f32_16x16x32_bf16 v[80:83], v[216:219], v[188:191], v[80:83]
	v_mfma_f32_16x16x32_bf16 v[76:79], v[204:207], v[196:199], v[76:79]
	v_mfma_f32_16x16x32_bf16 v[68:71], v[216:219], v[196:199], v[68:71]
	s_setprio 0
	s_mov_b32 m0, s48
	v_lshl_add_u64 v[152:153], v[220:221], 0, s[4:5]
	s_barrier
	ds_read_b128 v[168:171], v158 offset:49152
	ds_read_b128 v[172:175], v158 offset:50176
	ds_read_b128 v[176:179], v158 offset:51200
	ds_read_b128 v[180:183], v158 offset:52224
	ds_read_b128 v[184:187], v158 offset:53248
	ds_read_b128 v[188:191], v158 offset:54272
	ds_read_b128 v[192:195], v158 offset:55296
	ds_read_b128 v[196:199], v158 offset:56320
	global_load_lds_dwordx4 v[152:153], off
	v_lshl_add_u64 v[152:153], v[222:223], 0, s[4:5]
	s_mov_b32 m0, s49
	s_nop 0
	global_load_lds_dwordx4 v[152:153], off
	s_setprio 1
	s_barrier
	s_waitcnt lgkmcnt(0)
	v_mfma_f32_16x16x32_bf16 v[64:67], v[128:131], v[168:171], v[64:67]
	v_mfma_f32_16x16x32_bf16 v[48:51], v[160:163], v[168:171], v[48:51]
	v_mfma_f32_16x16x32_bf16 v[44:47], v[128:131], v[176:179], v[44:47]
	v_mfma_f32_16x16x32_bf16 v[32:35], v[160:163], v[176:179], v[32:35]
	v_mfma_f32_16x16x32_bf16 v[28:31], v[128:131], v[184:187], v[28:31]
	v_mfma_f32_16x16x32_bf16 v[16:19], v[160:163], v[184:187], v[16:19]
	v_mfma_f32_16x16x32_bf16 v[12:15], v[128:131], v[192:195], v[12:15]
	v_mfma_f32_16x16x32_bf16 v[0:3], v[160:163], v[192:195], v[0:3]
	v_mfma_f32_16x16x32_bf16 v[64:67], v[132:135], v[172:175], v[64:67]
	v_mfma_f32_16x16x32_bf16 v[48:51], v[164:167], v[172:175], v[48:51]
	v_mfma_f32_16x16x32_bf16 v[44:47], v[132:135], v[180:183], v[44:47]
	v_mfma_f32_16x16x32_bf16 v[32:35], v[164:167], v[180:183], v[32:35]
	v_mfma_f32_16x16x32_bf16 v[28:31], v[132:135], v[188:191], v[28:31]
	v_mfma_f32_16x16x32_bf16 v[16:19], v[164:167], v[188:191], v[16:19]
	v_mfma_f32_16x16x32_bf16 v[12:15], v[132:135], v[196:199], v[12:15]
	v_mfma_f32_16x16x32_bf16 v[0:3], v[164:167], v[196:199], v[0:3]
	s_setprio 0
	s_barrier
	s_add_u32 s34, s34, 0x80080
	s_addc_u32 s35, s35, 0
	s_add_i32 s36, s36, s39
	v_lshl_add_u64 v[128:129], s[34:35], 0, v[138:139]
	s_mov_b32 m0, s36
	s_nop 0
	global_load_lds_dwordx4 v[128:129], off
	v_lshl_add_u64 v[128:129], s[34:35], 0, v[142:143]
	s_add_i32 m0, s36, 0x2000
	s_nop 0
	global_load_lds_dwordx4 v[128:129], off
	s_waitcnt vmcnt(6)
	s_setprio 1
	s_barrier
	v_mfma_f32_16x16x32_bf16 v[56:59], v[200:203], v[168:171], v[56:59]
	v_mfma_f32_16x16x32_bf16 v[52:55], v[212:215], v[168:171], v[52:55]
	v_mfma_f32_16x16x32_bf16 v[40:43], v[200:203], v[176:179], v[40:43]
	v_mfma_f32_16x16x32_bf16 v[36:39], v[212:215], v[176:179], v[36:39]
	v_mfma_f32_16x16x32_bf16 v[24:27], v[200:203], v[184:187], v[24:27]
	v_mfma_f32_16x16x32_bf16 v[20:23], v[212:215], v[184:187], v[20:23]
	v_mfma_f32_16x16x32_bf16 v[8:11], v[200:203], v[192:195], v[8:11]
	v_mfma_f32_16x16x32_bf16 v[4:7], v[212:215], v[192:195], v[4:7]
	v_mfma_f32_16x16x32_bf16 v[56:59], v[204:207], v[172:175], v[56:59]
	v_mfma_f32_16x16x32_bf16 v[52:55], v[216:219], v[172:175], v[52:55]
	v_mfma_f32_16x16x32_bf16 v[40:43], v[204:207], v[180:183], v[40:43]
	v_mfma_f32_16x16x32_bf16 v[36:39], v[216:219], v[180:183], v[36:39]
	v_mfma_f32_16x16x32_bf16 v[24:27], v[204:207], v[188:191], v[24:27]
	v_mfma_f32_16x16x32_bf16 v[20:23], v[216:219], v[188:191], v[20:23]
	v_mfma_f32_16x16x32_bf16 v[8:11], v[204:207], v[196:199], v[8:11]
	v_mfma_f32_16x16x32_bf16 v[4:7], v[216:219], v[196:199], v[4:7]
	s_setprio 0
	s_add_i32 s59, s59, 2
	s_add_u32 s30, s30, 0x100
	s_addc_u32 s31, s31, 0
	s_add_u32 s55, s55, 0x100
	s_addc_u32 s58, s58, 0
	s_cmp_gt_u32 s59, 29
	s_barrier
	s_cbranch_scc0 .LBB0_262
	s_cmp_gt_i32 s0, 31
	s_cselect_b64 vcc, -1, 0
	s_and_b64 s[30:31], vcc, exec
	s_cselect_b32 s2, 0x200, 0
	v_lshl_add_u64 v[128:129], v[144:145], 0, s[2:3]
	global_load_dwordx4 v[132:135], v[128:129], off
	s_nop 0
	global_load_dwordx4 v[128:131], v[128:129], off offset:16
	v_cndmask_b32_e32 v121, v125, v121, vcc
	v_cndmask_b32_e32 v120, v124, v120, vcc
	v_cndmask_b32_e32 v101, v101, v109, vcc
	v_cndmask_b32_e32 v100, v100, v108, vcc
	v_cndmask_b32_e32 v123, v127, v123, vcc
	v_cndmask_b32_e32 v122, v126, v122, vcc
	v_cndmask_b32_e32 v103, v103, v111, vcc
	v_cndmask_b32_e32 v102, v102, v110, vcc
	v_cndmask_b32_e32 v111, v119, v115, vcc
	v_cndmask_b32_e32 v110, v118, v114, vcc
	v_cndmask_b32_e32 v99, v99, v107, vcc
	v_cndmask_b32_e32 v98, v98, v106, vcc
	v_cndmask_b32_e32 v109, v117, v113, vcc
	v_cndmask_b32_e32 v108, v116, v112, vcc
	v_cndmask_b32_e32 v89, v93, v89, vcc
	v_cndmask_b32_e32 v88, v92, v88, vcc
	v_cndmask_b32_e32 v73, v73, v81, vcc
	v_cndmask_b32_e32 v72, v72, v80, vcc
	v_cndmask_b32_e32 v105, v97, v105, vcc
	v_cndmask_b32_e32 v104, v96, v104, vcc
	v_cndmask_b32_e32 v74, v74, v82, vcc
	v_lshl_add_u32 v152, s0, 8, v155
	v_ashrrev_i32_e32 v153, 31, v152
	v_lshlrev_b64 v[162:163], 8, v[152:153]
	v_cndmask_b32_e32 v75, v75, v83, vcc
	v_lshl_add_u64 v[96:97], v[146:147], 0, v[162:163]
	v_cndmask_b32_e32 v91, v95, v91, vcc
	v_cndmask_b32_e32 v90, v94, v90, vcc
	v_or_b32_e32 v160, 16, v152
	v_ashrrev_i32_e32 v161, 31, v160
	v_lshlrev_b64 v[106:107], 8, v[160:161]
	v_cndmask_b32_e32 v61, v61, v69, vcc
	v_cndmask_b32_e32 v60, v60, v68, vcc
	v_cndmask_b32_e32 v57, v65, v57, vcc
	v_cndmask_b32_e32 v56, v64, v56, vcc
	v_cndmask_b32_e32 v49, v49, v53, vcc
	v_cndmask_b32_e32 v48, v48, v52, vcc
	v_cndmask_b32_e32 v62, v62, v70, vcc
	v_cndmask_b32_e32 v50, v50, v54, vcc
	v_cndmask_b32_e32 v41, v45, v41, vcc
	v_cndmask_b32_e32 v40, v44, v40, vcc
	v_cndmask_b32_e32 v33, v33, v37, vcc
	v_cndmask_b32_e32 v32, v32, v36, vcc
	v_cndmask_b32_e32 v25, v29, v25, vcc
	v_cndmask_b32_e32 v24, v28, v24, vcc
	v_cndmask_b32_e32 v17, v17, v21, vcc
	v_cndmask_b32_e32 v16, v16, v20, vcc
	v_cndmask_b32_e32 v34, v34, v38, vcc
	v_cndmask_b32_e32 v18, v18, v22, vcc
	v_cndmask_b32_e32 v9, v13, v9, vcc
	v_cndmask_b32_e32 v8, v12, v8, vcc
	v_cndmask_b32_e32 v1, v1, v5, vcc
	v_cndmask_b32_e32 v0, v0, v4, vcc
	v_cndmask_b32_e32 v63, v63, v71, vcc
	v_cndmask_b32_e32 v51, v51, v55, vcc
	v_cndmask_b32_e32 v2, v2, v6, vcc
	v_cndmask_b32_e32 v35, v35, v39, vcc
	v_cndmask_b32_e32 v59, v67, v59, vcc
	v_cndmask_b32_e32 v58, v66, v58, vcc
	v_cndmask_b32_e32 v19, v19, v23, vcc
	v_cndmask_b32_e32 v43, v47, v43, vcc
	v_cndmask_b32_e32 v42, v46, v42, vcc
	v_cndmask_b32_e32 v3, v3, v7, vcc
	v_cndmask_b32_e32 v27, v31, v27, vcc
	v_cndmask_b32_e32 v26, v30, v26, vcc
	v_cndmask_b32_e32 v11, v15, v11, vcc
	v_cndmask_b32_e32 v10, v14, v10, vcc
	s_mov_b32 s0, 0x9000
	s_mov_b64 s[34:35], s[28:29]
	s_mov_b64 s[30:31], s[26:27]
	s_waitcnt vmcnt(0)
	v_pk_add_f32 v[114:115], v[120:121], v[132:133]
	v_pk_add_f32 v[100:101], v[100:101], v[128:129]
	v_pk_add_f32 v[112:113], v[122:123], v[134:135]
	v_pk_add_f32 v[102:103], v[102:103], v[130:131]
	v_pk_add_f32 v[116:117], v[98:99], v[130:131]
	v_mul_f32_e32 v98, 0xbfb8aa3b, v114
	v_mul_f32_e32 v99, 0xbfb8aa3b, v100
	v_mul_f32_e32 v118, 0xbfb8aa3b, v115
	v_mul_f32_e32 v119, 0xbfb8aa3b, v101
	v_mul_f32_e32 v120, 0xbfb8aa3b, v112
	v_mul_f32_e32 v121, 0xbfb8aa3b, v102
	v_mul_f32_e32 v122, 0xbfb8aa3b, v113
	v_mul_f32_e32 v123, 0xbfb8aa3b, v103
	v_exp_f32_e32 v98, v98
	v_exp_f32_e32 v99, v99
	v_exp_f32_e32 v118, v118
	v_exp_f32_e32 v119, v119
	v_exp_f32_e32 v120, v120
	v_exp_f32_e32 v121, v121
	v_exp_f32_e32 v122, v122
	v_exp_f32_e32 v123, v123
	v_pk_add_f32 v[88:89], v[88:89], v[132:133]
	v_pk_add_f32 v[72:73], v[72:73], v[128:129]
	v_add_f32_e32 v98, 1.0, v98
	v_add_f32_e32 v99, 1.0, v99
	v_add_f32_e32 v118, 1.0, v118
	v_add_f32_e32 v119, 1.0, v119
	v_mul_f32_e32 v80, 0xbfb8aa3b, v88
	v_mul_f32_e32 v81, 0xbfb8aa3b, v72
	v_mul_f32_e32 v82, 0xbfb8aa3b, v89
	v_pk_add_f32 v[104:105], v[104:105], v[128:129]
	v_add_f32_e32 v120, 1.0, v120
	v_add_f32_e32 v121, 1.0, v121
	v_add_f32_e32 v122, 1.0, v122
	v_add_f32_e32 v123, 1.0, v123
	v_rcp_f32_e32 v98, v98
	v_rcp_f32_e32 v99, v99
	v_rcp_f32_e32 v118, v118
	v_rcp_f32_e32 v119, v119
	v_exp_f32_e32 v80, v80
	v_exp_f32_e32 v81, v81
	v_exp_f32_e32 v82, v82
	v_mul_f32_e32 v127, 0xbfb8aa3b, v105
	v_rcp_f32_e32 v120, v120
	v_rcp_f32_e32 v121, v121
	v_rcp_f32_e32 v122, v122
	v_rcp_f32_e32 v123, v123
	v_exp_f32_e32 v127, v127
	v_mul_f32_e32 v98, v114, v98
	v_mul_f32_e32 v100, v100, v99
	v_mul_f32_e32 v99, v115, v118
	v_mul_f32_e32 v101, v101, v119
	v_add_f32_e32 v80, 1.0, v80
	v_add_f32_e32 v81, 1.0, v81
	v_add_f32_e32 v82, 1.0, v82
	v_mul_f32_e32 v83, 0xbfb8aa3b, v73
	v_pk_add_f32 v[110:111], v[110:111], v[134:135]
	v_mul_f32_e32 v112, v112, v120
	v_mul_f32_e32 v102, v102, v121
	v_mul_f32_e32 v113, v113, v122
	v_mul_f32_e32 v103, v103, v123
	v_cvt_pk_bf16_f32 v98, v98, v99
	v_cvt_pk_bf16_f32 v99, v112, v113
	v_cvt_pk_bf16_f32 v100, v100, v101
	v_cvt_pk_bf16_f32 v101, v102, v103
	v_rcp_f32_e32 v80, v80
	v_rcp_f32_e32 v81, v81
	v_rcp_f32_e32 v82, v82
	v_exp_f32_e32 v83, v83
	global_store_dwordx4 v[96:97], v[98:101], off
	v_pk_add_f32 v[90:91], v[90:91], v[134:135]
	v_pk_add_f32 v[74:75], v[74:75], v[130:131]
	v_add_f32_e32 v99, 1.0, v127
	v_mul_f32_e32 v100, 0xbfb8aa3b, v110
	v_mul_f32_e32 v101, 0xbfb8aa3b, v116
	v_rcp_f32_e32 v99, v99
	v_exp_f32_e32 v100, v100
	v_exp_f32_e32 v101, v101
	v_pk_add_f32 v[108:109], v[108:109], v[132:133]
	v_mul_f32_e32 v88, v88, v80
	v_mul_f32_e32 v92, v72, v81
	v_mul_f32_e32 v72, v89, v82
	v_add_f32_e32 v80, 1.0, v83
	v_mul_f32_e32 v81, 0xbfb8aa3b, v90
	v_mul_f32_e32 v82, 0xbfb8aa3b, v74
	v_mul_f32_e32 v126, 0xbfb8aa3b, v109
	v_rcp_f32_e32 v80, v80
	v_exp_f32_e32 v81, v81
	v_exp_f32_e32 v82, v82
	v_mul_f32_e32 v124, 0xbfb8aa3b, v108
	v_exp_f32_e32 v126, v126
	v_mul_f32_e32 v105, v105, v99
	v_add_f32_e32 v99, 1.0, v100
	v_add_f32_e32 v100, 1.0, v101
	v_mul_f32_e32 v101, 0xbfb8aa3b, v111
	v_mul_f32_e32 v102, 0xbfb8aa3b, v117
	v_mul_f32_e32 v125, 0xbfb8aa3b, v104
	v_exp_f32_e32 v124, v124
	v_exp_f32_e32 v101, v101
	v_exp_f32_e32 v102, v102
	v_exp_f32_e32 v125, v125
	v_mul_f32_e32 v83, v73, v80
	v_add_f32_e32 v73, 1.0, v81
	v_add_f32_e32 v80, 1.0, v82
	v_mul_f32_e32 v81, 0xbfb8aa3b, v91
	v_mul_f32_e32 v82, 0xbfb8aa3b, v75
	v_add_f32_e32 v126, 1.0, v126
	v_exp_f32_e32 v81, v81
	v_exp_f32_e32 v82, v82
	v_add_f32_e32 v124, 1.0, v124
	v_rcp_f32_e32 v126, v126
	v_add_f32_e32 v101, 1.0, v101
	v_add_f32_e32 v102, 1.0, v102
	v_add_f32_e32 v125, 1.0, v125
	v_rcp_f32_e32 v124, v124
	v_rcp_f32_e32 v99, v99
	v_rcp_f32_e32 v100, v100
	v_rcp_f32_e32 v101, v101
	v_rcp_f32_e32 v102, v102
	v_rcp_f32_e32 v125, v125
	v_add_f32_e32 v81, 1.0, v81
	v_add_f32_e32 v82, 1.0, v82
	v_mul_f32_e32 v98, v109, v126
	v_rcp_f32_e32 v73, v73
	v_rcp_f32_e32 v80, v80
	v_rcp_f32_e32 v81, v81
	v_rcp_f32_e32 v82, v82
	v_mul_f32_e32 v108, v108, v124
	v_mul_f32_e32 v99, v110, v99
	v_mul_f32_e32 v109, v116, v100
	v_mul_f32_e32 v100, v111, v101
	v_mul_f32_e32 v101, v117, v102
	v_lshl_add_u64 v[102:103], v[146:147], 0, v[106:107]
	v_cvt_pk_bf16_f32 v98, v108, v98
	v_mul_f32_e32 v104, v104, v125
	v_cvt_pk_bf16_f32 v99, v99, v100
	v_cvt_pk_bf16_f32 v100, v104, v105
	v_cvt_pk_bf16_f32 v101, v109, v101
	global_store_dwordx4 v[102:103], v[98:101], off
	v_mul_f32_e32 v73, v90, v73
	v_mul_f32_e32 v89, v74, v80
	v_or_b32_e32 v98, 32, v152
	v_ashrrev_i32_e32 v99, 31, v98
	v_lshlrev_b64 v[98:99], 8, v[98:99]
	v_mul_f32_e32 v74, v91, v81
	v_mul_f32_e32 v75, v75, v82
	v_lshl_add_u64 v[80:81], v[146:147], 0, v[98:99]
	v_cvt_pk_bf16_f32 v72, v88, v72
	v_cvt_pk_bf16_f32 v73, v73, v74
	v_cvt_pk_bf16_f32 v74, v92, v83
	v_cvt_pk_bf16_f32 v75, v89, v75
	global_store_dwordx4 v[80:81], v[72:75], off
	v_pk_add_f32 v[60:61], v[60:61], v[128:129]
	v_pk_add_f32 v[56:57], v[56:57], v[132:133]
	v_cndmask_b32_e32 v75, v85, v77, vcc
	v_cndmask_b32_e32 v74, v84, v76, vcc
	v_pk_add_f32 v[74:75], v[74:75], v[132:133]
	v_mul_f32_e32 v69, 0xbfb8aa3b, v60
	v_mul_f32_e32 v68, 0xbfb8aa3b, v74
	v_mul_f32_e32 v70, 0xbfb8aa3b, v75
	v_pk_add_f32 v[48:49], v[48:49], v[128:129]
	v_exp_f32_e32 v68, v68
	v_exp_f32_e32 v69, v69
	v_exp_f32_e32 v70, v70
	v_mul_f32_e32 v52, 0xbfb8aa3b, v56
	v_mul_f32_e32 v53, 0xbfb8aa3b, v48
	v_mul_f32_e32 v54, 0xbfb8aa3b, v57
	v_exp_f32_e32 v52, v52
	v_exp_f32_e32 v53, v53
	v_exp_f32_e32 v54, v54
	v_pk_add_f32 v[40:41], v[40:41], v[132:133]
	v_pk_add_f32 v[32:33], v[32:33], v[128:129]
	v_mul_f32_e32 v36, 0xbfb8aa3b, v40
	v_mul_f32_e32 v37, 0xbfb8aa3b, v32
	v_mul_f32_e32 v38, 0xbfb8aa3b, v41
	v_pk_add_f32 v[24:25], v[24:25], v[132:133]
	v_pk_add_f32 v[16:17], v[16:17], v[128:129]
	v_exp_f32_e32 v36, v36
	v_exp_f32_e32 v37, v37
	v_exp_f32_e32 v38, v38
	v_mul_f32_e32 v20, 0xbfb8aa3b, v24
	v_mul_f32_e32 v21, 0xbfb8aa3b, v16
	v_mul_f32_e32 v22, 0xbfb8aa3b, v25
	v_add_f32_e32 v68, 1.0, v68
	v_add_f32_e32 v69, 1.0, v69
	v_add_f32_e32 v70, 1.0, v70
	v_mul_f32_e32 v71, 0xbfb8aa3b, v61
	v_exp_f32_e32 v20, v20
	v_exp_f32_e32 v21, v21
	v_exp_f32_e32 v22, v22
	v_pk_add_f32 v[8:9], v[8:9], v[132:133]
	v_pk_add_f32 v[0:1], v[0:1], v[128:129]
	v_rcp_f32_e32 v68, v68
	v_rcp_f32_e32 v69, v69
	v_rcp_f32_e32 v70, v70
	v_exp_f32_e32 v71, v71
	v_add_f32_e32 v52, 1.0, v52
	v_add_f32_e32 v53, 1.0, v53
	v_add_f32_e32 v54, 1.0, v54
	v_mul_f32_e32 v55, 0xbfb8aa3b, v49
	v_mul_f32_e32 v4, 0xbfb8aa3b, v8
	v_mul_f32_e32 v5, 0xbfb8aa3b, v0
	v_mul_f32_e32 v6, 0xbfb8aa3b, v9
	v_rcp_f32_e32 v52, v52
	v_rcp_f32_e32 v53, v53
	v_rcp_f32_e32 v54, v54
	v_exp_f32_e32 v55, v55
	v_exp_f32_e32 v4, v4
	v_exp_f32_e32 v5, v5
	v_exp_f32_e32 v6, v6
	v_cndmask_b32_e32 v77, v87, v79, vcc
	v_cndmask_b32_e32 v76, v86, v78, vcc
	v_add_f32_e32 v36, 1.0, v36
	v_add_f32_e32 v37, 1.0, v37
	v_add_f32_e32 v38, 1.0, v38
	v_mul_f32_e32 v39, 0xbfb8aa3b, v33
	v_pk_add_f32 v[76:77], v[76:77], v[134:135]
	v_pk_add_f32 v[62:63], v[62:63], v[130:131]
	v_rcp_f32_e32 v36, v36
	v_rcp_f32_e32 v37, v37
	v_rcp_f32_e32 v38, v38
	v_exp_f32_e32 v39, v39
	v_add_f32_e32 v20, 1.0, v20
	v_add_f32_e32 v21, 1.0, v21
	v_add_f32_e32 v22, 1.0, v22
	v_mul_f32_e32 v23, 0xbfb8aa3b, v17
	v_mul_f32_e32 v74, v74, v68
	v_mul_f32_e32 v78, v60, v69
	v_mul_f32_e32 v60, v75, v70
	v_add_f32_e32 v68, 1.0, v71
	v_mul_f32_e32 v69, 0xbfb8aa3b, v76
	v_mul_f32_e32 v70, 0xbfb8aa3b, v62
	v_pk_add_f32 v[58:59], v[58:59], v[134:135]
	v_pk_add_f32 v[50:51], v[50:51], v[130:131]
	v_rcp_f32_e32 v20, v20
	v_rcp_f32_e32 v21, v21
	v_rcp_f32_e32 v22, v22
	v_exp_f32_e32 v23, v23
	v_rcp_f32_e32 v68, v68
	v_exp_f32_e32 v69, v69
	v_exp_f32_e32 v70, v70
	v_mul_f32_e32 v52, v56, v52
	v_mul_f32_e32 v53, v48, v53
	v_mul_f32_e32 v48, v57, v54
	v_add_f32_e32 v54, 1.0, v55
	v_mul_f32_e32 v55, 0xbfb8aa3b, v58
	v_mul_f32_e32 v56, 0xbfb8aa3b, v50
	v_add_f32_e32 v4, 1.0, v4
	v_add_f32_e32 v5, 1.0, v5
	v_add_f32_e32 v6, 1.0, v6
	v_mul_f32_e32 v7, 0xbfb8aa3b, v1
	v_rcp_f32_e32 v54, v54
	v_exp_f32_e32 v55, v55
	v_exp_f32_e32 v56, v56
	v_pk_add_f32 v[42:43], v[42:43], v[134:135]
	v_pk_add_f32 v[34:35], v[34:35], v[130:131]
	v_rcp_f32_e32 v4, v4
	v_rcp_f32_e32 v5, v5
	v_rcp_f32_e32 v6, v6
	v_exp_f32_e32 v7, v7
	v_mul_f32_e32 v36, v40, v36
	v_mul_f32_e32 v37, v32, v37
	v_mul_f32_e32 v32, v41, v38
	v_add_f32_e32 v38, 1.0, v39
	v_mul_f32_e32 v39, 0xbfb8aa3b, v42
	v_mul_f32_e32 v40, 0xbfb8aa3b, v34
	v_pk_add_f32 v[26:27], v[26:27], v[134:135]
	v_pk_add_f32 v[18:19], v[18:19], v[130:131]
	v_rcp_f32_e32 v38, v38
	v_exp_f32_e32 v39, v39
	v_exp_f32_e32 v40, v40
	v_mul_f32_e32 v20, v24, v20
	v_mul_f32_e32 v21, v16, v21
	v_mul_f32_e32 v16, v25, v22
	v_add_f32_e32 v22, 1.0, v23
	v_mul_f32_e32 v23, 0xbfb8aa3b, v26
	v_mul_f32_e32 v24, 0xbfb8aa3b, v18
	v_mul_f32_e32 v71, v61, v68
	v_add_f32_e32 v61, 1.0, v69
	v_add_f32_e32 v68, 1.0, v70
	v_mul_f32_e32 v69, 0xbfb8aa3b, v77
	v_mul_f32_e32 v70, 0xbfb8aa3b, v63
	v_rcp_f32_e32 v22, v22
	v_exp_f32_e32 v23, v23
	v_exp_f32_e32 v24, v24
	v_pk_add_f32 v[10:11], v[10:11], v[134:135]
	v_pk_add_f32 v[2:3], v[2:3], v[130:131]
	v_exp_f32_e32 v69, v69
	v_exp_f32_e32 v70, v70
	v_mul_f32_e32 v54, v49, v54
	v_add_f32_e32 v49, 1.0, v55
	v_add_f32_e32 v55, 1.0, v56
	v_mul_f32_e32 v56, 0xbfb8aa3b, v59
	v_mul_f32_e32 v4, v8, v4
	v_mul_f32_e32 v5, v0, v5
	v_mul_f32_e32 v0, v9, v6
	v_add_f32_e32 v6, 1.0, v7
	v_mul_f32_e32 v7, 0xbfb8aa3b, v10
	v_mul_f32_e32 v8, 0xbfb8aa3b, v2
	v_exp_f32_e32 v56, v56
	v_rcp_f32_e32 v6, v6
	v_exp_f32_e32 v7, v7
	v_exp_f32_e32 v8, v8
	v_mul_f32_e32 v57, 0xbfb8aa3b, v51
	v_mul_f32_e32 v38, v33, v38
	v_add_f32_e32 v33, 1.0, v39
	v_add_f32_e32 v39, 1.0, v40
	v_mul_f32_e32 v40, 0xbfb8aa3b, v43
	v_mul_f32_e32 v41, 0xbfb8aa3b, v35
	v_exp_f32_e32 v57, v57
	v_exp_f32_e32 v40, v40
	v_exp_f32_e32 v41, v41
	v_mul_f32_e32 v22, v17, v22
	v_add_f32_e32 v17, 1.0, v23
	v_add_f32_e32 v23, 1.0, v24
	v_mul_f32_e32 v24, 0xbfb8aa3b, v27
	v_add_f32_e32 v69, 1.0, v69
	v_add_f32_e32 v70, 1.0, v70
	v_exp_f32_e32 v24, v24
	v_mul_f32_e32 v25, 0xbfb8aa3b, v19
	v_rcp_f32_e32 v61, v61
	v_rcp_f32_e32 v68, v68
	v_rcp_f32_e32 v69, v69
	v_rcp_f32_e32 v70, v70
	v_add_f32_e32 v56, 1.0, v56
	v_exp_f32_e32 v25, v25
	v_mul_f32_e32 v6, v1, v6
	v_add_f32_e32 v1, 1.0, v7
	v_add_f32_e32 v7, 1.0, v8
	v_mul_f32_e32 v8, 0xbfb8aa3b, v11
	v_or_b32_e32 v72, 48, v152
	v_rcp_f32_e32 v49, v49
	v_rcp_f32_e32 v55, v55
	v_rcp_f32_e32 v56, v56
	v_exp_f32_e32 v8, v8
	v_ashrrev_i32_e32 v73, 31, v72
	v_add_f32_e32 v57, 1.0, v57
	v_add_f32_e32 v40, 1.0, v40
	v_add_f32_e32 v41, 1.0, v41
	v_mul_f32_e32 v9, 0xbfb8aa3b, v3
	v_lshlrev_b64 v[72:73], 8, v[72:73]
	v_rcp_f32_e32 v57, v57
	v_rcp_f32_e32 v33, v33
	v_rcp_f32_e32 v39, v39
	v_rcp_f32_e32 v40, v40
	v_rcp_f32_e32 v41, v41
	v_add_f32_e32 v24, 1.0, v24
	v_exp_f32_e32 v9, v9
	v_mul_f32_e32 v61, v76, v61
	v_mul_f32_e32 v75, v62, v68
	v_mul_f32_e32 v62, v77, v69
	v_mul_f32_e32 v63, v63, v70
	v_lshl_add_u64 v[68:69], v[146:147], 0, v[72:73]
	v_rcp_f32_e32 v17, v17
	v_rcp_f32_e32 v23, v23
	v_rcp_f32_e32 v24, v24
	v_add_f32_e32 v25, 1.0, v25
	v_cvt_pk_bf16_f32 v60, v74, v60
	v_cvt_pk_bf16_f32 v61, v61, v62
	v_cvt_pk_bf16_f32 v62, v78, v71
	v_cvt_pk_bf16_f32 v63, v75, v63
	global_store_dwordx4 v[68:69], v[60:63], off
	v_mul_f32_e32 v49, v58, v49
	v_mul_f32_e32 v55, v50, v55
	v_mul_f32_e32 v50, v59, v56
	v_cvt_pk_bf16_f32 v48, v52, v48
	v_add_co_u32_e64 v52, s[0:1], s0, v96
	v_rcp_f32_e32 v25, v25
	v_add_f32_e32 v8, 1.0, v8
	v_cvt_pk_bf16_f32 v49, v49, v50
	v_cvt_pk_bf16_f32 v50, v53, v54
	v_addc_co_u32_e64 v53, s[0:1], 0, v97, s[0:1]
	v_rcp_f32_e32 v1, v1
	v_rcp_f32_e32 v7, v7
	v_rcp_f32_e32 v8, v8
	v_mul_f32_e32 v51, v51, v57
	v_mul_f32_e32 v33, v42, v33
	v_mul_f32_e32 v39, v34, v39
	v_mul_f32_e32 v34, v43, v40
	v_mul_f32_e32 v35, v35, v41
	s_mov_b32 s0, 0xa000
	v_add_f32_e32 v9, 1.0, v9
	v_cvt_pk_bf16_f32 v51, v55, v51
	global_store_dwordx4 v[52:53], v[48:51], off offset:-4096
	v_cvt_pk_bf16_f32 v32, v36, v32
	v_cvt_pk_bf16_f32 v33, v33, v34
	v_cvt_pk_bf16_f32 v34, v37, v38
	v_cvt_pk_bf16_f32 v35, v39, v35
	global_store_dwordx4 v[52:53], v[32:35], off
	v_mul_f32_e32 v17, v26, v17
	v_mul_f32_e32 v23, v18, v23
	v_mul_f32_e32 v18, v27, v24
	v_cvt_pk_bf16_f32 v16, v20, v16
	v_add_co_u32_e64 v20, s[0:1], s0, v96
	v_rcp_f32_e32 v9, v9
	v_mul_f32_e32 v19, v19, v25
	v_cvt_pk_bf16_f32 v17, v17, v18
	v_cvt_pk_bf16_f32 v18, v21, v22
	v_addc_co_u32_e64 v21, s[0:1], 0, v97, s[0:1]
	v_cvt_pk_bf16_f32 v19, v23, v19
	global_store_dwordx4 v[20:21], v[16:19], off
	v_mul_f32_e32 v1, v10, v1
	v_mul_f32_e32 v7, v2, v7
	v_mul_f32_e32 v2, v11, v8
	v_cvt_pk_bf16_f32 v0, v4, v0
	v_add_co_u32_e32 v4, vcc, 0xb000, v96
	v_cvt_pk_bf16_f32 v1, v1, v2
	v_cvt_pk_bf16_f32 v2, v5, v6
	v_mul_f32_e32 v3, v3, v9
	s_nop 0
	v_addc_co_u32_e32 v5, vcc, 0, v97, vcc
	s_and_b64 vcc, exec, s[8:9]
	s_mov_b32 s0, s14
	v_cvt_pk_bf16_f32 v3, v7, v3
	global_store_dwordx4 v[4:5], v[0:3], off
	s_cbranch_vccz .LBB0_255
	s_waitcnt vmcnt(0)
	s_cmpk_gt_u32 s33, 0xff
	s_cbranch_scc1 .LBB0_266
	s_barrier

.LBB0_654:
	ds_read_b128 v[144:147], v157
	ds_read_b128 v[148:151], v157 offset:1024
	ds_read_b128 v[160:163], v157 offset:2048
	ds_read_b128 v[164:167], v157 offset:3072
	s_add_u32 s24, s22, 0xfffc0080
	s_addc_u32 s25, s23, -1
	s_cmp_eq_u32 s49, 12
	s_cselect_b32 s27, s13, s25
	s_cselect_b32 s26, s19, s24
	s_cselect_b32 s25, s3, s48
	s_cselect_b32 s24, s42, s43
	v_lshl_add_u64 v[152:153], s[22:23], 0, v[136:137]
	s_add_i32 m0, s21, 0xc000
	ds_read_b128 v[168:171], v158
	ds_read_b128 v[176:179], v158 offset:1024
	ds_read_b128 v[180:183], v158 offset:2048
	ds_read_b128 v[184:187], v158 offset:3072
	ds_read_b128 v[188:191], v158 offset:4096
	ds_read_b128 v[192:195], v158 offset:5120
	ds_read_b128 v[196:199], v158 offset:6144
	ds_read_b128 v[200:203], v158 offset:7168
	global_load_lds_dwordx4 v[152:153], off
	v_lshl_add_u64 v[152:153], s[22:23], 0, v[138:139]
	s_add_i32 m0, s21, 0xe000
	s_nop 0
	global_load_lds_dwordx4 v[152:153], off
	s_waitcnt lgkmcnt(8)
	s_setprio 1
	s_barrier
	s_waitcnt lgkmcnt(0)
	v_mfma_f32_16x16x32_bf16 v[124:127], v[144:147], v[168:171], v[124:127]
	v_mfma_f32_16x16x32_bf16 v[120:123], v[160:163], v[168:171], v[120:123]
	v_mfma_f32_16x16x32_bf16 v[116:119], v[144:147], v[180:183], v[116:119]
	v_mfma_f32_16x16x32_bf16 v[112:115], v[160:163], v[180:183], v[112:115]
	v_mfma_f32_16x16x32_bf16 v[96:99], v[144:147], v[188:191], v[96:99]
	v_mfma_f32_16x16x32_bf16 v[88:91], v[160:163], v[188:191], v[88:91]
	v_mfma_f32_16x16x32_bf16 v[80:83], v[144:147], v[196:199], v[80:83]
	v_mfma_f32_16x16x32_bf16 v[72:75], v[160:163], v[196:199], v[72:75]
	v_mfma_f32_16x16x32_bf16 v[124:127], v[148:151], v[176:179], v[124:127]
	v_mfma_f32_16x16x32_bf16 v[120:123], v[164:167], v[176:179], v[120:123]
	v_mfma_f32_16x16x32_bf16 v[116:119], v[148:151], v[184:187], v[116:119]
	v_mfma_f32_16x16x32_bf16 v[112:115], v[164:167], v[184:187], v[112:115]
	v_mfma_f32_16x16x32_bf16 v[96:99], v[148:151], v[192:195], v[96:99]
	v_mfma_f32_16x16x32_bf16 v[88:91], v[164:167], v[192:195], v[88:91]
	v_mfma_f32_16x16x32_bf16 v[80:83], v[148:151], v[200:203], v[80:83]
	v_mfma_f32_16x16x32_bf16 v[72:75], v[164:167], v[200:203], v[72:75]
	s_setprio 0
	s_barrier
	s_add_i32 s50, s40, s29
	v_lshl_add_u64 v[152:153], s[24:25], 0, v[130:131]
	s_mov_b32 m0, s50
	ds_read_b128 v[204:207], v159
	ds_read_b128 v[212:215], v159 offset:1024
	ds_read_b128 v[216:219], v159 offset:2048
	ds_read_b128 v[220:223], v159 offset:3072
	global_load_lds_dwordx4 v[152:153], off
	v_lshl_add_u64 v[172:173], s[24:25], 0, v[134:135]
	s_add_i32 m0, s50, 0x2000
	s_nop 0
	global_load_lds_dwordx4 v[172:173], off
	s_setprio 1
	s_barrier
	s_waitcnt lgkmcnt(0)
	v_mfma_f32_16x16x32_bf16 v[108:111], v[204:207], v[168:171], v[108:111]
	v_mfma_f32_16x16x32_bf16 v[104:107], v[216:219], v[168:171], v[104:107]
	v_mfma_f32_16x16x32_bf16 v[100:103], v[204:207], v[180:183], v[100:103]
	v_mfma_f32_16x16x32_bf16 v[92:95], v[216:219], v[180:183], v[92:95]
	v_mfma_f32_16x16x32_bf16 v[84:87], v[204:207], v[188:191], v[84:87]
	v_mfma_f32_16x16x32_bf16 v[76:79], v[216:219], v[188:191], v[76:79]
	v_mfma_f32_16x16x32_bf16 v[68:71], v[204:207], v[196:199], v[68:71]
	v_mfma_f32_16x16x32_bf16 v[64:67], v[216:219], v[196:199], v[64:67]
	v_mfma_f32_16x16x32_bf16 v[108:111], v[212:215], v[176:179], v[108:111]
	v_mfma_f32_16x16x32_bf16 v[104:107], v[220:223], v[176:179], v[104:107]
	v_mfma_f32_16x16x32_bf16 v[100:103], v[212:215], v[184:187], v[100:103]
	v_mfma_f32_16x16x32_bf16 v[92:95], v[220:223], v[184:187], v[92:95]
	v_mfma_f32_16x16x32_bf16 v[84:87], v[212:215], v[192:195], v[84:87]
	v_mfma_f32_16x16x32_bf16 v[76:79], v[220:223], v[192:195], v[76:79]
	v_mfma_f32_16x16x32_bf16 v[68:71], v[212:215], v[200:203], v[68:71]
	v_mfma_f32_16x16x32_bf16 v[64:67], v[220:223], v[200:203], v[64:67]
	s_setprio 0
	s_mov_b32 m0, s21
	v_lshl_add_u64 v[208:209], s[26:27], 0, v[128:129]
	s_barrier
	ds_read_b128 v[168:171], v158 offset:16384
	ds_read_b128 v[176:179], v158 offset:17408
	ds_read_b128 v[180:183], v158 offset:18432
	ds_read_b128 v[184:187], v158 offset:19456
	ds_read_b128 v[188:191], v158 offset:20480
	ds_read_b128 v[192:195], v158 offset:21504
	ds_read_b128 v[196:199], v158 offset:22528
	ds_read_b128 v[200:203], v158 offset:23552
	global_load_lds_dwordx4 v[208:209], off
	v_lshl_add_u64 v[224:225], s[26:27], 0, v[132:133]
	s_mov_b32 m0, s30
	s_nop 0
	global_load_lds_dwordx4 v[224:225], off
	s_setprio 1
	s_barrier
	s_waitcnt lgkmcnt(0)
	v_mfma_f32_16x16x32_bf16 v[60:63], v[144:147], v[168:171], v[60:63]
	v_mfma_f32_16x16x32_bf16 v[56:59], v[160:163], v[168:171], v[56:59]
	v_mfma_f32_16x16x32_bf16 v[52:55], v[144:147], v[180:183], v[52:55]
	v_mfma_f32_16x16x32_bf16 v[48:51], v[160:163], v[180:183], v[48:51]
	v_mfma_f32_16x16x32_bf16 v[32:35], v[144:147], v[188:191], v[32:35]
	v_mfma_f32_16x16x32_bf16 v[24:27], v[160:163], v[188:191], v[24:27]
	v_mfma_f32_16x16x32_bf16 v[16:19], v[144:147], v[196:199], v[16:19]
	v_mfma_f32_16x16x32_bf16 v[8:11], v[160:163], v[196:199], v[8:11]
	v_mfma_f32_16x16x32_bf16 v[60:63], v[148:151], v[176:179], v[60:63]
	v_mfma_f32_16x16x32_bf16 v[56:59], v[164:167], v[176:179], v[56:59]
	v_mfma_f32_16x16x32_bf16 v[52:55], v[148:151], v[184:187], v[52:55]
	v_mfma_f32_16x16x32_bf16 v[48:51], v[164:167], v[184:187], v[48:51]
	v_mfma_f32_16x16x32_bf16 v[32:35], v[148:151], v[192:195], v[32:35]
	v_mfma_f32_16x16x32_bf16 v[24:27], v[164:167], v[192:195], v[24:27]
	v_mfma_f32_16x16x32_bf16 v[16:19], v[148:151], v[200:203], v[16:19]
	v_mfma_f32_16x16x32_bf16 v[8:11], v[164:167], v[200:203], v[8:11]
	s_setprio 0
	s_barrier
	s_add_u32 s50, s24, 0x40000
	s_addc_u32 s51, s25, 0
	s_add_i32 s52, s41, s29
	v_lshl_add_u64 v[144:145], s[50:51], 0, v[130:131]
	s_mov_b32 m0, s52
	s_nop 0
	global_load_lds_dwordx4 v[144:145], off
	v_lshl_add_u64 v[144:145], s[50:51], 0, v[134:135]
	s_add_i32 m0, s52, 0x2000
	s_nop 0
	global_load_lds_dwordx4 v[144:145], off
	s_waitcnt vmcnt(6)
	s_setprio 1
	s_barrier
	v_mfma_f32_16x16x32_bf16 v[44:47], v[204:207], v[168:171], v[44:47]
	v_mfma_f32_16x16x32_bf16 v[40:43], v[216:219], v[168:171], v[40:43]
	v_mfma_f32_16x16x32_bf16 v[36:39], v[204:207], v[180:183], v[36:39]
	v_mfma_f32_16x16x32_bf16 v[28:31], v[216:219], v[180:183], v[28:31]
	v_mfma_f32_16x16x32_bf16 v[20:23], v[204:207], v[188:191], v[20:23]
	v_mfma_f32_16x16x32_bf16 v[12:15], v[216:219], v[188:191], v[12:15]
	v_mfma_f32_16x16x32_bf16 v[4:7], v[204:207], v[196:199], v[4:7]
	v_mfma_f32_16x16x32_bf16 v[0:3], v[216:219], v[196:199], v[0:3]
	v_mfma_f32_16x16x32_bf16 v[44:47], v[212:215], v[176:179], v[44:47]
	v_mfma_f32_16x16x32_bf16 v[40:43], v[220:223], v[176:179], v[40:43]
	v_mfma_f32_16x16x32_bf16 v[36:39], v[212:215], v[184:187], v[36:39]
	v_mfma_f32_16x16x32_bf16 v[28:31], v[220:223], v[184:187], v[28:31]
	v_mfma_f32_16x16x32_bf16 v[20:23], v[212:215], v[192:195], v[20:23]
	v_mfma_f32_16x16x32_bf16 v[12:15], v[220:223], v[192:195], v[12:15]
	v_mfma_f32_16x16x32_bf16 v[4:7], v[212:215], v[200:203], v[4:7]
	v_mfma_f32_16x16x32_bf16 v[0:3], v[220:223], v[200:203], v[0:3]
	s_setprio 0
	s_add_i32 s50, 0, 0x18000
	v_add_u32_e32 v164, s50, v155
	s_barrier
	ds_read_b128 v[144:147], v164
	ds_read_b128 v[148:151], v164 offset:1024
	ds_read_b128 v[160:163], v164 offset:2048
	ds_read_b128 v[164:167], v164 offset:3072
	s_add_u32 s26, s26, 0x40000
	s_addc_u32 s27, s27, 0
	s_mov_b32 m0, s31
	v_lshl_add_u64 v[204:205], s[26:27], 0, v[128:129]
	ds_read_b128 v[168:171], v158 offset:32768
	ds_read_b128 v[176:179], v158 offset:33792
	ds_read_b128 v[180:183], v158 offset:34816
	ds_read_b128 v[184:187], v158 offset:35840
	ds_read_b128 v[188:191], v158 offset:36864
	ds_read_b128 v[192:195], v158 offset:37888
	ds_read_b128 v[196:199], v158 offset:38912
	ds_read_b128 v[200:203], v158 offset:39936
	global_load_lds_dwordx4 v[204:205], off
	v_lshl_add_u64 v[204:205], s[26:27], 0, v[132:133]
	s_mov_b32 m0, s33
	s_nop 0
	global_load_lds_dwordx4 v[204:205], off
	s_waitcnt lgkmcnt(8)
	s_setprio 1
	s_barrier
	s_waitcnt lgkmcnt(0)
	v_mfma_f32_16x16x32_bf16 v[124:127], v[144:147], v[168:171], v[124:127]
	v_mfma_f32_16x16x32_bf16 v[120:123], v[160:163], v[168:171], v[120:123]
	v_mfma_f32_16x16x32_bf16 v[116:119], v[144:147], v[180:183], v[116:119]
	v_mfma_f32_16x16x32_bf16 v[112:115], v[160:163], v[180:183], v[112:115]
	v_mfma_f32_16x16x32_bf16 v[96:99], v[144:147], v[188:191], v[96:99]
	v_mfma_f32_16x16x32_bf16 v[88:91], v[160:163], v[188:191], v[88:91]
	v_mfma_f32_16x16x32_bf16 v[80:83], v[144:147], v[196:199], v[80:83]
	v_mfma_f32_16x16x32_bf16 v[72:75], v[160:163], v[196:199], v[72:75]
	v_mfma_f32_16x16x32_bf16 v[124:127], v[148:151], v[176:179], v[124:127]
	v_mfma_f32_16x16x32_bf16 v[120:123], v[164:167], v[176:179], v[120:123]
	v_mfma_f32_16x16x32_bf16 v[116:119], v[148:151], v[184:187], v[116:119]
	v_mfma_f32_16x16x32_bf16 v[112:115], v[164:167], v[184:187], v[112:115]
	v_mfma_f32_16x16x32_bf16 v[96:99], v[148:151], v[192:195], v[96:99]
	v_mfma_f32_16x16x32_bf16 v[88:91], v[164:167], v[192:195], v[88:91]
	v_mfma_f32_16x16x32_bf16 v[80:83], v[148:151], v[200:203], v[80:83]
	v_mfma_f32_16x16x32_bf16 v[72:75], v[164:167], v[200:203], v[72:75]
	s_setprio 0
	s_barrier
	s_add_i32 s26, 0, 0x1c000
	s_add_i32 s27, s50, s29
	v_add_u32_e32 v175, s26, v155
	v_lshl_add_u64 v[152:153], v[152:153], 0, s[0:1]
	s_mov_b32 m0, s27
	ds_read_b128 v[204:207], v175
	ds_read_b128 v[212:215], v175 offset:1024
	ds_read_b128 v[216:219], v175 offset:2048
	ds_read_b128 v[220:223], v175 offset:3072
	global_load_lds_dwordx4 v[152:153], off
	v_lshl_add_u64 v[152:153], v[172:173], 0, s[0:1]
	s_add_i32 m0, s27, 0x2000
	s_nop 0
	global_load_lds_dwordx4 v[152:153], off
	s_setprio 1
	s_barrier
	s_waitcnt lgkmcnt(0)
	v_mfma_f32_16x16x32_bf16 v[108:111], v[204:207], v[168:171], v[108:111]
	v_mfma_f32_16x16x32_bf16 v[104:107], v[216:219], v[168:171], v[104:107]
	v_mfma_f32_16x16x32_bf16 v[100:103], v[204:207], v[180:183], v[100:103]
	v_mfma_f32_16x16x32_bf16 v[92:95], v[216:219], v[180:183], v[92:95]
	v_mfma_f32_16x16x32_bf16 v[84:87], v[204:207], v[188:191], v[84:87]
	v_mfma_f32_16x16x32_bf16 v[76:79], v[216:219], v[188:191], v[76:79]
	v_mfma_f32_16x16x32_bf16 v[68:71], v[204:207], v[196:199], v[68:71]
	v_mfma_f32_16x16x32_bf16 v[64:67], v[216:219], v[196:199], v[64:67]
	v_mfma_f32_16x16x32_bf16 v[108:111], v[212:215], v[176:179], v[108:111]
	v_mfma_f32_16x16x32_bf16 v[104:107], v[220:223], v[176:179], v[104:107]
	v_mfma_f32_16x16x32_bf16 v[100:103], v[212:215], v[184:187], v[100:103]
	v_mfma_f32_16x16x32_bf16 v[92:95], v[220:223], v[184:187], v[92:95]
	v_mfma_f32_16x16x32_bf16 v[84:87], v[212:215], v[192:195], v[84:87]
	v_mfma_f32_16x16x32_bf16 v[76:79], v[220:223], v[192:195], v[76:79]
	v_mfma_f32_16x16x32_bf16 v[68:71], v[212:215], v[200:203], v[68:71]
	v_mfma_f32_16x16x32_bf16 v[64:67], v[220:223], v[200:203], v[64:67]
	s_setprio 0
	s_mov_b32 m0, s35
	v_lshl_add_u64 v[152:153], v[208:209], 0, s[0:1]
	s_barrier
	ds_read_b128 v[168:171], v158 offset:49152
	ds_read_b128 v[176:179], v158 offset:50176
	ds_read_b128 v[180:183], v158 offset:51200
	ds_read_b128 v[184:187], v158 offset:52224
	ds_read_b128 v[188:191], v158 offset:53248
	ds_read_b128 v[192:195], v158 offset:54272
	ds_read_b128 v[196:199], v158 offset:55296
	ds_read_b128 v[200:203], v158 offset:56320
	global_load_lds_dwordx4 v[152:153], off
	v_lshl_add_u64 v[152:153], v[224:225], 0, s[0:1]
	s_mov_b32 m0, s36
	s_nop 0
	global_load_lds_dwordx4 v[152:153], off
	s_setprio 1
	s_barrier
	s_waitcnt lgkmcnt(0)
	v_mfma_f32_16x16x32_bf16 v[60:63], v[144:147], v[168:171], v[60:63]
	v_mfma_f32_16x16x32_bf16 v[56:59], v[160:163], v[168:171], v[56:59]
	v_mfma_f32_16x16x32_bf16 v[52:55], v[144:147], v[180:183], v[52:55]
	v_mfma_f32_16x16x32_bf16 v[48:51], v[160:163], v[180:183], v[48:51]
	v_mfma_f32_16x16x32_bf16 v[32:35], v[144:147], v[188:191], v[32:35]
	v_mfma_f32_16x16x32_bf16 v[24:27], v[160:163], v[188:191], v[24:27]
	v_mfma_f32_16x16x32_bf16 v[16:19], v[144:147], v[196:199], v[16:19]
	v_mfma_f32_16x16x32_bf16 v[8:11], v[160:163], v[196:199], v[8:11]
	v_mfma_f32_16x16x32_bf16 v[60:63], v[148:151], v[176:179], v[60:63]
	v_mfma_f32_16x16x32_bf16 v[56:59], v[164:167], v[176:179], v[56:59]
	v_mfma_f32_16x16x32_bf16 v[52:55], v[148:151], v[184:187], v[52:55]
	v_mfma_f32_16x16x32_bf16 v[48:51], v[164:167], v[184:187], v[48:51]
	v_mfma_f32_16x16x32_bf16 v[32:35], v[148:151], v[192:195], v[32:35]
	v_mfma_f32_16x16x32_bf16 v[24:27], v[164:167], v[192:195], v[24:27]
	v_mfma_f32_16x16x32_bf16 v[16:19], v[148:151], v[200:203], v[16:19]
	v_mfma_f32_16x16x32_bf16 v[8:11], v[164:167], v[200:203], v[8:11]
	s_setprio 0
	s_barrier
	s_add_u32 s24, s24, 0x40080
	s_addc_u32 s25, s25, 0
	s_add_i32 s26, s26, s29
	v_lshl_add_u64 v[144:145], s[24:25], 0, v[130:131]
	s_mov_b32 m0, s26
	s_nop 0
	global_load_lds_dwordx4 v[144:145], off
	v_lshl_add_u64 v[144:145], s[24:25], 0, v[134:135]
	s_add_i32 m0, s26, 0x2000
	s_nop 0
	global_load_lds_dwordx4 v[144:145], off
	s_waitcnt vmcnt(6)
	s_setprio 1
	s_barrier
	v_mfma_f32_16x16x32_bf16 v[44:47], v[204:207], v[168:171], v[44:47]
	v_mfma_f32_16x16x32_bf16 v[40:43], v[216:219], v[168:171], v[40:43]
	v_mfma_f32_16x16x32_bf16 v[36:39], v[204:207], v[180:183], v[36:39]
	v_mfma_f32_16x16x32_bf16 v[28:31], v[216:219], v[180:183], v[28:31]
	v_mfma_f32_16x16x32_bf16 v[20:23], v[204:207], v[188:191], v[20:23]
	v_mfma_f32_16x16x32_bf16 v[12:15], v[216:219], v[188:191], v[12:15]
	v_mfma_f32_16x16x32_bf16 v[4:7], v[204:207], v[196:199], v[4:7]
	v_mfma_f32_16x16x32_bf16 v[0:3], v[216:219], v[196:199], v[0:3]
	v_mfma_f32_16x16x32_bf16 v[44:47], v[212:215], v[176:179], v[44:47]
	v_mfma_f32_16x16x32_bf16 v[40:43], v[220:223], v[176:179], v[40:43]
	v_mfma_f32_16x16x32_bf16 v[36:39], v[212:215], v[184:187], v[36:39]
	v_mfma_f32_16x16x32_bf16 v[28:31], v[220:223], v[184:187], v[28:31]
	v_mfma_f32_16x16x32_bf16 v[20:23], v[212:215], v[192:195], v[20:23]
	v_mfma_f32_16x16x32_bf16 v[12:15], v[220:223], v[192:195], v[12:15]
	v_mfma_f32_16x16x32_bf16 v[4:7], v[212:215], v[200:203], v[4:7]
	v_mfma_f32_16x16x32_bf16 v[0:3], v[220:223], v[200:203], v[0:3]
	s_setprio 0
	s_add_i32 s49, s49, 2
	s_add_u32 s22, s22, 0x100
	s_addc_u32 s23, s23, 0
	s_add_u32 s43, s43, 0x100
	s_addc_u32 s48, s48, 0
	s_cmp_gt_u32 s49, 13
	s_barrier
	s_cbranch_scc0 .LBB0_654
	v_lshl_add_u32 v148, s18, 8, v154
	v_lshl_or_b32 v144, s20, 8, v156
	v_readlane_b32 s48, v253, 12
	v_ashrrev_i32_e32 v145, 31, v144
	v_ashrrev_i32_e32 v149, 31, v148
	v_readlane_b32 s49, v253, 13
	v_lshlrev_b64 v[150:151], 12, v[148:149]
	v_or_b32_e32 v172, 16, v148
	v_lshl_add_u64 v[146:147], v[144:145], 2, s[48:49]
	v_lshl_add_u64 v[150:151], v[146:147], 0, v[150:151]
	v_ashrrev_i32_e32 v173, 31, v172
	global_load_dwordx4 v[160:163], v[150:151], off
	global_load_dwordx4 v[164:167], v[150:151], off offset:16
	global_load_dwordx4 v[168:171], v[150:151], off offset:512
	global_load_dwordx4 v[176:179], v[150:151], off offset:528
	v_lshlrev_b64 v[150:151], 12, v[172:173]
	v_or_b32_e32 v152, 32, v148
	v_lshl_add_u64 v[150:151], v[146:147], 0, v[150:151]
	v_ashrrev_i32_e32 v153, 31, v152
	global_load_dwordx4 v[180:183], v[150:151], off
	global_load_dwordx4 v[184:187], v[150:151], off offset:16
	global_load_dwordx4 v[188:191], v[150:151], off offset:512
	global_load_dwordx4 v[192:195], v[150:151], off offset:528
	v_lshlrev_b64 v[150:151], 12, v[152:153]
	v_lshl_add_u64 v[208:209], v[146:147], 0, v[150:151]
	v_or_b32_e32 v150, 48, v148
	global_load_dwordx4 v[196:199], v[208:209], off
	global_load_dwordx4 v[200:203], v[208:209], off offset:16
	v_ashrrev_i32_e32 v151, 31, v150
	v_lshlrev_b64 v[204:205], 11, v[148:149]
	v_lshlrev_b64 v[216:217], 12, v[150:151]
	v_lshl_add_u64 v[218:219], s[10:11], 0, v[204:205]
	global_load_dwordx4 v[204:207], v[208:209], off offset:528
	global_load_dwordx4 v[212:215], v[208:209], off offset:512
	v_lshlrev_b64 v[144:145], 1, v[144:145]
	v_lshl_add_u64 v[208:209], v[146:147], 0, v[216:217]
	v_lshl_add_u64 v[232:233], v[218:219], 0, v[144:145]
	global_load_dwordx4 v[216:219], v[208:209], off offset:16
	global_load_dwordx4 v[220:223], v[208:209], off
	global_load_dwordx4 v[224:227], v[208:209], off offset:528
	global_load_dwordx4 v[228:231], v[208:209], off offset:512
	v_lshlrev_b64 v[172:173], 11, v[172:173]
	v_lshl_add_u64 v[172:173], s[10:11], 0, v[172:173]
	v_lshl_add_u64 v[172:173], v[172:173], 0, v[144:145]
	v_readlane_b32 s50, v253, 14
	v_readlane_b32 s51, v253, 15
	v_readlane_b32 s52, v253, 16
	v_readlane_b32 s53, v253, 17
	v_readlane_b32 s54, v253, 18
	v_readlane_b32 s55, v253, 19
	v_readlane_b32 s56, v253, 20
	v_readlane_b32 s57, v253, 21
	v_readlane_b32 s58, v253, 22
	v_readlane_b32 s59, v253, 23
	v_readlane_b32 s60, v253, 24
	v_readlane_b32 s61, v253, 25
	v_readlane_b32 s62, v253, 26
	v_readlane_b32 s63, v253, 27
	s_waitcnt vmcnt(0)
	v_pk_add_f32 v[126:127], v[126:127], v[162:163]
	v_pk_add_f32 v[124:125], v[124:125], v[160:161]
	v_pk_add_f32 v[160:161], v[122:123], v[166:167]
	v_pk_add_f32 v[162:163], v[120:121], v[164:165]
	v_pk_add_f32 v[164:165], v[110:111], v[170:171]
	v_pk_add_f32 v[166:167], v[108:109], v[168:169]
	v_pk_add_f32 v[168:169], v[106:107], v[178:179]
	v_cvt_pk_bf16_f32 v120, v124, v125
	v_cvt_pk_bf16_f32 v121, v126, v127
	v_cvt_pk_bf16_f32 v122, v162, v163
	v_cvt_pk_bf16_f32 v123, v160, v161
	v_pk_add_f32 v[106:107], v[112:113], v[184:185]
	global_store_dwordx4 v[232:233], v[120:123], off
	v_cvt_pk_bf16_f32 v112, v166, v167
	v_cvt_pk_bf16_f32 v113, v164, v165
	v_pk_add_f32 v[170:171], v[104:105], v[176:177]
	v_pk_add_f32 v[108:109], v[118:119], v[182:183]
	v_pk_add_f32 v[110:111], v[116:117], v[180:181]
	v_pk_add_f32 v[104:105], v[114:115], v[186:187]
	v_cvt_pk_bf16_f32 v114, v170, v171
	v_cvt_pk_bf16_f32 v115, v168, v169
	global_store_dwordx4 v[232:233], v[112:115], off offset:256
	v_mul_f32_e32 v175, v125, v125
	v_mul_f32_e32 v176, v127, v127
	v_cvt_pk_bf16_f32 v112, v110, v111
	v_cvt_pk_bf16_f32 v113, v108, v109
	v_mul_f32_e32 v125, v167, v167
	v_mul_f32_e32 v127, v165, v165
	v_cvt_pk_bf16_f32 v114, v106, v107
	v_cvt_pk_bf16_f32 v115, v104, v105
	global_store_dwordx4 v[172:173], v[112:115], off
	v_mul_f32_e32 v177, v163, v163
	v_mul_f32_e32 v178, v161, v161
	v_pk_add_f32 v[112:113], v[100:101], v[188:189]
	v_pk_add_f32 v[100:101], v[92:93], v[192:193]
	v_pk_add_f32 v[92:93], v[98:99], v[198:199]
	v_lshlrev_b64 v[98:99], 11, v[152:153]
	v_mul_f32_e32 v161, v171, v171
	v_fmac_f32_e32 v175, v124, v124
	v_fmac_f32_e32 v176, v126, v126
	v_fmac_f32_e32 v125, v166, v166
	v_fmac_f32_e32 v127, v164, v164
	v_lshl_add_u64 v[98:99], s[10:11], 0, v[98:99]
	v_mul_f32_e32 v163, v169, v169
	v_fmac_f32_e32 v177, v162, v162
	v_fmac_f32_e32 v161, v170, v170
	v_add_f32_e32 v116, v175, v176
	v_add_f32_e32 v117, v125, v127
	v_lshl_add_u64 v[118:119], v[98:99], 0, v[144:145]
	v_pk_add_f32 v[98:99], v[84:85], v[212:213]
	v_pk_add_f32 v[84:85], v[76:77], v[204:205]
	v_pk_add_f32 v[76:77], v[82:83], v[222:223]
	v_lshlrev_b64 v[82:83], 11, v[150:151]
	v_fmac_f32_e32 v178, v160, v160
	v_fmac_f32_e32 v163, v168, v168
	v_add_f32_e32 v116, v116, v177
	v_add_f32_e32 v117, v117, v161
	v_lshl_add_u64 v[82:83], s[10:11], 0, v[82:83]
	v_add_f32_e32 v116, v178, v116
	v_add_f32_e32 v117, v163, v117
	v_cvt_pk_bf16_f32 v114, v112, v113
	v_lshl_add_u64 v[122:123], v[82:83], 0, v[144:145]
	v_pk_add_f32 v[82:83], v[68:69], v[228:229]
	v_pk_add_f32 v[68:69], v[64:65], v[224:225]
	v_and_b32_e32 v65, 64, v174
	v_add_f32_e32 v120, v116, v117
	v_pk_add_f32 v[102:103], v[102:103], v[190:191]
	v_pk_add_f32 v[94:95], v[94:95], v[194:195]
	v_cvt_pk_bf16_f32 v115, v102, v103
	v_cvt_pk_bf16_f32 v116, v100, v101
	v_pk_add_f32 v[96:97], v[96:97], v[196:197]
	v_cvt_pk_bf16_f32 v117, v94, v95
	global_store_dwordx4 v[172:173], v[114:117], off offset:256
	v_xor_b32_e32 v64, 16, v174
	v_add_u32_e32 v65, 64, v65
	v_cvt_pk_bf16_f32 v114, v96, v97
	v_pk_add_f32 v[90:91], v[90:91], v[202:203]
	v_pk_add_f32 v[88:89], v[88:89], v[200:201]
	v_cvt_pk_bf16_f32 v115, v92, v93
	v_cmp_lt_i32_e32 vcc, v64, v65
	v_cvt_pk_bf16_f32 v116, v88, v89
	v_cvt_pk_bf16_f32 v117, v90, v91
	global_store_dwordx4 v[118:119], v[114:117], off
	v_pk_add_f32 v[86:87], v[86:87], v[214:215]
	v_pk_add_f32 v[78:79], v[78:79], v[206:207]
	v_cvt_pk_bf16_f32 v114, v98, v99
	v_cvt_pk_bf16_f32 v115, v86, v87
	v_cvt_pk_bf16_f32 v116, v84, v85
	v_pk_add_f32 v[80:81], v[80:81], v[220:221]
	v_cvt_pk_bf16_f32 v117, v78, v79
	global_store_dwordx4 v[118:119], v[114:117], off offset:256
	v_cndmask_b32_e32 v64, v174, v64, vcc
	v_pk_add_f32 v[74:75], v[74:75], v[218:219]
	v_cvt_pk_bf16_f32 v114, v80, v81
	v_pk_add_f32 v[72:73], v[72:73], v[216:217]
	v_cvt_pk_bf16_f32 v115, v76, v77
	v_pk_add_f32 v[70:71], v[70:71], v[230:231]
	v_cvt_pk_bf16_f32 v116, v72, v73
	v_cvt_pk_bf16_f32 v117, v74, v75
	global_store_dwordx4 v[122:123], v[114:117], off
	v_pk_add_f32 v[66:67], v[66:67], v[226:227]
	v_cvt_pk_bf16_f32 v118, v82, v83
	v_cvt_pk_bf16_f32 v119, v70, v71
	s_nop 0
	v_lshlrev_b32_e32 v114, 2, v64
	ds_bpermute_b32 v64, v114, v120
	v_xor_b32_e32 v115, 32, v174
	v_cmp_lt_i32_e32 vcc, v115, v65
	s_waitcnt lgkmcnt(0)
	v_add_f32_e32 v116, v120, v64
	v_cndmask_b32_e32 v65, v174, v115, vcc
	v_lshlrev_b32_e32 v115, 2, v65
	ds_bpermute_b32 v117, v115, v116
	v_lshl_add_u64 v[64:65], v[148:149], 2, s[66:67]
	v_cvt_pk_bf16_f32 v120, v68, v69
	v_cvt_pk_bf16_f32 v121, v66, v67
	global_store_dwordx4 v[122:123], v[118:121], off offset:256
	s_and_saveexec_b64 s[18:19], s[6:7]
	s_cbranch_execz .LBB0_657
	s_waitcnt lgkmcnt(0)
	v_add_f32_e32 v116, v116, v117
	global_atomic_add_f32 v[64:65], v116, off

.LBB0_712:
	ds_read_b128 v[144:147], v151
	ds_read_b128 v[156:159], v151 offset:1024
	ds_read_b128 v[160:163], v151 offset:2048
	ds_read_b128 v[164:167], v151 offset:3072
	s_add_u32 s26, s2, 0xfffc0080
	s_addc_u32 s27, s3, -1
	s_cmp_eq_u32 s56, 12
	s_cselect_b32 s29, s21, s27
	s_cselect_b32 s28, s52, s26
	s_cselect_b32 s27, s19, s55
	s_cselect_b32 s26, s53, s54
	v_lshl_add_u64 v[172:173], s[2:3], 0, v[136:137]
	s_add_i32 m0, s34, 0xc000
	ds_read_b128 v[168:171], v152
	ds_read_b128 v[176:179], v152 offset:1024
	ds_read_b128 v[180:183], v152 offset:2048
	ds_read_b128 v[184:187], v152 offset:3072
	ds_read_b128 v[188:191], v152 offset:4096
	ds_read_b128 v[192:195], v152 offset:5120
	ds_read_b128 v[196:199], v152 offset:6144
	ds_read_b128 v[200:203], v152 offset:7168
	global_load_lds_dwordx4 v[172:173], off
	v_lshl_add_u64 v[172:173], s[2:3], 0, v[138:139]
	s_add_i32 m0, s34, 0xe000
	s_nop 0
	global_load_lds_dwordx4 v[172:173], off
	s_waitcnt lgkmcnt(8)
	s_setprio 1
	s_barrier
	s_waitcnt lgkmcnt(0)
	v_mfma_f32_16x16x32_bf16 v[124:127], v[144:147], v[168:171], v[124:127]
	v_mfma_f32_16x16x32_bf16 v[120:123], v[160:163], v[168:171], v[120:123]
	v_mfma_f32_16x16x32_bf16 v[116:119], v[144:147], v[180:183], v[116:119]
	v_mfma_f32_16x16x32_bf16 v[112:115], v[160:163], v[180:183], v[112:115]
	v_mfma_f32_16x16x32_bf16 v[104:107], v[144:147], v[188:191], v[104:107]
	v_mfma_f32_16x16x32_bf16 v[96:99], v[160:163], v[188:191], v[96:99]
	v_mfma_f32_16x16x32_bf16 v[76:79], v[144:147], v[196:199], v[76:79]
	v_mfma_f32_16x16x32_bf16 v[72:75], v[160:163], v[196:199], v[72:75]
	v_mfma_f32_16x16x32_bf16 v[124:127], v[156:159], v[176:179], v[124:127]
	v_mfma_f32_16x16x32_bf16 v[120:123], v[164:167], v[176:179], v[120:123]
	v_mfma_f32_16x16x32_bf16 v[116:119], v[156:159], v[184:187], v[116:119]
	v_mfma_f32_16x16x32_bf16 v[112:115], v[164:167], v[184:187], v[112:115]
	v_mfma_f32_16x16x32_bf16 v[104:107], v[156:159], v[192:195], v[104:107]
	v_mfma_f32_16x16x32_bf16 v[96:99], v[164:167], v[192:195], v[96:99]
	v_mfma_f32_16x16x32_bf16 v[76:79], v[156:159], v[200:203], v[76:79]
	v_mfma_f32_16x16x32_bf16 v[72:75], v[164:167], v[200:203], v[72:75]
	s_setprio 0
	s_barrier
	s_add_i32 s57, s43, s33
	v_lshl_add_u64 v[172:173], s[26:27], 0, v[130:131]
	s_mov_b32 m0, s57
	ds_read_b128 v[204:207], v153
	ds_read_b128 v[212:215], v153 offset:1024
	ds_read_b128 v[216:219], v153 offset:2048
	ds_read_b128 v[220:223], v153 offset:3072
	global_load_lds_dwordx4 v[172:173], off
	v_lshl_add_u64 v[208:209], s[26:27], 0, v[134:135]
	s_add_i32 m0, s57, 0x2000
	s_nop 0
	global_load_lds_dwordx4 v[208:209], off
	s_setprio 1
	s_barrier
	s_waitcnt lgkmcnt(0)
	v_mfma_f32_16x16x32_bf16 v[108:111], v[204:207], v[168:171], v[108:111]
	v_mfma_f32_16x16x32_bf16 v[100:103], v[216:219], v[168:171], v[100:103]
	v_mfma_f32_16x16x32_bf16 v[92:95], v[204:207], v[180:183], v[92:95]
	v_mfma_f32_16x16x32_bf16 v[88:91], v[216:219], v[180:183], v[88:91]
	v_mfma_f32_16x16x32_bf16 v[84:87], v[204:207], v[188:191], v[84:87]
	v_mfma_f32_16x16x32_bf16 v[80:83], v[216:219], v[188:191], v[80:83]
	v_mfma_f32_16x16x32_bf16 v[68:71], v[204:207], v[196:199], v[68:71]
	v_mfma_f32_16x16x32_bf16 v[64:67], v[216:219], v[196:199], v[64:67]
	v_mfma_f32_16x16x32_bf16 v[108:111], v[212:215], v[176:179], v[108:111]
	v_mfma_f32_16x16x32_bf16 v[100:103], v[220:223], v[176:179], v[100:103]
	v_mfma_f32_16x16x32_bf16 v[92:95], v[212:215], v[184:187], v[92:95]
	v_mfma_f32_16x16x32_bf16 v[88:91], v[220:223], v[184:187], v[88:91]
	v_mfma_f32_16x16x32_bf16 v[84:87], v[212:215], v[192:195], v[84:87]
	v_mfma_f32_16x16x32_bf16 v[80:83], v[220:223], v[192:195], v[80:83]
	v_mfma_f32_16x16x32_bf16 v[68:71], v[212:215], v[200:203], v[68:71]
	v_mfma_f32_16x16x32_bf16 v[64:67], v[220:223], v[200:203], v[64:67]
	s_setprio 0
	s_mov_b32 m0, s34
	v_lshl_add_u64 v[224:225], s[28:29], 0, v[128:129]
	s_barrier
	ds_read_b128 v[168:171], v152 offset:16384
	ds_read_b128 v[176:179], v152 offset:17408
	ds_read_b128 v[180:183], v152 offset:18432
	ds_read_b128 v[184:187], v152 offset:19456
	ds_read_b128 v[188:191], v152 offset:20480
	ds_read_b128 v[192:195], v152 offset:21504
	ds_read_b128 v[196:199], v152 offset:22528
	ds_read_b128 v[200:203], v152 offset:23552
	global_load_lds_dwordx4 v[224:225], off
	v_lshl_add_u64 v[226:227], s[28:29], 0, v[132:133]
	s_mov_b32 m0, s35
	s_nop 0
	global_load_lds_dwordx4 v[226:227], off
	s_setprio 1
	s_barrier
	s_waitcnt lgkmcnt(0)
	v_mfma_f32_16x16x32_bf16 v[60:63], v[144:147], v[168:171], v[60:63]
	v_mfma_f32_16x16x32_bf16 v[56:59], v[160:163], v[168:171], v[56:59]
	v_mfma_f32_16x16x32_bf16 v[44:47], v[144:147], v[180:183], v[44:47]
	v_mfma_f32_16x16x32_bf16 v[40:43], v[160:163], v[180:183], v[40:43]
	v_mfma_f32_16x16x32_bf16 v[28:31], v[144:147], v[188:191], v[28:31]
	v_mfma_f32_16x16x32_bf16 v[24:27], v[160:163], v[188:191], v[24:27]
	v_mfma_f32_16x16x32_bf16 v[12:15], v[144:147], v[196:199], v[12:15]
	v_mfma_f32_16x16x32_bf16 v[8:11], v[160:163], v[196:199], v[8:11]
	v_mfma_f32_16x16x32_bf16 v[60:63], v[156:159], v[176:179], v[60:63]
	v_mfma_f32_16x16x32_bf16 v[56:59], v[164:167], v[176:179], v[56:59]
	v_mfma_f32_16x16x32_bf16 v[44:47], v[156:159], v[184:187], v[44:47]
	v_mfma_f32_16x16x32_bf16 v[40:43], v[164:167], v[184:187], v[40:43]
	v_mfma_f32_16x16x32_bf16 v[28:31], v[156:159], v[192:195], v[28:31]
	v_mfma_f32_16x16x32_bf16 v[24:27], v[164:167], v[192:195], v[24:27]
	v_mfma_f32_16x16x32_bf16 v[12:15], v[156:159], v[200:203], v[12:15]
	v_mfma_f32_16x16x32_bf16 v[8:11], v[164:167], v[200:203], v[8:11]
	s_setprio 0
	s_barrier
	s_add_u32 s58, s26, 0x40000
	s_addc_u32 s59, s27, 0
	s_add_i32 s57, s48, s33
	v_lshl_add_u64 v[144:145], s[58:59], 0, v[130:131]
	s_mov_b32 m0, s57
	s_nop 0
	global_load_lds_dwordx4 v[144:145], off
	v_lshl_add_u64 v[144:145], s[58:59], 0, v[134:135]
	s_add_i32 m0, s57, 0x2000
	s_nop 0
	global_load_lds_dwordx4 v[144:145], off
	s_waitcnt vmcnt(6)
	s_setprio 1
	s_barrier
	v_mfma_f32_16x16x32_bf16 v[52:55], v[204:207], v[168:171], v[52:55]
	v_mfma_f32_16x16x32_bf16 v[48:51], v[216:219], v[168:171], v[48:51]
	v_mfma_f32_16x16x32_bf16 v[36:39], v[204:207], v[180:183], v[36:39]
	v_mfma_f32_16x16x32_bf16 v[32:35], v[216:219], v[180:183], v[32:35]
	v_mfma_f32_16x16x32_bf16 v[20:23], v[204:207], v[188:191], v[20:23]
	v_mfma_f32_16x16x32_bf16 v[16:19], v[216:219], v[188:191], v[16:19]
	v_mfma_f32_16x16x32_bf16 v[4:7], v[204:207], v[196:199], v[4:7]
	v_mfma_f32_16x16x32_bf16 v[0:3], v[216:219], v[196:199], v[0:3]
	v_mfma_f32_16x16x32_bf16 v[52:55], v[212:215], v[176:179], v[52:55]
	v_mfma_f32_16x16x32_bf16 v[48:51], v[220:223], v[176:179], v[48:51]
	v_mfma_f32_16x16x32_bf16 v[36:39], v[212:215], v[184:187], v[36:39]
	v_mfma_f32_16x16x32_bf16 v[32:35], v[220:223], v[184:187], v[32:35]
	v_mfma_f32_16x16x32_bf16 v[20:23], v[212:215], v[192:195], v[20:23]
	v_mfma_f32_16x16x32_bf16 v[16:19], v[220:223], v[192:195], v[16:19]
	v_mfma_f32_16x16x32_bf16 v[4:7], v[212:215], v[200:203], v[4:7]
	v_mfma_f32_16x16x32_bf16 v[0:3], v[220:223], v[200:203], v[0:3]
	s_setprio 0
	s_add_i32 s57, 0, 0x18000
	v_add_u32_e32 v155, s57, v149
	s_barrier
	ds_read_b128 v[144:147], v155
	ds_read_b128 v[156:159], v155 offset:1024
	ds_read_b128 v[160:163], v155 offset:2048
	ds_read_b128 v[164:167], v155 offset:3072
	s_add_u32 s28, s28, 0x40000
	s_addc_u32 s29, s29, 0
	s_mov_b32 m0, s36
	v_lshl_add_u64 v[204:205], s[28:29], 0, v[128:129]
	ds_read_b128 v[168:171], v152 offset:32768
	ds_read_b128 v[176:179], v152 offset:33792
	ds_read_b128 v[180:183], v152 offset:34816
	ds_read_b128 v[184:187], v152 offset:35840
	ds_read_b128 v[188:191], v152 offset:36864
	ds_read_b128 v[192:195], v152 offset:37888
	ds_read_b128 v[196:199], v152 offset:38912
	ds_read_b128 v[200:203], v152 offset:39936
	global_load_lds_dwordx4 v[204:205], off
	v_lshl_add_u64 v[204:205], s[28:29], 0, v[132:133]
	s_mov_b32 m0, s37
	s_nop 0
	global_load_lds_dwordx4 v[204:205], off
	s_waitcnt lgkmcnt(8)
	s_setprio 1
	s_barrier
	s_waitcnt lgkmcnt(0)
	v_mfma_f32_16x16x32_bf16 v[124:127], v[144:147], v[168:171], v[124:127]
	v_mfma_f32_16x16x32_bf16 v[120:123], v[160:163], v[168:171], v[120:123]
	v_mfma_f32_16x16x32_bf16 v[116:119], v[144:147], v[180:183], v[116:119]
	v_mfma_f32_16x16x32_bf16 v[112:115], v[160:163], v[180:183], v[112:115]
	v_mfma_f32_16x16x32_bf16 v[104:107], v[144:147], v[188:191], v[104:107]
	v_mfma_f32_16x16x32_bf16 v[96:99], v[160:163], v[188:191], v[96:99]
	v_mfma_f32_16x16x32_bf16 v[76:79], v[144:147], v[196:199], v[76:79]
	v_mfma_f32_16x16x32_bf16 v[72:75], v[160:163], v[196:199], v[72:75]
	v_mfma_f32_16x16x32_bf16 v[124:127], v[156:159], v[176:179], v[124:127]
	v_mfma_f32_16x16x32_bf16 v[120:123], v[164:167], v[176:179], v[120:123]
	v_mfma_f32_16x16x32_bf16 v[116:119], v[156:159], v[184:187], v[116:119]
	v_mfma_f32_16x16x32_bf16 v[112:115], v[164:167], v[184:187], v[112:115]
	v_mfma_f32_16x16x32_bf16 v[104:107], v[156:159], v[192:195], v[104:107]
	v_mfma_f32_16x16x32_bf16 v[96:99], v[164:167], v[192:195], v[96:99]
	v_mfma_f32_16x16x32_bf16 v[76:79], v[156:159], v[200:203], v[76:79]
	v_mfma_f32_16x16x32_bf16 v[72:75], v[164:167], v[200:203], v[72:75]
	s_setprio 0
	s_barrier
	s_add_i32 s28, 0, 0x1c000
	s_add_i32 s29, s57, s33
	v_add_u32_e32 v155, s28, v149
	v_lshl_add_u64 v[172:173], v[172:173], 0, s[8:9]
	s_mov_b32 m0, s29
	ds_read_b128 v[204:207], v155
	ds_read_b128 v[212:215], v155 offset:1024
	ds_read_b128 v[216:219], v155 offset:2048
	ds_read_b128 v[220:223], v155 offset:3072
	global_load_lds_dwordx4 v[172:173], off
	v_lshl_add_u64 v[172:173], v[208:209], 0, s[8:9]
	s_add_i32 m0, s29, 0x2000
	s_nop 0
	global_load_lds_dwordx4 v[172:173], off
	s_setprio 1
	s_barrier
	s_waitcnt lgkmcnt(0)
	v_mfma_f32_16x16x32_bf16 v[108:111], v[204:207], v[168:171], v[108:111]
	v_mfma_f32_16x16x32_bf16 v[100:103], v[216:219], v[168:171], v[100:103]
	v_mfma_f32_16x16x32_bf16 v[92:95], v[204:207], v[180:183], v[92:95]
	v_mfma_f32_16x16x32_bf16 v[88:91], v[216:219], v[180:183], v[88:91]
	v_mfma_f32_16x16x32_bf16 v[84:87], v[204:207], v[188:191], v[84:87]
	v_mfma_f32_16x16x32_bf16 v[80:83], v[216:219], v[188:191], v[80:83]
	v_mfma_f32_16x16x32_bf16 v[68:71], v[204:207], v[196:199], v[68:71]
	v_mfma_f32_16x16x32_bf16 v[64:67], v[216:219], v[196:199], v[64:67]
	v_mfma_f32_16x16x32_bf16 v[108:111], v[212:215], v[176:179], v[108:111]
	v_mfma_f32_16x16x32_bf16 v[100:103], v[220:223], v[176:179], v[100:103]
	v_mfma_f32_16x16x32_bf16 v[92:95], v[212:215], v[184:187], v[92:95]
	v_mfma_f32_16x16x32_bf16 v[88:91], v[220:223], v[184:187], v[88:91]
	v_mfma_f32_16x16x32_bf16 v[84:87], v[212:215], v[192:195], v[84:87]
	v_mfma_f32_16x16x32_bf16 v[80:83], v[220:223], v[192:195], v[80:83]
	v_mfma_f32_16x16x32_bf16 v[68:71], v[212:215], v[200:203], v[68:71]
	v_mfma_f32_16x16x32_bf16 v[64:67], v[220:223], v[200:203], v[64:67]
	s_setprio 0
	s_mov_b32 m0, s39
	v_lshl_add_u64 v[172:173], v[224:225], 0, s[8:9]
	s_barrier
	ds_read_b128 v[168:171], v152 offset:49152
	ds_read_b128 v[176:179], v152 offset:50176
	ds_read_b128 v[180:183], v152 offset:51200
	ds_read_b128 v[184:187], v152 offset:52224
	ds_read_b128 v[188:191], v152 offset:53248
	ds_read_b128 v[192:195], v152 offset:54272
	ds_read_b128 v[196:199], v152 offset:55296
	ds_read_b128 v[200:203], v152 offset:56320
	global_load_lds_dwordx4 v[172:173], off
	v_lshl_add_u64 v[172:173], v[226:227], 0, s[8:9]
	s_mov_b32 m0, s40
	s_nop 0
	global_load_lds_dwordx4 v[172:173], off
	s_setprio 1
	s_barrier
	s_waitcnt lgkmcnt(0)
	v_mfma_f32_16x16x32_bf16 v[60:63], v[144:147], v[168:171], v[60:63]
	v_mfma_f32_16x16x32_bf16 v[56:59], v[160:163], v[168:171], v[56:59]
	v_mfma_f32_16x16x32_bf16 v[44:47], v[144:147], v[180:183], v[44:47]
	v_mfma_f32_16x16x32_bf16 v[40:43], v[160:163], v[180:183], v[40:43]
	v_mfma_f32_16x16x32_bf16 v[28:31], v[144:147], v[188:191], v[28:31]
	v_mfma_f32_16x16x32_bf16 v[24:27], v[160:163], v[188:191], v[24:27]
	v_mfma_f32_16x16x32_bf16 v[12:15], v[144:147], v[196:199], v[12:15]
	v_mfma_f32_16x16x32_bf16 v[8:11], v[160:163], v[196:199], v[8:11]
	v_mfma_f32_16x16x32_bf16 v[60:63], v[156:159], v[176:179], v[60:63]
	v_mfma_f32_16x16x32_bf16 v[56:59], v[164:167], v[176:179], v[56:59]
	v_mfma_f32_16x16x32_bf16 v[44:47], v[156:159], v[184:187], v[44:47]
	v_mfma_f32_16x16x32_bf16 v[40:43], v[164:167], v[184:187], v[40:43]
	v_mfma_f32_16x16x32_bf16 v[28:31], v[156:159], v[192:195], v[28:31]
	v_mfma_f32_16x16x32_bf16 v[24:27], v[164:167], v[192:195], v[24:27]
	v_mfma_f32_16x16x32_bf16 v[12:15], v[156:159], v[200:203], v[12:15]
	v_mfma_f32_16x16x32_bf16 v[8:11], v[164:167], v[200:203], v[8:11]
	s_setprio 0
	s_barrier
	s_add_u32 s26, s26, 0x40080
	s_addc_u32 s27, s27, 0
	s_add_i32 s28, s28, s33
	v_lshl_add_u64 v[144:145], s[26:27], 0, v[130:131]
	s_mov_b32 m0, s28
	s_nop 0
	global_load_lds_dwordx4 v[144:145], off
	v_lshl_add_u64 v[144:145], s[26:27], 0, v[134:135]
	s_add_i32 m0, s28, 0x2000
	s_nop 0
	global_load_lds_dwordx4 v[144:145], off
	s_waitcnt vmcnt(6)
	s_setprio 1
	s_barrier
	v_mfma_f32_16x16x32_bf16 v[52:55], v[204:207], v[168:171], v[52:55]
	v_mfma_f32_16x16x32_bf16 v[48:51], v[216:219], v[168:171], v[48:51]
	v_mfma_f32_16x16x32_bf16 v[36:39], v[204:207], v[180:183], v[36:39]
	v_mfma_f32_16x16x32_bf16 v[32:35], v[216:219], v[180:183], v[32:35]
	v_mfma_f32_16x16x32_bf16 v[20:23], v[204:207], v[188:191], v[20:23]
	v_mfma_f32_16x16x32_bf16 v[16:19], v[216:219], v[188:191], v[16:19]
	v_mfma_f32_16x16x32_bf16 v[4:7], v[204:207], v[196:199], v[4:7]
	v_mfma_f32_16x16x32_bf16 v[0:3], v[216:219], v[196:199], v[0:3]
	v_mfma_f32_16x16x32_bf16 v[52:55], v[212:215], v[176:179], v[52:55]
	v_mfma_f32_16x16x32_bf16 v[48:51], v[220:223], v[176:179], v[48:51]
	v_mfma_f32_16x16x32_bf16 v[36:39], v[212:215], v[184:187], v[36:39]
	v_mfma_f32_16x16x32_bf16 v[32:35], v[220:223], v[184:187], v[32:35]
	v_mfma_f32_16x16x32_bf16 v[20:23], v[212:215], v[192:195], v[20:23]
	v_mfma_f32_16x16x32_bf16 v[16:19], v[220:223], v[192:195], v[16:19]
	v_mfma_f32_16x16x32_bf16 v[4:7], v[212:215], v[200:203], v[4:7]
	v_mfma_f32_16x16x32_bf16 v[0:3], v[220:223], v[200:203], v[0:3]
	s_setprio 0
	s_add_i32 s56, s56, 2
	s_add_u32 s2, s2, 0x100
	s_addc_u32 s3, s3, 0
	s_add_u32 s54, s54, 0x100
	s_addc_u32 s55, s55, 0
	s_cmp_gt_u32 s56, 13
	s_barrier
	s_cbranch_scc0 .LBB0_712
	v_lshl_add_u32 v146, s0, 8, v148
	v_ashrrev_i32_e32 v147, 31, v146
	v_lshl_add_u64 v[144:145], v[146:147], 2, s[66:67]
	global_load_dword v155, v[144:145], off
	global_load_dword v164, v[144:145], off offset:64
	global_load_dword v165, v[144:145], off offset:128
	global_load_dword v166, v[144:145], off offset:192
	global_load_dword v167, v[144:145], off offset:512
	global_load_dword v168, v[144:145], off offset:576
	global_load_dword v169, v[144:145], off offset:640
	global_load_dword v170, v[144:145], off offset:704
	v_lshl_or_b32 v144, s1, 8, v150
	v_ashrrev_i32_e32 v145, 31, v144
	v_lshlrev_b64 v[160:161], 10, v[146:147]
	v_lshlrev_b64 v[162:163], 1, v[144:145]
	v_lshl_add_u64 v[144:145], s[92:93], 0, v[160:161]
	v_or_b32_e32 v156, 16, v146
	v_ashrrev_i32_e32 v157, 31, v156
	v_or_b32_e32 v158, 32, v146
	v_lshlrev_b64 v[156:157], 10, v[156:157]
	v_lshl_add_u64 v[144:145], v[144:145], 0, v[162:163]
	v_ashrrev_i32_e32 v159, 31, v158
	v_lshl_add_u64 v[156:157], s[92:93], 0, v[156:157]
	v_lshlrev_b64 v[158:159], 10, v[158:159]
	v_lshl_add_u64 v[156:157], v[156:157], 0, v[162:163]
	v_lshl_add_u64 v[158:159], s[92:93], 0, v[158:159]
	v_lshl_add_u64 v[158:159], v[158:159], 0, v[162:163]
	s_mov_b64 s[26:27], s[24:25]
	s_waitcnt vmcnt(0)
	v_fmamk_f32 v147, v155, 0x3a800000, v154
	v_fmamk_f32 v155, v164, 0x3a800000, v154
	v_fmamk_f32 v160, v165, 0x3a800000, v154
	v_mul_f32_e32 v161, 0x4b800000, v147
	v_mul_f32_e32 v164, 0x4b800000, v155
	v_cmp_gt_f32_e32 vcc, s49, v147
	v_cmp_gt_f32_e64 s[0:1], s49, v155
	v_mul_f32_e32 v165, 0x4b800000, v160
	v_cndmask_b32_e32 v147, v147, v161, vcc
	v_cndmask_b32_e64 v155, v155, v164, s[0:1]
	v_cmp_gt_f32_e64 s[2:3], s49, v160
	v_rsq_f32_e32 v147, v147
	v_rsq_f32_e32 v155, v155
	v_cndmask_b32_e64 v160, v160, v165, s[2:3]
	v_rsq_f32_e32 v160, v160
	v_mul_f32_e32 v161, 0x45800000, v147
	v_mul_f32_e32 v164, 0x45800000, v155
	v_cndmask_b32_e32 v147, v147, v161, vcc
	v_mul_f32_e32 v165, 0x45800000, v160
	v_cndmask_b32_e64 v155, v155, v164, s[0:1]
	v_cndmask_b32_e64 v161, v160, v165, s[2:3]
	v_mul_f32_e32 v160, 0x3e0293ee, v147
	v_mul_f32_e32 v164, 0x3e0293ee, v155
	v_fmamk_f32 v171, v166, 0x3a800000, v154
	v_mul_f32_e32 v166, 0x3e0293ee, v161
	v_pk_mul_f32 v[126:127], v[126:127], v[160:161] op_sel_hi:[1,0]
	v_pk_mul_f32 v[124:125], v[124:125], v[160:161] op_sel_hi:[1,0]
	v_pk_mul_f32 v[122:123], v[122:123], v[160:161] op_sel_hi:[1,0]
	v_pk_mul_f32 v[120:121], v[120:121], v[160:161] op_sel_hi:[1,0]
	v_pk_mul_f32 v[110:111], v[110:111], v[160:161] op_sel_hi:[1,0]
	v_pk_mul_f32 v[108:109], v[108:109], v[160:161] op_sel_hi:[1,0]
	v_pk_mul_f32 v[102:103], v[102:103], v[160:161] op_sel_hi:[1,0]
	v_pk_mul_f32 v[100:101], v[100:101], v[160:161] op_sel_hi:[1,0]
	v_pk_mul_f32 v[118:119], v[118:119], v[164:165] op_sel_hi:[1,0]
	v_pk_mul_f32 v[116:117], v[116:117], v[164:165] op_sel_hi:[1,0]
	v_pk_mul_f32 v[114:115], v[114:115], v[164:165] op_sel_hi:[1,0]
	v_pk_mul_f32 v[112:113], v[112:113], v[164:165] op_sel_hi:[1,0]
	v_pk_mul_f32 v[94:95], v[94:95], v[164:165] op_sel_hi:[1,0]
	v_pk_mul_f32 v[92:93], v[92:93], v[164:165] op_sel_hi:[1,0]
	v_pk_mul_f32 v[160:161], v[90:91], v[164:165] op_sel_hi:[1,0]
	v_pk_mul_f32 v[164:165], v[88:89], v[164:165] op_sel_hi:[1,0]
	v_cvt_pk_bf16_f32 v88, v124, v125
	v_cvt_pk_bf16_f32 v89, v126, v127
	v_cvt_pk_bf16_f32 v90, v120, v121
	v_cvt_pk_bf16_f32 v91, v122, v123
	global_store_dwordx4 v[144:145], v[88:91], off
	v_fmamk_f32 v167, v167, 0x3a800000, v154
	v_pk_mul_f32 v[106:107], v[106:107], v[166:167] op_sel_hi:[1,0]
	v_cvt_pk_bf16_f32 v88, v108, v109
	v_cvt_pk_bf16_f32 v89, v110, v111
	v_cvt_pk_bf16_f32 v90, v100, v101
	v_cvt_pk_bf16_f32 v91, v102, v103
	global_store_dwordx4 v[144:145], v[88:91], off offset:256
	v_pk_mul_f32 v[104:105], v[104:105], v[166:167] op_sel_hi:[1,0]
	v_pk_mul_f32 v[98:99], v[98:99], v[166:167] op_sel_hi:[1,0]
	v_cvt_pk_bf16_f32 v88, v116, v117
	v_cvt_pk_bf16_f32 v89, v118, v119
	v_cvt_pk_bf16_f32 v90, v112, v113
	v_cvt_pk_bf16_f32 v91, v114, v115
	global_store_dwordx4 v[156:157], v[88:91], off
	v_pk_mul_f32 v[96:97], v[96:97], v[166:167] op_sel_hi:[1,0]
	v_pk_mul_f32 v[86:87], v[86:87], v[166:167] op_sel_hi:[1,0]
	v_cvt_pk_bf16_f32 v88, v92, v93
	v_cvt_pk_bf16_f32 v89, v94, v95
	v_cvt_pk_bf16_f32 v90, v164, v165
	v_cvt_pk_bf16_f32 v91, v160, v161
	global_store_dwordx4 v[156:157], v[88:91], off offset:256
	v_pk_mul_f32 v[84:85], v[84:85], v[166:167] op_sel_hi:[1,0]
	v_cmp_gt_f32_e32 vcc, s49, v171
	v_cvt_pk_bf16_f32 v88, v104, v105
	v_cvt_pk_bf16_f32 v89, v106, v107
	v_cvt_pk_bf16_f32 v90, v96, v97
	v_cvt_pk_bf16_f32 v91, v98, v99
	global_store_dwordx4 v[158:159], v[88:91], off
	s_mov_b64 s[0:1], 0x20000
	v_fmamk_f32 v168, v168, 0x3a800000, v154
	v_pk_mul_f32 v[88:89], v[82:83], v[166:167] op_sel_hi:[1,0]
	v_pk_mul_f32 v[82:83], v[80:81], v[166:167] op_sel_hi:[1,0]
	v_cvt_pk_bf16_f32 v80, v84, v85
	v_cvt_pk_bf16_f32 v81, v86, v87
	v_fmamk_f32 v169, v169, 0x3a800000, v154
	v_cvt_pk_bf16_f32 v82, v82, v83
	v_cvt_pk_bf16_f32 v83, v88, v89
	global_store_dwordx4 v[158:159], v[80:83], off offset:256
	v_fmamk_f32 v170, v170, 0x3a800000, v154
	s_mov_b64 s[2:3], s[22:23]
	v_mul_f32_e32 v82, 0x4b800000, v171
	v_cndmask_b32_e32 v82, v171, v82, vcc
	v_rsq_f32_e32 v82, v82
	v_or_b32_e32 v80, 48, v146
	v_ashrrev_i32_e32 v81, 31, v80
	v_lshlrev_b64 v[80:81], 10, v[80:81]
	v_mul_f32_e32 v83, 0x45800000, v82
	v_cndmask_b32_e32 v82, v82, v83, vcc
	v_lshl_add_u64 v[80:81], s[92:93], 0, v[80:81]
	v_mul_f32_e32 v82, 0x3e0293ee, v82
	v_lshl_add_u64 v[80:81], v[80:81], 0, v[162:163]
	v_pk_mul_f32 v[78:79], v[78:79], v[82:83] op_sel_hi:[1,0]
	v_pk_mul_f32 v[76:77], v[76:77], v[82:83] op_sel_hi:[1,0]
	v_pk_mul_f32 v[84:85], v[74:75], v[82:83] op_sel_hi:[1,0]
	v_pk_mul_f32 v[74:75], v[72:73], v[82:83] op_sel_hi:[1,0]
	v_cvt_pk_bf16_f32 v72, v76, v77
	v_cvt_pk_bf16_f32 v73, v78, v79
	v_pk_mul_f32 v[70:71], v[70:71], v[82:83] op_sel_hi:[1,0]
	v_cvt_pk_bf16_f32 v74, v74, v75
	v_cvt_pk_bf16_f32 v75, v84, v85
	global_store_dwordx4 v[80:81], v[72:75], off
	v_pk_mul_f32 v[68:69], v[68:69], v[82:83] op_sel_hi:[1,0]
	v_cmp_gt_f32_e32 vcc, s49, v167
	v_pk_mul_f32 v[72:73], v[66:67], v[82:83] op_sel_hi:[1,0]
	v_pk_mul_f32 v[66:67], v[64:65], v[82:83] op_sel_hi:[1,0]
	v_cvt_pk_bf16_f32 v64, v68, v69
	v_cvt_pk_bf16_f32 v65, v70, v71
	s_nop 0
	v_cvt_pk_bf16_f32 v66, v66, v67
	v_mul_f32_e32 v67, 0x4b800000, v167
	v_cndmask_b32_e32 v67, v167, v67, vcc
	v_rsq_f32_e32 v68, v67
	v_cvt_pk_bf16_f32 v67, v72, v73
	global_store_dwordx4 v[80:81], v[64:67], off offset:256
	s_nop 1
	v_mul_f32_e32 v66, 0x45800000, v68
	v_cndmask_b32_e32 v66, v68, v66, vcc
	v_mul_f32_e32 v66, 0x3e0293ee, v66
	v_lshl_add_u64 v[64:65], v[144:145], 0, s[0:1]
	v_pk_mul_f32 v[60:61], v[60:61], v[66:67] op_sel_hi:[1,0]
	s_mov_b32 s0, 0x20000
	v_pk_mul_f32 v[68:69], v[58:59], v[66:67] op_sel_hi:[1,0]
	v_pk_mul_f32 v[58:59], v[56:57], v[66:67] op_sel_hi:[1,0]
	v_cvt_pk_bf16_f32 v56, v60, v61
	v_add_co_u32_e32 v60, vcc, s0, v144
	v_pk_mul_f32 v[62:63], v[62:63], v[66:67] op_sel_hi:[1,0]
	s_nop 0
	v_addc_co_u32_e32 v61, vcc, 0, v145, vcc
	v_cvt_pk_bf16_f32 v57, v62, v63
	v_cvt_pk_bf16_f32 v58, v58, v59
	v_cvt_pk_bf16_f32 v59, v68, v69
	global_store_dwordx4 v[60:61], v[56:59], off
	v_pk_mul_f32 v[54:55], v[54:55], v[66:67] op_sel_hi:[1,0]
	v_pk_mul_f32 v[52:53], v[52:53], v[66:67] op_sel_hi:[1,0]
	v_pk_mul_f32 v[56:57], v[50:51], v[66:67] op_sel_hi:[1,0]
	v_pk_mul_f32 v[50:51], v[48:49], v[66:67] op_sel_hi:[1,0]
	v_cvt_pk_bf16_f32 v48, v52, v53
	v_cvt_pk_bf16_f32 v49, v54, v55
	v_cmp_gt_f32_e32 vcc, s49, v168
	v_cvt_pk_bf16_f32 v50, v50, v51
	v_mul_f32_e32 v51, 0x4b800000, v168
	s_mov_b64 s[0:1], 0x24000
	v_cndmask_b32_e32 v51, v168, v51, vcc
	v_rsq_f32_e32 v52, v51
	v_cvt_pk_bf16_f32 v51, v56, v57
	global_store_dwordx4 v[64:65], v[48:51], off offset:256
	s_nop 1
	v_mul_f32_e32 v50, 0x45800000, v52
	v_cndmask_b32_e32 v50, v52, v50, vcc
	v_mul_f32_e32 v50, 0x3e0293ee, v50
	v_lshl_add_u64 v[48:49], v[144:145], 0, s[0:1]
	v_pk_mul_f32 v[44:45], v[44:45], v[50:51] op_sel_hi:[1,0]
	s_mov_b32 s0, 0x24000
	v_pk_mul_f32 v[52:53], v[42:43], v[50:51] op_sel_hi:[1,0]
	v_pk_mul_f32 v[42:43], v[40:41], v[50:51] op_sel_hi:[1,0]
	v_cvt_pk_bf16_f32 v40, v44, v45
	v_add_co_u32_e32 v44, vcc, s0, v144
	v_pk_mul_f32 v[46:47], v[46:47], v[50:51] op_sel_hi:[1,0]
	s_nop 0
	v_addc_co_u32_e32 v45, vcc, 0, v145, vcc
	v_cvt_pk_bf16_f32 v41, v46, v47
	v_cvt_pk_bf16_f32 v42, v42, v43
	v_cvt_pk_bf16_f32 v43, v52, v53
	global_store_dwordx4 v[44:45], v[40:43], off
	v_pk_mul_f32 v[38:39], v[38:39], v[50:51] op_sel_hi:[1,0]
	v_pk_mul_f32 v[36:37], v[36:37], v[50:51] op_sel_hi:[1,0]
	v_pk_mul_f32 v[40:41], v[34:35], v[50:51] op_sel_hi:[1,0]
	v_pk_mul_f32 v[34:35], v[32:33], v[50:51] op_sel_hi:[1,0]
	v_cvt_pk_bf16_f32 v32, v36, v37
	v_cvt_pk_bf16_f32 v33, v38, v39
	v_cmp_gt_f32_e32 vcc, s49, v169
	v_cvt_pk_bf16_f32 v34, v34, v35
	v_mul_f32_e32 v35, 0x4b800000, v169
	s_mov_b32 s1, s18
	v_cndmask_b32_e32 v35, v169, v35, vcc
	v_rsq_f32_e32 v36, v35
	v_cvt_pk_bf16_f32 v35, v40, v41
	global_store_dwordx4 v[48:49], v[32:35], off offset:256
	s_mov_b32 s0, s20
	s_nop 0
	v_mul_f32_e32 v34, 0x45800000, v36
	v_cndmask_b32_e32 v34, v36, v34, vcc
	v_mul_f32_e32 v34, 0x3e0293ee, v34
	v_pk_mul_f32 v[28:29], v[28:29], v[34:35] op_sel_hi:[1,0]
	v_pk_mul_f32 v[36:37], v[26:27], v[34:35] op_sel_hi:[1,0]
	v_pk_mul_f32 v[26:27], v[24:25], v[34:35] op_sel_hi:[1,0]
	v_cvt_pk_bf16_f32 v24, v28, v29
	v_add_co_u32_e32 v28, vcc, s50, v144
	v_pk_mul_f32 v[30:31], v[30:31], v[34:35] op_sel_hi:[1,0]
	s_nop 0
	v_addc_co_u32_e32 v29, vcc, 0, v145, vcc
	v_cvt_pk_bf16_f32 v25, v30, v31
	v_cvt_pk_bf16_f32 v26, v26, v27
	v_cvt_pk_bf16_f32 v27, v36, v37
	global_store_dwordx4 v[28:29], v[24:27], off
	v_pk_mul_f32 v[22:23], v[22:23], v[34:35] op_sel_hi:[1,0]
	v_pk_mul_f32 v[20:21], v[20:21], v[34:35] op_sel_hi:[1,0]
	v_pk_mul_f32 v[24:25], v[18:19], v[34:35] op_sel_hi:[1,0]
	v_pk_mul_f32 v[18:19], v[16:17], v[34:35] op_sel_hi:[1,0]
	v_cvt_pk_bf16_f32 v16, v20, v21
	v_cvt_pk_bf16_f32 v17, v22, v23
	v_cmp_gt_f32_e32 vcc, s49, v170
	v_cvt_pk_bf16_f32 v18, v18, v19
	v_mul_f32_e32 v19, 0x4b800000, v170
	v_lshl_add_u64 v[32:33], v[144:145], 0, s[12:13]
	v_cndmask_b32_e32 v19, v170, v19, vcc
	v_rsq_f32_e32 v20, v19
	v_cvt_pk_bf16_f32 v19, v24, v25
	global_store_dwordx4 v[32:33], v[16:19], off offset:256
	s_nop 1
	v_mul_f32_e32 v18, 0x45800000, v20
	v_cndmask_b32_e32 v18, v20, v18, vcc
	v_mul_f32_e32 v18, 0x3e0293ee, v18
	v_pk_mul_f32 v[12:13], v[12:13], v[18:19] op_sel_hi:[1,0]
	v_pk_mul_f32 v[20:21], v[10:11], v[18:19] op_sel_hi:[1,0]
	v_pk_mul_f32 v[10:11], v[8:9], v[18:19] op_sel_hi:[1,0]
	v_cvt_pk_bf16_f32 v8, v12, v13
	v_add_co_u32_e32 v12, vcc, s51, v144
	v_pk_mul_f32 v[14:15], v[14:15], v[18:19] op_sel_hi:[1,0]
	s_nop 0
	v_addc_co_u32_e32 v13, vcc, 0, v145, vcc
	v_cvt_pk_bf16_f32 v9, v14, v15
	v_lshl_add_u64 v[16:17], v[144:145], 0, s[16:17]
	v_cvt_pk_bf16_f32 v10, v10, v11
	v_cvt_pk_bf16_f32 v11, v20, v21
	global_store_dwordx4 v[12:13], v[8:11], off
	s_and_b64 vcc, exec, s[6:7]
	v_pk_mul_f32 v[6:7], v[6:7], v[18:19] op_sel_hi:[1,0]
	v_pk_mul_f32 v[8:9], v[2:3], v[18:19] op_sel_hi:[1,0]
	v_pk_mul_f32 v[2:3], v[0:1], v[18:19] op_sel_hi:[1,0]
	v_pk_mul_f32 v[4:5], v[4:5], v[18:19] op_sel_hi:[1,0]
	s_nop 0
	v_cvt_pk_bf16_f32 v0, v4, v5
	v_cvt_pk_bf16_f32 v1, v6, v7
	v_cvt_pk_bf16_f32 v2, v2, v3
	v_cvt_pk_bf16_f32 v3, v8, v9
	global_store_dwordx4 v[16:17], v[0:3], off offset:256
	s_cbranch_vccz .LBB0_705
	s_waitcnt vmcnt(0)
	s_cmpk_gt_u32 s30, 0xff
	s_cbranch_scc1 .LBB0_716
	s_barrier

.LBB0_792:
	ds_read_b128 v[144:147], v178
	ds_read_b128 v[148:151], v178 offset:1024
	ds_read_b128 v[152:155], v178 offset:2048
	ds_read_b128 v[156:159], v178 offset:3072
	s_add_u32 s40, s38, 0xfffe0080
	s_addc_u32 s41, s39, -1
	s_cmp_eq_u32 s63, 4
	s_cselect_b32 s43, s27, s41
	s_cselect_b32 s42, s35, s40
	s_cselect_b32 s41, s25, s62
	s_cselect_b32 s40, s60, s61
	v_lshl_add_u64 v[172:173], s[38:39], 0, v[136:137]
	s_add_i32 m0, s37, 0xc000
	ds_read_b128 v[160:163], v179
	ds_read_b128 v[164:167], v179 offset:1024
	ds_read_b128 v[168:171], v179 offset:2048
	ds_read_b128 v[182:185], v179 offset:3072
	ds_read_b128 v[186:189], v179 offset:4096
	ds_read_b128 v[190:193], v179 offset:5120
	ds_read_b128 v[194:197], v179 offset:6144
	ds_read_b128 v[198:201], v179 offset:7168
	global_load_lds_dwordx4 v[172:173], off
	v_lshl_add_u64 v[172:173], s[38:39], 0, v[138:139]
	s_add_i32 m0, s37, 0xe000
	s_nop 0
	global_load_lds_dwordx4 v[172:173], off
	s_waitcnt lgkmcnt(8)
	s_setprio 1
	s_barrier
	s_waitcnt lgkmcnt(0)
	v_mfma_f32_16x16x32_bf16 v[124:127], v[144:147], v[160:163], v[124:127]
	v_mfma_f32_16x16x32_bf16 v[120:123], v[152:155], v[160:163], v[120:123]
	v_mfma_f32_16x16x32_bf16 v[108:111], v[144:147], v[168:171], v[108:111]
	v_mfma_f32_16x16x32_bf16 v[104:107], v[152:155], v[168:171], v[104:107]
	v_mfma_f32_16x16x32_bf16 v[96:99], v[144:147], v[186:189], v[96:99]
	v_mfma_f32_16x16x32_bf16 v[88:91], v[152:155], v[186:189], v[88:91]
	v_mfma_f32_16x16x32_bf16 v[80:83], v[144:147], v[194:197], v[80:83]
	v_mfma_f32_16x16x32_bf16 v[72:75], v[152:155], v[194:197], v[72:75]
	v_mfma_f32_16x16x32_bf16 v[124:127], v[148:151], v[164:167], v[124:127]
	v_mfma_f32_16x16x32_bf16 v[120:123], v[156:159], v[164:167], v[120:123]
	v_mfma_f32_16x16x32_bf16 v[108:111], v[148:151], v[182:185], v[108:111]
	v_mfma_f32_16x16x32_bf16 v[104:107], v[156:159], v[182:185], v[104:107]
	v_mfma_f32_16x16x32_bf16 v[96:99], v[148:151], v[190:193], v[96:99]
	v_mfma_f32_16x16x32_bf16 v[88:91], v[156:159], v[190:193], v[88:91]
	v_mfma_f32_16x16x32_bf16 v[80:83], v[148:151], v[198:201], v[80:83]
	v_mfma_f32_16x16x32_bf16 v[72:75], v[156:159], v[198:201], v[72:75]
	s_setprio 0
	s_barrier
	s_add_i32 s64, s58, s48
	v_lshl_add_u64 v[172:173], s[40:41], 0, v[130:131]
	s_mov_b32 m0, s64
	ds_read_b128 v[202:205], v180
	ds_read_b128 v[206:209], v180 offset:1024
	ds_read_b128 v[212:215], v180 offset:2048
	ds_read_b128 v[216:219], v180 offset:3072
	global_load_lds_dwordx4 v[172:173], off
	v_lshl_add_u64 v[220:221], s[40:41], 0, v[134:135]
	s_add_i32 m0, s64, 0x2000
	s_nop 0
	global_load_lds_dwordx4 v[220:221], off
	s_setprio 1
	s_barrier
	s_waitcnt lgkmcnt(0)
	v_mfma_f32_16x16x32_bf16 v[116:119], v[202:205], v[160:163], v[116:119]
	v_mfma_f32_16x16x32_bf16 v[112:115], v[212:215], v[160:163], v[112:115]
	v_mfma_f32_16x16x32_bf16 v[100:103], v[202:205], v[168:171], v[100:103]
	v_mfma_f32_16x16x32_bf16 v[92:95], v[212:215], v[168:171], v[92:95]
	v_mfma_f32_16x16x32_bf16 v[84:87], v[202:205], v[186:189], v[84:87]
	v_mfma_f32_16x16x32_bf16 v[76:79], v[212:215], v[186:189], v[76:79]
	v_mfma_f32_16x16x32_bf16 v[68:71], v[202:205], v[194:197], v[68:71]
	v_mfma_f32_16x16x32_bf16 v[64:67], v[212:215], v[194:197], v[64:67]
	v_mfma_f32_16x16x32_bf16 v[116:119], v[206:209], v[164:167], v[116:119]
	v_mfma_f32_16x16x32_bf16 v[112:115], v[216:219], v[164:167], v[112:115]
	v_mfma_f32_16x16x32_bf16 v[100:103], v[206:209], v[182:185], v[100:103]
	v_mfma_f32_16x16x32_bf16 v[92:95], v[216:219], v[182:185], v[92:95]
	v_mfma_f32_16x16x32_bf16 v[84:87], v[206:209], v[190:193], v[84:87]
	v_mfma_f32_16x16x32_bf16 v[76:79], v[216:219], v[190:193], v[76:79]
	v_mfma_f32_16x16x32_bf16 v[68:71], v[206:209], v[198:201], v[68:71]
	v_mfma_f32_16x16x32_bf16 v[64:67], v[216:219], v[198:201], v[64:67]
	s_setprio 0
	s_mov_b32 m0, s37
	v_lshl_add_u64 v[222:223], s[42:43], 0, v[128:129]
	s_barrier
	ds_read_b128 v[160:163], v179 offset:16384
	ds_read_b128 v[164:167], v179 offset:17408
	ds_read_b128 v[168:171], v179 offset:18432
	ds_read_b128 v[182:185], v179 offset:19456
	ds_read_b128 v[186:189], v179 offset:20480
	ds_read_b128 v[190:193], v179 offset:21504
	ds_read_b128 v[194:197], v179 offset:22528
	ds_read_b128 v[198:201], v179 offset:23552
	global_load_lds_dwordx4 v[222:223], off
	v_lshl_add_u64 v[224:225], s[42:43], 0, v[132:133]
	s_mov_b32 m0, s49
	s_nop 0
	global_load_lds_dwordx4 v[224:225], off
	s_setprio 1
	s_barrier
	s_waitcnt lgkmcnt(0)
	v_mfma_f32_16x16x32_bf16 v[60:63], v[144:147], v[160:163], v[60:63]
	v_mfma_f32_16x16x32_bf16 v[56:59], v[152:155], v[160:163], v[56:59]
	v_mfma_f32_16x16x32_bf16 v[44:47], v[144:147], v[168:171], v[44:47]
	v_mfma_f32_16x16x32_bf16 v[40:43], v[152:155], v[168:171], v[40:43]
	v_mfma_f32_16x16x32_bf16 v[32:35], v[144:147], v[186:189], v[32:35]
	v_mfma_f32_16x16x32_bf16 v[24:27], v[152:155], v[186:189], v[24:27]
	v_mfma_f32_16x16x32_bf16 v[16:19], v[144:147], v[194:197], v[16:19]
	v_mfma_f32_16x16x32_bf16 v[8:11], v[152:155], v[194:197], v[8:11]
	v_mfma_f32_16x16x32_bf16 v[60:63], v[148:151], v[164:167], v[60:63]
	v_mfma_f32_16x16x32_bf16 v[56:59], v[156:159], v[164:167], v[56:59]
	v_mfma_f32_16x16x32_bf16 v[44:47], v[148:151], v[182:185], v[44:47]
	v_mfma_f32_16x16x32_bf16 v[40:43], v[156:159], v[182:185], v[40:43]
	v_mfma_f32_16x16x32_bf16 v[32:35], v[148:151], v[190:193], v[32:35]
	v_mfma_f32_16x16x32_bf16 v[24:27], v[156:159], v[190:193], v[24:27]
	v_mfma_f32_16x16x32_bf16 v[16:19], v[148:151], v[198:201], v[16:19]
	v_mfma_f32_16x16x32_bf16 v[8:11], v[156:159], v[198:201], v[8:11]
	s_setprio 0
	s_barrier
	s_add_u32 s64, s40, 0x20000
	s_addc_u32 s65, s41, 0
	s_add_i32 s66, s59, s48
	v_lshl_add_u64 v[144:145], s[64:65], 0, v[130:131]
	s_mov_b32 m0, s66
	s_nop 0
	global_load_lds_dwordx4 v[144:145], off
	v_lshl_add_u64 v[144:145], s[64:65], 0, v[134:135]
	s_add_i32 m0, s66, 0x2000
	s_nop 0
	global_load_lds_dwordx4 v[144:145], off
	s_waitcnt vmcnt(6)
	s_setprio 1
	s_barrier
	v_mfma_f32_16x16x32_bf16 v[52:55], v[202:205], v[160:163], v[52:55]
	v_mfma_f32_16x16x32_bf16 v[48:51], v[212:215], v[160:163], v[48:51]
	v_mfma_f32_16x16x32_bf16 v[36:39], v[202:205], v[168:171], v[36:39]
	v_mfma_f32_16x16x32_bf16 v[28:31], v[212:215], v[168:171], v[28:31]
	v_mfma_f32_16x16x32_bf16 v[20:23], v[202:205], v[186:189], v[20:23]
	v_mfma_f32_16x16x32_bf16 v[12:15], v[212:215], v[186:189], v[12:15]
	v_mfma_f32_16x16x32_bf16 v[4:7], v[202:205], v[194:197], v[4:7]
	v_mfma_f32_16x16x32_bf16 v[0:3], v[212:215], v[194:197], v[0:3]
	v_mfma_f32_16x16x32_bf16 v[52:55], v[206:209], v[164:167], v[52:55]
	v_mfma_f32_16x16x32_bf16 v[48:51], v[216:219], v[164:167], v[48:51]
	v_mfma_f32_16x16x32_bf16 v[36:39], v[206:209], v[182:185], v[36:39]
	v_mfma_f32_16x16x32_bf16 v[28:31], v[216:219], v[182:185], v[28:31]
	v_mfma_f32_16x16x32_bf16 v[20:23], v[206:209], v[190:193], v[20:23]
	v_mfma_f32_16x16x32_bf16 v[12:15], v[216:219], v[190:193], v[12:15]
	v_mfma_f32_16x16x32_bf16 v[4:7], v[206:209], v[198:201], v[4:7]
	v_mfma_f32_16x16x32_bf16 v[0:3], v[216:219], v[198:201], v[0:3]
	s_setprio 0
	s_add_i32 s64, 0, 0x18000
	v_add_u32_e32 v156, s64, v176
	s_barrier
	ds_read_b128 v[144:147], v156
	ds_read_b128 v[148:151], v156 offset:1024
	ds_read_b128 v[152:155], v156 offset:2048
	ds_read_b128 v[156:159], v156 offset:3072
	s_add_u32 s42, s42, 0x20000
	s_addc_u32 s43, s43, 0
	s_mov_b32 m0, s50
	v_lshl_add_u64 v[202:203], s[42:43], 0, v[128:129]
	ds_read_b128 v[160:163], v179 offset:32768
	ds_read_b128 v[164:167], v179 offset:33792
	ds_read_b128 v[168:171], v179 offset:34816
	ds_read_b128 v[182:185], v179 offset:35840
	ds_read_b128 v[186:189], v179 offset:36864
	ds_read_b128 v[190:193], v179 offset:37888
	ds_read_b128 v[194:197], v179 offset:38912
	ds_read_b128 v[198:201], v179 offset:39936
	global_load_lds_dwordx4 v[202:203], off
	v_lshl_add_u64 v[202:203], s[42:43], 0, v[132:133]
	s_mov_b32 m0, s51
	s_nop 0
	global_load_lds_dwordx4 v[202:203], off
	s_waitcnt lgkmcnt(8)
	s_setprio 1
	s_barrier
	s_waitcnt lgkmcnt(0)
	v_mfma_f32_16x16x32_bf16 v[124:127], v[144:147], v[160:163], v[124:127]
	v_mfma_f32_16x16x32_bf16 v[120:123], v[152:155], v[160:163], v[120:123]
	v_mfma_f32_16x16x32_bf16 v[108:111], v[144:147], v[168:171], v[108:111]
	v_mfma_f32_16x16x32_bf16 v[104:107], v[152:155], v[168:171], v[104:107]
	v_mfma_f32_16x16x32_bf16 v[96:99], v[144:147], v[186:189], v[96:99]
	v_mfma_f32_16x16x32_bf16 v[88:91], v[152:155], v[186:189], v[88:91]
	v_mfma_f32_16x16x32_bf16 v[80:83], v[144:147], v[194:197], v[80:83]
	v_mfma_f32_16x16x32_bf16 v[72:75], v[152:155], v[194:197], v[72:75]
	v_mfma_f32_16x16x32_bf16 v[124:127], v[148:151], v[164:167], v[124:127]
	v_mfma_f32_16x16x32_bf16 v[120:123], v[156:159], v[164:167], v[120:123]
	v_mfma_f32_16x16x32_bf16 v[108:111], v[148:151], v[182:185], v[108:111]
	v_mfma_f32_16x16x32_bf16 v[104:107], v[156:159], v[182:185], v[104:107]
	v_mfma_f32_16x16x32_bf16 v[96:99], v[148:151], v[190:193], v[96:99]
	v_mfma_f32_16x16x32_bf16 v[88:91], v[156:159], v[190:193], v[88:91]
	v_mfma_f32_16x16x32_bf16 v[80:83], v[148:151], v[198:201], v[80:83]
	v_mfma_f32_16x16x32_bf16 v[72:75], v[156:159], v[198:201], v[72:75]
	s_setprio 0
	s_barrier
	s_add_i32 s42, 0, 0x1c000
	s_add_i32 s43, s64, s48
	v_add_u32_e32 v181, s42, v176
	v_lshl_add_u64 v[172:173], v[172:173], 0, s[0:1]
	s_mov_b32 m0, s43
	ds_read_b128 v[202:205], v181
	ds_read_b128 v[206:209], v181 offset:1024
	ds_read_b128 v[212:215], v181 offset:2048
	ds_read_b128 v[216:219], v181 offset:3072
	global_load_lds_dwordx4 v[172:173], off
	v_lshl_add_u64 v[172:173], v[220:221], 0, s[0:1]
	s_add_i32 m0, s43, 0x2000
	s_nop 0
	global_load_lds_dwordx4 v[172:173], off
	s_setprio 1
	s_barrier
	s_waitcnt lgkmcnt(0)
	v_mfma_f32_16x16x32_bf16 v[116:119], v[202:205], v[160:163], v[116:119]
	v_mfma_f32_16x16x32_bf16 v[112:115], v[212:215], v[160:163], v[112:115]
	v_mfma_f32_16x16x32_bf16 v[100:103], v[202:205], v[168:171], v[100:103]
	v_mfma_f32_16x16x32_bf16 v[92:95], v[212:215], v[168:171], v[92:95]
	v_mfma_f32_16x16x32_bf16 v[84:87], v[202:205], v[186:189], v[84:87]
	v_mfma_f32_16x16x32_bf16 v[76:79], v[212:215], v[186:189], v[76:79]
	v_mfma_f32_16x16x32_bf16 v[68:71], v[202:205], v[194:197], v[68:71]
	v_mfma_f32_16x16x32_bf16 v[64:67], v[212:215], v[194:197], v[64:67]
	v_mfma_f32_16x16x32_bf16 v[116:119], v[206:209], v[164:167], v[116:119]
	v_mfma_f32_16x16x32_bf16 v[112:115], v[216:219], v[164:167], v[112:115]
	v_mfma_f32_16x16x32_bf16 v[100:103], v[206:209], v[182:185], v[100:103]
	v_mfma_f32_16x16x32_bf16 v[92:95], v[216:219], v[182:185], v[92:95]
	v_mfma_f32_16x16x32_bf16 v[84:87], v[206:209], v[190:193], v[84:87]
	v_mfma_f32_16x16x32_bf16 v[76:79], v[216:219], v[190:193], v[76:79]
	v_mfma_f32_16x16x32_bf16 v[68:71], v[206:209], v[198:201], v[68:71]
	v_mfma_f32_16x16x32_bf16 v[64:67], v[216:219], v[198:201], v[64:67]
	s_setprio 0
	s_mov_b32 m0, s53
	v_lshl_add_u64 v[172:173], v[222:223], 0, s[0:1]
	s_barrier
	ds_read_b128 v[160:163], v179 offset:49152
	ds_read_b128 v[164:167], v179 offset:50176
	ds_read_b128 v[168:171], v179 offset:51200
	ds_read_b128 v[182:185], v179 offset:52224
	ds_read_b128 v[186:189], v179 offset:53248
	ds_read_b128 v[190:193], v179 offset:54272
	ds_read_b128 v[194:197], v179 offset:55296
	ds_read_b128 v[198:201], v179 offset:56320
	global_load_lds_dwordx4 v[172:173], off
	v_lshl_add_u64 v[172:173], v[224:225], 0, s[0:1]
	s_mov_b32 m0, s54
	s_nop 0
	global_load_lds_dwordx4 v[172:173], off
	s_setprio 1
	s_barrier
	s_waitcnt lgkmcnt(0)
	v_mfma_f32_16x16x32_bf16 v[60:63], v[144:147], v[160:163], v[60:63]
	v_mfma_f32_16x16x32_bf16 v[56:59], v[152:155], v[160:163], v[56:59]
	v_mfma_f32_16x16x32_bf16 v[44:47], v[144:147], v[168:171], v[44:47]
	v_mfma_f32_16x16x32_bf16 v[40:43], v[152:155], v[168:171], v[40:43]
	v_mfma_f32_16x16x32_bf16 v[32:35], v[144:147], v[186:189], v[32:35]
	v_mfma_f32_16x16x32_bf16 v[24:27], v[152:155], v[186:189], v[24:27]
	v_mfma_f32_16x16x32_bf16 v[16:19], v[144:147], v[194:197], v[16:19]
	v_mfma_f32_16x16x32_bf16 v[8:11], v[152:155], v[194:197], v[8:11]
	v_mfma_f32_16x16x32_bf16 v[60:63], v[148:151], v[164:167], v[60:63]
	v_mfma_f32_16x16x32_bf16 v[56:59], v[156:159], v[164:167], v[56:59]
	v_mfma_f32_16x16x32_bf16 v[44:47], v[148:151], v[182:185], v[44:47]
	v_mfma_f32_16x16x32_bf16 v[40:43], v[156:159], v[182:185], v[40:43]
	v_mfma_f32_16x16x32_bf16 v[32:35], v[148:151], v[190:193], v[32:35]
	v_mfma_f32_16x16x32_bf16 v[24:27], v[156:159], v[190:193], v[24:27]
	v_mfma_f32_16x16x32_bf16 v[16:19], v[148:151], v[198:201], v[16:19]
	v_mfma_f32_16x16x32_bf16 v[8:11], v[156:159], v[198:201], v[8:11]
	s_setprio 0
	s_barrier
	s_add_u32 s40, s40, 0x20080
	s_addc_u32 s41, s41, 0
	s_add_i32 s42, s42, s48
	v_lshl_add_u64 v[144:145], s[40:41], 0, v[130:131]
	s_mov_b32 m0, s42
	s_nop 0
	global_load_lds_dwordx4 v[144:145], off
	v_lshl_add_u64 v[144:145], s[40:41], 0, v[134:135]
	s_add_i32 m0, s42, 0x2000
	s_nop 0
	global_load_lds_dwordx4 v[144:145], off
	s_waitcnt vmcnt(6)
	s_setprio 1
	s_barrier
	v_mfma_f32_16x16x32_bf16 v[52:55], v[202:205], v[160:163], v[52:55]
	v_mfma_f32_16x16x32_bf16 v[48:51], v[212:215], v[160:163], v[48:51]
	v_mfma_f32_16x16x32_bf16 v[36:39], v[202:205], v[168:171], v[36:39]
	v_mfma_f32_16x16x32_bf16 v[28:31], v[212:215], v[168:171], v[28:31]
	v_mfma_f32_16x16x32_bf16 v[20:23], v[202:205], v[186:189], v[20:23]
	v_mfma_f32_16x16x32_bf16 v[12:15], v[212:215], v[186:189], v[12:15]
	v_mfma_f32_16x16x32_bf16 v[4:7], v[202:205], v[194:197], v[4:7]
	v_mfma_f32_16x16x32_bf16 v[0:3], v[212:215], v[194:197], v[0:3]
	v_mfma_f32_16x16x32_bf16 v[52:55], v[206:209], v[164:167], v[52:55]
	v_mfma_f32_16x16x32_bf16 v[48:51], v[216:219], v[164:167], v[48:51]
	v_mfma_f32_16x16x32_bf16 v[36:39], v[206:209], v[182:185], v[36:39]
	v_mfma_f32_16x16x32_bf16 v[28:31], v[216:219], v[182:185], v[28:31]
	v_mfma_f32_16x16x32_bf16 v[20:23], v[206:209], v[190:193], v[20:23]
	v_mfma_f32_16x16x32_bf16 v[12:15], v[216:219], v[190:193], v[12:15]
	v_mfma_f32_16x16x32_bf16 v[4:7], v[206:209], v[198:201], v[4:7]
	v_mfma_f32_16x16x32_bf16 v[0:3], v[216:219], v[198:201], v[0:3]
	s_setprio 0
	s_add_i32 s63, s63, 2
	s_add_u32 s38, s38, 0x100
	s_addc_u32 s39, s39, 0
	s_add_u32 s61, s61, 0x100
	s_addc_u32 s62, s62, 0
	s_cmp_gt_u32 s63, 5
	s_barrier
	s_cbranch_scc0 .LBB0_792
	v_lshl_or_b32 v144, s36, 8, v177
	v_lshl_add_u32 v150, s34, 8, v175
	v_ashrrev_i32_e32 v145, 31, v144
	v_ashrrev_i32_e32 v151, 31, v150
	v_lshlrev_b64 v[144:145], 1, v[144:145]
	v_lshl_add_u64 v[146:147], s[10:11], 0, v[144:145]
	v_lshlrev_b64 v[148:149], 11, v[150:151]
	v_lshl_add_u64 v[152:153], v[146:147], 0, v[148:149]
	global_load_dwordx4 v[156:159], v[152:153], off
	global_load_dwordx4 v[160:163], v[152:153], off offset:256
	v_or_b32_e32 v152, 16, v150
	v_ashrrev_i32_e32 v153, 31, v152
	v_lshlrev_b64 v[170:171], 11, v[152:153]
	v_lshl_add_u64 v[152:153], v[146:147], 0, v[170:171]
	global_load_dwordx4 v[164:167], v[152:153], off
	global_load_dwordx4 v[182:185], v[152:153], off offset:256
	v_or_b32_e32 v152, 32, v150
	v_ashrrev_i32_e32 v153, 31, v152
	v_lshlrev_b64 v[154:155], 11, v[152:153]
	v_lshl_add_u64 v[152:153], v[146:147], 0, v[154:155]
	global_load_dwordx4 v[186:189], v[152:153], off
	global_load_dwordx4 v[190:193], v[152:153], off offset:256
	v_or_b32_e32 v152, 48, v150
	v_ashrrev_i32_e32 v153, 31, v152
	v_lshlrev_b64 v[152:153], 11, v[152:153]
	v_lshl_add_u64 v[168:169], v[146:147], 0, v[152:153]
	global_load_dwordx4 v[194:197], v[168:169], off
	global_load_dwordx4 v[198:201], v[168:169], off offset:256
	s_waitcnt vmcnt(0)
	v_lshlrev_b32_e32 v202, 16, v156
	v_and_b32_e32 v203, 0xffff0000, v156
	v_lshlrev_b32_e32 v204, 16, v157
	v_and_b32_e32 v205, 0xffff0000, v157
	v_lshlrev_b32_e32 v206, 16, v158
	v_and_b32_e32 v207, 0xffff0000, v158
	v_lshlrev_b32_e32 v208, 16, v159
	v_and_b32_e32 v209, 0xffff0000, v159
	v_pk_add_f32 v[126:127], v[126:127], v[204:205]
	v_pk_add_f32 v[124:125], v[124:125], v[202:203]
	v_lshlrev_b32_e32 v224, 16, v166
	v_and_b32_e32 v225, 0xffff0000, v166
	v_lshlrev_b32_e32 v226, 16, v167
	v_and_b32_e32 v227, 0xffff0000, v167
	v_lshlrev_b32_e32 v212, 16, v160
	v_lshlrev_b32_e32 v166, 16, v194
	v_and_b32_e32 v167, 0xffff0000, v194
	v_lshlrev_b32_e32 v172, 16, v195
	v_and_b32_e32 v173, 0xffff0000, v195
	v_pk_add_f32 v[194:195], v[122:123], v[208:209]
	v_pk_add_f32 v[122:123], v[120:121], v[206:207]
	v_mul_f32_e32 v120, v125, v125
	v_mul_f32_e32 v121, v127, v127
	v_fmac_f32_e32 v120, v124, v124
	v_fmac_f32_e32 v121, v126, v126
	v_add_f32_e32 v120, v120, v121
	v_mul_f32_e32 v121, v123, v123
	v_fmac_f32_e32 v121, v122, v122
	v_add_f32_e32 v120, v121, v120
	v_mul_f32_e32 v121, v195, v195
	v_fmac_f32_e32 v121, v194, v194
	v_and_b32_e32 v213, 0xffff0000, v160
	v_lshlrev_b32_e32 v214, 16, v161
	v_and_b32_e32 v215, 0xffff0000, v161
	v_add_f32_e32 v181, v121, v120
	v_cvt_pk_bf16_f32 v120, v124, v125
	v_lshl_add_u64 v[124:125], s[90:91], 0, v[148:149]
	v_lshlrev_b32_e32 v216, 16, v162
	v_and_b32_e32 v217, 0xffff0000, v162
	v_lshlrev_b32_e32 v218, 16, v163
	v_and_b32_e32 v219, 0xffff0000, v163
	v_cvt_pk_bf16_f32 v121, v126, v127
	v_lshl_add_u64 v[124:125], v[124:125], 0, v[144:145]
	v_pk_add_f32 v[118:119], v[118:119], v[214:215]
	v_pk_add_f32 v[116:117], v[116:117], v[212:213]
	v_cvt_pk_bf16_f32 v122, v122, v123
	v_cvt_pk_bf16_f32 v123, v194, v195
	global_store_dwordx4 v[124:125], v[120:123], off
	v_lshlrev_b32_e32 v220, 16, v164
	v_and_b32_e32 v221, 0xffff0000, v164
	v_pk_add_f32 v[120:121], v[114:115], v[218:219]
	v_pk_add_f32 v[114:115], v[112:113], v[216:217]
	v_mul_f32_e32 v112, v117, v117
	v_mul_f32_e32 v113, v119, v119
	v_fmac_f32_e32 v112, v116, v116
	v_fmac_f32_e32 v113, v118, v118
	v_add_f32_e32 v112, v112, v113
	v_mul_f32_e32 v113, v115, v115
	v_fmac_f32_e32 v113, v114, v114
	v_add_f32_e32 v112, v113, v112
	v_mul_f32_e32 v113, v121, v121
	v_fmac_f32_e32 v113, v120, v120
	v_add_f32_e32 v112, v113, v112
	v_lshlrev_b32_e32 v222, 16, v165
	v_and_b32_e32 v223, 0xffff0000, v165
	v_add_f32_e32 v126, v181, v112
	v_cvt_pk_bf16_f32 v112, v116, v117
	v_cvt_pk_bf16_f32 v113, v118, v119
	v_lshl_add_u64 v[116:117], s[90:91], 0, v[170:171]
	v_lshlrev_b32_e32 v230, 16, v184
	v_and_b32_e32 v231, 0xffff0000, v184
	v_lshlrev_b32_e32 v232, 16, v186
	v_and_b32_e32 v233, 0xffff0000, v186
	v_lshlrev_b32_e32 v186, 16, v187
	v_and_b32_e32 v187, 0xffff0000, v187
	v_cvt_pk_bf16_f32 v114, v114, v115
	v_cvt_pk_bf16_f32 v115, v120, v121
	global_store_dwordx4 v[124:125], v[112:115], off offset:256
	v_pk_add_f32 v[110:111], v[110:111], v[222:223]
	v_pk_add_f32 v[108:109], v[108:109], v[220:221]
	v_lshl_add_u64 v[118:119], v[116:117], 0, v[144:145]
	v_cvt_pk_bf16_f32 v112, v108, v109
	v_cvt_pk_bf16_f32 v113, v110, v111
	v_lshlrev_b32_e32 v228, 16, v182
	v_and_b32_e32 v229, 0xffff0000, v182
	v_lshlrev_b32_e32 v182, 16, v183
	v_and_b32_e32 v183, 0xffff0000, v183
	v_lshlrev_b32_e32 v184, 16, v185
	v_and_b32_e32 v185, 0xffff0000, v185
	v_lshlrev_b32_e32 v238, 16, v192
	v_and_b32_e32 v239, 0xffff0000, v192
	v_pk_add_f32 v[106:107], v[106:107], v[226:227]
	v_pk_add_f32 v[104:105], v[104:105], v[224:225]
	v_lshlrev_b32_e32 v156, 16, v200
	v_cvt_pk_bf16_f32 v114, v104, v105
	v_cvt_pk_bf16_f32 v115, v106, v107
	global_store_dwordx4 v[118:119], v[112:115], off
	v_and_b32_e32 v157, 0xffff0000, v200
	v_pk_add_f32 v[102:103], v[102:103], v[182:183]
	v_pk_add_f32 v[112:113], v[92:93], v[230:231]
	v_pk_add_f32 v[92:93], v[98:99], v[186:187]
	v_lshl_add_u64 v[98:99], s[90:91], 0, v[154:155]
	v_pk_add_f32 v[100:101], v[100:101], v[228:229]
	v_pk_add_f32 v[94:95], v[94:95], v[184:185]
	v_cvt_pk_bf16_f32 v114, v100, v101
	v_cvt_pk_bf16_f32 v115, v102, v103
	v_cvt_pk_bf16_f32 v116, v112, v113
	v_lshlrev_b32_e32 v234, 16, v188
	v_cvt_pk_bf16_f32 v117, v94, v95
	global_store_dwordx4 v[118:119], v[114:117], off offset:256
	v_lshl_add_u64 v[118:119], v[98:99], 0, v[144:145]
	v_pk_add_f32 v[98:99], v[76:77], v[238:239]
	v_pk_add_f32 v[76:77], v[82:83], v[172:173]
	v_lshl_add_u64 v[82:83], s[90:91], 0, v[152:153]
	v_lshl_add_u64 v[122:123], v[82:83], 0, v[144:145]
	v_pk_add_f32 v[82:83], v[64:65], v[156:157]
	v_and_b32_e32 v65, 64, v174
	v_and_b32_e32 v235, 0xffff0000, v188
	v_lshlrev_b32_e32 v188, 16, v189
	v_and_b32_e32 v189, 0xffff0000, v189
	v_lshlrev_b32_e32 v236, 16, v190
	v_and_b32_e32 v237, 0xffff0000, v190
	v_pk_add_f32 v[96:97], v[96:97], v[232:233]
	v_xor_b32_e32 v64, 16, v174
	v_cvt_pk_bf16_f32 v114, v96, v97
	v_add_u32_e32 v65, 64, v65
	v_lshlrev_b32_e32 v190, 16, v191
	v_and_b32_e32 v191, 0xffff0000, v191
	v_lshlrev_b32_e32 v192, 16, v193
	v_and_b32_e32 v193, 0xffff0000, v193
	v_pk_add_f32 v[90:91], v[90:91], v[188:189]
	v_pk_add_f32 v[88:89], v[88:89], v[234:235]
	v_cvt_pk_bf16_f32 v115, v92, v93
	v_pk_add_f32 v[84:85], v[84:85], v[236:237]
	v_cvt_pk_bf16_f32 v116, v88, v89
	v_cvt_pk_bf16_f32 v117, v90, v91
	global_store_dwordx4 v[118:119], v[114:117], off
	v_cmp_lt_i32_e32 vcc, v64, v65
	v_lshlrev_b32_e32 v164, 16, v196
	v_cvt_pk_bf16_f32 v114, v84, v85
	v_and_b32_e32 v165, 0xffff0000, v196
	v_lshlrev_b32_e32 v168, 16, v197
	v_and_b32_e32 v169, 0xffff0000, v197
	v_pk_add_f32 v[86:87], v[86:87], v[190:191]
	v_pk_add_f32 v[78:79], v[78:79], v[192:193]
	v_cvt_pk_bf16_f32 v115, v86, v87
	v_cvt_pk_bf16_f32 v116, v98, v99
	v_pk_add_f32 v[80:81], v[80:81], v[166:167]
	v_cvt_pk_bf16_f32 v117, v78, v79
	global_store_dwordx4 v[118:119], v[114:117], off offset:256
	v_cndmask_b32_e32 v64, v174, v64, vcc
	v_pk_add_f32 v[74:75], v[74:75], v[168:169]
	v_cvt_pk_bf16_f32 v114, v80, v81
	v_pk_add_f32 v[72:73], v[72:73], v[164:165]
	v_cvt_pk_bf16_f32 v115, v76, v77
	v_lshlrev_b32_e32 v158, 16, v198
	v_cvt_pk_bf16_f32 v116, v72, v73
	v_cvt_pk_bf16_f32 v117, v74, v75
	global_store_dwordx4 v[122:123], v[114:117], off
	v_and_b32_e32 v159, 0xffff0000, v198
	v_lshlrev_b32_e32 v162, 16, v199
	v_lshlrev_b32_e32 v114, 2, v64
	ds_bpermute_b32 v64, v114, v126
	v_xor_b32_e32 v115, 32, v174
	v_cmp_lt_i32_e32 vcc, v115, v65
	v_and_b32_e32 v163, 0xffff0000, v199
	v_lshlrev_b32_e32 v160, 16, v201
	v_cndmask_b32_e32 v65, v174, v115, vcc
	v_lshlrev_b32_e32 v115, 2, v65
	s_waitcnt lgkmcnt(0)
	v_add_f32_e32 v116, v126, v64
	ds_bpermute_b32 v117, v115, v116
	v_and_b32_e32 v161, 0xffff0000, v201
	v_pk_add_f32 v[70:71], v[70:71], v[162:163]
	v_pk_add_f32 v[68:69], v[68:69], v[158:159]
	v_pk_add_f32 v[66:67], v[66:67], v[160:161]
	v_lshl_add_u64 v[64:65], v[150:151], 2, s[2:3]
	v_cvt_pk_bf16_f32 v118, v68, v69
	v_cvt_pk_bf16_f32 v119, v70, v71
	v_cvt_pk_bf16_f32 v120, v82, v83
	v_cvt_pk_bf16_f32 v121, v66, v67
	global_store_dwordx4 v[122:123], v[118:121], off offset:256
	s_and_saveexec_b64 s[34:35], s[6:7]
	s_cbranch_execz .LBB0_795
	s_waitcnt lgkmcnt(0)
	v_add_f32_e32 v116, v116, v117
	global_atomic_add_f32 v[64:65], v116, off

.LBB0_850:
	ds_read_b128 v[144:147], v151
	ds_read_b128 v[156:159], v151 offset:1024
	ds_read_b128 v[160:163], v151 offset:2048
	ds_read_b128 v[164:167], v151 offset:3072
	s_add_u32 s36, s34, 0xfffc0080
	s_addc_u32 s37, s35, -1
	s_cmp_eq_u32 s66, 12
	s_cselect_b32 s39, s27, s37
	s_cselect_b32 s38, s62, s36
	s_cselect_b32 s37, s25, s65
	s_cselect_b32 s36, s63, s64
	v_lshl_add_u64 v[172:173], s[34:35], 0, v[136:137]
	s_add_i32 m0, s42, 0xc000
	ds_read_b128 v[168:171], v152
	ds_read_b128 v[176:179], v152 offset:1024
	ds_read_b128 v[180:183], v152 offset:2048
	ds_read_b128 v[184:187], v152 offset:3072
	ds_read_b128 v[188:191], v152 offset:4096
	ds_read_b128 v[192:195], v152 offset:5120
	ds_read_b128 v[196:199], v152 offset:6144
	ds_read_b128 v[200:203], v152 offset:7168
	global_load_lds_dwordx4 v[172:173], off
	v_lshl_add_u64 v[172:173], s[34:35], 0, v[138:139]
	s_add_i32 m0, s42, 0xe000
	s_nop 0
	global_load_lds_dwordx4 v[172:173], off
	s_waitcnt lgkmcnt(8)
	s_setprio 1
	s_barrier
	s_waitcnt lgkmcnt(0)
	v_mfma_f32_16x16x32_bf16 v[124:127], v[144:147], v[168:171], v[124:127]
	v_mfma_f32_16x16x32_bf16 v[120:123], v[160:163], v[168:171], v[120:123]
	v_mfma_f32_16x16x32_bf16 v[116:119], v[144:147], v[180:183], v[116:119]
	v_mfma_f32_16x16x32_bf16 v[112:115], v[160:163], v[180:183], v[112:115]
	v_mfma_f32_16x16x32_bf16 v[92:95], v[144:147], v[188:191], v[92:95]
	v_mfma_f32_16x16x32_bf16 v[88:91], v[160:163], v[188:191], v[88:91]
	v_mfma_f32_16x16x32_bf16 v[76:79], v[144:147], v[196:199], v[76:79]
	v_mfma_f32_16x16x32_bf16 v[72:75], v[160:163], v[196:199], v[72:75]
	v_mfma_f32_16x16x32_bf16 v[124:127], v[156:159], v[176:179], v[124:127]
	v_mfma_f32_16x16x32_bf16 v[120:123], v[164:167], v[176:179], v[120:123]
	v_mfma_f32_16x16x32_bf16 v[116:119], v[156:159], v[184:187], v[116:119]
	v_mfma_f32_16x16x32_bf16 v[112:115], v[164:167], v[184:187], v[112:115]
	v_mfma_f32_16x16x32_bf16 v[92:95], v[156:159], v[192:195], v[92:95]
	v_mfma_f32_16x16x32_bf16 v[88:91], v[164:167], v[192:195], v[88:91]
	v_mfma_f32_16x16x32_bf16 v[76:79], v[156:159], v[200:203], v[76:79]
	v_mfma_f32_16x16x32_bf16 v[72:75], v[164:167], v[200:203], v[72:75]
	s_setprio 0
	s_barrier
	s_add_i32 s67, s55, s41
	v_lshl_add_u64 v[172:173], s[36:37], 0, v[130:131]
	s_mov_b32 m0, s67
	ds_read_b128 v[204:207], v153
	ds_read_b128 v[212:215], v153 offset:1024
	ds_read_b128 v[216:219], v153 offset:2048
	ds_read_b128 v[220:223], v153 offset:3072
	global_load_lds_dwordx4 v[172:173], off
	v_lshl_add_u64 v[208:209], s[36:37], 0, v[134:135]
	s_add_i32 m0, s67, 0x2000
	s_nop 0
	global_load_lds_dwordx4 v[208:209], off
	s_setprio 1
	s_barrier
	s_waitcnt lgkmcnt(0)
	v_mfma_f32_16x16x32_bf16 v[108:111], v[204:207], v[168:171], v[108:111]
	v_mfma_f32_16x16x32_bf16 v[104:107], v[216:219], v[168:171], v[104:107]
	v_mfma_f32_16x16x32_bf16 v[100:103], v[204:207], v[180:183], v[100:103]
	v_mfma_f32_16x16x32_bf16 v[96:99], v[216:219], v[180:183], v[96:99]
	v_mfma_f32_16x16x32_bf16 v[84:87], v[204:207], v[188:191], v[84:87]
	v_mfma_f32_16x16x32_bf16 v[80:83], v[216:219], v[188:191], v[80:83]
	v_mfma_f32_16x16x32_bf16 v[68:71], v[204:207], v[196:199], v[68:71]
	v_mfma_f32_16x16x32_bf16 v[64:67], v[216:219], v[196:199], v[64:67]
	v_mfma_f32_16x16x32_bf16 v[108:111], v[212:215], v[176:179], v[108:111]
	v_mfma_f32_16x16x32_bf16 v[104:107], v[220:223], v[176:179], v[104:107]
	v_mfma_f32_16x16x32_bf16 v[100:103], v[212:215], v[184:187], v[100:103]
	v_mfma_f32_16x16x32_bf16 v[96:99], v[220:223], v[184:187], v[96:99]
	v_mfma_f32_16x16x32_bf16 v[84:87], v[212:215], v[192:195], v[84:87]
	v_mfma_f32_16x16x32_bf16 v[80:83], v[220:223], v[192:195], v[80:83]
	v_mfma_f32_16x16x32_bf16 v[68:71], v[212:215], v[200:203], v[68:71]
	v_mfma_f32_16x16x32_bf16 v[64:67], v[220:223], v[200:203], v[64:67]
	s_setprio 0
	s_mov_b32 m0, s42
	v_lshl_add_u64 v[224:225], s[38:39], 0, v[128:129]
	s_barrier
	ds_read_b128 v[168:171], v152 offset:16384
	ds_read_b128 v[176:179], v152 offset:17408
	ds_read_b128 v[180:183], v152 offset:18432
	ds_read_b128 v[184:187], v152 offset:19456
	ds_read_b128 v[188:191], v152 offset:20480
	ds_read_b128 v[192:195], v152 offset:21504
	ds_read_b128 v[196:199], v152 offset:22528
	ds_read_b128 v[200:203], v152 offset:23552
	global_load_lds_dwordx4 v[224:225], off
	v_lshl_add_u64 v[226:227], s[38:39], 0, v[132:133]
	s_mov_b32 m0, s43
	s_nop 0
	global_load_lds_dwordx4 v[226:227], off
	s_setprio 1
	s_barrier
	s_waitcnt lgkmcnt(0)
	v_mfma_f32_16x16x32_bf16 v[60:63], v[144:147], v[168:171], v[60:63]
	v_mfma_f32_16x16x32_bf16 v[56:59], v[160:163], v[168:171], v[56:59]
	v_mfma_f32_16x16x32_bf16 v[44:47], v[144:147], v[180:183], v[44:47]
	v_mfma_f32_16x16x32_bf16 v[40:43], v[160:163], v[180:183], v[40:43]
	v_mfma_f32_16x16x32_bf16 v[28:31], v[144:147], v[188:191], v[28:31]
	v_mfma_f32_16x16x32_bf16 v[24:27], v[160:163], v[188:191], v[24:27]
	v_mfma_f32_16x16x32_bf16 v[12:15], v[144:147], v[196:199], v[12:15]
	v_mfma_f32_16x16x32_bf16 v[8:11], v[160:163], v[196:199], v[8:11]
	v_mfma_f32_16x16x32_bf16 v[60:63], v[156:159], v[176:179], v[60:63]
	v_mfma_f32_16x16x32_bf16 v[56:59], v[164:167], v[176:179], v[56:59]
	v_mfma_f32_16x16x32_bf16 v[44:47], v[156:159], v[184:187], v[44:47]
	v_mfma_f32_16x16x32_bf16 v[40:43], v[164:167], v[184:187], v[40:43]
	v_mfma_f32_16x16x32_bf16 v[28:31], v[156:159], v[192:195], v[28:31]
	v_mfma_f32_16x16x32_bf16 v[24:27], v[164:167], v[192:195], v[24:27]
	v_mfma_f32_16x16x32_bf16 v[12:15], v[156:159], v[200:203], v[12:15]
	v_mfma_f32_16x16x32_bf16 v[8:11], v[164:167], v[200:203], v[8:11]
	s_setprio 0
	s_barrier
	s_add_u32 s68, s36, 0x40000
	s_addc_u32 s69, s37, 0
	s_add_i32 s67, s56, s41
	v_lshl_add_u64 v[144:145], s[68:69], 0, v[130:131]
	s_mov_b32 m0, s67
	s_nop 0
	global_load_lds_dwordx4 v[144:145], off
	v_lshl_add_u64 v[144:145], s[68:69], 0, v[134:135]
	s_add_i32 m0, s67, 0x2000
	s_nop 0
	global_load_lds_dwordx4 v[144:145], off
	s_waitcnt vmcnt(6)
	s_setprio 1
	s_barrier
	v_mfma_f32_16x16x32_bf16 v[52:55], v[204:207], v[168:171], v[52:55]
	v_mfma_f32_16x16x32_bf16 v[48:51], v[216:219], v[168:171], v[48:51]
	v_mfma_f32_16x16x32_bf16 v[36:39], v[204:207], v[180:183], v[36:39]
	v_mfma_f32_16x16x32_bf16 v[32:35], v[216:219], v[180:183], v[32:35]
	v_mfma_f32_16x16x32_bf16 v[20:23], v[204:207], v[188:191], v[20:23]
	v_mfma_f32_16x16x32_bf16 v[16:19], v[216:219], v[188:191], v[16:19]
	v_mfma_f32_16x16x32_bf16 v[4:7], v[204:207], v[196:199], v[4:7]
	v_mfma_f32_16x16x32_bf16 v[0:3], v[216:219], v[196:199], v[0:3]
	v_mfma_f32_16x16x32_bf16 v[52:55], v[212:215], v[176:179], v[52:55]
	v_mfma_f32_16x16x32_bf16 v[48:51], v[220:223], v[176:179], v[48:51]
	v_mfma_f32_16x16x32_bf16 v[36:39], v[212:215], v[184:187], v[36:39]
	v_mfma_f32_16x16x32_bf16 v[32:35], v[220:223], v[184:187], v[32:35]
	v_mfma_f32_16x16x32_bf16 v[20:23], v[212:215], v[192:195], v[20:23]
	v_mfma_f32_16x16x32_bf16 v[16:19], v[220:223], v[192:195], v[16:19]
	v_mfma_f32_16x16x32_bf16 v[4:7], v[212:215], v[200:203], v[4:7]
	v_mfma_f32_16x16x32_bf16 v[0:3], v[220:223], v[200:203], v[0:3]
	s_setprio 0
	s_add_i32 s67, 0, 0x18000
	v_add_u32_e32 v155, s67, v149
	s_barrier
	ds_read_b128 v[144:147], v155
	ds_read_b128 v[156:159], v155 offset:1024
	ds_read_b128 v[160:163], v155 offset:2048
	ds_read_b128 v[164:167], v155 offset:3072
	s_add_u32 s38, s38, 0x40000
	s_addc_u32 s39, s39, 0
	s_mov_b32 m0, s48
	v_lshl_add_u64 v[204:205], s[38:39], 0, v[128:129]
	ds_read_b128 v[168:171], v152 offset:32768
	ds_read_b128 v[176:179], v152 offset:33792
	ds_read_b128 v[180:183], v152 offset:34816
	ds_read_b128 v[184:187], v152 offset:35840
	ds_read_b128 v[188:191], v152 offset:36864
	ds_read_b128 v[192:195], v152 offset:37888
	ds_read_b128 v[196:199], v152 offset:38912
	ds_read_b128 v[200:203], v152 offset:39936
	global_load_lds_dwordx4 v[204:205], off
	v_lshl_add_u64 v[204:205], s[38:39], 0, v[132:133]
	s_mov_b32 m0, s49
	s_nop 0
	global_load_lds_dwordx4 v[204:205], off
	s_waitcnt lgkmcnt(8)
	s_setprio 1
	s_barrier
	s_waitcnt lgkmcnt(0)
	v_mfma_f32_16x16x32_bf16 v[124:127], v[144:147], v[168:171], v[124:127]
	v_mfma_f32_16x16x32_bf16 v[120:123], v[160:163], v[168:171], v[120:123]
	v_mfma_f32_16x16x32_bf16 v[116:119], v[144:147], v[180:183], v[116:119]
	v_mfma_f32_16x16x32_bf16 v[112:115], v[160:163], v[180:183], v[112:115]
	v_mfma_f32_16x16x32_bf16 v[92:95], v[144:147], v[188:191], v[92:95]
	v_mfma_f32_16x16x32_bf16 v[88:91], v[160:163], v[188:191], v[88:91]
	v_mfma_f32_16x16x32_bf16 v[76:79], v[144:147], v[196:199], v[76:79]
	v_mfma_f32_16x16x32_bf16 v[72:75], v[160:163], v[196:199], v[72:75]
	v_mfma_f32_16x16x32_bf16 v[124:127], v[156:159], v[176:179], v[124:127]
	v_mfma_f32_16x16x32_bf16 v[120:123], v[164:167], v[176:179], v[120:123]
	v_mfma_f32_16x16x32_bf16 v[116:119], v[156:159], v[184:187], v[116:119]
	v_mfma_f32_16x16x32_bf16 v[112:115], v[164:167], v[184:187], v[112:115]
	v_mfma_f32_16x16x32_bf16 v[92:95], v[156:159], v[192:195], v[92:95]
	v_mfma_f32_16x16x32_bf16 v[88:91], v[164:167], v[192:195], v[88:91]
	v_mfma_f32_16x16x32_bf16 v[76:79], v[156:159], v[200:203], v[76:79]
	v_mfma_f32_16x16x32_bf16 v[72:75], v[164:167], v[200:203], v[72:75]
	s_setprio 0
	s_barrier
	s_add_i32 s38, 0, 0x1c000
	s_add_i32 s39, s67, s41
	v_add_u32_e32 v155, s38, v149
	v_lshl_add_u64 v[172:173], v[172:173], 0, s[8:9]
	s_mov_b32 m0, s39
	ds_read_b128 v[204:207], v155
	ds_read_b128 v[212:215], v155 offset:1024
	ds_read_b128 v[216:219], v155 offset:2048
	ds_read_b128 v[220:223], v155 offset:3072
	global_load_lds_dwordx4 v[172:173], off
	v_lshl_add_u64 v[172:173], v[208:209], 0, s[8:9]
	s_add_i32 m0, s39, 0x2000
	s_nop 0
	global_load_lds_dwordx4 v[172:173], off
	s_setprio 1
	s_barrier
	s_waitcnt lgkmcnt(0)
	v_mfma_f32_16x16x32_bf16 v[108:111], v[204:207], v[168:171], v[108:111]
	v_mfma_f32_16x16x32_bf16 v[104:107], v[216:219], v[168:171], v[104:107]
	v_mfma_f32_16x16x32_bf16 v[100:103], v[204:207], v[180:183], v[100:103]
	v_mfma_f32_16x16x32_bf16 v[96:99], v[216:219], v[180:183], v[96:99]
	v_mfma_f32_16x16x32_bf16 v[84:87], v[204:207], v[188:191], v[84:87]
	v_mfma_f32_16x16x32_bf16 v[80:83], v[216:219], v[188:191], v[80:83]
	v_mfma_f32_16x16x32_bf16 v[68:71], v[204:207], v[196:199], v[68:71]
	v_mfma_f32_16x16x32_bf16 v[64:67], v[216:219], v[196:199], v[64:67]
	v_mfma_f32_16x16x32_bf16 v[108:111], v[212:215], v[176:179], v[108:111]
	v_mfma_f32_16x16x32_bf16 v[104:107], v[220:223], v[176:179], v[104:107]
	v_mfma_f32_16x16x32_bf16 v[100:103], v[212:215], v[184:187], v[100:103]
	v_mfma_f32_16x16x32_bf16 v[96:99], v[220:223], v[184:187], v[96:99]
	v_mfma_f32_16x16x32_bf16 v[84:87], v[212:215], v[192:195], v[84:87]
	v_mfma_f32_16x16x32_bf16 v[80:83], v[220:223], v[192:195], v[80:83]
	v_mfma_f32_16x16x32_bf16 v[68:71], v[212:215], v[200:203], v[68:71]
	v_mfma_f32_16x16x32_bf16 v[64:67], v[220:223], v[200:203], v[64:67]
	s_setprio 0
	s_mov_b32 m0, s51
	v_lshl_add_u64 v[172:173], v[224:225], 0, s[8:9]
	s_barrier
	ds_read_b128 v[168:171], v152 offset:49152
	ds_read_b128 v[176:179], v152 offset:50176
	ds_read_b128 v[180:183], v152 offset:51200
	ds_read_b128 v[184:187], v152 offset:52224
	ds_read_b128 v[188:191], v152 offset:53248
	ds_read_b128 v[192:195], v152 offset:54272
	ds_read_b128 v[196:199], v152 offset:55296
	ds_read_b128 v[200:203], v152 offset:56320
	global_load_lds_dwordx4 v[172:173], off
	v_lshl_add_u64 v[172:173], v[226:227], 0, s[8:9]
	s_mov_b32 m0, s52
	s_nop 0
	global_load_lds_dwordx4 v[172:173], off
	s_setprio 1
	s_barrier
	s_waitcnt lgkmcnt(0)
	v_mfma_f32_16x16x32_bf16 v[60:63], v[144:147], v[168:171], v[60:63]
	v_mfma_f32_16x16x32_bf16 v[56:59], v[160:163], v[168:171], v[56:59]
	v_mfma_f32_16x16x32_bf16 v[44:47], v[144:147], v[180:183], v[44:47]
	v_mfma_f32_16x16x32_bf16 v[40:43], v[160:163], v[180:183], v[40:43]
	v_mfma_f32_16x16x32_bf16 v[28:31], v[144:147], v[188:191], v[28:31]
	v_mfma_f32_16x16x32_bf16 v[24:27], v[160:163], v[188:191], v[24:27]
	v_mfma_f32_16x16x32_bf16 v[12:15], v[144:147], v[196:199], v[12:15]
	v_mfma_f32_16x16x32_bf16 v[8:11], v[160:163], v[196:199], v[8:11]
	v_mfma_f32_16x16x32_bf16 v[60:63], v[156:159], v[176:179], v[60:63]
	v_mfma_f32_16x16x32_bf16 v[56:59], v[164:167], v[176:179], v[56:59]
	v_mfma_f32_16x16x32_bf16 v[44:47], v[156:159], v[184:187], v[44:47]
	v_mfma_f32_16x16x32_bf16 v[40:43], v[164:167], v[184:187], v[40:43]
	v_mfma_f32_16x16x32_bf16 v[28:31], v[156:159], v[192:195], v[28:31]
	v_mfma_f32_16x16x32_bf16 v[24:27], v[164:167], v[192:195], v[24:27]
	v_mfma_f32_16x16x32_bf16 v[12:15], v[156:159], v[200:203], v[12:15]
	v_mfma_f32_16x16x32_bf16 v[8:11], v[164:167], v[200:203], v[8:11]
	s_setprio 0
	s_barrier
	s_add_u32 s36, s36, 0x40080
	s_addc_u32 s37, s37, 0
	s_add_i32 s38, s38, s41
	v_lshl_add_u64 v[144:145], s[36:37], 0, v[130:131]
	s_mov_b32 m0, s38
	s_nop 0
	global_load_lds_dwordx4 v[144:145], off
	v_lshl_add_u64 v[144:145], s[36:37], 0, v[134:135]
	s_add_i32 m0, s38, 0x2000
	s_nop 0
	global_load_lds_dwordx4 v[144:145], off
	s_waitcnt vmcnt(6)
	s_setprio 1
	s_barrier
	v_mfma_f32_16x16x32_bf16 v[52:55], v[204:207], v[168:171], v[52:55]
	v_mfma_f32_16x16x32_bf16 v[48:51], v[216:219], v[168:171], v[48:51]
	v_mfma_f32_16x16x32_bf16 v[36:39], v[204:207], v[180:183], v[36:39]
	v_mfma_f32_16x16x32_bf16 v[32:35], v[216:219], v[180:183], v[32:35]
	v_mfma_f32_16x16x32_bf16 v[20:23], v[204:207], v[188:191], v[20:23]
	v_mfma_f32_16x16x32_bf16 v[16:19], v[216:219], v[188:191], v[16:19]
	v_mfma_f32_16x16x32_bf16 v[4:7], v[204:207], v[196:199], v[4:7]
	v_mfma_f32_16x16x32_bf16 v[0:3], v[216:219], v[196:199], v[0:3]
	v_mfma_f32_16x16x32_bf16 v[52:55], v[212:215], v[176:179], v[52:55]
	v_mfma_f32_16x16x32_bf16 v[48:51], v[220:223], v[176:179], v[48:51]
	v_mfma_f32_16x16x32_bf16 v[36:39], v[212:215], v[184:187], v[36:39]
	v_mfma_f32_16x16x32_bf16 v[32:35], v[220:223], v[184:187], v[32:35]
	v_mfma_f32_16x16x32_bf16 v[20:23], v[212:215], v[192:195], v[20:23]
	v_mfma_f32_16x16x32_bf16 v[16:19], v[220:223], v[192:195], v[16:19]
	v_mfma_f32_16x16x32_bf16 v[4:7], v[212:215], v[200:203], v[4:7]
	v_mfma_f32_16x16x32_bf16 v[0:3], v[220:223], v[200:203], v[0:3]
	s_setprio 0
	s_add_i32 s66, s66, 2
	s_add_u32 s34, s34, 0x100
	s_addc_u32 s35, s35, 0
	s_add_u32 s64, s64, 0x100
	s_addc_u32 s65, s65, 0
	s_cmp_gt_u32 s66, 13
	s_barrier
	s_cbranch_scc0 .LBB0_850
	v_lshl_add_u32 v146, s0, 8, v148
	v_ashrrev_i32_e32 v147, 31, v146
	v_lshl_add_u64 v[144:145], v[146:147], 2, s[2:3]
	global_load_dword v155, v[144:145], off
	global_load_dword v162, v[144:145], off offset:64
	global_load_dword v163, v[144:145], off offset:128
	global_load_dword v164, v[144:145], off offset:192
	global_load_dword v165, v[144:145], off offset:512
	global_load_dword v166, v[144:145], off offset:576
	global_load_dword v167, v[144:145], off offset:640
	global_load_dword v168, v[144:145], off offset:704
	v_lshl_or_b32 v144, s1, 8, v150
	v_ashrrev_i32_e32 v145, 31, v144
	v_lshlrev_b64 v[158:159], 13, v[146:147]
	v_lshlrev_b64 v[160:161], 1, v[144:145]
	v_lshl_add_u64 v[144:145], s[92:93], 0, v[158:159]
	v_lshl_add_u64 v[144:145], v[144:145], 0, v[160:161]
	v_or_b32_e32 v156, 16, v146
	v_ashrrev_i32_e32 v157, 31, v156
	v_lshlrev_b64 v[156:157], 13, v[156:157]
	v_lshl_add_u64 v[156:157], s[92:93], 0, v[156:157]
	v_lshl_add_u64 v[156:157], v[156:157], 0, v[160:161]
	s_mov_b64 s[36:37], s[30:31]
	s_mov_b64 s[34:35], s[28:29]
	s_waitcnt vmcnt(0)
	v_fmamk_f32 v147, v155, 0x3a800000, v154
	v_mul_f32_e32 v158, 0x4b800000, v147
	v_cmp_gt_f32_e32 vcc, s57, v147
	v_fmamk_f32 v155, v162, 0x3a800000, v154
	v_mul_f32_e32 v162, 0x4b800000, v155
	v_cndmask_b32_e32 v147, v147, v158, vcc
	v_rsq_f32_e32 v158, v147
	v_cmp_gt_f32_e64 s[0:1], s57, v155
	v_fmamk_f32 v159, v163, 0x3a800000, v154
	v_fmamk_f32 v163, v164, 0x3a800000, v154
	v_cndmask_b32_e64 v155, v155, v162, s[0:1]
	v_rsq_f32_e32 v155, v155
	v_mul_f32_e32 v162, 0x45800000, v158
	v_cndmask_b32_e32 v158, v158, v162, vcc
	v_pk_mul_f32 v[124:125], v[124:125], v[158:159] op_sel_hi:[1,0]
	v_pk_mul_f32 v[104:105], v[104:105], v[158:159] op_sel_hi:[1,0]
	v_fmamk_f32 v164, v165, 0x3a800000, v154
	v_fmamk_f32 v165, v166, 0x3a800000, v154
	v_fmamk_f32 v166, v167, 0x3a800000, v154
	v_mul_f32_e32 v167, 0x45800000, v155
	v_pk_mul_f32 v[126:127], v[126:127], v[158:159] op_sel_hi:[1,0]
	v_pk_mul_f32 v[122:123], v[122:123], v[158:159] op_sel_hi:[1,0]
	v_pk_mul_f32 v[120:121], v[120:121], v[158:159] op_sel_hi:[1,0]
	v_pk_mul_f32 v[108:109], v[108:109], v[158:159] op_sel_hi:[1,0]
	v_pk_mul_f32 v[106:107], v[106:107], v[158:159] op_sel_hi:[1,0]
	v_max_f32_e32 v124, 0, v124
	v_max_f32_e32 v125, 0, v125
	v_max_f32_e32 v104, 0, v104
	v_cndmask_b32_e64 v162, v155, v167, s[0:1]
	v_pk_mul_f32 v[110:111], v[110:111], v[158:159] op_sel_hi:[1,0]
	v_max_f32_e32 v120, 0, v120
	v_max_f32_e32 v121, 0, v121
	v_max_f32_e32 v126, 0, v126
	v_max_f32_e32 v122, 0, v122
	v_max_f32_e32 v127, 0, v127
	v_max_f32_e32 v123, 0, v123
	v_max_f32_e32 v108, 0, v108
	v_max_f32_e32 v109, 0, v109
	v_max_f32_e32 v105, 0, v105
	v_max_f32_e32 v106, 0, v106
	v_max_f32_e32 v107, 0, v107
	v_mul_f32_e32 v124, v124, v124
	v_mul_f32_e32 v125, v125, v125
	v_mul_f32_e32 v155, v104, v104
	v_cvt_pk_bf16_f32 v104, v124, v125
	v_fmamk_f32 v147, v168, 0x3a800000, v154
	v_pk_mul_f32 v[112:113], v[112:113], v[162:163] op_sel_hi:[1,0]
	v_max_f32_e32 v110, 0, v110
	v_max_f32_e32 v111, 0, v111
	v_mul_f32_e32 v120, v120, v120
	v_mul_f32_e32 v121, v121, v121
	v_mul_f32_e32 v126, v126, v126
	v_mul_f32_e32 v122, v122, v122
	v_mul_f32_e32 v127, v127, v127
	v_mul_f32_e32 v123, v123, v123
	v_mul_f32_e32 v108, v108, v108
	v_mul_f32_e32 v109, v109, v109
	v_mul_f32_e32 v158, v105, v105
	v_mul_f32_e32 v167, v106, v106
	v_mul_f32_e32 v168, v107, v107
	v_cvt_pk_bf16_f32 v105, v126, v127
	v_cvt_pk_bf16_f32 v106, v120, v121
	v_cvt_pk_bf16_f32 v107, v122, v123
	global_store_dwordx4 v[144:145], v[104:107], off nt
	v_pk_mul_f32 v[116:117], v[116:117], v[162:163] op_sel_hi:[1,0]
	v_mul_f32_e32 v110, v110, v110
	v_cvt_pk_bf16_f32 v104, v108, v109
	v_mul_f32_e32 v111, v111, v111
	v_cvt_pk_bf16_f32 v105, v110, v111
	v_cvt_pk_bf16_f32 v106, v155, v158
	v_cvt_pk_bf16_f32 v107, v167, v168
	global_store_dwordx4 v[144:145], v[104:107], off offset:256 nt
	v_pk_mul_f32 v[118:119], v[118:119], v[162:163] op_sel_hi:[1,0]
	v_pk_mul_f32 v[114:115], v[114:115], v[162:163] op_sel_hi:[1,0]
	v_max_f32_e32 v104, 0, v112
	v_mul_f32_e32 v106, v104, v104
	v_max_f32_e32 v104, 0, v117
	v_max_f32_e32 v116, 0, v116
	v_max_f32_e32 v107, 0, v113
	v_mul_f32_e32 v104, v104, v104
	v_pk_mul_f32 v[98:99], v[98:99], v[162:163] op_sel_hi:[1,0]
	v_pk_mul_f32 v[96:97], v[96:97], v[162:163] op_sel_hi:[1,0]
	v_mul_f32_e32 v105, v116, v116
	v_mul_f32_e32 v107, v107, v107
	v_max_f32_e32 v108, 0, v118
	v_max_f32_e32 v109, 0, v114
	v_max_f32_e32 v110, 0, v119
	v_max_f32_e32 v111, 0, v115
	v_cvt_pk_bf16_f32 v104, v105, v104
	v_pk_mul_f32 v[102:103], v[102:103], v[162:163] op_sel_hi:[1,0]
	v_pk_mul_f32 v[100:101], v[100:101], v[162:163] op_sel_hi:[1,0]
	v_max_f32_e32 v96, 0, v96
	v_max_f32_e32 v97, 0, v97
	v_max_f32_e32 v98, 0, v98
	v_mul_f32_e32 v108, v108, v108
	v_mul_f32_e32 v109, v109, v109
	v_mul_f32_e32 v110, v110, v110
	v_mul_f32_e32 v111, v111, v111
	v_cvt_pk_bf16_f32 v105, v108, v110
	v_cvt_pk_bf16_f32 v106, v106, v107
	v_cvt_pk_bf16_f32 v107, v109, v111
	global_store_dwordx4 v[156:157], v[104:107], off nt
	v_max_f32_e32 v100, 0, v100
	v_max_f32_e32 v99, 0, v99
	v_mul_f32_e32 v104, v96, v96
	v_max_f32_e32 v96, 0, v101
	v_mul_f32_e32 v101, v97, v97
	v_max_f32_e32 v97, 0, v102
	v_mul_f32_e32 v102, v98, v98
	v_max_f32_e32 v98, 0, v103
	v_mul_f32_e32 v96, v96, v96
	v_mul_f32_e32 v97, v97, v97
	v_mul_f32_e32 v98, v98, v98
	v_mul_f32_e32 v100, v100, v100
	v_mul_f32_e32 v99, v99, v99
	v_cvt_pk_bf16_f32 v96, v100, v96
	v_cvt_pk_bf16_f32 v97, v97, v98
	v_cvt_pk_bf16_f32 v98, v104, v101
	v_cvt_pk_bf16_f32 v99, v102, v99
	global_store_dwordx4 v[156:157], v[96:99], off offset:256 nt
	v_cmp_gt_f32_e32 vcc, s57, v159
	s_mov_b64 s[0:1], 0x100000
	v_mul_f32_e32 v98, 0x4b800000, v159
	v_cndmask_b32_e32 v98, v159, v98, vcc
	v_rsq_f32_e32 v98, v98
	v_or_b32_e32 v96, 32, v146
	v_ashrrev_i32_e32 v97, 31, v96
	v_lshlrev_b64 v[96:97], 13, v[96:97]
	v_mul_f32_e32 v99, 0x45800000, v98
	v_cndmask_b32_e32 v98, v98, v99, vcc
	v_pk_mul_f32 v[88:89], v[88:89], v[98:99] op_sel_hi:[1,0]
	v_pk_mul_f32 v[92:93], v[92:93], v[98:99] op_sel_hi:[1,0]
	v_pk_mul_f32 v[90:91], v[90:91], v[98:99] op_sel_hi:[1,0]
	v_max_f32_e32 v88, 0, v88
	v_pk_mul_f32 v[94:95], v[94:95], v[98:99] op_sel_hi:[1,0]
	v_mul_f32_e32 v99, v88, v88
	v_max_f32_e32 v88, 0, v93
	v_max_f32_e32 v89, 0, v89
	v_max_f32_e32 v90, 0, v90
	v_lshl_add_u64 v[96:97], s[92:93], 0, v[96:97]
	v_max_f32_e32 v92, 0, v92
	v_mul_f32_e32 v88, v88, v88
	v_mul_f32_e32 v93, v89, v89
	v_max_f32_e32 v89, 0, v94
	v_mul_f32_e32 v94, v90, v90
	v_max_f32_e32 v90, 0, v95
	v_max_f32_e32 v91, 0, v91
	v_pk_mul_f32 v[82:83], v[82:83], v[98:99] op_sel_hi:[1,0]
	v_pk_mul_f32 v[80:81], v[80:81], v[98:99] op_sel_hi:[1,0]
	v_lshl_add_u64 v[96:97], v[96:97], 0, v[160:161]
	v_mul_f32_e32 v92, v92, v92
	v_mul_f32_e32 v89, v89, v89
	v_mul_f32_e32 v90, v90, v90
	v_mul_f32_e32 v91, v91, v91
	v_cvt_pk_bf16_f32 v88, v92, v88
	v_pk_mul_f32 v[86:87], v[86:87], v[98:99] op_sel_hi:[1,0]
	v_pk_mul_f32 v[84:85], v[84:85], v[98:99] op_sel_hi:[1,0]
	v_max_f32_e32 v80, 0, v80
	v_max_f32_e32 v81, 0, v81
	v_max_f32_e32 v82, 0, v82
	v_cvt_pk_bf16_f32 v89, v89, v90
	v_cvt_pk_bf16_f32 v90, v99, v93
	v_cvt_pk_bf16_f32 v91, v94, v91
	global_store_dwordx4 v[96:97], v[88:91], off nt
	v_max_f32_e32 v84, 0, v84
	v_max_f32_e32 v83, 0, v83
	v_mul_f32_e32 v88, v80, v80
	v_max_f32_e32 v80, 0, v85
	v_mul_f32_e32 v85, v81, v81
	v_max_f32_e32 v81, 0, v86
	v_mul_f32_e32 v86, v82, v82
	v_max_f32_e32 v82, 0, v87
	v_mul_f32_e32 v80, v80, v80
	v_mul_f32_e32 v81, v81, v81
	v_mul_f32_e32 v82, v82, v82
	v_mul_f32_e32 v84, v84, v84
	v_mul_f32_e32 v83, v83, v83
	v_cvt_pk_bf16_f32 v80, v84, v80
	v_cvt_pk_bf16_f32 v81, v81, v82
	v_cvt_pk_bf16_f32 v82, v88, v85
	v_cvt_pk_bf16_f32 v83, v86, v83
	global_store_dwordx4 v[96:97], v[80:83], off offset:256 nt
	v_cmp_gt_f32_e32 vcc, s57, v163
	s_nop 0
	v_mul_f32_e32 v82, 0x4b800000, v163
	v_cndmask_b32_e32 v82, v163, v82, vcc
	v_rsq_f32_e32 v82, v82
	v_or_b32_e32 v80, 48, v146
	v_ashrrev_i32_e32 v81, 31, v80
	v_lshlrev_b64 v[80:81], 13, v[80:81]
	v_mul_f32_e32 v83, 0x45800000, v82
	v_cndmask_b32_e32 v82, v82, v83, vcc
	v_pk_mul_f32 v[72:73], v[72:73], v[82:83] op_sel_hi:[1,0]
	v_pk_mul_f32 v[76:77], v[76:77], v[82:83] op_sel_hi:[1,0]
	v_pk_mul_f32 v[74:75], v[74:75], v[82:83] op_sel_hi:[1,0]
	v_max_f32_e32 v72, 0, v72
	v_pk_mul_f32 v[78:79], v[78:79], v[82:83] op_sel_hi:[1,0]
	v_mul_f32_e32 v83, v72, v72
	v_max_f32_e32 v72, 0, v77
	v_max_f32_e32 v73, 0, v73
	v_max_f32_e32 v74, 0, v74
	v_lshl_add_u64 v[80:81], s[92:93], 0, v[80:81]
	v_max_f32_e32 v76, 0, v76
	v_mul_f32_e32 v72, v72, v72
	v_mul_f32_e32 v77, v73, v73
	v_max_f32_e32 v73, 0, v78
	v_mul_f32_e32 v78, v74, v74
	v_max_f32_e32 v74, 0, v79
	v_max_f32_e32 v75, 0, v75
	v_pk_mul_f32 v[64:65], v[64:65], v[82:83] op_sel_hi:[1,0]
	v_lshl_add_u64 v[80:81], v[80:81], 0, v[160:161]
	v_mul_f32_e32 v76, v76, v76
	v_mul_f32_e32 v73, v73, v73
	v_mul_f32_e32 v74, v74, v74
	v_mul_f32_e32 v75, v75, v75
	v_cvt_pk_bf16_f32 v72, v76, v72
	v_pk_mul_f32 v[68:69], v[68:69], v[82:83] op_sel_hi:[1,0]
	v_max_f32_e32 v64, 0, v64
	v_cvt_pk_bf16_f32 v73, v73, v74
	v_cvt_pk_bf16_f32 v74, v83, v77
	v_cvt_pk_bf16_f32 v75, v78, v75
	global_store_dwordx4 v[80:81], v[72:75], off nt
	v_max_f32_e32 v68, 0, v68
	v_mul_f32_e32 v68, v68, v68
	v_mul_f32_e32 v72, v64, v64
	v_max_f32_e32 v64, 0, v69
	v_mul_f32_e32 v64, v64, v64
	v_cvt_pk_bf16_f32 v64, v68, v64
	v_mul_f32_e32 v68, 0x4b800000, v164
	v_cmp_gt_f32_e32 vcc, s57, v164
	v_pk_mul_f32 v[66:67], v[66:67], v[82:83] op_sel_hi:[1,0]
	v_pk_mul_f32 v[70:71], v[70:71], v[82:83] op_sel_hi:[1,0]
	v_cndmask_b32_e32 v68, v164, v68, vcc
	v_max_f32_e32 v65, 0, v65
	v_max_f32_e32 v66, 0, v66
	v_rsq_f32_e32 v68, v68
	v_mul_f32_e32 v69, v65, v65
	v_max_f32_e32 v65, 0, v70
	v_mul_f32_e32 v70, v66, v66
	v_max_f32_e32 v66, 0, v71
	v_mul_f32_e32 v65, v65, v65
	v_max_f32_e32 v67, 0, v67
	v_mul_f32_e32 v66, v66, v66
	v_mul_f32_e32 v67, v67, v67
	v_cvt_pk_bf16_f32 v65, v65, v66
	v_cvt_pk_bf16_f32 v66, v72, v69
	v_cvt_pk_bf16_f32 v67, v70, v67
	global_store_dwordx4 v[80:81], v[64:67], off offset:256 nt
	s_nop 1
	v_mul_f32_e32 v66, 0x45800000, v68
	v_cndmask_b32_e32 v66, v68, v66, vcc
	v_pk_mul_f32 v[56:57], v[56:57], v[66:67] op_sel_hi:[1,0]
	v_pk_mul_f32 v[60:61], v[60:61], v[66:67] op_sel_hi:[1,0]
	v_pk_mul_f32 v[58:59], v[58:59], v[66:67] op_sel_hi:[1,0]
	v_max_f32_e32 v56, 0, v56
	v_pk_mul_f32 v[62:63], v[62:63], v[66:67] op_sel_hi:[1,0]
	v_max_f32_e32 v60, 0, v60
	v_mul_f32_e32 v67, v56, v56
	v_max_f32_e32 v56, 0, v61
	v_max_f32_e32 v57, 0, v57
	v_max_f32_e32 v58, 0, v58
	v_mul_f32_e32 v60, v60, v60
	v_mul_f32_e32 v56, v56, v56
	v_mul_f32_e32 v61, v57, v57
	v_max_f32_e32 v57, 0, v62
	v_mul_f32_e32 v62, v58, v58
	v_max_f32_e32 v58, 0, v63
	v_mul_f32_e32 v57, v57, v57
	v_max_f32_e32 v59, 0, v59
	v_mul_f32_e32 v58, v58, v58
	v_cvt_pk_bf16_f32 v56, v60, v56
	v_add_co_u32_e32 v60, vcc, s58, v144
	v_pk_mul_f32 v[48:49], v[48:49], v[66:67] op_sel_hi:[1,0]
	v_mul_f32_e32 v59, v59, v59
	v_cvt_pk_bf16_f32 v57, v57, v58
	v_cvt_pk_bf16_f32 v58, v67, v61
	v_addc_co_u32_e32 v61, vcc, 0, v145, vcc
	v_pk_mul_f32 v[52:53], v[52:53], v[66:67] op_sel_hi:[1,0]
	v_max_f32_e32 v48, 0, v48
	v_cvt_pk_bf16_f32 v59, v62, v59
	global_store_dwordx4 v[60:61], v[56:59], off nt
	v_max_f32_e32 v52, 0, v52
	v_mul_f32_e32 v52, v52, v52
	v_mul_f32_e32 v56, v48, v48
	v_max_f32_e32 v48, 0, v53
	v_mul_f32_e32 v48, v48, v48
	v_cvt_pk_bf16_f32 v48, v52, v48
	v_mul_f32_e32 v52, 0x4b800000, v165
	v_cmp_gt_f32_e32 vcc, s57, v165
	v_pk_mul_f32 v[50:51], v[50:51], v[66:67] op_sel_hi:[1,0]
	v_pk_mul_f32 v[54:55], v[54:55], v[66:67] op_sel_hi:[1,0]
	v_cndmask_b32_e32 v52, v165, v52, vcc
	v_max_f32_e32 v49, 0, v49
	v_max_f32_e32 v50, 0, v50
	v_rsq_f32_e32 v52, v52
	v_mul_f32_e32 v53, v49, v49
	v_max_f32_e32 v49, 0, v54
	v_mul_f32_e32 v54, v50, v50
	v_max_f32_e32 v50, 0, v55
	v_mul_f32_e32 v49, v49, v49
	v_max_f32_e32 v51, 0, v51
	v_mul_f32_e32 v50, v50, v50
	v_lshl_add_u64 v[64:65], v[144:145], 0, s[0:1]
	v_mul_f32_e32 v51, v51, v51
	v_cvt_pk_bf16_f32 v49, v49, v50
	v_cvt_pk_bf16_f32 v50, v56, v53
	v_cvt_pk_bf16_f32 v51, v54, v51
	global_store_dwordx4 v[64:65], v[48:51], off offset:256 nt
	s_mov_b32 s1, s24
	s_mov_b32 s0, s26
	v_mul_f32_e32 v50, 0x45800000, v52
	v_cndmask_b32_e32 v50, v52, v50, vcc
	v_pk_mul_f32 v[40:41], v[40:41], v[50:51] op_sel_hi:[1,0]
	v_pk_mul_f32 v[44:45], v[44:45], v[50:51] op_sel_hi:[1,0]
	v_pk_mul_f32 v[42:43], v[42:43], v[50:51] op_sel_hi:[1,0]
	v_max_f32_e32 v40, 0, v40
	v_pk_mul_f32 v[46:47], v[46:47], v[50:51] op_sel_hi:[1,0]
	v_max_f32_e32 v44, 0, v44
	v_mul_f32_e32 v51, v40, v40
	v_max_f32_e32 v40, 0, v45
	v_max_f32_e32 v41, 0, v41
	v_max_f32_e32 v42, 0, v42
	v_mul_f32_e32 v44, v44, v44
	v_mul_f32_e32 v40, v40, v40
	v_mul_f32_e32 v45, v41, v41
	v_max_f32_e32 v41, 0, v46
	v_mul_f32_e32 v46, v42, v42
	v_max_f32_e32 v42, 0, v47
	v_mul_f32_e32 v41, v41, v41
	v_max_f32_e32 v43, 0, v43
	v_mul_f32_e32 v42, v42, v42
	v_cvt_pk_bf16_f32 v40, v44, v40
	v_add_co_u32_e32 v44, vcc, s59, v144
	v_pk_mul_f32 v[32:33], v[32:33], v[50:51] op_sel_hi:[1,0]
	v_mul_f32_e32 v43, v43, v43
	v_cvt_pk_bf16_f32 v41, v41, v42
	v_cvt_pk_bf16_f32 v42, v51, v45
	v_addc_co_u32_e32 v45, vcc, 0, v145, vcc
	v_pk_mul_f32 v[36:37], v[36:37], v[50:51] op_sel_hi:[1,0]
	v_max_f32_e32 v32, 0, v32
	v_cvt_pk_bf16_f32 v43, v46, v43
	global_store_dwordx4 v[44:45], v[40:43], off nt
	v_max_f32_e32 v36, 0, v36
	v_mul_f32_e32 v36, v36, v36
	v_mul_f32_e32 v40, v32, v32
	v_max_f32_e32 v32, 0, v37
	v_mul_f32_e32 v32, v32, v32
	v_cvt_pk_bf16_f32 v32, v36, v32
	v_mul_f32_e32 v36, 0x4b800000, v166
	v_cmp_gt_f32_e32 vcc, s57, v166
	v_pk_mul_f32 v[34:35], v[34:35], v[50:51] op_sel_hi:[1,0]
	v_pk_mul_f32 v[38:39], v[38:39], v[50:51] op_sel_hi:[1,0]
	v_cndmask_b32_e32 v36, v166, v36, vcc
	v_max_f32_e32 v33, 0, v33
	v_max_f32_e32 v34, 0, v34
	v_rsq_f32_e32 v36, v36
	v_mul_f32_e32 v37, v33, v33
	v_max_f32_e32 v33, 0, v38
	v_mul_f32_e32 v38, v34, v34
	v_max_f32_e32 v34, 0, v39
	v_mul_f32_e32 v33, v33, v33
	v_max_f32_e32 v35, 0, v35
	v_mul_f32_e32 v34, v34, v34
	v_lshl_add_u64 v[48:49], v[144:145], 0, s[18:19]
	v_mul_f32_e32 v35, v35, v35
	v_cvt_pk_bf16_f32 v33, v33, v34
	v_cvt_pk_bf16_f32 v34, v40, v37
	v_cvt_pk_bf16_f32 v35, v38, v35
	global_store_dwordx4 v[48:49], v[32:35], off offset:256 nt
	s_nop 1
	v_mul_f32_e32 v34, 0x45800000, v36
	v_cndmask_b32_e32 v34, v36, v34, vcc
	v_pk_mul_f32 v[24:25], v[24:25], v[34:35] op_sel_hi:[1,0]
	v_pk_mul_f32 v[28:29], v[28:29], v[34:35] op_sel_hi:[1,0]
	v_pk_mul_f32 v[26:27], v[26:27], v[34:35] op_sel_hi:[1,0]
	v_max_f32_e32 v24, 0, v24
	v_pk_mul_f32 v[30:31], v[30:31], v[34:35] op_sel_hi:[1,0]
	v_max_f32_e32 v28, 0, v28
	v_mul_f32_e32 v35, v24, v24
	v_max_f32_e32 v24, 0, v29
	v_max_f32_e32 v25, 0, v25
	v_max_f32_e32 v26, 0, v26
	v_mul_f32_e32 v28, v28, v28
	v_mul_f32_e32 v24, v24, v24
	v_mul_f32_e32 v29, v25, v25
	v_max_f32_e32 v25, 0, v30
	v_mul_f32_e32 v30, v26, v26
	v_max_f32_e32 v26, 0, v31
	v_mul_f32_e32 v25, v25, v25
	v_max_f32_e32 v27, 0, v27
	v_mul_f32_e32 v26, v26, v26
	v_cvt_pk_bf16_f32 v24, v28, v24
	v_add_co_u32_e32 v28, vcc, s60, v144
	v_pk_mul_f32 v[16:17], v[16:17], v[34:35] op_sel_hi:[1,0]
	v_mul_f32_e32 v27, v27, v27
	v_cvt_pk_bf16_f32 v25, v25, v26
	v_cvt_pk_bf16_f32 v26, v35, v29
	v_addc_co_u32_e32 v29, vcc, 0, v145, vcc
	v_pk_mul_f32 v[20:21], v[20:21], v[34:35] op_sel_hi:[1,0]
	v_max_f32_e32 v16, 0, v16
	v_cvt_pk_bf16_f32 v27, v30, v27
	global_store_dwordx4 v[28:29], v[24:27], off nt
	v_max_f32_e32 v20, 0, v20
	v_mul_f32_e32 v20, v20, v20
	v_mul_f32_e32 v24, v16, v16
	v_max_f32_e32 v16, 0, v21
	v_mul_f32_e32 v16, v16, v16
	v_cvt_pk_bf16_f32 v16, v20, v16
	v_mul_f32_e32 v20, 0x4b800000, v147
	v_cmp_gt_f32_e32 vcc, s57, v147
	v_pk_mul_f32 v[18:19], v[18:19], v[34:35] op_sel_hi:[1,0]
	v_pk_mul_f32 v[22:23], v[22:23], v[34:35] op_sel_hi:[1,0]
	v_cndmask_b32_e32 v20, v147, v20, vcc
	v_max_f32_e32 v17, 0, v17
	v_max_f32_e32 v18, 0, v18
	v_rsq_f32_e32 v20, v20
	v_mul_f32_e32 v21, v17, v17
	v_max_f32_e32 v17, 0, v22
	v_mul_f32_e32 v22, v18, v18
	v_max_f32_e32 v18, 0, v23
	v_mul_f32_e32 v17, v17, v17
	v_max_f32_e32 v19, 0, v19
	v_mul_f32_e32 v18, v18, v18
	v_lshl_add_u64 v[32:33], v[144:145], 0, s[20:21]
	v_mul_f32_e32 v19, v19, v19
	v_cvt_pk_bf16_f32 v17, v17, v18
	v_cvt_pk_bf16_f32 v18, v24, v21
	v_cvt_pk_bf16_f32 v19, v22, v19
	global_store_dwordx4 v[32:33], v[16:19], off offset:256 nt
	s_nop 1
	v_mul_f32_e32 v18, 0x45800000, v20
	v_cndmask_b32_e32 v18, v20, v18, vcc
	v_pk_mul_f32 v[8:9], v[8:9], v[18:19] op_sel_hi:[1,0]
	v_pk_mul_f32 v[12:13], v[12:13], v[18:19] op_sel_hi:[1,0]
	v_pk_mul_f32 v[10:11], v[10:11], v[18:19] op_sel_hi:[1,0]
	v_max_f32_e32 v8, 0, v8
	v_pk_mul_f32 v[14:15], v[14:15], v[18:19] op_sel_hi:[1,0]
	v_max_f32_e32 v12, 0, v12
	v_mul_f32_e32 v19, v8, v8
	v_max_f32_e32 v8, 0, v13
	v_max_f32_e32 v9, 0, v9
	v_max_f32_e32 v10, 0, v10
	v_mul_f32_e32 v12, v12, v12
	v_mul_f32_e32 v8, v8, v8
	v_mul_f32_e32 v13, v9, v9
	v_max_f32_e32 v9, 0, v14
	v_mul_f32_e32 v14, v10, v10
	v_max_f32_e32 v10, 0, v15
	v_mul_f32_e32 v9, v9, v9
	v_max_f32_e32 v11, 0, v11
	v_mul_f32_e32 v10, v10, v10
	v_cvt_pk_bf16_f32 v8, v12, v8
	v_add_co_u32_e32 v12, vcc, s61, v144
	v_pk_mul_f32 v[2:3], v[2:3], v[18:19] op_sel_hi:[1,0]
	v_pk_mul_f32 v[0:1], v[0:1], v[18:19] op_sel_hi:[1,0]
	v_mul_f32_e32 v11, v11, v11
	v_cvt_pk_bf16_f32 v9, v9, v10
	v_cvt_pk_bf16_f32 v10, v19, v13
	v_addc_co_u32_e32 v13, vcc, 0, v145, vcc
	v_pk_mul_f32 v[6:7], v[6:7], v[18:19] op_sel_hi:[1,0]
	v_pk_mul_f32 v[4:5], v[4:5], v[18:19] op_sel_hi:[1,0]
	v_max_f32_e32 v0, 0, v0
	v_max_f32_e32 v1, 0, v1
	v_max_f32_e32 v2, 0, v2
	v_cvt_pk_bf16_f32 v11, v14, v11
	global_store_dwordx4 v[12:13], v[8:11], off nt
	v_max_f32_e32 v3, 0, v3
	v_lshl_add_u64 v[16:17], v[144:145], 0, s[22:23]
	v_mul_f32_e32 v8, v0, v0
	v_max_f32_e32 v0, 0, v5
	v_mul_f32_e32 v5, v1, v1
	v_max_f32_e32 v1, 0, v6
	v_mul_f32_e32 v6, v2, v2
	v_max_f32_e32 v2, 0, v7
	v_max_f32_e32 v4, 0, v4
	v_mul_f32_e32 v0, v0, v0
	v_mul_f32_e32 v1, v1, v1
	v_mul_f32_e32 v2, v2, v2
	v_mul_f32_e32 v3, v3, v3
	s_and_b64 vcc, exec, s[6:7]
	v_mul_f32_e32 v4, v4, v4
	v_cvt_pk_bf16_f32 v0, v4, v0
	v_cvt_pk_bf16_f32 v1, v1, v2
	v_cvt_pk_bf16_f32 v2, v8, v5
	v_cvt_pk_bf16_f32 v3, v6, v3
	global_store_dwordx4 v[16:17], v[0:3], off offset:256 nt
	s_cbranch_vccz .LBB0_843
	s_waitcnt vmcnt(0)
	s_cmpk_gt_u32 s33, 0xff
	s_cbranch_scc1 .LBB0_854
	s_barrier

.LBB0_896:
	ds_read_b128 v[144:147], v178
	ds_read_b128 v[148:151], v178 offset:1024
	ds_read_b128 v[152:155], v178 offset:2048
	ds_read_b128 v[156:159], v178 offset:3072
	s_add_u32 s42, s40, 0xfff00080
	s_addc_u32 s43, s41, -1
	s_cmp_eq_u32 s65, 60
	s_cselect_b32 s49, s29, s43
	s_cselect_b32 s48, s37, s42
	s_cselect_b32 s43, s27, s64
	s_cselect_b32 s42, s62, s63
	v_lshl_add_u64 v[172:173], s[40:41], 0, v[136:137]
	s_add_i32 m0, s39, 0xc000
	ds_read_b128 v[160:163], v179
	ds_read_b128 v[164:167], v179 offset:1024
	ds_read_b128 v[168:171], v179 offset:2048
	ds_read_b128 v[182:185], v179 offset:3072
	ds_read_b128 v[186:189], v179 offset:4096
	ds_read_b128 v[190:193], v179 offset:5120
	ds_read_b128 v[194:197], v179 offset:6144
	ds_read_b128 v[198:201], v179 offset:7168
	global_load_lds_dwordx4 v[172:173], off
	v_lshl_add_u64 v[172:173], s[40:41], 0, v[138:139]
	s_add_i32 m0, s39, 0xe000
	s_nop 0
	global_load_lds_dwordx4 v[172:173], off
	s_waitcnt lgkmcnt(8)
	s_setprio 1
	s_barrier
	s_waitcnt lgkmcnt(0)
	v_mfma_f32_16x16x32_bf16 v[124:127], v[144:147], v[160:163], v[124:127]
	v_mfma_f32_16x16x32_bf16 v[120:123], v[152:155], v[160:163], v[120:123]
	v_mfma_f32_16x16x32_bf16 v[108:111], v[144:147], v[168:171], v[108:111]
	v_mfma_f32_16x16x32_bf16 v[104:107], v[152:155], v[168:171], v[104:107]
	v_mfma_f32_16x16x32_bf16 v[96:99], v[144:147], v[186:189], v[96:99]
	v_mfma_f32_16x16x32_bf16 v[88:91], v[152:155], v[186:189], v[88:91]
	v_mfma_f32_16x16x32_bf16 v[80:83], v[144:147], v[194:197], v[80:83]
	v_mfma_f32_16x16x32_bf16 v[72:75], v[152:155], v[194:197], v[72:75]
	v_mfma_f32_16x16x32_bf16 v[124:127], v[148:151], v[164:167], v[124:127]
	v_mfma_f32_16x16x32_bf16 v[120:123], v[156:159], v[164:167], v[120:123]
	v_mfma_f32_16x16x32_bf16 v[108:111], v[148:151], v[182:185], v[108:111]
	v_mfma_f32_16x16x32_bf16 v[104:107], v[156:159], v[182:185], v[104:107]
	v_mfma_f32_16x16x32_bf16 v[96:99], v[148:151], v[190:193], v[96:99]
	v_mfma_f32_16x16x32_bf16 v[88:91], v[156:159], v[190:193], v[88:91]
	v_mfma_f32_16x16x32_bf16 v[80:83], v[148:151], v[198:201], v[80:83]
	v_mfma_f32_16x16x32_bf16 v[72:75], v[156:159], v[198:201], v[72:75]
	s_setprio 0
	s_barrier
	s_add_i32 s66, s60, s50
	v_lshl_add_u64 v[172:173], s[42:43], 0, v[130:131]
	s_mov_b32 m0, s66
	ds_read_b128 v[202:205], v180
	ds_read_b128 v[206:209], v180 offset:1024
	ds_read_b128 v[212:215], v180 offset:2048
	ds_read_b128 v[216:219], v180 offset:3072
	global_load_lds_dwordx4 v[172:173], off
	v_lshl_add_u64 v[220:221], s[42:43], 0, v[134:135]
	s_add_i32 m0, s66, 0x2000
	s_nop 0
	global_load_lds_dwordx4 v[220:221], off
	s_setprio 1
	s_barrier
	s_waitcnt lgkmcnt(0)
	v_mfma_f32_16x16x32_bf16 v[116:119], v[202:205], v[160:163], v[116:119]
	v_mfma_f32_16x16x32_bf16 v[112:115], v[212:215], v[160:163], v[112:115]
	v_mfma_f32_16x16x32_bf16 v[100:103], v[202:205], v[168:171], v[100:103]
	v_mfma_f32_16x16x32_bf16 v[92:95], v[212:215], v[168:171], v[92:95]
	v_mfma_f32_16x16x32_bf16 v[84:87], v[202:205], v[186:189], v[84:87]
	v_mfma_f32_16x16x32_bf16 v[76:79], v[212:215], v[186:189], v[76:79]
	v_mfma_f32_16x16x32_bf16 v[68:71], v[202:205], v[194:197], v[68:71]
	v_mfma_f32_16x16x32_bf16 v[64:67], v[212:215], v[194:197], v[64:67]
	v_mfma_f32_16x16x32_bf16 v[116:119], v[206:209], v[164:167], v[116:119]
	v_mfma_f32_16x16x32_bf16 v[112:115], v[216:219], v[164:167], v[112:115]
	v_mfma_f32_16x16x32_bf16 v[100:103], v[206:209], v[182:185], v[100:103]
	v_mfma_f32_16x16x32_bf16 v[92:95], v[216:219], v[182:185], v[92:95]
	v_mfma_f32_16x16x32_bf16 v[84:87], v[206:209], v[190:193], v[84:87]
	v_mfma_f32_16x16x32_bf16 v[76:79], v[216:219], v[190:193], v[76:79]
	v_mfma_f32_16x16x32_bf16 v[68:71], v[206:209], v[198:201], v[68:71]
	v_mfma_f32_16x16x32_bf16 v[64:67], v[216:219], v[198:201], v[64:67]
	s_setprio 0
	s_mov_b32 m0, s39
	v_lshl_add_u64 v[222:223], s[48:49], 0, v[128:129]
	s_barrier
	ds_read_b128 v[160:163], v179 offset:16384
	ds_read_b128 v[164:167], v179 offset:17408
	ds_read_b128 v[168:171], v179 offset:18432
	ds_read_b128 v[182:185], v179 offset:19456
	ds_read_b128 v[186:189], v179 offset:20480
	ds_read_b128 v[190:193], v179 offset:21504
	ds_read_b128 v[194:197], v179 offset:22528
	ds_read_b128 v[198:201], v179 offset:23552
	global_load_lds_dwordx4 v[222:223], off
	v_lshl_add_u64 v[224:225], s[48:49], 0, v[132:133]
	s_mov_b32 m0, s51
	s_nop 0
	global_load_lds_dwordx4 v[224:225], off
	s_setprio 1
	s_barrier
	s_waitcnt lgkmcnt(0)
	v_mfma_f32_16x16x32_bf16 v[60:63], v[144:147], v[160:163], v[60:63]
	v_mfma_f32_16x16x32_bf16 v[56:59], v[152:155], v[160:163], v[56:59]
	v_mfma_f32_16x16x32_bf16 v[44:47], v[144:147], v[168:171], v[44:47]
	v_mfma_f32_16x16x32_bf16 v[40:43], v[152:155], v[168:171], v[40:43]
	v_mfma_f32_16x16x32_bf16 v[32:35], v[144:147], v[186:189], v[32:35]
	v_mfma_f32_16x16x32_bf16 v[24:27], v[152:155], v[186:189], v[24:27]
	v_mfma_f32_16x16x32_bf16 v[16:19], v[144:147], v[194:197], v[16:19]
	v_mfma_f32_16x16x32_bf16 v[8:11], v[152:155], v[194:197], v[8:11]
	v_mfma_f32_16x16x32_bf16 v[60:63], v[148:151], v[164:167], v[60:63]
	v_mfma_f32_16x16x32_bf16 v[56:59], v[156:159], v[164:167], v[56:59]
	v_mfma_f32_16x16x32_bf16 v[44:47], v[148:151], v[182:185], v[44:47]
	v_mfma_f32_16x16x32_bf16 v[40:43], v[156:159], v[182:185], v[40:43]
	v_mfma_f32_16x16x32_bf16 v[32:35], v[148:151], v[190:193], v[32:35]
	v_mfma_f32_16x16x32_bf16 v[24:27], v[156:159], v[190:193], v[24:27]
	v_mfma_f32_16x16x32_bf16 v[16:19], v[148:151], v[198:201], v[16:19]
	v_mfma_f32_16x16x32_bf16 v[8:11], v[156:159], v[198:201], v[8:11]
	s_setprio 0
	s_barrier
	s_add_u32 s66, s42, 0x100000
	s_addc_u32 s67, s43, 0
	s_add_i32 s68, s61, s50
	v_lshl_add_u64 v[144:145], s[66:67], 0, v[130:131]
	s_mov_b32 m0, s68
	s_nop 0
	global_load_lds_dwordx4 v[144:145], off
	v_lshl_add_u64 v[144:145], s[66:67], 0, v[134:135]
	s_add_i32 m0, s68, 0x2000
	s_nop 0
	global_load_lds_dwordx4 v[144:145], off
	s_waitcnt vmcnt(6)
	s_setprio 1
	s_barrier
	v_mfma_f32_16x16x32_bf16 v[52:55], v[202:205], v[160:163], v[52:55]
	v_mfma_f32_16x16x32_bf16 v[48:51], v[212:215], v[160:163], v[48:51]
	v_mfma_f32_16x16x32_bf16 v[36:39], v[202:205], v[168:171], v[36:39]
	v_mfma_f32_16x16x32_bf16 v[28:31], v[212:215], v[168:171], v[28:31]
	v_mfma_f32_16x16x32_bf16 v[20:23], v[202:205], v[186:189], v[20:23]
	v_mfma_f32_16x16x32_bf16 v[12:15], v[212:215], v[186:189], v[12:15]
	v_mfma_f32_16x16x32_bf16 v[4:7], v[202:205], v[194:197], v[4:7]
	v_mfma_f32_16x16x32_bf16 v[0:3], v[212:215], v[194:197], v[0:3]
	v_mfma_f32_16x16x32_bf16 v[52:55], v[206:209], v[164:167], v[52:55]
	v_mfma_f32_16x16x32_bf16 v[48:51], v[216:219], v[164:167], v[48:51]
	v_mfma_f32_16x16x32_bf16 v[36:39], v[206:209], v[182:185], v[36:39]
	v_mfma_f32_16x16x32_bf16 v[28:31], v[216:219], v[182:185], v[28:31]
	v_mfma_f32_16x16x32_bf16 v[20:23], v[206:209], v[190:193], v[20:23]
	v_mfma_f32_16x16x32_bf16 v[12:15], v[216:219], v[190:193], v[12:15]
	v_mfma_f32_16x16x32_bf16 v[4:7], v[206:209], v[198:201], v[4:7]
	v_mfma_f32_16x16x32_bf16 v[0:3], v[216:219], v[198:201], v[0:3]
	s_setprio 0
	s_add_i32 s66, 0, 0x18000
	v_add_u32_e32 v156, s66, v176
	s_barrier
	ds_read_b128 v[144:147], v156
	ds_read_b128 v[148:151], v156 offset:1024
	ds_read_b128 v[152:155], v156 offset:2048
	ds_read_b128 v[156:159], v156 offset:3072
	s_add_u32 s48, s48, 0x100000
	s_addc_u32 s49, s49, 0
	s_mov_b32 m0, s52
	v_lshl_add_u64 v[202:203], s[48:49], 0, v[128:129]
	ds_read_b128 v[160:163], v179 offset:32768
	ds_read_b128 v[164:167], v179 offset:33792
	ds_read_b128 v[168:171], v179 offset:34816
	ds_read_b128 v[182:185], v179 offset:35840
	ds_read_b128 v[186:189], v179 offset:36864
	ds_read_b128 v[190:193], v179 offset:37888
	ds_read_b128 v[194:197], v179 offset:38912
	ds_read_b128 v[198:201], v179 offset:39936
	global_load_lds_dwordx4 v[202:203], off
	v_lshl_add_u64 v[202:203], s[48:49], 0, v[132:133]
	s_mov_b32 m0, s53
	s_nop 0
	global_load_lds_dwordx4 v[202:203], off
	s_waitcnt lgkmcnt(8)
	s_setprio 1
	s_barrier
	s_waitcnt lgkmcnt(0)
	v_mfma_f32_16x16x32_bf16 v[124:127], v[144:147], v[160:163], v[124:127]
	v_mfma_f32_16x16x32_bf16 v[120:123], v[152:155], v[160:163], v[120:123]
	v_mfma_f32_16x16x32_bf16 v[108:111], v[144:147], v[168:171], v[108:111]
	v_mfma_f32_16x16x32_bf16 v[104:107], v[152:155], v[168:171], v[104:107]
	v_mfma_f32_16x16x32_bf16 v[96:99], v[144:147], v[186:189], v[96:99]
	v_mfma_f32_16x16x32_bf16 v[88:91], v[152:155], v[186:189], v[88:91]
	v_mfma_f32_16x16x32_bf16 v[80:83], v[144:147], v[194:197], v[80:83]
	v_mfma_f32_16x16x32_bf16 v[72:75], v[152:155], v[194:197], v[72:75]
	v_mfma_f32_16x16x32_bf16 v[124:127], v[148:151], v[164:167], v[124:127]
	v_mfma_f32_16x16x32_bf16 v[120:123], v[156:159], v[164:167], v[120:123]
	v_mfma_f32_16x16x32_bf16 v[108:111], v[148:151], v[182:185], v[108:111]
	v_mfma_f32_16x16x32_bf16 v[104:107], v[156:159], v[182:185], v[104:107]
	v_mfma_f32_16x16x32_bf16 v[96:99], v[148:151], v[190:193], v[96:99]
	v_mfma_f32_16x16x32_bf16 v[88:91], v[156:159], v[190:193], v[88:91]
	v_mfma_f32_16x16x32_bf16 v[80:83], v[148:151], v[198:201], v[80:83]
	v_mfma_f32_16x16x32_bf16 v[72:75], v[156:159], v[198:201], v[72:75]
	s_setprio 0
	s_barrier
	s_add_i32 s48, 0, 0x1c000
	s_add_i32 s49, s66, s50
	v_add_u32_e32 v181, s48, v176
	v_lshl_add_u64 v[172:173], v[172:173], 0, s[0:1]
	s_mov_b32 m0, s49
	ds_read_b128 v[202:205], v181
	ds_read_b128 v[206:209], v181 offset:1024
	ds_read_b128 v[212:215], v181 offset:2048
	ds_read_b128 v[216:219], v181 offset:3072
	global_load_lds_dwordx4 v[172:173], off
	v_lshl_add_u64 v[172:173], v[220:221], 0, s[0:1]
	s_add_i32 m0, s49, 0x2000
	s_nop 0
	global_load_lds_dwordx4 v[172:173], off
	s_setprio 1
	s_barrier
	s_waitcnt lgkmcnt(0)
	v_mfma_f32_16x16x32_bf16 v[116:119], v[202:205], v[160:163], v[116:119]
	v_mfma_f32_16x16x32_bf16 v[112:115], v[212:215], v[160:163], v[112:115]
	v_mfma_f32_16x16x32_bf16 v[100:103], v[202:205], v[168:171], v[100:103]
	v_mfma_f32_16x16x32_bf16 v[92:95], v[212:215], v[168:171], v[92:95]
	v_mfma_f32_16x16x32_bf16 v[84:87], v[202:205], v[186:189], v[84:87]
	v_mfma_f32_16x16x32_bf16 v[76:79], v[212:215], v[186:189], v[76:79]
	v_mfma_f32_16x16x32_bf16 v[68:71], v[202:205], v[194:197], v[68:71]
	v_mfma_f32_16x16x32_bf16 v[64:67], v[212:215], v[194:197], v[64:67]
	v_mfma_f32_16x16x32_bf16 v[116:119], v[206:209], v[164:167], v[116:119]
	v_mfma_f32_16x16x32_bf16 v[112:115], v[216:219], v[164:167], v[112:115]
	v_mfma_f32_16x16x32_bf16 v[100:103], v[206:209], v[182:185], v[100:103]
	v_mfma_f32_16x16x32_bf16 v[92:95], v[216:219], v[182:185], v[92:95]
	v_mfma_f32_16x16x32_bf16 v[84:87], v[206:209], v[190:193], v[84:87]
	v_mfma_f32_16x16x32_bf16 v[76:79], v[216:219], v[190:193], v[76:79]
	v_mfma_f32_16x16x32_bf16 v[68:71], v[206:209], v[198:201], v[68:71]
	v_mfma_f32_16x16x32_bf16 v[64:67], v[216:219], v[198:201], v[64:67]
	s_setprio 0
	s_mov_b32 m0, s55
	v_lshl_add_u64 v[172:173], v[222:223], 0, s[0:1]
	s_barrier
	ds_read_b128 v[160:163], v179 offset:49152
	ds_read_b128 v[164:167], v179 offset:50176
	ds_read_b128 v[168:171], v179 offset:51200
	ds_read_b128 v[182:185], v179 offset:52224
	ds_read_b128 v[186:189], v179 offset:53248
	ds_read_b128 v[190:193], v179 offset:54272
	ds_read_b128 v[194:197], v179 offset:55296
	ds_read_b128 v[198:201], v179 offset:56320
	global_load_lds_dwordx4 v[172:173], off
	v_lshl_add_u64 v[172:173], v[224:225], 0, s[0:1]
	s_mov_b32 m0, s56
	s_nop 0
	global_load_lds_dwordx4 v[172:173], off
	s_setprio 1
	s_barrier
	s_waitcnt lgkmcnt(0)
	v_mfma_f32_16x16x32_bf16 v[60:63], v[144:147], v[160:163], v[60:63]
	v_mfma_f32_16x16x32_bf16 v[56:59], v[152:155], v[160:163], v[56:59]
	v_mfma_f32_16x16x32_bf16 v[44:47], v[144:147], v[168:171], v[44:47]
	v_mfma_f32_16x16x32_bf16 v[40:43], v[152:155], v[168:171], v[40:43]
	v_mfma_f32_16x16x32_bf16 v[32:35], v[144:147], v[186:189], v[32:35]
	v_mfma_f32_16x16x32_bf16 v[24:27], v[152:155], v[186:189], v[24:27]
	v_mfma_f32_16x16x32_bf16 v[16:19], v[144:147], v[194:197], v[16:19]
	v_mfma_f32_16x16x32_bf16 v[8:11], v[152:155], v[194:197], v[8:11]
	v_mfma_f32_16x16x32_bf16 v[60:63], v[148:151], v[164:167], v[60:63]
	v_mfma_f32_16x16x32_bf16 v[56:59], v[156:159], v[164:167], v[56:59]
	v_mfma_f32_16x16x32_bf16 v[44:47], v[148:151], v[182:185], v[44:47]
	v_mfma_f32_16x16x32_bf16 v[40:43], v[156:159], v[182:185], v[40:43]
	v_mfma_f32_16x16x32_bf16 v[32:35], v[148:151], v[190:193], v[32:35]
	v_mfma_f32_16x16x32_bf16 v[24:27], v[156:159], v[190:193], v[24:27]
	v_mfma_f32_16x16x32_bf16 v[16:19], v[148:151], v[198:201], v[16:19]
	v_mfma_f32_16x16x32_bf16 v[8:11], v[156:159], v[198:201], v[8:11]
	s_setprio 0
	s_barrier
	s_add_u32 s42, s42, 0x100080
	s_addc_u32 s43, s43, 0
	s_add_i32 s48, s48, s50
	v_lshl_add_u64 v[144:145], s[42:43], 0, v[130:131]
	s_mov_b32 m0, s48
	s_nop 0
	global_load_lds_dwordx4 v[144:145], off
	v_lshl_add_u64 v[144:145], s[42:43], 0, v[134:135]
	s_add_i32 m0, s48, 0x2000
	s_nop 0
	global_load_lds_dwordx4 v[144:145], off
	s_waitcnt vmcnt(6)
	s_setprio 1
	s_barrier
	v_mfma_f32_16x16x32_bf16 v[52:55], v[202:205], v[160:163], v[52:55]
	v_mfma_f32_16x16x32_bf16 v[48:51], v[212:215], v[160:163], v[48:51]
	v_mfma_f32_16x16x32_bf16 v[36:39], v[202:205], v[168:171], v[36:39]
	v_mfma_f32_16x16x32_bf16 v[28:31], v[212:215], v[168:171], v[28:31]
	v_mfma_f32_16x16x32_bf16 v[20:23], v[202:205], v[186:189], v[20:23]
	v_mfma_f32_16x16x32_bf16 v[12:15], v[212:215], v[186:189], v[12:15]
	v_mfma_f32_16x16x32_bf16 v[4:7], v[202:205], v[194:197], v[4:7]
	v_mfma_f32_16x16x32_bf16 v[0:3], v[212:215], v[194:197], v[0:3]
	v_mfma_f32_16x16x32_bf16 v[52:55], v[206:209], v[164:167], v[52:55]
	v_mfma_f32_16x16x32_bf16 v[48:51], v[216:219], v[164:167], v[48:51]
	v_mfma_f32_16x16x32_bf16 v[36:39], v[206:209], v[182:185], v[36:39]
	v_mfma_f32_16x16x32_bf16 v[28:31], v[216:219], v[182:185], v[28:31]
	v_mfma_f32_16x16x32_bf16 v[20:23], v[206:209], v[190:193], v[20:23]
	v_mfma_f32_16x16x32_bf16 v[12:15], v[216:219], v[190:193], v[12:15]
	v_mfma_f32_16x16x32_bf16 v[4:7], v[206:209], v[198:201], v[4:7]
	v_mfma_f32_16x16x32_bf16 v[0:3], v[216:219], v[198:201], v[0:3]
	s_setprio 0
	s_add_i32 s65, s65, 2
	s_add_u32 s40, s40, 0x100
	s_addc_u32 s41, s41, 0
	s_add_u32 s63, s63, 0x100
	s_addc_u32 s64, s64, 0
	s_cmp_gt_u32 s65, 61
	s_barrier
	s_cbranch_scc0 .LBB0_896
	v_lshl_or_b32 v144, s38, 8, v177
	v_lshl_add_u32 v150, s36, 8, v175
	v_ashrrev_i32_e32 v145, 31, v144
	v_ashrrev_i32_e32 v151, 31, v150
	v_lshlrev_b64 v[144:145], 1, v[144:145]
	v_lshl_add_u64 v[146:147], s[90:91], 0, v[144:145]
	v_lshlrev_b64 v[148:149], 11, v[150:151]
	v_lshl_add_u64 v[152:153], v[146:147], 0, v[148:149]
	global_load_dwordx4 v[156:159], v[152:153], off
	global_load_dwordx4 v[160:163], v[152:153], off offset:256
	v_or_b32_e32 v152, 16, v150
	v_ashrrev_i32_e32 v153, 31, v152
	v_lshlrev_b64 v[170:171], 11, v[152:153]
	v_lshl_add_u64 v[152:153], v[146:147], 0, v[170:171]
	global_load_dwordx4 v[164:167], v[152:153], off
	global_load_dwordx4 v[182:185], v[152:153], off offset:256
	v_or_b32_e32 v152, 32, v150
	v_ashrrev_i32_e32 v153, 31, v152
	v_lshlrev_b64 v[154:155], 11, v[152:153]
	v_lshl_add_u64 v[152:153], v[146:147], 0, v[154:155]
	global_load_dwordx4 v[186:189], v[152:153], off
	global_load_dwordx4 v[190:193], v[152:153], off offset:256
	v_or_b32_e32 v152, 48, v150
	v_ashrrev_i32_e32 v153, 31, v152
	v_lshlrev_b64 v[152:153], 11, v[152:153]
	v_lshl_add_u64 v[168:169], v[146:147], 0, v[152:153]
	global_load_dwordx4 v[194:197], v[168:169], off
	global_load_dwordx4 v[198:201], v[168:169], off offset:256
	s_waitcnt vmcnt(0)
	v_lshlrev_b32_e32 v202, 16, v156
	v_and_b32_e32 v203, 0xffff0000, v156
	v_lshlrev_b32_e32 v204, 16, v157
	v_and_b32_e32 v205, 0xffff0000, v157
	v_lshlrev_b32_e32 v206, 16, v158
	v_and_b32_e32 v207, 0xffff0000, v158
	v_lshlrev_b32_e32 v208, 16, v159
	v_and_b32_e32 v209, 0xffff0000, v159
	v_pk_add_f32 v[126:127], v[126:127], v[204:205]
	v_pk_add_f32 v[124:125], v[124:125], v[202:203]
	v_lshlrev_b32_e32 v224, 16, v166
	v_and_b32_e32 v225, 0xffff0000, v166
	v_lshlrev_b32_e32 v226, 16, v167
	v_and_b32_e32 v227, 0xffff0000, v167
	v_lshlrev_b32_e32 v212, 16, v160
	v_lshlrev_b32_e32 v166, 16, v194
	v_and_b32_e32 v167, 0xffff0000, v194
	v_lshlrev_b32_e32 v172, 16, v195
	v_and_b32_e32 v173, 0xffff0000, v195
	v_pk_add_f32 v[194:195], v[122:123], v[208:209]
	v_pk_add_f32 v[122:123], v[120:121], v[206:207]
	v_mul_f32_e32 v120, v125, v125
	v_mul_f32_e32 v121, v127, v127
	v_fmac_f32_e32 v120, v124, v124
	v_fmac_f32_e32 v121, v126, v126
	v_add_f32_e32 v120, v120, v121
	v_mul_f32_e32 v121, v123, v123
	v_fmac_f32_e32 v121, v122, v122
	v_add_f32_e32 v120, v121, v120
	v_mul_f32_e32 v121, v195, v195
	v_fmac_f32_e32 v121, v194, v194
	v_and_b32_e32 v213, 0xffff0000, v160
	v_lshlrev_b32_e32 v214, 16, v161
	v_and_b32_e32 v215, 0xffff0000, v161
	v_add_f32_e32 v181, v121, v120
	v_cvt_pk_bf16_f32 v120, v124, v125
	v_lshl_add_u64 v[124:125], s[10:11], 0, v[148:149]
	v_lshlrev_b32_e32 v216, 16, v162
	v_and_b32_e32 v217, 0xffff0000, v162
	v_lshlrev_b32_e32 v218, 16, v163
	v_and_b32_e32 v219, 0xffff0000, v163
	v_cvt_pk_bf16_f32 v121, v126, v127
	v_lshl_add_u64 v[124:125], v[124:125], 0, v[144:145]
	v_pk_add_f32 v[118:119], v[118:119], v[214:215]
	v_pk_add_f32 v[116:117], v[116:117], v[212:213]
	v_cvt_pk_bf16_f32 v122, v122, v123
	v_cvt_pk_bf16_f32 v123, v194, v195
	global_store_dwordx4 v[124:125], v[120:123], off
	v_lshlrev_b32_e32 v220, 16, v164
	v_and_b32_e32 v221, 0xffff0000, v164
	v_pk_add_f32 v[120:121], v[114:115], v[218:219]
	v_pk_add_f32 v[114:115], v[112:113], v[216:217]
	v_mul_f32_e32 v112, v117, v117
	v_mul_f32_e32 v113, v119, v119
	v_fmac_f32_e32 v112, v116, v116
	v_fmac_f32_e32 v113, v118, v118
	v_add_f32_e32 v112, v112, v113
	v_mul_f32_e32 v113, v115, v115
	v_fmac_f32_e32 v113, v114, v114
	v_add_f32_e32 v112, v113, v112
	v_mul_f32_e32 v113, v121, v121
	v_fmac_f32_e32 v113, v120, v120
	v_add_f32_e32 v112, v113, v112
	v_lshlrev_b32_e32 v222, 16, v165
	v_and_b32_e32 v223, 0xffff0000, v165
	v_add_f32_e32 v126, v181, v112
	v_cvt_pk_bf16_f32 v112, v116, v117
	v_cvt_pk_bf16_f32 v113, v118, v119
	v_lshl_add_u64 v[116:117], s[10:11], 0, v[170:171]
	v_lshlrev_b32_e32 v230, 16, v184
	v_and_b32_e32 v231, 0xffff0000, v184
	v_lshlrev_b32_e32 v232, 16, v186
	v_and_b32_e32 v233, 0xffff0000, v186
	v_lshlrev_b32_e32 v186, 16, v187
	v_and_b32_e32 v187, 0xffff0000, v187
	v_cvt_pk_bf16_f32 v114, v114, v115
	v_cvt_pk_bf16_f32 v115, v120, v121
	global_store_dwordx4 v[124:125], v[112:115], off offset:256
	v_pk_add_f32 v[110:111], v[110:111], v[222:223]
	v_pk_add_f32 v[108:109], v[108:109], v[220:221]
	v_lshl_add_u64 v[118:119], v[116:117], 0, v[144:145]
	v_cvt_pk_bf16_f32 v112, v108, v109
	v_cvt_pk_bf16_f32 v113, v110, v111
	v_lshlrev_b32_e32 v228, 16, v182
	v_and_b32_e32 v229, 0xffff0000, v182
	v_lshlrev_b32_e32 v182, 16, v183
	v_and_b32_e32 v183, 0xffff0000, v183
	v_lshlrev_b32_e32 v184, 16, v185
	v_and_b32_e32 v185, 0xffff0000, v185
	v_lshlrev_b32_e32 v238, 16, v192
	v_and_b32_e32 v239, 0xffff0000, v192
	v_pk_add_f32 v[106:107], v[106:107], v[226:227]
	v_pk_add_f32 v[104:105], v[104:105], v[224:225]
	v_lshlrev_b32_e32 v156, 16, v200
	v_cvt_pk_bf16_f32 v114, v104, v105
	v_cvt_pk_bf16_f32 v115, v106, v107
	global_store_dwordx4 v[118:119], v[112:115], off
	v_and_b32_e32 v157, 0xffff0000, v200
	v_pk_add_f32 v[102:103], v[102:103], v[182:183]
	v_pk_add_f32 v[112:113], v[92:93], v[230:231]
	v_pk_add_f32 v[92:93], v[98:99], v[186:187]
	v_lshl_add_u64 v[98:99], s[10:11], 0, v[154:155]
	v_pk_add_f32 v[100:101], v[100:101], v[228:229]
	v_pk_add_f32 v[94:95], v[94:95], v[184:185]
	v_cvt_pk_bf16_f32 v114, v100, v101
	v_cvt_pk_bf16_f32 v115, v102, v103
	v_cvt_pk_bf16_f32 v116, v112, v113
	v_lshlrev_b32_e32 v234, 16, v188
	v_cvt_pk_bf16_f32 v117, v94, v95
	global_store_dwordx4 v[118:119], v[114:117], off offset:256
	v_lshl_add_u64 v[118:119], v[98:99], 0, v[144:145]
	v_pk_add_f32 v[98:99], v[76:77], v[238:239]
	v_pk_add_f32 v[76:77], v[82:83], v[172:173]
	v_lshl_add_u64 v[82:83], s[10:11], 0, v[152:153]
	v_lshl_add_u64 v[122:123], v[82:83], 0, v[144:145]
	v_pk_add_f32 v[82:83], v[64:65], v[156:157]
	v_and_b32_e32 v65, 64, v174
	v_and_b32_e32 v235, 0xffff0000, v188
	v_lshlrev_b32_e32 v188, 16, v189
	v_and_b32_e32 v189, 0xffff0000, v189
	v_lshlrev_b32_e32 v236, 16, v190
	v_and_b32_e32 v237, 0xffff0000, v190
	v_pk_add_f32 v[96:97], v[96:97], v[232:233]
	v_xor_b32_e32 v64, 16, v174
	v_cvt_pk_bf16_f32 v114, v96, v97
	v_add_u32_e32 v65, 64, v65
	v_lshlrev_b32_e32 v190, 16, v191
	v_and_b32_e32 v191, 0xffff0000, v191
	v_lshlrev_b32_e32 v192, 16, v193
	v_and_b32_e32 v193, 0xffff0000, v193
	v_pk_add_f32 v[90:91], v[90:91], v[188:189]
	v_pk_add_f32 v[88:89], v[88:89], v[234:235]
	v_cvt_pk_bf16_f32 v115, v92, v93
	v_pk_add_f32 v[84:85], v[84:85], v[236:237]
	v_cvt_pk_bf16_f32 v116, v88, v89
	v_cvt_pk_bf16_f32 v117, v90, v91
	global_store_dwordx4 v[118:119], v[114:117], off
	v_cmp_lt_i32_e32 vcc, v64, v65
	v_lshlrev_b32_e32 v164, 16, v196
	v_cvt_pk_bf16_f32 v114, v84, v85
	v_and_b32_e32 v165, 0xffff0000, v196
	v_lshlrev_b32_e32 v168, 16, v197
	v_and_b32_e32 v169, 0xffff0000, v197
	v_pk_add_f32 v[86:87], v[86:87], v[190:191]
	v_pk_add_f32 v[78:79], v[78:79], v[192:193]
	v_cvt_pk_bf16_f32 v115, v86, v87
	v_cvt_pk_bf16_f32 v116, v98, v99
	v_pk_add_f32 v[80:81], v[80:81], v[166:167]
	v_cvt_pk_bf16_f32 v117, v78, v79
	global_store_dwordx4 v[118:119], v[114:117], off offset:256
	v_cndmask_b32_e32 v64, v174, v64, vcc
	v_pk_add_f32 v[74:75], v[74:75], v[168:169]
	v_cvt_pk_bf16_f32 v114, v80, v81
	v_pk_add_f32 v[72:73], v[72:73], v[164:165]
	v_cvt_pk_bf16_f32 v115, v76, v77
	v_lshlrev_b32_e32 v158, 16, v198
	v_cvt_pk_bf16_f32 v116, v72, v73
	v_cvt_pk_bf16_f32 v117, v74, v75
	global_store_dwordx4 v[122:123], v[114:117], off
	v_and_b32_e32 v159, 0xffff0000, v198
	v_lshlrev_b32_e32 v162, 16, v199
	v_lshlrev_b32_e32 v114, 2, v64
	ds_bpermute_b32 v64, v114, v126
	v_xor_b32_e32 v115, 32, v174
	v_cmp_lt_i32_e32 vcc, v115, v65
	v_and_b32_e32 v163, 0xffff0000, v199
	v_lshlrev_b32_e32 v160, 16, v201
	v_cndmask_b32_e32 v65, v174, v115, vcc
	v_lshlrev_b32_e32 v115, 2, v65
	s_waitcnt lgkmcnt(0)
	v_add_f32_e32 v116, v126, v64
	ds_bpermute_b32 v117, v115, v116
	v_and_b32_e32 v161, 0xffff0000, v201
	v_pk_add_f32 v[70:71], v[70:71], v[162:163]
	v_pk_add_f32 v[68:69], v[68:69], v[158:159]
	v_pk_add_f32 v[66:67], v[66:67], v[160:161]
	v_lshl_add_u64 v[64:65], v[150:151], 2, s[18:19]
	v_cvt_pk_bf16_f32 v118, v68, v69
	v_cvt_pk_bf16_f32 v119, v70, v71
	v_cvt_pk_bf16_f32 v120, v82, v83
	v_cvt_pk_bf16_f32 v121, v66, v67
	global_store_dwordx4 v[122:123], v[118:121], off offset:256
	s_and_saveexec_b64 s[36:37], s[6:7]
	s_cbranch_execz .LBB0_899
	s_waitcnt lgkmcnt(0)
	v_add_f32_e32 v116, v116, v117
	global_atomic_add_f32 v[64:65], v116, off

.LBB0_946:
	ds_read_b128 v[144:147], v153
	ds_read_b128 v[158:161], v153 offset:1024
	ds_read_b128 v[162:165], v153 offset:2048
	ds_read_b128 v[166:169], v153 offset:3072
	s_add_u32 s28, s2, 0xfffc0080
	s_addc_u32 s29, s3, -1
	s_cmp_eq_u32 s58, 12
	s_cselect_b32 s31, s23, s29
	s_cselect_b32 s30, s54, s28
	s_cselect_b32 s29, s21, s57
	s_cselect_b32 s28, s55, s56
	v_lshl_add_u64 v[148:149], s[2:3], 0, v[136:137]
	s_add_i32 m0, s37, 0xc000
	ds_read_b128 v[170:173], v154
	ds_read_b128 v[176:179], v154 offset:1024
	ds_read_b128 v[180:183], v154 offset:2048
	ds_read_b128 v[184:187], v154 offset:3072
	ds_read_b128 v[188:191], v154 offset:4096
	ds_read_b128 v[192:195], v154 offset:5120
	ds_read_b128 v[196:199], v154 offset:6144
	ds_read_b128 v[200:203], v154 offset:7168
	global_load_lds_dwordx4 v[148:149], off
	v_lshl_add_u64 v[148:149], s[2:3], 0, v[138:139]
	s_add_i32 m0, s37, 0xe000
	s_nop 0
	global_load_lds_dwordx4 v[148:149], off
	s_waitcnt lgkmcnt(8)
	s_setprio 1
	s_barrier
	s_waitcnt lgkmcnt(0)
	v_mfma_f32_16x16x32_bf16 v[124:127], v[144:147], v[170:173], v[124:127]
	v_mfma_f32_16x16x32_bf16 v[120:123], v[162:165], v[170:173], v[120:123]
	v_mfma_f32_16x16x32_bf16 v[116:119], v[144:147], v[180:183], v[116:119]
	v_mfma_f32_16x16x32_bf16 v[112:115], v[162:165], v[180:183], v[112:115]
	v_mfma_f32_16x16x32_bf16 v[104:107], v[144:147], v[188:191], v[104:107]
	v_mfma_f32_16x16x32_bf16 v[96:99], v[162:165], v[188:191], v[96:99]
	v_mfma_f32_16x16x32_bf16 v[76:79], v[144:147], v[196:199], v[76:79]
	v_mfma_f32_16x16x32_bf16 v[72:75], v[162:165], v[196:199], v[72:75]
	v_mfma_f32_16x16x32_bf16 v[124:127], v[158:161], v[176:179], v[124:127]
	v_mfma_f32_16x16x32_bf16 v[120:123], v[166:169], v[176:179], v[120:123]
	v_mfma_f32_16x16x32_bf16 v[116:119], v[158:161], v[184:187], v[116:119]
	v_mfma_f32_16x16x32_bf16 v[112:115], v[166:169], v[184:187], v[112:115]
	v_mfma_f32_16x16x32_bf16 v[104:107], v[158:161], v[192:195], v[104:107]
	v_mfma_f32_16x16x32_bf16 v[96:99], v[166:169], v[192:195], v[96:99]
	v_mfma_f32_16x16x32_bf16 v[76:79], v[158:161], v[200:203], v[76:79]
	v_mfma_f32_16x16x32_bf16 v[72:75], v[166:169], v[200:203], v[72:75]
	s_setprio 0
	s_barrier
	s_add_i32 s59, s50, s34
	v_lshl_add_u64 v[148:149], s[28:29], 0, v[132:133]
	s_mov_b32 m0, s59
	ds_read_b128 v[204:207], v155
	ds_read_b128 v[212:215], v155 offset:1024
	ds_read_b128 v[216:219], v155 offset:2048
	ds_read_b128 v[220:223], v155 offset:3072
	global_load_lds_dwordx4 v[148:149], off
	v_lshl_add_u64 v[208:209], s[28:29], 0, v[128:129]
	s_add_i32 m0, s59, 0x2000
	s_nop 0
	global_load_lds_dwordx4 v[208:209], off
	s_setprio 1
	s_barrier
	s_waitcnt lgkmcnt(0)
	v_mfma_f32_16x16x32_bf16 v[108:111], v[204:207], v[170:173], v[108:111]
	v_mfma_f32_16x16x32_bf16 v[100:103], v[216:219], v[170:173], v[100:103]
	v_mfma_f32_16x16x32_bf16 v[92:95], v[204:207], v[180:183], v[92:95]
	v_mfma_f32_16x16x32_bf16 v[88:91], v[216:219], v[180:183], v[88:91]
	v_mfma_f32_16x16x32_bf16 v[84:87], v[204:207], v[188:191], v[84:87]
	v_mfma_f32_16x16x32_bf16 v[80:83], v[216:219], v[188:191], v[80:83]
	v_mfma_f32_16x16x32_bf16 v[68:71], v[204:207], v[196:199], v[68:71]
	v_mfma_f32_16x16x32_bf16 v[64:67], v[216:219], v[196:199], v[64:67]
	v_mfma_f32_16x16x32_bf16 v[108:111], v[212:215], v[176:179], v[108:111]
	v_mfma_f32_16x16x32_bf16 v[100:103], v[220:223], v[176:179], v[100:103]
	v_mfma_f32_16x16x32_bf16 v[92:95], v[212:215], v[184:187], v[92:95]
	v_mfma_f32_16x16x32_bf16 v[88:91], v[220:223], v[184:187], v[88:91]
	v_mfma_f32_16x16x32_bf16 v[84:87], v[212:215], v[192:195], v[84:87]
	v_mfma_f32_16x16x32_bf16 v[80:83], v[220:223], v[192:195], v[80:83]
	v_mfma_f32_16x16x32_bf16 v[68:71], v[212:215], v[200:203], v[68:71]
	v_mfma_f32_16x16x32_bf16 v[64:67], v[220:223], v[200:203], v[64:67]
	s_setprio 0
	s_mov_b32 m0, s37
	v_lshl_add_u64 v[224:225], s[30:31], 0, v[134:135]
	s_barrier
	ds_read_b128 v[170:173], v154 offset:16384
	ds_read_b128 v[176:179], v154 offset:17408
	ds_read_b128 v[180:183], v154 offset:18432
	ds_read_b128 v[184:187], v154 offset:19456
	ds_read_b128 v[188:191], v154 offset:20480
	ds_read_b128 v[192:195], v154 offset:21504
	ds_read_b128 v[196:199], v154 offset:22528
	ds_read_b128 v[200:203], v154 offset:23552
	global_load_lds_dwordx4 v[224:225], off
	v_lshl_add_u64 v[226:227], s[30:31], 0, v[130:131]
	s_mov_b32 m0, s38
	s_nop 0
	global_load_lds_dwordx4 v[226:227], off
	s_setprio 1
	s_barrier
	s_waitcnt lgkmcnt(0)
	v_mfma_f32_16x16x32_bf16 v[60:63], v[144:147], v[170:173], v[60:63]
	v_mfma_f32_16x16x32_bf16 v[56:59], v[162:165], v[170:173], v[56:59]
	v_mfma_f32_16x16x32_bf16 v[44:47], v[144:147], v[180:183], v[44:47]
	v_mfma_f32_16x16x32_bf16 v[40:43], v[162:165], v[180:183], v[40:43]
	v_mfma_f32_16x16x32_bf16 v[28:31], v[144:147], v[188:191], v[28:31]
	v_mfma_f32_16x16x32_bf16 v[24:27], v[162:165], v[188:191], v[24:27]
	v_mfma_f32_16x16x32_bf16 v[12:15], v[144:147], v[196:199], v[12:15]
	v_mfma_f32_16x16x32_bf16 v[8:11], v[162:165], v[196:199], v[8:11]
	v_mfma_f32_16x16x32_bf16 v[60:63], v[158:161], v[176:179], v[60:63]
	v_mfma_f32_16x16x32_bf16 v[56:59], v[166:169], v[176:179], v[56:59]
	v_mfma_f32_16x16x32_bf16 v[44:47], v[158:161], v[184:187], v[44:47]
	v_mfma_f32_16x16x32_bf16 v[40:43], v[166:169], v[184:187], v[40:43]
	v_mfma_f32_16x16x32_bf16 v[28:31], v[158:161], v[192:195], v[28:31]
	v_mfma_f32_16x16x32_bf16 v[24:27], v[166:169], v[192:195], v[24:27]
	v_mfma_f32_16x16x32_bf16 v[12:15], v[158:161], v[200:203], v[12:15]
	v_mfma_f32_16x16x32_bf16 v[8:11], v[166:169], v[200:203], v[8:11]
	s_setprio 0
	s_barrier
	s_add_u32 s60, s28, 0x40000
	s_addc_u32 s61, s29, 0
	s_add_i32 s59, s51, s34
	v_lshl_add_u64 v[144:145], s[60:61], 0, v[132:133]
	s_mov_b32 m0, s59
	s_nop 0
	global_load_lds_dwordx4 v[144:145], off
	v_lshl_add_u64 v[144:145], s[60:61], 0, v[128:129]
	s_add_i32 m0, s59, 0x2000
	s_nop 0
	global_load_lds_dwordx4 v[144:145], off
	s_waitcnt vmcnt(6)
	s_setprio 1
	s_barrier
	v_mfma_f32_16x16x32_bf16 v[52:55], v[204:207], v[170:173], v[52:55]
	v_mfma_f32_16x16x32_bf16 v[48:51], v[216:219], v[170:173], v[48:51]
	v_mfma_f32_16x16x32_bf16 v[36:39], v[204:207], v[180:183], v[36:39]
	v_mfma_f32_16x16x32_bf16 v[32:35], v[216:219], v[180:183], v[32:35]
	v_mfma_f32_16x16x32_bf16 v[20:23], v[204:207], v[188:191], v[20:23]
	v_mfma_f32_16x16x32_bf16 v[16:19], v[216:219], v[188:191], v[16:19]
	v_mfma_f32_16x16x32_bf16 v[4:7], v[204:207], v[196:199], v[4:7]
	v_mfma_f32_16x16x32_bf16 v[0:3], v[216:219], v[196:199], v[0:3]
	v_mfma_f32_16x16x32_bf16 v[52:55], v[212:215], v[176:179], v[52:55]
	v_mfma_f32_16x16x32_bf16 v[48:51], v[220:223], v[176:179], v[48:51]
	v_mfma_f32_16x16x32_bf16 v[36:39], v[212:215], v[184:187], v[36:39]
	v_mfma_f32_16x16x32_bf16 v[32:35], v[220:223], v[184:187], v[32:35]
	v_mfma_f32_16x16x32_bf16 v[20:23], v[212:215], v[192:195], v[20:23]
	v_mfma_f32_16x16x32_bf16 v[16:19], v[220:223], v[192:195], v[16:19]
	v_mfma_f32_16x16x32_bf16 v[4:7], v[212:215], v[200:203], v[4:7]
	v_mfma_f32_16x16x32_bf16 v[0:3], v[220:223], v[200:203], v[0:3]
	s_setprio 0
	s_add_i32 s59, 0, 0x18000
	v_add_u32_e32 v157, s59, v151
	s_barrier
	ds_read_b128 v[144:147], v157
	ds_read_b128 v[158:161], v157 offset:1024
	ds_read_b128 v[162:165], v157 offset:2048
	ds_read_b128 v[166:169], v157 offset:3072
	s_add_u32 s30, s30, 0x40000
	s_addc_u32 s31, s31, 0
	s_mov_b32 m0, s39
	v_lshl_add_u64 v[204:205], s[30:31], 0, v[134:135]
	ds_read_b128 v[170:173], v154 offset:32768
	ds_read_b128 v[176:179], v154 offset:33792
	ds_read_b128 v[180:183], v154 offset:34816
	ds_read_b128 v[184:187], v154 offset:35840
	ds_read_b128 v[188:191], v154 offset:36864
	ds_read_b128 v[192:195], v154 offset:37888
	ds_read_b128 v[196:199], v154 offset:38912
	ds_read_b128 v[200:203], v154 offset:39936
	global_load_lds_dwordx4 v[204:205], off
	v_lshl_add_u64 v[204:205], s[30:31], 0, v[130:131]
	s_mov_b32 m0, s40
	s_nop 0
	global_load_lds_dwordx4 v[204:205], off
	s_waitcnt lgkmcnt(8)
	s_setprio 1
	s_barrier
	s_waitcnt lgkmcnt(0)
	v_mfma_f32_16x16x32_bf16 v[124:127], v[144:147], v[170:173], v[124:127]
	v_mfma_f32_16x16x32_bf16 v[120:123], v[162:165], v[170:173], v[120:123]
	v_mfma_f32_16x16x32_bf16 v[116:119], v[144:147], v[180:183], v[116:119]
	v_mfma_f32_16x16x32_bf16 v[112:115], v[162:165], v[180:183], v[112:115]
	v_mfma_f32_16x16x32_bf16 v[104:107], v[144:147], v[188:191], v[104:107]
	v_mfma_f32_16x16x32_bf16 v[96:99], v[162:165], v[188:191], v[96:99]
	v_mfma_f32_16x16x32_bf16 v[76:79], v[144:147], v[196:199], v[76:79]
	v_mfma_f32_16x16x32_bf16 v[72:75], v[162:165], v[196:199], v[72:75]
	v_mfma_f32_16x16x32_bf16 v[124:127], v[158:161], v[176:179], v[124:127]
	v_mfma_f32_16x16x32_bf16 v[120:123], v[166:169], v[176:179], v[120:123]
	v_mfma_f32_16x16x32_bf16 v[116:119], v[158:161], v[184:187], v[116:119]
	v_mfma_f32_16x16x32_bf16 v[112:115], v[166:169], v[184:187], v[112:115]
	v_mfma_f32_16x16x32_bf16 v[104:107], v[158:161], v[192:195], v[104:107]
	v_mfma_f32_16x16x32_bf16 v[96:99], v[166:169], v[192:195], v[96:99]
	v_mfma_f32_16x16x32_bf16 v[76:79], v[158:161], v[200:203], v[76:79]
	v_mfma_f32_16x16x32_bf16 v[72:75], v[166:169], v[200:203], v[72:75]
	s_setprio 0
	s_barrier
	s_add_i32 s30, 0, 0x1c000
	s_add_i32 s31, s59, s34
	v_add_u32_e32 v157, s30, v151
	v_lshl_add_u64 v[148:149], v[148:149], 0, s[8:9]
	s_mov_b32 m0, s31
	ds_read_b128 v[204:207], v157
	ds_read_b128 v[212:215], v157 offset:1024
	ds_read_b128 v[216:219], v157 offset:2048
	ds_read_b128 v[220:223], v157 offset:3072
	global_load_lds_dwordx4 v[148:149], off
	v_lshl_add_u64 v[148:149], v[208:209], 0, s[8:9]
	s_add_i32 m0, s31, 0x2000
	s_nop 0
	global_load_lds_dwordx4 v[148:149], off
	s_setprio 1
	s_barrier
	s_waitcnt lgkmcnt(0)
	v_mfma_f32_16x16x32_bf16 v[108:111], v[204:207], v[170:173], v[108:111]
	v_mfma_f32_16x16x32_bf16 v[100:103], v[216:219], v[170:173], v[100:103]
	v_mfma_f32_16x16x32_bf16 v[92:95], v[204:207], v[180:183], v[92:95]
	v_mfma_f32_16x16x32_bf16 v[88:91], v[216:219], v[180:183], v[88:91]
	v_mfma_f32_16x16x32_bf16 v[84:87], v[204:207], v[188:191], v[84:87]
	v_mfma_f32_16x16x32_bf16 v[80:83], v[216:219], v[188:191], v[80:83]
	v_mfma_f32_16x16x32_bf16 v[68:71], v[204:207], v[196:199], v[68:71]
	v_mfma_f32_16x16x32_bf16 v[64:67], v[216:219], v[196:199], v[64:67]
	v_mfma_f32_16x16x32_bf16 v[108:111], v[212:215], v[176:179], v[108:111]
	v_mfma_f32_16x16x32_bf16 v[100:103], v[220:223], v[176:179], v[100:103]
	v_mfma_f32_16x16x32_bf16 v[92:95], v[212:215], v[184:187], v[92:95]
	v_mfma_f32_16x16x32_bf16 v[88:91], v[220:223], v[184:187], v[88:91]
	v_mfma_f32_16x16x32_bf16 v[84:87], v[212:215], v[192:195], v[84:87]
	v_mfma_f32_16x16x32_bf16 v[80:83], v[220:223], v[192:195], v[80:83]
	v_mfma_f32_16x16x32_bf16 v[68:71], v[212:215], v[200:203], v[68:71]
	v_mfma_f32_16x16x32_bf16 v[64:67], v[220:223], v[200:203], v[64:67]
	s_setprio 0
	s_mov_b32 m0, s42
	v_lshl_add_u64 v[148:149], v[224:225], 0, s[8:9]
	s_barrier
	ds_read_b128 v[170:173], v154 offset:49152
	ds_read_b128 v[176:179], v154 offset:50176
	ds_read_b128 v[180:183], v154 offset:51200
	ds_read_b128 v[184:187], v154 offset:52224
	ds_read_b128 v[188:191], v154 offset:53248
	ds_read_b128 v[192:195], v154 offset:54272
	ds_read_b128 v[196:199], v154 offset:55296
	ds_read_b128 v[200:203], v154 offset:56320
	global_load_lds_dwordx4 v[148:149], off
	v_lshl_add_u64 v[148:149], v[226:227], 0, s[8:9]
	s_mov_b32 m0, s43
	s_nop 0
	global_load_lds_dwordx4 v[148:149], off
	s_setprio 1
	s_barrier
	s_waitcnt lgkmcnt(0)
	v_mfma_f32_16x16x32_bf16 v[60:63], v[144:147], v[170:173], v[60:63]
	v_mfma_f32_16x16x32_bf16 v[56:59], v[162:165], v[170:173], v[56:59]
	v_mfma_f32_16x16x32_bf16 v[44:47], v[144:147], v[180:183], v[44:47]
	v_mfma_f32_16x16x32_bf16 v[40:43], v[162:165], v[180:183], v[40:43]
	v_mfma_f32_16x16x32_bf16 v[28:31], v[144:147], v[188:191], v[28:31]
	v_mfma_f32_16x16x32_bf16 v[24:27], v[162:165], v[188:191], v[24:27]
	v_mfma_f32_16x16x32_bf16 v[12:15], v[144:147], v[196:199], v[12:15]
	v_mfma_f32_16x16x32_bf16 v[8:11], v[162:165], v[196:199], v[8:11]
	v_mfma_f32_16x16x32_bf16 v[60:63], v[158:161], v[176:179], v[60:63]
	v_mfma_f32_16x16x32_bf16 v[56:59], v[166:169], v[176:179], v[56:59]
	v_mfma_f32_16x16x32_bf16 v[44:47], v[158:161], v[184:187], v[44:47]
	v_mfma_f32_16x16x32_bf16 v[40:43], v[166:169], v[184:187], v[40:43]
	v_mfma_f32_16x16x32_bf16 v[28:31], v[158:161], v[192:195], v[28:31]
	v_mfma_f32_16x16x32_bf16 v[24:27], v[166:169], v[192:195], v[24:27]
	v_mfma_f32_16x16x32_bf16 v[12:15], v[158:161], v[200:203], v[12:15]
	v_mfma_f32_16x16x32_bf16 v[8:11], v[166:169], v[200:203], v[8:11]
	s_setprio 0
	s_barrier
	s_add_u32 s28, s28, 0x40080
	s_addc_u32 s29, s29, 0
	s_add_i32 s30, s30, s34
	v_lshl_add_u64 v[144:145], s[28:29], 0, v[132:133]
	s_mov_b32 m0, s30
	s_nop 0
	global_load_lds_dwordx4 v[144:145], off
	v_lshl_add_u64 v[144:145], s[28:29], 0, v[128:129]
	s_add_i32 m0, s30, 0x2000
	s_nop 0
	global_load_lds_dwordx4 v[144:145], off
	s_waitcnt vmcnt(6)
	s_setprio 1
	s_barrier
	v_mfma_f32_16x16x32_bf16 v[52:55], v[204:207], v[170:173], v[52:55]
	v_mfma_f32_16x16x32_bf16 v[48:51], v[216:219], v[170:173], v[48:51]
	v_mfma_f32_16x16x32_bf16 v[36:39], v[204:207], v[180:183], v[36:39]
	v_mfma_f32_16x16x32_bf16 v[32:35], v[216:219], v[180:183], v[32:35]
	v_mfma_f32_16x16x32_bf16 v[20:23], v[204:207], v[188:191], v[20:23]
	v_mfma_f32_16x16x32_bf16 v[16:19], v[216:219], v[188:191], v[16:19]
	v_mfma_f32_16x16x32_bf16 v[4:7], v[204:207], v[196:199], v[4:7]
	v_mfma_f32_16x16x32_bf16 v[0:3], v[216:219], v[196:199], v[0:3]
	v_mfma_f32_16x16x32_bf16 v[52:55], v[212:215], v[176:179], v[52:55]
	v_mfma_f32_16x16x32_bf16 v[48:51], v[220:223], v[176:179], v[48:51]
	v_mfma_f32_16x16x32_bf16 v[36:39], v[212:215], v[184:187], v[36:39]
	v_mfma_f32_16x16x32_bf16 v[32:35], v[220:223], v[184:187], v[32:35]
	v_mfma_f32_16x16x32_bf16 v[20:23], v[212:215], v[192:195], v[20:23]
	v_mfma_f32_16x16x32_bf16 v[16:19], v[220:223], v[192:195], v[16:19]
	v_mfma_f32_16x16x32_bf16 v[4:7], v[212:215], v[200:203], v[4:7]
	v_mfma_f32_16x16x32_bf16 v[0:3], v[220:223], v[200:203], v[0:3]
	s_setprio 0
	s_add_i32 s58, s58, 2
	s_add_u32 s2, s2, 0x100
	s_addc_u32 s3, s3, 0
	s_add_u32 s56, s56, 0x100
	s_addc_u32 s57, s57, 0
	s_cmp_gt_u32 s58, 13
	s_barrier
	s_cbranch_scc0 .LBB0_946
	v_lshl_add_u32 v144, s0, 8, v150
	v_ashrrev_i32_e32 v145, 31, v144
	v_lshl_add_u64 v[146:147], v[144:145], 2, s[18:19]
	global_load_dword v145, v[146:147], off
	global_load_dword v157, v[146:147], off offset:64
	global_load_dword v164, v[146:147], off offset:128
	global_load_dword v165, v[146:147], off offset:192
	global_load_dword v166, v[146:147], off offset:512
	global_load_dword v167, v[146:147], off offset:576
	global_load_dword v168, v[146:147], off offset:640
	global_load_dword v169, v[146:147], off offset:704
	v_mov_b64_e32 v[146:147], s[92:93]
	v_or_b32_e32 v160, 16, v144
	v_or_b32_e32 v162, 32, v144
	v_lshl_or_b32 v148, s1, 8, v152
	v_mad_i64_i32 v[158:159], s[0:1], v144, s52, v[146:147]
	v_mad_i64_i32 v[160:161], s[0:1], v160, s52, v[146:147]
	v_mad_i64_i32 v[162:163], s[0:1], v162, s52, v[146:147]
	v_ashrrev_i32_e32 v149, 31, v148
	v_lshlrev_b64 v[148:149], 1, v[148:149]
	v_lshl_add_u64 v[158:159], v[158:159], 0, v[148:149]
	v_lshl_add_u64 v[160:161], v[160:161], 0, v[148:149]
	v_lshl_add_u64 v[162:163], v[162:163], 0, v[148:149]
	v_add_u32_e32 v170, 0x80, v144
	s_mov_b64 s[28:29], s[26:27]
	s_waitcnt vmcnt(0)
	v_fmamk_f32 v145, v145, 0x3a800000, v156
	v_fmamk_f32 v157, v157, 0x3a800000, v156
	v_fmamk_f32 v164, v164, 0x3a800000, v156
	v_fmamk_f32 v171, v165, 0x3a800000, v156
	v_fmamk_f32 v172, v166, 0x3a800000, v156
	v_mul_f32_e32 v165, 0x4b800000, v145
	v_mul_f32_e32 v166, 0x4b800000, v157
	v_cmp_gt_f32_e32 vcc, s53, v145
	v_cmp_gt_f32_e64 s[0:1], s53, v157
	v_fmamk_f32 v173, v167, 0x3a800000, v156
	v_mul_f32_e32 v167, 0x4b800000, v164
	v_cndmask_b32_e32 v145, v145, v165, vcc
	v_cndmask_b32_e64 v157, v157, v166, s[0:1]
	v_cmp_gt_f32_e64 s[2:3], s53, v164
	v_rsq_f32_e32 v145, v145
	v_rsq_f32_e32 v157, v157
	v_cndmask_b32_e64 v164, v164, v167, s[2:3]
	v_rsq_f32_e32 v165, v164
	v_mul_f32_e32 v164, 0x45800000, v145
	v_mul_f32_e32 v166, 0x45800000, v157
	v_cndmask_b32_e32 v164, v145, v164, vcc
	v_mul_f32_e32 v167, 0x45800000, v165
	v_cndmask_b32_e64 v166, v157, v166, s[0:1]
	v_fmamk_f32 v175, v168, 0x3a800000, v156
	v_cndmask_b32_e64 v168, v165, v167, s[2:3]
	v_pk_mul_f32 v[126:127], v[126:127], v[164:165] op_sel_hi:[1,0]
	v_pk_mul_f32 v[124:125], v[124:125], v[164:165] op_sel_hi:[1,0]
	v_pk_mul_f32 v[122:123], v[122:123], v[164:165] op_sel_hi:[1,0]
	v_pk_mul_f32 v[120:121], v[120:121], v[164:165] op_sel_hi:[1,0]
	v_pk_mul_f32 v[110:111], v[110:111], v[164:165] op_sel_hi:[1,0]
	v_pk_mul_f32 v[108:109], v[108:109], v[164:165] op_sel_hi:[1,0]
	v_pk_mul_f32 v[102:103], v[102:103], v[164:165] op_sel_hi:[1,0]
	v_pk_mul_f32 v[100:101], v[100:101], v[164:165] op_sel_hi:[1,0]
	v_pk_mul_f32 v[118:119], v[118:119], v[166:167] op_sel_hi:[1,0]
	v_pk_mul_f32 v[116:117], v[116:117], v[166:167] op_sel_hi:[1,0]
	v_pk_mul_f32 v[114:115], v[114:115], v[166:167] op_sel_hi:[1,0]
	v_pk_mul_f32 v[112:113], v[112:113], v[166:167] op_sel_hi:[1,0]
	v_pk_mul_f32 v[94:95], v[94:95], v[166:167] op_sel_hi:[1,0]
	v_pk_mul_f32 v[92:93], v[92:93], v[166:167] op_sel_hi:[1,0]
	v_pk_mul_f32 v[164:165], v[90:91], v[166:167] op_sel_hi:[1,0]
	v_pk_mul_f32 v[166:167], v[88:89], v[166:167] op_sel_hi:[1,0]
	v_cvt_pk_bf16_f32 v88, v124, v125
	v_cvt_pk_bf16_f32 v89, v126, v127
	v_cvt_pk_bf16_f32 v90, v120, v121
	v_cvt_pk_bf16_f32 v91, v122, v123
	global_store_dwordx4 v[158:159], v[88:91], off nt
	v_fmamk_f32 v169, v169, 0x3a800000, v156
	v_pk_mul_f32 v[106:107], v[106:107], v[168:169] op_sel_hi:[1,0]
	v_cvt_pk_bf16_f32 v88, v108, v109
	v_cvt_pk_bf16_f32 v89, v110, v111
	v_cvt_pk_bf16_f32 v90, v100, v101
	v_cvt_pk_bf16_f32 v91, v102, v103
	global_store_dwordx4 v[158:159], v[88:91], off offset:256 nt
	v_pk_mul_f32 v[104:105], v[104:105], v[168:169] op_sel_hi:[1,0]
	v_pk_mul_f32 v[98:99], v[98:99], v[168:169] op_sel_hi:[1,0]
	v_cvt_pk_bf16_f32 v88, v116, v117
	v_cvt_pk_bf16_f32 v89, v118, v119
	v_cvt_pk_bf16_f32 v90, v112, v113
	v_cvt_pk_bf16_f32 v91, v114, v115
	global_store_dwordx4 v[160:161], v[88:91], off nt
	v_pk_mul_f32 v[96:97], v[96:97], v[168:169] op_sel_hi:[1,0]
	v_pk_mul_f32 v[86:87], v[86:87], v[168:169] op_sel_hi:[1,0]
	v_cvt_pk_bf16_f32 v88, v92, v93
	v_cvt_pk_bf16_f32 v89, v94, v95
	v_cvt_pk_bf16_f32 v90, v166, v167
	v_cvt_pk_bf16_f32 v91, v164, v165
	global_store_dwordx4 v[160:161], v[88:91], off offset:256 nt
	v_pk_mul_f32 v[84:85], v[84:85], v[168:169] op_sel_hi:[1,0]
	v_cmp_gt_f32_e32 vcc, s53, v171
	v_cvt_pk_bf16_f32 v88, v104, v105
	v_cvt_pk_bf16_f32 v89, v106, v107
	v_cvt_pk_bf16_f32 v90, v96, v97
	v_cvt_pk_bf16_f32 v91, v98, v99
	global_store_dwordx4 v[162:163], v[88:91], off nt
	s_mov_b64 s[2:3], s[24:25]
	s_nop 0
	v_pk_mul_f32 v[88:89], v[82:83], v[168:169] op_sel_hi:[1,0]
	v_pk_mul_f32 v[82:83], v[80:81], v[168:169] op_sel_hi:[1,0]
	v_cvt_pk_bf16_f32 v80, v84, v85
	v_cvt_pk_bf16_f32 v81, v86, v87
	s_nop 0
	v_cvt_pk_bf16_f32 v82, v82, v83
	v_cvt_pk_bf16_f32 v83, v88, v89
	global_store_dwordx4 v[162:163], v[80:83], off offset:256 nt
	s_nop 1
	v_mul_f32_e32 v81, 0x4b800000, v171
	v_cndmask_b32_e32 v81, v171, v81, vcc
	v_rsq_f32_e32 v82, v81
	v_or_b32_e32 v80, 48, v144
	v_mad_i64_i32 v[80:81], s[0:1], v80, s52, v[146:147]
	v_mul_f32_e32 v83, 0x45800000, v82
	v_cndmask_b32_e32 v82, v82, v83, vcc
	v_lshl_add_u64 v[80:81], v[80:81], 0, v[148:149]
	v_pk_mul_f32 v[78:79], v[78:79], v[82:83] op_sel_hi:[1,0]
	v_pk_mul_f32 v[76:77], v[76:77], v[82:83] op_sel_hi:[1,0]
	v_pk_mul_f32 v[84:85], v[74:75], v[82:83] op_sel_hi:[1,0]
	v_pk_mul_f32 v[74:75], v[72:73], v[82:83] op_sel_hi:[1,0]
	v_cvt_pk_bf16_f32 v72, v76, v77
	v_cvt_pk_bf16_f32 v73, v78, v79
	v_pk_mul_f32 v[68:69], v[68:69], v[82:83] op_sel_hi:[1,0]
	v_cvt_pk_bf16_f32 v74, v74, v75
	v_cvt_pk_bf16_f32 v75, v84, v85
	global_store_dwordx4 v[80:81], v[72:75], off nt
	v_pk_mul_f32 v[70:71], v[70:71], v[82:83] op_sel_hi:[1,0]
	v_cmp_gt_f32_e32 vcc, s53, v172
	v_pk_mul_f32 v[72:73], v[66:67], v[82:83] op_sel_hi:[1,0]
	v_pk_mul_f32 v[66:67], v[64:65], v[82:83] op_sel_hi:[1,0]
	v_cvt_pk_bf16_f32 v64, v68, v69
	v_cvt_pk_bf16_f32 v65, v70, v71
	s_nop 0
	v_cvt_pk_bf16_f32 v66, v66, v67
	v_cvt_pk_bf16_f32 v67, v72, v73
	global_store_dwordx4 v[80:81], v[64:67], off offset:256 nt
	s_nop 1
	v_mul_f32_e32 v64, 0x4b800000, v172
	v_cndmask_b32_e32 v64, v172, v64, vcc
	v_rsq_f32_e32 v66, v64
	v_mad_i64_i32 v[64:65], s[0:1], v170, s52, v[146:147]
	v_lshl_add_u64 v[64:65], v[64:65], 0, v[148:149]
	v_mul_f32_e32 v67, 0x45800000, v66
	v_cndmask_b32_e32 v66, v66, v67, vcc
	v_pk_mul_f32 v[62:63], v[62:63], v[66:67] op_sel_hi:[1,0]
	v_pk_mul_f32 v[60:61], v[60:61], v[66:67] op_sel_hi:[1,0]
	v_pk_mul_f32 v[68:69], v[58:59], v[66:67] op_sel_hi:[1,0]
	v_pk_mul_f32 v[58:59], v[56:57], v[66:67] op_sel_hi:[1,0]
	v_cvt_pk_bf16_f32 v56, v60, v61
	v_cvt_pk_bf16_f32 v57, v62, v63
	v_pk_mul_f32 v[54:55], v[54:55], v[66:67] op_sel_hi:[1,0]
	v_cvt_pk_bf16_f32 v58, v58, v59
	v_cvt_pk_bf16_f32 v59, v68, v69
	global_store_dwordx4 v[64:65], v[56:59], off nt
	v_pk_mul_f32 v[52:53], v[52:53], v[66:67] op_sel_hi:[1,0]
	v_cmp_gt_f32_e32 vcc, s53, v173
	v_pk_mul_f32 v[56:57], v[50:51], v[66:67] op_sel_hi:[1,0]
	v_pk_mul_f32 v[50:51], v[48:49], v[66:67] op_sel_hi:[1,0]
	v_cvt_pk_bf16_f32 v48, v52, v53
	v_cvt_pk_bf16_f32 v49, v54, v55
	s_nop 0
	v_cvt_pk_bf16_f32 v50, v50, v51
	v_cvt_pk_bf16_f32 v51, v56, v57
	global_store_dwordx4 v[64:65], v[48:51], off offset:256 nt
	s_nop 1
	v_mul_f32_e32 v49, 0x4b800000, v173
	v_cndmask_b32_e32 v49, v173, v49, vcc
	v_rsq_f32_e32 v50, v49
	v_add_u32_e32 v48, 0x90, v144
	v_mad_i64_i32 v[48:49], s[0:1], v48, s52, v[146:147]
	v_mul_f32_e32 v51, 0x45800000, v50
	v_cndmask_b32_e32 v50, v50, v51, vcc
	v_lshl_add_u64 v[48:49], v[48:49], 0, v[148:149]
	v_pk_mul_f32 v[46:47], v[46:47], v[50:51] op_sel_hi:[1,0]
	v_pk_mul_f32 v[44:45], v[44:45], v[50:51] op_sel_hi:[1,0]
	v_pk_mul_f32 v[52:53], v[42:43], v[50:51] op_sel_hi:[1,0]
	v_pk_mul_f32 v[42:43], v[40:41], v[50:51] op_sel_hi:[1,0]
	v_cvt_pk_bf16_f32 v40, v44, v45
	v_cvt_pk_bf16_f32 v41, v46, v47
	v_pk_mul_f32 v[38:39], v[38:39], v[50:51] op_sel_hi:[1,0]
	v_cvt_pk_bf16_f32 v42, v42, v43
	v_cvt_pk_bf16_f32 v43, v52, v53
	global_store_dwordx4 v[48:49], v[40:43], off nt
	v_pk_mul_f32 v[36:37], v[36:37], v[50:51] op_sel_hi:[1,0]
	v_cmp_gt_f32_e32 vcc, s53, v175
	v_pk_mul_f32 v[40:41], v[34:35], v[50:51] op_sel_hi:[1,0]
	v_pk_mul_f32 v[34:35], v[32:33], v[50:51] op_sel_hi:[1,0]
	v_cvt_pk_bf16_f32 v32, v36, v37
	v_cvt_pk_bf16_f32 v33, v38, v39
	s_nop 0
	v_cvt_pk_bf16_f32 v34, v34, v35
	v_cvt_pk_bf16_f32 v35, v40, v41
	global_store_dwordx4 v[48:49], v[32:35], off offset:256 nt
	s_nop 1
	v_mul_f32_e32 v33, 0x4b800000, v175
	v_cndmask_b32_e32 v33, v175, v33, vcc
	v_rsq_f32_e32 v34, v33
	v_add_u32_e32 v32, 0xa0, v144
	v_mad_i64_i32 v[32:33], s[0:1], v32, s52, v[146:147]
	v_mul_f32_e32 v35, 0x45800000, v34
	v_cndmask_b32_e32 v34, v34, v35, vcc
	v_lshl_add_u64 v[32:33], v[32:33], 0, v[148:149]
	v_pk_mul_f32 v[30:31], v[30:31], v[34:35] op_sel_hi:[1,0]
	v_pk_mul_f32 v[28:29], v[28:29], v[34:35] op_sel_hi:[1,0]
	v_pk_mul_f32 v[36:37], v[26:27], v[34:35] op_sel_hi:[1,0]
	v_pk_mul_f32 v[26:27], v[24:25], v[34:35] op_sel_hi:[1,0]
	v_cvt_pk_bf16_f32 v24, v28, v29
	v_cvt_pk_bf16_f32 v25, v30, v31
	v_pk_mul_f32 v[22:23], v[22:23], v[34:35] op_sel_hi:[1,0]
	v_cvt_pk_bf16_f32 v26, v26, v27
	v_cvt_pk_bf16_f32 v27, v36, v37
	global_store_dwordx4 v[32:33], v[24:27], off nt
	v_pk_mul_f32 v[20:21], v[20:21], v[34:35] op_sel_hi:[1,0]
	v_cmp_gt_f32_e32 vcc, s53, v169
	v_pk_mul_f32 v[24:25], v[18:19], v[34:35] op_sel_hi:[1,0]
	v_pk_mul_f32 v[18:19], v[16:17], v[34:35] op_sel_hi:[1,0]
	v_cvt_pk_bf16_f32 v16, v20, v21
	v_cvt_pk_bf16_f32 v17, v22, v23
	s_nop 0
	v_cvt_pk_bf16_f32 v18, v18, v19
	v_cvt_pk_bf16_f32 v19, v24, v25
	global_store_dwordx4 v[32:33], v[16:19], off offset:256 nt
	s_nop 1
	v_mul_f32_e32 v17, 0x4b800000, v169
	v_cndmask_b32_e32 v17, v169, v17, vcc
	v_rsq_f32_e32 v18, v17
	v_add_u32_e32 v16, 0xb0, v144
	v_mad_i64_i32 v[16:17], s[0:1], v16, s52, v[146:147]
	v_mul_f32_e32 v19, 0x45800000, v18
	v_cndmask_b32_e32 v18, v18, v19, vcc
	v_lshl_add_u64 v[16:17], v[16:17], 0, v[148:149]
	v_pk_mul_f32 v[14:15], v[14:15], v[18:19] op_sel_hi:[1,0]
	v_pk_mul_f32 v[12:13], v[12:13], v[18:19] op_sel_hi:[1,0]
	v_pk_mul_f32 v[20:21], v[10:11], v[18:19] op_sel_hi:[1,0]
	v_pk_mul_f32 v[10:11], v[8:9], v[18:19] op_sel_hi:[1,0]
	v_cvt_pk_bf16_f32 v8, v12, v13
	v_cvt_pk_bf16_f32 v9, v14, v15
	s_and_b64 vcc, exec, s[6:7]
	v_cvt_pk_bf16_f32 v10, v10, v11
	v_cvt_pk_bf16_f32 v11, v20, v21
	global_store_dwordx4 v[16:17], v[8:11], off nt
	s_mov_b32 s1, s20
	s_mov_b32 s0, s22
	v_pk_mul_f32 v[8:9], v[2:3], v[18:19] op_sel_hi:[1,0]
	v_pk_mul_f32 v[2:3], v[0:1], v[18:19] op_sel_hi:[1,0]
	v_pk_mul_f32 v[6:7], v[6:7], v[18:19] op_sel_hi:[1,0]
	v_pk_mul_f32 v[4:5], v[4:5], v[18:19] op_sel_hi:[1,0]
	s_nop 0
	v_cvt_pk_bf16_f32 v0, v4, v5
	v_cvt_pk_bf16_f32 v1, v6, v7
	v_cvt_pk_bf16_f32 v2, v2, v3
	v_cvt_pk_bf16_f32 v3, v8, v9
	global_store_dwordx4 v[16:17], v[0:3], off offset:256 nt
	s_cbranch_vccz .LBB0_943
	s_waitcnt vmcnt(0)
	s_cmpk_gt_u32 s33, 0xff
	s_cbranch_scc1 .LBB0_950
	s_barrier

.LBB0_1022:
	ds_read_b128 v[144:147], v178
	ds_read_b128 v[148:151], v178 offset:1024
	ds_read_b128 v[152:155], v178 offset:2048
	ds_read_b128 v[156:159], v178 offset:3072
	s_add_u32 s42, s40, 0xfffc0080
	s_addc_u32 s43, s41, -1
	s_cmp_eq_u32 s64, 12
	s_cselect_b32 s49, s29, s43
	s_cselect_b32 s48, s37, s42
	s_cselect_b32 s43, s27, s63
	s_cselect_b32 s42, s61, s62
	v_lshl_add_u64 v[172:173], s[40:41], 0, v[136:137]
	s_add_i32 m0, s39, 0xc000
	ds_read_b128 v[160:163], v179
	ds_read_b128 v[164:167], v179 offset:1024
	ds_read_b128 v[168:171], v179 offset:2048
	ds_read_b128 v[182:185], v179 offset:3072
	ds_read_b128 v[186:189], v179 offset:4096
	ds_read_b128 v[190:193], v179 offset:5120
	ds_read_b128 v[194:197], v179 offset:6144
	ds_read_b128 v[198:201], v179 offset:7168
	global_load_lds_dwordx4 v[172:173], off
	v_lshl_add_u64 v[172:173], s[40:41], 0, v[138:139]
	s_add_i32 m0, s39, 0xe000
	s_nop 0
	global_load_lds_dwordx4 v[172:173], off
	s_waitcnt lgkmcnt(8)
	s_setprio 1
	s_barrier
	s_waitcnt lgkmcnt(0)
	v_mfma_f32_16x16x32_bf16 v[124:127], v[144:147], v[160:163], v[124:127]
	v_mfma_f32_16x16x32_bf16 v[120:123], v[152:155], v[160:163], v[120:123]
	v_mfma_f32_16x16x32_bf16 v[108:111], v[144:147], v[168:171], v[108:111]
	v_mfma_f32_16x16x32_bf16 v[104:107], v[152:155], v[168:171], v[104:107]
	v_mfma_f32_16x16x32_bf16 v[96:99], v[144:147], v[186:189], v[96:99]
	v_mfma_f32_16x16x32_bf16 v[88:91], v[152:155], v[186:189], v[88:91]
	v_mfma_f32_16x16x32_bf16 v[80:83], v[144:147], v[194:197], v[80:83]
	v_mfma_f32_16x16x32_bf16 v[72:75], v[152:155], v[194:197], v[72:75]
	v_mfma_f32_16x16x32_bf16 v[124:127], v[148:151], v[164:167], v[124:127]
	v_mfma_f32_16x16x32_bf16 v[120:123], v[156:159], v[164:167], v[120:123]
	v_mfma_f32_16x16x32_bf16 v[108:111], v[148:151], v[182:185], v[108:111]
	v_mfma_f32_16x16x32_bf16 v[104:107], v[156:159], v[182:185], v[104:107]
	v_mfma_f32_16x16x32_bf16 v[96:99], v[148:151], v[190:193], v[96:99]
	v_mfma_f32_16x16x32_bf16 v[88:91], v[156:159], v[190:193], v[88:91]
	v_mfma_f32_16x16x32_bf16 v[80:83], v[148:151], v[198:201], v[80:83]
	v_mfma_f32_16x16x32_bf16 v[72:75], v[156:159], v[198:201], v[72:75]
	s_setprio 0
	s_barrier
	s_add_i32 s65, s59, s50
	v_lshl_add_u64 v[172:173], s[42:43], 0, v[130:131]
	s_mov_b32 m0, s65
	ds_read_b128 v[202:205], v180
	ds_read_b128 v[206:209], v180 offset:1024
	ds_read_b128 v[212:215], v180 offset:2048
	ds_read_b128 v[216:219], v180 offset:3072
	global_load_lds_dwordx4 v[172:173], off
	v_lshl_add_u64 v[220:221], s[42:43], 0, v[134:135]
	s_add_i32 m0, s65, 0x2000
	s_nop 0
	global_load_lds_dwordx4 v[220:221], off
	s_setprio 1
	s_barrier
	s_waitcnt lgkmcnt(0)
	v_mfma_f32_16x16x32_bf16 v[116:119], v[202:205], v[160:163], v[116:119]
	v_mfma_f32_16x16x32_bf16 v[112:115], v[212:215], v[160:163], v[112:115]
	v_mfma_f32_16x16x32_bf16 v[100:103], v[202:205], v[168:171], v[100:103]
	v_mfma_f32_16x16x32_bf16 v[92:95], v[212:215], v[168:171], v[92:95]
	v_mfma_f32_16x16x32_bf16 v[84:87], v[202:205], v[186:189], v[84:87]
	v_mfma_f32_16x16x32_bf16 v[76:79], v[212:215], v[186:189], v[76:79]
	v_mfma_f32_16x16x32_bf16 v[68:71], v[202:205], v[194:197], v[68:71]
	v_mfma_f32_16x16x32_bf16 v[64:67], v[212:215], v[194:197], v[64:67]
	v_mfma_f32_16x16x32_bf16 v[116:119], v[206:209], v[164:167], v[116:119]
	v_mfma_f32_16x16x32_bf16 v[112:115], v[216:219], v[164:167], v[112:115]
	v_mfma_f32_16x16x32_bf16 v[100:103], v[206:209], v[182:185], v[100:103]
	v_mfma_f32_16x16x32_bf16 v[92:95], v[216:219], v[182:185], v[92:95]
	v_mfma_f32_16x16x32_bf16 v[84:87], v[206:209], v[190:193], v[84:87]
	v_mfma_f32_16x16x32_bf16 v[76:79], v[216:219], v[190:193], v[76:79]
	v_mfma_f32_16x16x32_bf16 v[68:71], v[206:209], v[198:201], v[68:71]
	v_mfma_f32_16x16x32_bf16 v[64:67], v[216:219], v[198:201], v[64:67]
	s_setprio 0
	s_mov_b32 m0, s39
	v_lshl_add_u64 v[222:223], s[48:49], 0, v[128:129]
	s_barrier
	ds_read_b128 v[160:163], v179 offset:16384
	ds_read_b128 v[164:167], v179 offset:17408
	ds_read_b128 v[168:171], v179 offset:18432
	ds_read_b128 v[182:185], v179 offset:19456
	ds_read_b128 v[186:189], v179 offset:20480
	ds_read_b128 v[190:193], v179 offset:21504
	ds_read_b128 v[194:197], v179 offset:22528
	ds_read_b128 v[198:201], v179 offset:23552
	global_load_lds_dwordx4 v[222:223], off
	v_lshl_add_u64 v[224:225], s[48:49], 0, v[132:133]
	s_mov_b32 m0, s51
	s_nop 0
	global_load_lds_dwordx4 v[224:225], off
	s_setprio 1
	s_barrier
	s_waitcnt lgkmcnt(0)
	v_mfma_f32_16x16x32_bf16 v[60:63], v[144:147], v[160:163], v[60:63]
	v_mfma_f32_16x16x32_bf16 v[56:59], v[152:155], v[160:163], v[56:59]
	v_mfma_f32_16x16x32_bf16 v[44:47], v[144:147], v[168:171], v[44:47]
	v_mfma_f32_16x16x32_bf16 v[40:43], v[152:155], v[168:171], v[40:43]
	v_mfma_f32_16x16x32_bf16 v[32:35], v[144:147], v[186:189], v[32:35]
	v_mfma_f32_16x16x32_bf16 v[24:27], v[152:155], v[186:189], v[24:27]
	v_mfma_f32_16x16x32_bf16 v[16:19], v[144:147], v[194:197], v[16:19]
	v_mfma_f32_16x16x32_bf16 v[8:11], v[152:155], v[194:197], v[8:11]
	v_mfma_f32_16x16x32_bf16 v[60:63], v[148:151], v[164:167], v[60:63]
	v_mfma_f32_16x16x32_bf16 v[56:59], v[156:159], v[164:167], v[56:59]
	v_mfma_f32_16x16x32_bf16 v[44:47], v[148:151], v[182:185], v[44:47]
	v_mfma_f32_16x16x32_bf16 v[40:43], v[156:159], v[182:185], v[40:43]
	v_mfma_f32_16x16x32_bf16 v[32:35], v[148:151], v[190:193], v[32:35]
	v_mfma_f32_16x16x32_bf16 v[24:27], v[156:159], v[190:193], v[24:27]
	v_mfma_f32_16x16x32_bf16 v[16:19], v[148:151], v[198:201], v[16:19]
	v_mfma_f32_16x16x32_bf16 v[8:11], v[156:159], v[198:201], v[8:11]
	s_setprio 0
	s_barrier
	s_add_u32 s66, s42, 0x40000
	s_addc_u32 s67, s43, 0
	s_add_i32 s65, s60, s50
	v_lshl_add_u64 v[144:145], s[66:67], 0, v[130:131]
	s_mov_b32 m0, s65
	s_nop 0
	global_load_lds_dwordx4 v[144:145], off
	v_lshl_add_u64 v[144:145], s[66:67], 0, v[134:135]
	s_add_i32 m0, s65, 0x2000
	s_nop 0
	global_load_lds_dwordx4 v[144:145], off
	s_waitcnt vmcnt(6)
	s_setprio 1
	s_barrier
	v_mfma_f32_16x16x32_bf16 v[52:55], v[202:205], v[160:163], v[52:55]
	v_mfma_f32_16x16x32_bf16 v[48:51], v[212:215], v[160:163], v[48:51]
	v_mfma_f32_16x16x32_bf16 v[36:39], v[202:205], v[168:171], v[36:39]
	v_mfma_f32_16x16x32_bf16 v[28:31], v[212:215], v[168:171], v[28:31]
	v_mfma_f32_16x16x32_bf16 v[20:23], v[202:205], v[186:189], v[20:23]
	v_mfma_f32_16x16x32_bf16 v[12:15], v[212:215], v[186:189], v[12:15]
	v_mfma_f32_16x16x32_bf16 v[4:7], v[202:205], v[194:197], v[4:7]
	v_mfma_f32_16x16x32_bf16 v[0:3], v[212:215], v[194:197], v[0:3]
	v_mfma_f32_16x16x32_bf16 v[52:55], v[206:209], v[164:167], v[52:55]
	v_mfma_f32_16x16x32_bf16 v[48:51], v[216:219], v[164:167], v[48:51]
	v_mfma_f32_16x16x32_bf16 v[36:39], v[206:209], v[182:185], v[36:39]
	v_mfma_f32_16x16x32_bf16 v[28:31], v[216:219], v[182:185], v[28:31]
	v_mfma_f32_16x16x32_bf16 v[20:23], v[206:209], v[190:193], v[20:23]
	v_mfma_f32_16x16x32_bf16 v[12:15], v[216:219], v[190:193], v[12:15]
	v_mfma_f32_16x16x32_bf16 v[4:7], v[206:209], v[198:201], v[4:7]
	v_mfma_f32_16x16x32_bf16 v[0:3], v[216:219], v[198:201], v[0:3]
	s_setprio 0
	s_add_i32 s65, 0, 0x18000
	v_add_u32_e32 v156, s65, v176
	s_barrier
	ds_read_b128 v[144:147], v156
	ds_read_b128 v[148:151], v156 offset:1024
	ds_read_b128 v[152:155], v156 offset:2048
	ds_read_b128 v[156:159], v156 offset:3072
	s_add_u32 s48, s48, 0x40000
	s_addc_u32 s49, s49, 0
	s_mov_b32 m0, s52
	v_lshl_add_u64 v[202:203], s[48:49], 0, v[128:129]
	ds_read_b128 v[160:163], v179 offset:32768
	ds_read_b128 v[164:167], v179 offset:33792
	ds_read_b128 v[168:171], v179 offset:34816
	ds_read_b128 v[182:185], v179 offset:35840
	ds_read_b128 v[186:189], v179 offset:36864
	ds_read_b128 v[190:193], v179 offset:37888
	ds_read_b128 v[194:197], v179 offset:38912
	ds_read_b128 v[198:201], v179 offset:39936
	global_load_lds_dwordx4 v[202:203], off
	v_lshl_add_u64 v[202:203], s[48:49], 0, v[132:133]
	s_mov_b32 m0, s53
	s_nop 0
	global_load_lds_dwordx4 v[202:203], off
	s_waitcnt lgkmcnt(8)
	s_setprio 1
	s_barrier
	s_waitcnt lgkmcnt(0)
	v_mfma_f32_16x16x32_bf16 v[124:127], v[144:147], v[160:163], v[124:127]
	v_mfma_f32_16x16x32_bf16 v[120:123], v[152:155], v[160:163], v[120:123]
	v_mfma_f32_16x16x32_bf16 v[108:111], v[144:147], v[168:171], v[108:111]
	v_mfma_f32_16x16x32_bf16 v[104:107], v[152:155], v[168:171], v[104:107]
	v_mfma_f32_16x16x32_bf16 v[96:99], v[144:147], v[186:189], v[96:99]
	v_mfma_f32_16x16x32_bf16 v[88:91], v[152:155], v[186:189], v[88:91]
	v_mfma_f32_16x16x32_bf16 v[80:83], v[144:147], v[194:197], v[80:83]
	v_mfma_f32_16x16x32_bf16 v[72:75], v[152:155], v[194:197], v[72:75]
	v_mfma_f32_16x16x32_bf16 v[124:127], v[148:151], v[164:167], v[124:127]
	v_mfma_f32_16x16x32_bf16 v[120:123], v[156:159], v[164:167], v[120:123]
	v_mfma_f32_16x16x32_bf16 v[108:111], v[148:151], v[182:185], v[108:111]
	v_mfma_f32_16x16x32_bf16 v[104:107], v[156:159], v[182:185], v[104:107]
	v_mfma_f32_16x16x32_bf16 v[96:99], v[148:151], v[190:193], v[96:99]
	v_mfma_f32_16x16x32_bf16 v[88:91], v[156:159], v[190:193], v[88:91]
	v_mfma_f32_16x16x32_bf16 v[80:83], v[148:151], v[198:201], v[80:83]
	v_mfma_f32_16x16x32_bf16 v[72:75], v[156:159], v[198:201], v[72:75]
	s_setprio 0
	s_barrier
	s_add_i32 s48, 0, 0x1c000
	s_add_i32 s49, s65, s50
	v_add_u32_e32 v181, s48, v176
	v_lshl_add_u64 v[172:173], v[172:173], 0, s[2:3]
	s_mov_b32 m0, s49
	ds_read_b128 v[202:205], v181
	ds_read_b128 v[206:209], v181 offset:1024
	ds_read_b128 v[212:215], v181 offset:2048
	ds_read_b128 v[216:219], v181 offset:3072
	global_load_lds_dwordx4 v[172:173], off
	v_lshl_add_u64 v[172:173], v[220:221], 0, s[2:3]
	s_add_i32 m0, s49, 0x2000
	s_nop 0
	global_load_lds_dwordx4 v[172:173], off
	s_setprio 1
	s_barrier
	s_waitcnt lgkmcnt(0)
	v_mfma_f32_16x16x32_bf16 v[116:119], v[202:205], v[160:163], v[116:119]
	v_mfma_f32_16x16x32_bf16 v[112:115], v[212:215], v[160:163], v[112:115]
	v_mfma_f32_16x16x32_bf16 v[100:103], v[202:205], v[168:171], v[100:103]
	v_mfma_f32_16x16x32_bf16 v[92:95], v[212:215], v[168:171], v[92:95]
	v_mfma_f32_16x16x32_bf16 v[84:87], v[202:205], v[186:189], v[84:87]
	v_mfma_f32_16x16x32_bf16 v[76:79], v[212:215], v[186:189], v[76:79]
	v_mfma_f32_16x16x32_bf16 v[68:71], v[202:205], v[194:197], v[68:71]
	v_mfma_f32_16x16x32_bf16 v[64:67], v[212:215], v[194:197], v[64:67]
	v_mfma_f32_16x16x32_bf16 v[116:119], v[206:209], v[164:167], v[116:119]
	v_mfma_f32_16x16x32_bf16 v[112:115], v[216:219], v[164:167], v[112:115]
	v_mfma_f32_16x16x32_bf16 v[100:103], v[206:209], v[182:185], v[100:103]
	v_mfma_f32_16x16x32_bf16 v[92:95], v[216:219], v[182:185], v[92:95]
	v_mfma_f32_16x16x32_bf16 v[84:87], v[206:209], v[190:193], v[84:87]
	v_mfma_f32_16x16x32_bf16 v[76:79], v[216:219], v[190:193], v[76:79]
	v_mfma_f32_16x16x32_bf16 v[68:71], v[206:209], v[198:201], v[68:71]
	v_mfma_f32_16x16x32_bf16 v[64:67], v[216:219], v[198:201], v[64:67]
	s_setprio 0
	s_mov_b32 m0, s55
	v_lshl_add_u64 v[172:173], v[222:223], 0, s[2:3]
	s_barrier
	ds_read_b128 v[160:163], v179 offset:49152
	ds_read_b128 v[164:167], v179 offset:50176
	ds_read_b128 v[168:171], v179 offset:51200
	ds_read_b128 v[182:185], v179 offset:52224
	ds_read_b128 v[186:189], v179 offset:53248
	ds_read_b128 v[190:193], v179 offset:54272
	ds_read_b128 v[194:197], v179 offset:55296
	ds_read_b128 v[198:201], v179 offset:56320
	global_load_lds_dwordx4 v[172:173], off
	v_lshl_add_u64 v[172:173], v[224:225], 0, s[2:3]
	s_mov_b32 m0, s56
	s_nop 0
	global_load_lds_dwordx4 v[172:173], off
	s_setprio 1
	s_barrier
	s_waitcnt lgkmcnt(0)
	v_mfma_f32_16x16x32_bf16 v[60:63], v[144:147], v[160:163], v[60:63]
	v_mfma_f32_16x16x32_bf16 v[56:59], v[152:155], v[160:163], v[56:59]
	v_mfma_f32_16x16x32_bf16 v[44:47], v[144:147], v[168:171], v[44:47]
	v_mfma_f32_16x16x32_bf16 v[40:43], v[152:155], v[168:171], v[40:43]
	v_mfma_f32_16x16x32_bf16 v[32:35], v[144:147], v[186:189], v[32:35]
	v_mfma_f32_16x16x32_bf16 v[24:27], v[152:155], v[186:189], v[24:27]
	v_mfma_f32_16x16x32_bf16 v[16:19], v[144:147], v[194:197], v[16:19]
	v_mfma_f32_16x16x32_bf16 v[8:11], v[152:155], v[194:197], v[8:11]
	v_mfma_f32_16x16x32_bf16 v[60:63], v[148:151], v[164:167], v[60:63]
	v_mfma_f32_16x16x32_bf16 v[56:59], v[156:159], v[164:167], v[56:59]
	v_mfma_f32_16x16x32_bf16 v[44:47], v[148:151], v[182:185], v[44:47]
	v_mfma_f32_16x16x32_bf16 v[40:43], v[156:159], v[182:185], v[40:43]
	v_mfma_f32_16x16x32_bf16 v[32:35], v[148:151], v[190:193], v[32:35]
	v_mfma_f32_16x16x32_bf16 v[24:27], v[156:159], v[190:193], v[24:27]
	v_mfma_f32_16x16x32_bf16 v[16:19], v[148:151], v[198:201], v[16:19]
	v_mfma_f32_16x16x32_bf16 v[8:11], v[156:159], v[198:201], v[8:11]
	s_setprio 0
	s_barrier
	s_add_u32 s42, s42, 0x40080
	s_addc_u32 s43, s43, 0
	s_add_i32 s48, s48, s50
	v_lshl_add_u64 v[144:145], s[42:43], 0, v[130:131]
	s_mov_b32 m0, s48
	s_nop 0
	global_load_lds_dwordx4 v[144:145], off
	v_lshl_add_u64 v[144:145], s[42:43], 0, v[134:135]
	s_add_i32 m0, s48, 0x2000
	s_nop 0
	global_load_lds_dwordx4 v[144:145], off
	s_waitcnt vmcnt(6)
	s_setprio 1
	s_barrier
	v_mfma_f32_16x16x32_bf16 v[52:55], v[202:205], v[160:163], v[52:55]
	v_mfma_f32_16x16x32_bf16 v[48:51], v[212:215], v[160:163], v[48:51]
	v_mfma_f32_16x16x32_bf16 v[36:39], v[202:205], v[168:171], v[36:39]
	v_mfma_f32_16x16x32_bf16 v[28:31], v[212:215], v[168:171], v[28:31]
	v_mfma_f32_16x16x32_bf16 v[20:23], v[202:205], v[186:189], v[20:23]
	v_mfma_f32_16x16x32_bf16 v[12:15], v[212:215], v[186:189], v[12:15]
	v_mfma_f32_16x16x32_bf16 v[4:7], v[202:205], v[194:197], v[4:7]
	v_mfma_f32_16x16x32_bf16 v[0:3], v[212:215], v[194:197], v[0:3]
	v_mfma_f32_16x16x32_bf16 v[52:55], v[206:209], v[164:167], v[52:55]
	v_mfma_f32_16x16x32_bf16 v[48:51], v[216:219], v[164:167], v[48:51]
	v_mfma_f32_16x16x32_bf16 v[36:39], v[206:209], v[182:185], v[36:39]
	v_mfma_f32_16x16x32_bf16 v[28:31], v[216:219], v[182:185], v[28:31]
	v_mfma_f32_16x16x32_bf16 v[20:23], v[206:209], v[190:193], v[20:23]
	v_mfma_f32_16x16x32_bf16 v[12:15], v[216:219], v[190:193], v[12:15]
	v_mfma_f32_16x16x32_bf16 v[4:7], v[206:209], v[198:201], v[4:7]
	v_mfma_f32_16x16x32_bf16 v[0:3], v[216:219], v[198:201], v[0:3]
	s_setprio 0
	s_add_i32 s64, s64, 2
	s_add_u32 s40, s40, 0x100
	s_addc_u32 s41, s41, 0
	s_add_u32 s62, s62, 0x100
	s_addc_u32 s63, s63, 0
	s_cmp_gt_u32 s64, 13
	s_barrier
	s_cbranch_scc0 .LBB0_1022
	v_lshl_or_b32 v144, s38, 8, v177
	v_lshl_add_u32 v150, s36, 8, v175
	v_ashrrev_i32_e32 v145, 31, v144
	v_ashrrev_i32_e32 v151, 31, v150
	v_lshlrev_b64 v[144:145], 1, v[144:145]
	v_lshl_add_u64 v[146:147], s[10:11], 0, v[144:145]
	v_lshlrev_b64 v[148:149], 11, v[150:151]
	v_lshl_add_u64 v[152:153], v[146:147], 0, v[148:149]
	global_load_dwordx4 v[156:159], v[152:153], off
	global_load_dwordx4 v[160:163], v[152:153], off offset:256
	v_or_b32_e32 v152, 16, v150
	v_ashrrev_i32_e32 v153, 31, v152
	v_lshlrev_b64 v[170:171], 11, v[152:153]
	v_lshl_add_u64 v[152:153], v[146:147], 0, v[170:171]
	global_load_dwordx4 v[164:167], v[152:153], off
	global_load_dwordx4 v[182:185], v[152:153], off offset:256
	v_or_b32_e32 v152, 32, v150
	v_ashrrev_i32_e32 v153, 31, v152
	v_lshlrev_b64 v[154:155], 11, v[152:153]
	v_lshl_add_u64 v[152:153], v[146:147], 0, v[154:155]
	global_load_dwordx4 v[186:189], v[152:153], off
	global_load_dwordx4 v[190:193], v[152:153], off offset:256
	v_or_b32_e32 v152, 48, v150
	v_ashrrev_i32_e32 v153, 31, v152
	v_lshlrev_b64 v[152:153], 11, v[152:153]
	v_lshl_add_u64 v[168:169], v[146:147], 0, v[152:153]
	global_load_dwordx4 v[194:197], v[168:169], off
	global_load_dwordx4 v[198:201], v[168:169], off offset:256
	s_waitcnt vmcnt(0)
	v_lshlrev_b32_e32 v202, 16, v156
	v_and_b32_e32 v203, 0xffff0000, v156
	v_lshlrev_b32_e32 v204, 16, v157
	v_and_b32_e32 v205, 0xffff0000, v157
	v_lshlrev_b32_e32 v206, 16, v158
	v_and_b32_e32 v207, 0xffff0000, v158
	v_lshlrev_b32_e32 v208, 16, v159
	v_and_b32_e32 v209, 0xffff0000, v159
	v_pk_add_f32 v[126:127], v[126:127], v[204:205]
	v_pk_add_f32 v[124:125], v[124:125], v[202:203]
	v_lshlrev_b32_e32 v224, 16, v166
	v_and_b32_e32 v225, 0xffff0000, v166
	v_lshlrev_b32_e32 v226, 16, v167
	v_and_b32_e32 v227, 0xffff0000, v167
	v_lshlrev_b32_e32 v212, 16, v160
	v_lshlrev_b32_e32 v166, 16, v194
	v_and_b32_e32 v167, 0xffff0000, v194
	v_lshlrev_b32_e32 v172, 16, v195
	v_and_b32_e32 v173, 0xffff0000, v195
	v_pk_add_f32 v[194:195], v[122:123], v[208:209]
	v_pk_add_f32 v[122:123], v[120:121], v[206:207]
	v_mul_f32_e32 v120, v125, v125
	v_mul_f32_e32 v121, v127, v127
	v_fmac_f32_e32 v120, v124, v124
	v_fmac_f32_e32 v121, v126, v126
	v_add_f32_e32 v120, v120, v121
	v_mul_f32_e32 v121, v123, v123
	v_fmac_f32_e32 v121, v122, v122
	v_add_f32_e32 v120, v121, v120
	v_mul_f32_e32 v121, v195, v195
	v_fmac_f32_e32 v121, v194, v194
	v_and_b32_e32 v213, 0xffff0000, v160
	v_lshlrev_b32_e32 v214, 16, v161
	v_and_b32_e32 v215, 0xffff0000, v161
	v_add_f32_e32 v181, v121, v120
	v_cvt_pk_bf16_f32 v120, v124, v125
	v_lshl_add_u64 v[124:125], s[10:11], 0, v[148:149]
	v_lshlrev_b32_e32 v216, 16, v162
	v_and_b32_e32 v217, 0xffff0000, v162
	v_lshlrev_b32_e32 v218, 16, v163
	v_and_b32_e32 v219, 0xffff0000, v163
	v_cvt_pk_bf16_f32 v121, v126, v127
	v_lshl_add_u64 v[124:125], v[124:125], 0, v[144:145]
	v_pk_add_f32 v[118:119], v[118:119], v[214:215]
	v_pk_add_f32 v[116:117], v[116:117], v[212:213]
	v_cvt_pk_bf16_f32 v122, v122, v123
	v_cvt_pk_bf16_f32 v123, v194, v195
	global_store_dwordx4 v[124:125], v[120:123], off
	v_lshlrev_b32_e32 v220, 16, v164
	v_and_b32_e32 v221, 0xffff0000, v164
	v_pk_add_f32 v[120:121], v[114:115], v[218:219]
	v_pk_add_f32 v[114:115], v[112:113], v[216:217]
	v_mul_f32_e32 v112, v117, v117
	v_mul_f32_e32 v113, v119, v119
	v_fmac_f32_e32 v112, v116, v116
	v_fmac_f32_e32 v113, v118, v118
	v_add_f32_e32 v112, v112, v113
	v_mul_f32_e32 v113, v115, v115
	v_fmac_f32_e32 v113, v114, v114
	v_add_f32_e32 v112, v113, v112
	v_mul_f32_e32 v113, v121, v121
	v_fmac_f32_e32 v113, v120, v120
	v_add_f32_e32 v112, v113, v112
	v_lshlrev_b32_e32 v222, 16, v165
	v_and_b32_e32 v223, 0xffff0000, v165
	v_add_f32_e32 v126, v181, v112
	v_cvt_pk_bf16_f32 v112, v116, v117
	v_cvt_pk_bf16_f32 v113, v118, v119
	v_lshl_add_u64 v[116:117], s[10:11], 0, v[170:171]
	v_lshlrev_b32_e32 v230, 16, v184
	v_and_b32_e32 v231, 0xffff0000, v184
	v_lshlrev_b32_e32 v232, 16, v186
	v_and_b32_e32 v233, 0xffff0000, v186
	v_lshlrev_b32_e32 v186, 16, v187
	v_and_b32_e32 v187, 0xffff0000, v187
	v_cvt_pk_bf16_f32 v114, v114, v115
	v_cvt_pk_bf16_f32 v115, v120, v121
	global_store_dwordx4 v[124:125], v[112:115], off offset:256
	v_pk_add_f32 v[110:111], v[110:111], v[222:223]
	v_pk_add_f32 v[108:109], v[108:109], v[220:221]
	v_lshl_add_u64 v[118:119], v[116:117], 0, v[144:145]
	v_cvt_pk_bf16_f32 v112, v108, v109
	v_cvt_pk_bf16_f32 v113, v110, v111
	v_lshlrev_b32_e32 v228, 16, v182
	v_and_b32_e32 v229, 0xffff0000, v182
	v_lshlrev_b32_e32 v182, 16, v183
	v_and_b32_e32 v183, 0xffff0000, v183
	v_lshlrev_b32_e32 v184, 16, v185
	v_and_b32_e32 v185, 0xffff0000, v185
	v_lshlrev_b32_e32 v238, 16, v192
	v_and_b32_e32 v239, 0xffff0000, v192
	v_pk_add_f32 v[106:107], v[106:107], v[226:227]
	v_pk_add_f32 v[104:105], v[104:105], v[224:225]
	v_lshlrev_b32_e32 v156, 16, v200
	v_cvt_pk_bf16_f32 v114, v104, v105
	v_cvt_pk_bf16_f32 v115, v106, v107
	global_store_dwordx4 v[118:119], v[112:115], off
	v_and_b32_e32 v157, 0xffff0000, v200
	v_pk_add_f32 v[102:103], v[102:103], v[182:183]
	v_pk_add_f32 v[112:113], v[92:93], v[230:231]
	v_pk_add_f32 v[92:93], v[98:99], v[186:187]
	v_lshl_add_u64 v[98:99], s[10:11], 0, v[154:155]
	v_pk_add_f32 v[100:101], v[100:101], v[228:229]
	v_pk_add_f32 v[94:95], v[94:95], v[184:185]
	v_cvt_pk_bf16_f32 v114, v100, v101
	v_cvt_pk_bf16_f32 v115, v102, v103
	v_cvt_pk_bf16_f32 v116, v112, v113
	v_lshlrev_b32_e32 v234, 16, v188
	v_cvt_pk_bf16_f32 v117, v94, v95
	global_store_dwordx4 v[118:119], v[114:117], off offset:256
	v_lshl_add_u64 v[118:119], v[98:99], 0, v[144:145]
	v_pk_add_f32 v[98:99], v[76:77], v[238:239]
	v_pk_add_f32 v[76:77], v[82:83], v[172:173]
	v_lshl_add_u64 v[82:83], s[10:11], 0, v[152:153]
	v_lshl_add_u64 v[122:123], v[82:83], 0, v[144:145]
	v_pk_add_f32 v[82:83], v[64:65], v[156:157]
	v_and_b32_e32 v65, 64, v174
	v_and_b32_e32 v235, 0xffff0000, v188
	v_lshlrev_b32_e32 v188, 16, v189
	v_and_b32_e32 v189, 0xffff0000, v189
	v_lshlrev_b32_e32 v236, 16, v190
	v_and_b32_e32 v237, 0xffff0000, v190
	v_pk_add_f32 v[96:97], v[96:97], v[232:233]
	v_xor_b32_e32 v64, 16, v174
	v_cvt_pk_bf16_f32 v114, v96, v97
	v_add_u32_e32 v65, 64, v65
	v_lshlrev_b32_e32 v190, 16, v191
	v_and_b32_e32 v191, 0xffff0000, v191
	v_lshlrev_b32_e32 v192, 16, v193
	v_and_b32_e32 v193, 0xffff0000, v193
	v_pk_add_f32 v[90:91], v[90:91], v[188:189]
	v_pk_add_f32 v[88:89], v[88:89], v[234:235]
	v_cvt_pk_bf16_f32 v115, v92, v93
	v_pk_add_f32 v[84:85], v[84:85], v[236:237]
	v_cvt_pk_bf16_f32 v116, v88, v89
	v_cvt_pk_bf16_f32 v117, v90, v91
	global_store_dwordx4 v[118:119], v[114:117], off
	v_cmp_lt_i32_e32 vcc, v64, v65
	v_lshlrev_b32_e32 v164, 16, v196
	v_cvt_pk_bf16_f32 v114, v84, v85
	v_and_b32_e32 v165, 0xffff0000, v196
	v_lshlrev_b32_e32 v168, 16, v197
	v_and_b32_e32 v169, 0xffff0000, v197
	v_pk_add_f32 v[86:87], v[86:87], v[190:191]
	v_pk_add_f32 v[78:79], v[78:79], v[192:193]
	v_cvt_pk_bf16_f32 v115, v86, v87
	v_cvt_pk_bf16_f32 v116, v98, v99
	v_pk_add_f32 v[80:81], v[80:81], v[166:167]
	v_cvt_pk_bf16_f32 v117, v78, v79
	global_store_dwordx4 v[118:119], v[114:117], off offset:256
	v_cndmask_b32_e32 v64, v174, v64, vcc
	v_pk_add_f32 v[74:75], v[74:75], v[168:169]
	v_cvt_pk_bf16_f32 v114, v80, v81
	v_pk_add_f32 v[72:73], v[72:73], v[164:165]
	v_cvt_pk_bf16_f32 v115, v76, v77
	v_lshlrev_b32_e32 v158, 16, v198
	v_cvt_pk_bf16_f32 v116, v72, v73
	v_cvt_pk_bf16_f32 v117, v74, v75
	global_store_dwordx4 v[122:123], v[114:117], off
	v_and_b32_e32 v159, 0xffff0000, v198
	v_lshlrev_b32_e32 v162, 16, v199
	v_lshlrev_b32_e32 v114, 2, v64
	ds_bpermute_b32 v64, v114, v126
	v_xor_b32_e32 v115, 32, v174
	v_cmp_lt_i32_e32 vcc, v115, v65
	v_and_b32_e32 v163, 0xffff0000, v199
	v_lshlrev_b32_e32 v160, 16, v201
	v_cndmask_b32_e32 v65, v174, v115, vcc
	v_lshlrev_b32_e32 v115, 2, v65
	s_waitcnt lgkmcnt(0)
	v_add_f32_e32 v116, v126, v64
	ds_bpermute_b32 v117, v115, v116
	v_and_b32_e32 v161, 0xffff0000, v201
	v_pk_add_f32 v[70:71], v[70:71], v[162:163]
	v_pk_add_f32 v[68:69], v[68:69], v[158:159]
	v_pk_add_f32 v[66:67], v[66:67], v[160:161]
	v_lshl_add_u64 v[64:65], v[150:151], 2, s[18:19]
	v_cvt_pk_bf16_f32 v118, v68, v69
	v_cvt_pk_bf16_f32 v119, v70, v71
	v_cvt_pk_bf16_f32 v120, v82, v83
	v_cvt_pk_bf16_f32 v121, v66, v67
	global_store_dwordx4 v[122:123], v[118:121], off offset:256
	s_and_saveexec_b64 s[36:37], s[6:7]
	s_cbranch_execz .LBB0_1025
	s_waitcnt lgkmcnt(0)
	v_add_f32_e32 v116, v116, v117
	global_atomic_add_f32 v[64:65], v116, off

.LBB0_1080:
	ds_read_b128 v[144:147], v151
	ds_read_b128 v[156:159], v151 offset:1024
	ds_read_b128 v[160:163], v151 offset:2048
	ds_read_b128 v[164:167], v151 offset:3072
	s_add_u32 s36, s2, 0xfffc0080
	s_addc_u32 s37, s3, -1
	s_cmp_eq_u32 s67, 12
	s_cselect_b32 s39, s29, s37
	s_cselect_b32 s38, s63, s36
	s_cselect_b32 s37, s27, s66
	s_cselect_b32 s36, s64, s65
	v_lshl_add_u64 v[172:173], s[2:3], 0, v[136:137]
	s_add_i32 m0, s48, 0xc000
	ds_read_b128 v[168:171], v152
	ds_read_b128 v[176:179], v152 offset:1024
	ds_read_b128 v[180:183], v152 offset:2048
	ds_read_b128 v[184:187], v152 offset:3072
	ds_read_b128 v[188:191], v152 offset:4096
	ds_read_b128 v[192:195], v152 offset:5120
	ds_read_b128 v[196:199], v152 offset:6144
	ds_read_b128 v[200:203], v152 offset:7168
	global_load_lds_dwordx4 v[172:173], off
	v_lshl_add_u64 v[172:173], s[2:3], 0, v[138:139]
	s_add_i32 m0, s48, 0xe000
	s_nop 0
	global_load_lds_dwordx4 v[172:173], off
	s_waitcnt lgkmcnt(8)
	s_setprio 1
	s_barrier
	s_waitcnt lgkmcnt(0)
	v_mfma_f32_16x16x32_bf16 v[124:127], v[144:147], v[168:171], v[124:127]
	v_mfma_f32_16x16x32_bf16 v[120:123], v[160:163], v[168:171], v[120:123]
	v_mfma_f32_16x16x32_bf16 v[116:119], v[144:147], v[180:183], v[116:119]
	v_mfma_f32_16x16x32_bf16 v[112:115], v[160:163], v[180:183], v[112:115]
	v_mfma_f32_16x16x32_bf16 v[104:107], v[144:147], v[188:191], v[104:107]
	v_mfma_f32_16x16x32_bf16 v[96:99], v[160:163], v[188:191], v[96:99]
	v_mfma_f32_16x16x32_bf16 v[76:79], v[144:147], v[196:199], v[76:79]
	v_mfma_f32_16x16x32_bf16 v[72:75], v[160:163], v[196:199], v[72:75]
	v_mfma_f32_16x16x32_bf16 v[124:127], v[156:159], v[176:179], v[124:127]
	v_mfma_f32_16x16x32_bf16 v[120:123], v[164:167], v[176:179], v[120:123]
	v_mfma_f32_16x16x32_bf16 v[116:119], v[156:159], v[184:187], v[116:119]
	v_mfma_f32_16x16x32_bf16 v[112:115], v[164:167], v[184:187], v[112:115]
	v_mfma_f32_16x16x32_bf16 v[104:107], v[156:159], v[192:195], v[104:107]
	v_mfma_f32_16x16x32_bf16 v[96:99], v[164:167], v[192:195], v[96:99]
	v_mfma_f32_16x16x32_bf16 v[76:79], v[156:159], v[200:203], v[76:79]
	v_mfma_f32_16x16x32_bf16 v[72:75], v[164:167], v[200:203], v[72:75]
	s_setprio 0
	s_barrier
	s_add_i32 s68, s56, s43
	v_lshl_add_u64 v[172:173], s[36:37], 0, v[130:131]
	s_mov_b32 m0, s68
	ds_read_b128 v[204:207], v153
	ds_read_b128 v[212:215], v153 offset:1024
	ds_read_b128 v[216:219], v153 offset:2048
	ds_read_b128 v[220:223], v153 offset:3072
	global_load_lds_dwordx4 v[172:173], off
	v_lshl_add_u64 v[208:209], s[36:37], 0, v[134:135]
	s_add_i32 m0, s68, 0x2000
	s_nop 0
	global_load_lds_dwordx4 v[208:209], off
	s_setprio 1
	s_barrier
	s_waitcnt lgkmcnt(0)
	v_mfma_f32_16x16x32_bf16 v[108:111], v[204:207], v[168:171], v[108:111]
	v_mfma_f32_16x16x32_bf16 v[100:103], v[216:219], v[168:171], v[100:103]
	v_mfma_f32_16x16x32_bf16 v[92:95], v[204:207], v[180:183], v[92:95]
	v_mfma_f32_16x16x32_bf16 v[88:91], v[216:219], v[180:183], v[88:91]
	v_mfma_f32_16x16x32_bf16 v[84:87], v[204:207], v[188:191], v[84:87]
	v_mfma_f32_16x16x32_bf16 v[80:83], v[216:219], v[188:191], v[80:83]
	v_mfma_f32_16x16x32_bf16 v[68:71], v[204:207], v[196:199], v[68:71]
	v_mfma_f32_16x16x32_bf16 v[64:67], v[216:219], v[196:199], v[64:67]
	v_mfma_f32_16x16x32_bf16 v[108:111], v[212:215], v[176:179], v[108:111]
	v_mfma_f32_16x16x32_bf16 v[100:103], v[220:223], v[176:179], v[100:103]
	v_mfma_f32_16x16x32_bf16 v[92:95], v[212:215], v[184:187], v[92:95]
	v_mfma_f32_16x16x32_bf16 v[88:91], v[220:223], v[184:187], v[88:91]
	v_mfma_f32_16x16x32_bf16 v[84:87], v[212:215], v[192:195], v[84:87]
	v_mfma_f32_16x16x32_bf16 v[80:83], v[220:223], v[192:195], v[80:83]
	v_mfma_f32_16x16x32_bf16 v[68:71], v[212:215], v[200:203], v[68:71]
	v_mfma_f32_16x16x32_bf16 v[64:67], v[220:223], v[200:203], v[64:67]
	s_setprio 0
	s_mov_b32 m0, s48
	v_lshl_add_u64 v[224:225], s[38:39], 0, v[128:129]
	s_barrier
	ds_read_b128 v[168:171], v152 offset:16384
	ds_read_b128 v[176:179], v152 offset:17408
	ds_read_b128 v[180:183], v152 offset:18432
	ds_read_b128 v[184:187], v152 offset:19456
	ds_read_b128 v[188:191], v152 offset:20480
	ds_read_b128 v[192:195], v152 offset:21504
	ds_read_b128 v[196:199], v152 offset:22528
	ds_read_b128 v[200:203], v152 offset:23552
	global_load_lds_dwordx4 v[224:225], off
	v_lshl_add_u64 v[226:227], s[38:39], 0, v[132:133]
	s_mov_b32 m0, s49
	s_nop 0
	global_load_lds_dwordx4 v[226:227], off
	s_setprio 1
	s_barrier
	s_waitcnt lgkmcnt(0)
	v_mfma_f32_16x16x32_bf16 v[60:63], v[144:147], v[168:171], v[60:63]
	v_mfma_f32_16x16x32_bf16 v[56:59], v[160:163], v[168:171], v[56:59]
	v_mfma_f32_16x16x32_bf16 v[44:47], v[144:147], v[180:183], v[44:47]
	v_mfma_f32_16x16x32_bf16 v[40:43], v[160:163], v[180:183], v[40:43]
	v_mfma_f32_16x16x32_bf16 v[28:31], v[144:147], v[188:191], v[28:31]
	v_mfma_f32_16x16x32_bf16 v[24:27], v[160:163], v[188:191], v[24:27]
	v_mfma_f32_16x16x32_bf16 v[12:15], v[144:147], v[196:199], v[12:15]
	v_mfma_f32_16x16x32_bf16 v[8:11], v[160:163], v[196:199], v[8:11]
	v_mfma_f32_16x16x32_bf16 v[60:63], v[156:159], v[176:179], v[60:63]
	v_mfma_f32_16x16x32_bf16 v[56:59], v[164:167], v[176:179], v[56:59]
	v_mfma_f32_16x16x32_bf16 v[44:47], v[156:159], v[184:187], v[44:47]
	v_mfma_f32_16x16x32_bf16 v[40:43], v[164:167], v[184:187], v[40:43]
	v_mfma_f32_16x16x32_bf16 v[28:31], v[156:159], v[192:195], v[28:31]
	v_mfma_f32_16x16x32_bf16 v[24:27], v[164:167], v[192:195], v[24:27]
	v_mfma_f32_16x16x32_bf16 v[12:15], v[156:159], v[200:203], v[12:15]
	v_mfma_f32_16x16x32_bf16 v[8:11], v[164:167], v[200:203], v[8:11]
	s_setprio 0
	s_barrier
	s_add_u32 s68, s36, 0x40000
	s_addc_u32 s69, s37, 0
	s_add_i32 s70, s57, s43
	v_lshl_add_u64 v[144:145], s[68:69], 0, v[130:131]
	s_mov_b32 m0, s70
	s_nop 0
	global_load_lds_dwordx4 v[144:145], off
	v_lshl_add_u64 v[144:145], s[68:69], 0, v[134:135]
	s_add_i32 m0, s70, 0x2000
	s_nop 0
	global_load_lds_dwordx4 v[144:145], off
	s_waitcnt vmcnt(6)
	s_setprio 1
	s_barrier
	v_mfma_f32_16x16x32_bf16 v[52:55], v[204:207], v[168:171], v[52:55]
	v_mfma_f32_16x16x32_bf16 v[48:51], v[216:219], v[168:171], v[48:51]
	v_mfma_f32_16x16x32_bf16 v[36:39], v[204:207], v[180:183], v[36:39]
	v_mfma_f32_16x16x32_bf16 v[32:35], v[216:219], v[180:183], v[32:35]
	v_mfma_f32_16x16x32_bf16 v[20:23], v[204:207], v[188:191], v[20:23]
	v_mfma_f32_16x16x32_bf16 v[16:19], v[216:219], v[188:191], v[16:19]
	v_mfma_f32_16x16x32_bf16 v[4:7], v[204:207], v[196:199], v[4:7]
	v_mfma_f32_16x16x32_bf16 v[0:3], v[216:219], v[196:199], v[0:3]
	v_mfma_f32_16x16x32_bf16 v[52:55], v[212:215], v[176:179], v[52:55]
	v_mfma_f32_16x16x32_bf16 v[48:51], v[220:223], v[176:179], v[48:51]
	v_mfma_f32_16x16x32_bf16 v[36:39], v[212:215], v[184:187], v[36:39]
	v_mfma_f32_16x16x32_bf16 v[32:35], v[220:223], v[184:187], v[32:35]
	v_mfma_f32_16x16x32_bf16 v[20:23], v[212:215], v[192:195], v[20:23]
	v_mfma_f32_16x16x32_bf16 v[16:19], v[220:223], v[192:195], v[16:19]
	v_mfma_f32_16x16x32_bf16 v[4:7], v[212:215], v[200:203], v[4:7]
	v_mfma_f32_16x16x32_bf16 v[0:3], v[220:223], v[200:203], v[0:3]
	s_setprio 0
	s_add_i32 s68, 0, 0x18000
	v_add_u32_e32 v155, s68, v149
	s_barrier
	ds_read_b128 v[144:147], v155
	ds_read_b128 v[156:159], v155 offset:1024
	ds_read_b128 v[160:163], v155 offset:2048
	ds_read_b128 v[164:167], v155 offset:3072
	s_add_u32 s38, s38, 0x40000
	s_addc_u32 s39, s39, 0
	s_mov_b32 m0, s50
	v_lshl_add_u64 v[204:205], s[38:39], 0, v[128:129]
	ds_read_b128 v[168:171], v152 offset:32768
	ds_read_b128 v[176:179], v152 offset:33792
	ds_read_b128 v[180:183], v152 offset:34816
	ds_read_b128 v[184:187], v152 offset:35840
	ds_read_b128 v[188:191], v152 offset:36864
	ds_read_b128 v[192:195], v152 offset:37888
	ds_read_b128 v[196:199], v152 offset:38912
	ds_read_b128 v[200:203], v152 offset:39936
	global_load_lds_dwordx4 v[204:205], off
	v_lshl_add_u64 v[204:205], s[38:39], 0, v[132:133]
	s_mov_b32 m0, s51
	s_nop 0
	global_load_lds_dwordx4 v[204:205], off
	s_waitcnt lgkmcnt(8)
	s_setprio 1
	s_barrier
	s_waitcnt lgkmcnt(0)
	v_mfma_f32_16x16x32_bf16 v[124:127], v[144:147], v[168:171], v[124:127]
	v_mfma_f32_16x16x32_bf16 v[120:123], v[160:163], v[168:171], v[120:123]
	v_mfma_f32_16x16x32_bf16 v[116:119], v[144:147], v[180:183], v[116:119]
	v_mfma_f32_16x16x32_bf16 v[112:115], v[160:163], v[180:183], v[112:115]
	v_mfma_f32_16x16x32_bf16 v[104:107], v[144:147], v[188:191], v[104:107]
	v_mfma_f32_16x16x32_bf16 v[96:99], v[160:163], v[188:191], v[96:99]
	v_mfma_f32_16x16x32_bf16 v[76:79], v[144:147], v[196:199], v[76:79]
	v_mfma_f32_16x16x32_bf16 v[72:75], v[160:163], v[196:199], v[72:75]
	v_mfma_f32_16x16x32_bf16 v[124:127], v[156:159], v[176:179], v[124:127]
	v_mfma_f32_16x16x32_bf16 v[120:123], v[164:167], v[176:179], v[120:123]
	v_mfma_f32_16x16x32_bf16 v[116:119], v[156:159], v[184:187], v[116:119]
	v_mfma_f32_16x16x32_bf16 v[112:115], v[164:167], v[184:187], v[112:115]
	v_mfma_f32_16x16x32_bf16 v[104:107], v[156:159], v[192:195], v[104:107]
	v_mfma_f32_16x16x32_bf16 v[96:99], v[164:167], v[192:195], v[96:99]
	v_mfma_f32_16x16x32_bf16 v[76:79], v[156:159], v[200:203], v[76:79]
	v_mfma_f32_16x16x32_bf16 v[72:75], v[164:167], v[200:203], v[72:75]
	s_setprio 0
	s_barrier
	s_add_i32 s38, 0, 0x1c000
	s_add_i32 s39, s68, s43
	v_add_u32_e32 v155, s38, v149
	v_lshl_add_u64 v[172:173], v[172:173], 0, s[8:9]
	s_mov_b32 m0, s39
	ds_read_b128 v[204:207], v155
	ds_read_b128 v[212:215], v155 offset:1024
	ds_read_b128 v[216:219], v155 offset:2048
	ds_read_b128 v[220:223], v155 offset:3072
	global_load_lds_dwordx4 v[172:173], off
	v_lshl_add_u64 v[172:173], v[208:209], 0, s[8:9]
	s_add_i32 m0, s39, 0x2000
	s_nop 0
	global_load_lds_dwordx4 v[172:173], off
	s_setprio 1
	s_barrier
	s_waitcnt lgkmcnt(0)
	v_mfma_f32_16x16x32_bf16 v[108:111], v[204:207], v[168:171], v[108:111]
	v_mfma_f32_16x16x32_bf16 v[100:103], v[216:219], v[168:171], v[100:103]
	v_mfma_f32_16x16x32_bf16 v[92:95], v[204:207], v[180:183], v[92:95]
	v_mfma_f32_16x16x32_bf16 v[88:91], v[216:219], v[180:183], v[88:91]
	v_mfma_f32_16x16x32_bf16 v[84:87], v[204:207], v[188:191], v[84:87]
	v_mfma_f32_16x16x32_bf16 v[80:83], v[216:219], v[188:191], v[80:83]
	v_mfma_f32_16x16x32_bf16 v[68:71], v[204:207], v[196:199], v[68:71]
	v_mfma_f32_16x16x32_bf16 v[64:67], v[216:219], v[196:199], v[64:67]
	v_mfma_f32_16x16x32_bf16 v[108:111], v[212:215], v[176:179], v[108:111]
	v_mfma_f32_16x16x32_bf16 v[100:103], v[220:223], v[176:179], v[100:103]
	v_mfma_f32_16x16x32_bf16 v[92:95], v[212:215], v[184:187], v[92:95]
	v_mfma_f32_16x16x32_bf16 v[88:91], v[220:223], v[184:187], v[88:91]
	v_mfma_f32_16x16x32_bf16 v[84:87], v[212:215], v[192:195], v[84:87]
	v_mfma_f32_16x16x32_bf16 v[80:83], v[220:223], v[192:195], v[80:83]
	v_mfma_f32_16x16x32_bf16 v[68:71], v[212:215], v[200:203], v[68:71]
	v_mfma_f32_16x16x32_bf16 v[64:67], v[220:223], v[200:203], v[64:67]
	s_setprio 0
	s_mov_b32 m0, s53
	v_lshl_add_u64 v[172:173], v[224:225], 0, s[8:9]
	s_barrier
	ds_read_b128 v[168:171], v152 offset:49152
	ds_read_b128 v[176:179], v152 offset:50176
	ds_read_b128 v[180:183], v152 offset:51200
	ds_read_b128 v[184:187], v152 offset:52224
	ds_read_b128 v[188:191], v152 offset:53248
	ds_read_b128 v[192:195], v152 offset:54272
	ds_read_b128 v[196:199], v152 offset:55296
	ds_read_b128 v[200:203], v152 offset:56320
	global_load_lds_dwordx4 v[172:173], off
	v_lshl_add_u64 v[172:173], v[226:227], 0, s[8:9]
	s_mov_b32 m0, s54
	s_nop 0
	global_load_lds_dwordx4 v[172:173], off
	s_setprio 1
	s_barrier
	s_waitcnt lgkmcnt(0)
	v_mfma_f32_16x16x32_bf16 v[60:63], v[144:147], v[168:171], v[60:63]
	v_mfma_f32_16x16x32_bf16 v[56:59], v[160:163], v[168:171], v[56:59]
	v_mfma_f32_16x16x32_bf16 v[44:47], v[144:147], v[180:183], v[44:47]
	v_mfma_f32_16x16x32_bf16 v[40:43], v[160:163], v[180:183], v[40:43]
	v_mfma_f32_16x16x32_bf16 v[28:31], v[144:147], v[188:191], v[28:31]
	v_mfma_f32_16x16x32_bf16 v[24:27], v[160:163], v[188:191], v[24:27]
	v_mfma_f32_16x16x32_bf16 v[12:15], v[144:147], v[196:199], v[12:15]
	v_mfma_f32_16x16x32_bf16 v[8:11], v[160:163], v[196:199], v[8:11]
	v_mfma_f32_16x16x32_bf16 v[60:63], v[156:159], v[176:179], v[60:63]
	v_mfma_f32_16x16x32_bf16 v[56:59], v[164:167], v[176:179], v[56:59]
	v_mfma_f32_16x16x32_bf16 v[44:47], v[156:159], v[184:187], v[44:47]
	v_mfma_f32_16x16x32_bf16 v[40:43], v[164:167], v[184:187], v[40:43]
	v_mfma_f32_16x16x32_bf16 v[28:31], v[156:159], v[192:195], v[28:31]
	v_mfma_f32_16x16x32_bf16 v[24:27], v[164:167], v[192:195], v[24:27]
	v_mfma_f32_16x16x32_bf16 v[12:15], v[156:159], v[200:203], v[12:15]
	v_mfma_f32_16x16x32_bf16 v[8:11], v[164:167], v[200:203], v[8:11]
	s_setprio 0
	s_barrier
	s_add_u32 s36, s36, 0x40080
	s_addc_u32 s37, s37, 0
	s_add_i32 s38, s38, s43
	v_lshl_add_u64 v[144:145], s[36:37], 0, v[130:131]
	s_mov_b32 m0, s38
	s_nop 0
	global_load_lds_dwordx4 v[144:145], off
	v_lshl_add_u64 v[144:145], s[36:37], 0, v[134:135]
	s_add_i32 m0, s38, 0x2000
	s_nop 0
	global_load_lds_dwordx4 v[144:145], off
	s_waitcnt vmcnt(6)
	s_setprio 1
	s_barrier
	v_mfma_f32_16x16x32_bf16 v[52:55], v[204:207], v[168:171], v[52:55]
	v_mfma_f32_16x16x32_bf16 v[48:51], v[216:219], v[168:171], v[48:51]
	v_mfma_f32_16x16x32_bf16 v[36:39], v[204:207], v[180:183], v[36:39]
	v_mfma_f32_16x16x32_bf16 v[32:35], v[216:219], v[180:183], v[32:35]
	v_mfma_f32_16x16x32_bf16 v[20:23], v[204:207], v[188:191], v[20:23]
	v_mfma_f32_16x16x32_bf16 v[16:19], v[216:219], v[188:191], v[16:19]
	v_mfma_f32_16x16x32_bf16 v[4:7], v[204:207], v[196:199], v[4:7]
	v_mfma_f32_16x16x32_bf16 v[0:3], v[216:219], v[196:199], v[0:3]
	v_mfma_f32_16x16x32_bf16 v[52:55], v[212:215], v[176:179], v[52:55]
	v_mfma_f32_16x16x32_bf16 v[48:51], v[220:223], v[176:179], v[48:51]
	v_mfma_f32_16x16x32_bf16 v[36:39], v[212:215], v[184:187], v[36:39]
	v_mfma_f32_16x16x32_bf16 v[32:35], v[220:223], v[184:187], v[32:35]
	v_mfma_f32_16x16x32_bf16 v[20:23], v[212:215], v[192:195], v[20:23]
	v_mfma_f32_16x16x32_bf16 v[16:19], v[220:223], v[192:195], v[16:19]
	v_mfma_f32_16x16x32_bf16 v[4:7], v[212:215], v[200:203], v[4:7]
	v_mfma_f32_16x16x32_bf16 v[0:3], v[220:223], v[200:203], v[0:3]
	s_setprio 0
	s_add_i32 s67, s67, 2
	s_add_u32 s2, s2, 0x100
	s_addc_u32 s3, s3, 0
	s_add_u32 s65, s65, 0x100
	s_addc_u32 s66, s66, 0
	s_cmp_gt_u32 s67, 13
	s_barrier
	s_cbranch_scc0 .LBB0_1080
	v_lshl_add_u32 v146, s0, 8, v148
	v_ashrrev_i32_e32 v147, 31, v146
	v_lshl_add_u64 v[144:145], v[146:147], 2, s[18:19]
	global_load_dword v155, v[144:145], off
	global_load_dword v164, v[144:145], off offset:64
	global_load_dword v165, v[144:145], off offset:128
	global_load_dword v166, v[144:145], off offset:192
	global_load_dword v167, v[144:145], off offset:512
	global_load_dword v168, v[144:145], off offset:576
	global_load_dword v169, v[144:145], off offset:640
	global_load_dword v170, v[144:145], off offset:704
	v_lshl_or_b32 v144, s1, 8, v150
	v_ashrrev_i32_e32 v145, 31, v144
	v_lshlrev_b64 v[160:161], 10, v[146:147]
	v_lshlrev_b64 v[162:163], 1, v[144:145]
	v_lshl_add_u64 v[144:145], s[92:93], 0, v[160:161]
	v_or_b32_e32 v156, 16, v146
	v_ashrrev_i32_e32 v157, 31, v156
	v_or_b32_e32 v158, 32, v146
	v_lshlrev_b64 v[156:157], 10, v[156:157]
	v_lshl_add_u64 v[144:145], v[144:145], 0, v[162:163]
	v_ashrrev_i32_e32 v159, 31, v158
	v_lshl_add_u64 v[156:157], s[92:93], 0, v[156:157]
	v_lshlrev_b64 v[158:159], 10, v[158:159]
	v_lshl_add_u64 v[156:157], v[156:157], 0, v[162:163]
	v_lshl_add_u64 v[158:159], s[92:93], 0, v[158:159]
	v_lshl_add_u64 v[158:159], v[158:159], 0, v[162:163]
	s_mov_b64 s[36:37], s[34:35]
	s_waitcnt vmcnt(0)
	v_fmamk_f32 v147, v155, 0x3a800000, v154
	v_fmamk_f32 v155, v164, 0x3a800000, v154
	v_fmamk_f32 v160, v165, 0x3a800000, v154
	v_mul_f32_e32 v161, 0x4b800000, v147
	v_mul_f32_e32 v164, 0x4b800000, v155
	v_cmp_gt_f32_e32 vcc, s58, v147
	v_cmp_gt_f32_e64 s[0:1], s58, v155
	v_mul_f32_e32 v165, 0x4b800000, v160
	v_cndmask_b32_e32 v147, v147, v161, vcc
	v_cndmask_b32_e64 v155, v155, v164, s[0:1]
	v_cmp_gt_f32_e64 s[2:3], s58, v160
	v_rsq_f32_e32 v147, v147
	v_rsq_f32_e32 v155, v155
	v_cndmask_b32_e64 v160, v160, v165, s[2:3]
	v_rsq_f32_e32 v160, v160
	v_mul_f32_e32 v161, 0x45800000, v147
	v_mul_f32_e32 v164, 0x45800000, v155
	v_cndmask_b32_e32 v147, v147, v161, vcc
	v_mul_f32_e32 v165, 0x45800000, v160
	v_cndmask_b32_e64 v155, v155, v164, s[0:1]
	v_cndmask_b32_e64 v161, v160, v165, s[2:3]
	v_mul_f32_e32 v160, 0x3e0293ee, v147
	v_mul_f32_e32 v164, 0x3e0293ee, v155
	v_fmamk_f32 v171, v166, 0x3a800000, v154
	v_mul_f32_e32 v166, 0x3e0293ee, v161
	v_pk_mul_f32 v[126:127], v[126:127], v[160:161] op_sel_hi:[1,0]
	v_pk_mul_f32 v[124:125], v[124:125], v[160:161] op_sel_hi:[1,0]
	v_pk_mul_f32 v[122:123], v[122:123], v[160:161] op_sel_hi:[1,0]
	v_pk_mul_f32 v[120:121], v[120:121], v[160:161] op_sel_hi:[1,0]
	v_pk_mul_f32 v[110:111], v[110:111], v[160:161] op_sel_hi:[1,0]
	v_pk_mul_f32 v[108:109], v[108:109], v[160:161] op_sel_hi:[1,0]
	v_pk_mul_f32 v[102:103], v[102:103], v[160:161] op_sel_hi:[1,0]
	v_pk_mul_f32 v[100:101], v[100:101], v[160:161] op_sel_hi:[1,0]
	v_pk_mul_f32 v[118:119], v[118:119], v[164:165] op_sel_hi:[1,0]
	v_pk_mul_f32 v[116:117], v[116:117], v[164:165] op_sel_hi:[1,0]
	v_pk_mul_f32 v[114:115], v[114:115], v[164:165] op_sel_hi:[1,0]
	v_pk_mul_f32 v[112:113], v[112:113], v[164:165] op_sel_hi:[1,0]
	v_pk_mul_f32 v[94:95], v[94:95], v[164:165] op_sel_hi:[1,0]
	v_pk_mul_f32 v[92:93], v[92:93], v[164:165] op_sel_hi:[1,0]
	v_pk_mul_f32 v[160:161], v[90:91], v[164:165] op_sel_hi:[1,0]
	v_pk_mul_f32 v[164:165], v[88:89], v[164:165] op_sel_hi:[1,0]
	v_cvt_pk_bf16_f32 v88, v124, v125
	v_cvt_pk_bf16_f32 v89, v126, v127
	v_cvt_pk_bf16_f32 v90, v120, v121
	v_cvt_pk_bf16_f32 v91, v122, v123
	global_store_dwordx4 v[144:145], v[88:91], off
	v_fmamk_f32 v167, v167, 0x3a800000, v154
	v_pk_mul_f32 v[106:107], v[106:107], v[166:167] op_sel_hi:[1,0]
	v_cvt_pk_bf16_f32 v88, v108, v109
	v_cvt_pk_bf16_f32 v89, v110, v111
	v_cvt_pk_bf16_f32 v90, v100, v101
	v_cvt_pk_bf16_f32 v91, v102, v103
	global_store_dwordx4 v[144:145], v[88:91], off offset:256
	v_pk_mul_f32 v[104:105], v[104:105], v[166:167] op_sel_hi:[1,0]
	v_pk_mul_f32 v[98:99], v[98:99], v[166:167] op_sel_hi:[1,0]
	v_cvt_pk_bf16_f32 v88, v116, v117
	v_cvt_pk_bf16_f32 v89, v118, v119
	v_cvt_pk_bf16_f32 v90, v112, v113
	v_cvt_pk_bf16_f32 v91, v114, v115
	global_store_dwordx4 v[156:157], v[88:91], off
	v_pk_mul_f32 v[96:97], v[96:97], v[166:167] op_sel_hi:[1,0]
	v_pk_mul_f32 v[86:87], v[86:87], v[166:167] op_sel_hi:[1,0]
	v_cvt_pk_bf16_f32 v88, v92, v93
	v_cvt_pk_bf16_f32 v89, v94, v95
	v_cvt_pk_bf16_f32 v90, v164, v165
	v_cvt_pk_bf16_f32 v91, v160, v161
	global_store_dwordx4 v[156:157], v[88:91], off offset:256
	v_pk_mul_f32 v[84:85], v[84:85], v[166:167] op_sel_hi:[1,0]
	v_cmp_gt_f32_e32 vcc, s58, v171
	v_cvt_pk_bf16_f32 v88, v104, v105
	v_cvt_pk_bf16_f32 v89, v106, v107
	v_cvt_pk_bf16_f32 v90, v96, v97
	v_cvt_pk_bf16_f32 v91, v98, v99
	global_store_dwordx4 v[158:159], v[88:91], off
	v_fmamk_f32 v168, v168, 0x3a800000, v154
	v_fmamk_f32 v169, v169, 0x3a800000, v154
	v_pk_mul_f32 v[88:89], v[82:83], v[166:167] op_sel_hi:[1,0]
	v_pk_mul_f32 v[82:83], v[80:81], v[166:167] op_sel_hi:[1,0]
	v_cvt_pk_bf16_f32 v80, v84, v85
	v_cvt_pk_bf16_f32 v81, v86, v87
	v_fmamk_f32 v170, v170, 0x3a800000, v154
	v_cvt_pk_bf16_f32 v82, v82, v83
	v_cvt_pk_bf16_f32 v83, v88, v89
	global_store_dwordx4 v[158:159], v[80:83], off offset:256
	s_mov_b32 s1, s26
	s_mov_b32 s0, s28
	v_mul_f32_e32 v82, 0x4b800000, v171
	v_cndmask_b32_e32 v82, v171, v82, vcc
	v_rsq_f32_e32 v82, v82
	v_or_b32_e32 v80, 48, v146
	v_ashrrev_i32_e32 v81, 31, v80
	v_lshlrev_b64 v[80:81], 10, v[80:81]
	v_mul_f32_e32 v83, 0x45800000, v82
	v_cndmask_b32_e32 v82, v82, v83, vcc
	v_lshl_add_u64 v[80:81], s[92:93], 0, v[80:81]
	v_mul_f32_e32 v82, 0x3e0293ee, v82
	v_lshl_add_u64 v[80:81], v[80:81], 0, v[162:163]
	v_pk_mul_f32 v[78:79], v[78:79], v[82:83] op_sel_hi:[1,0]
	v_pk_mul_f32 v[76:77], v[76:77], v[82:83] op_sel_hi:[1,0]
	v_pk_mul_f32 v[84:85], v[74:75], v[82:83] op_sel_hi:[1,0]
	v_pk_mul_f32 v[74:75], v[72:73], v[82:83] op_sel_hi:[1,0]
	v_cvt_pk_bf16_f32 v72, v76, v77
	v_cvt_pk_bf16_f32 v73, v78, v79
	v_pk_mul_f32 v[70:71], v[70:71], v[82:83] op_sel_hi:[1,0]
	v_cvt_pk_bf16_f32 v74, v74, v75
	v_cvt_pk_bf16_f32 v75, v84, v85
	global_store_dwordx4 v[80:81], v[72:75], off
	v_pk_mul_f32 v[68:69], v[68:69], v[82:83] op_sel_hi:[1,0]
	v_cmp_gt_f32_e32 vcc, s58, v167
	v_pk_mul_f32 v[72:73], v[66:67], v[82:83] op_sel_hi:[1,0]
	v_pk_mul_f32 v[66:67], v[64:65], v[82:83] op_sel_hi:[1,0]
	v_cvt_pk_bf16_f32 v64, v68, v69
	v_cvt_pk_bf16_f32 v65, v70, v71
	s_mov_b64 s[2:3], s[30:31]
	v_cvt_pk_bf16_f32 v66, v66, v67
	v_mul_f32_e32 v67, 0x4b800000, v167
	v_cndmask_b32_e32 v67, v167, v67, vcc
	v_rsq_f32_e32 v68, v67
	v_cvt_pk_bf16_f32 v67, v72, v73
	global_store_dwordx4 v[80:81], v[64:67], off offset:256
	s_nop 1
	v_mul_f32_e32 v66, 0x45800000, v68
	v_cndmask_b32_e32 v66, v68, v66, vcc
	v_mul_f32_e32 v66, 0x3e0293ee, v66
	v_pk_mul_f32 v[60:61], v[60:61], v[66:67] op_sel_hi:[1,0]
	v_pk_mul_f32 v[68:69], v[58:59], v[66:67] op_sel_hi:[1,0]
	v_pk_mul_f32 v[58:59], v[56:57], v[66:67] op_sel_hi:[1,0]
	v_cvt_pk_bf16_f32 v56, v60, v61
	v_add_co_u32_e32 v60, vcc, s59, v144
	v_pk_mul_f32 v[62:63], v[62:63], v[66:67] op_sel_hi:[1,0]
	s_nop 0
	v_addc_co_u32_e32 v61, vcc, 0, v145, vcc
	v_cvt_pk_bf16_f32 v57, v62, v63
	v_cvt_pk_bf16_f32 v58, v58, v59
	v_cvt_pk_bf16_f32 v59, v68, v69
	global_store_dwordx4 v[60:61], v[56:59], off
	v_pk_mul_f32 v[54:55], v[54:55], v[66:67] op_sel_hi:[1,0]
	v_pk_mul_f32 v[52:53], v[52:53], v[66:67] op_sel_hi:[1,0]
	v_pk_mul_f32 v[56:57], v[50:51], v[66:67] op_sel_hi:[1,0]
	v_pk_mul_f32 v[50:51], v[48:49], v[66:67] op_sel_hi:[1,0]
	v_cvt_pk_bf16_f32 v48, v52, v53
	v_cvt_pk_bf16_f32 v49, v54, v55
	v_cmp_gt_f32_e32 vcc, s58, v168
	v_cvt_pk_bf16_f32 v50, v50, v51
	v_mul_f32_e32 v51, 0x4b800000, v168
	v_lshl_add_u64 v[64:65], v[144:145], 0, s[14:15]
	v_cndmask_b32_e32 v51, v168, v51, vcc
	v_rsq_f32_e32 v52, v51
	v_cvt_pk_bf16_f32 v51, v56, v57
	global_store_dwordx4 v[64:65], v[48:51], off offset:256
	s_nop 1
	v_mul_f32_e32 v50, 0x45800000, v52
	v_cndmask_b32_e32 v50, v52, v50, vcc
	v_mul_f32_e32 v50, 0x3e0293ee, v50
	v_pk_mul_f32 v[44:45], v[44:45], v[50:51] op_sel_hi:[1,0]
	v_pk_mul_f32 v[52:53], v[42:43], v[50:51] op_sel_hi:[1,0]
	v_pk_mul_f32 v[42:43], v[40:41], v[50:51] op_sel_hi:[1,0]
	v_cvt_pk_bf16_f32 v40, v44, v45
	v_add_co_u32_e32 v44, vcc, s60, v144
	v_pk_mul_f32 v[46:47], v[46:47], v[50:51] op_sel_hi:[1,0]
	s_nop 0
	v_addc_co_u32_e32 v45, vcc, 0, v145, vcc
	v_cvt_pk_bf16_f32 v41, v46, v47
	v_cvt_pk_bf16_f32 v42, v42, v43
	v_cvt_pk_bf16_f32 v43, v52, v53
	global_store_dwordx4 v[44:45], v[40:43], off
	v_pk_mul_f32 v[38:39], v[38:39], v[50:51] op_sel_hi:[1,0]
	v_pk_mul_f32 v[36:37], v[36:37], v[50:51] op_sel_hi:[1,0]
	v_pk_mul_f32 v[40:41], v[34:35], v[50:51] op_sel_hi:[1,0]
	v_pk_mul_f32 v[34:35], v[32:33], v[50:51] op_sel_hi:[1,0]
	v_cvt_pk_bf16_f32 v32, v36, v37
	v_cvt_pk_bf16_f32 v33, v38, v39
	v_cmp_gt_f32_e32 vcc, s58, v169
	v_cvt_pk_bf16_f32 v34, v34, v35
	v_mul_f32_e32 v35, 0x4b800000, v169
	v_lshl_add_u64 v[48:49], v[144:145], 0, s[20:21]
	v_cndmask_b32_e32 v35, v169, v35, vcc
	v_rsq_f32_e32 v36, v35
	v_cvt_pk_bf16_f32 v35, v40, v41
	global_store_dwordx4 v[48:49], v[32:35], off offset:256
	s_nop 1
	v_mul_f32_e32 v34, 0x45800000, v36
	v_cndmask_b32_e32 v34, v36, v34, vcc
	v_mul_f32_e32 v34, 0x3e0293ee, v34
	v_pk_mul_f32 v[28:29], v[28:29], v[34:35] op_sel_hi:[1,0]
	v_pk_mul_f32 v[36:37], v[26:27], v[34:35] op_sel_hi:[1,0]
	v_pk_mul_f32 v[26:27], v[24:25], v[34:35] op_sel_hi:[1,0]
	v_cvt_pk_bf16_f32 v24, v28, v29
	v_add_co_u32_e32 v28, vcc, s61, v144
	v_pk_mul_f32 v[30:31], v[30:31], v[34:35] op_sel_hi:[1,0]
	s_nop 0
	v_addc_co_u32_e32 v29, vcc, 0, v145, vcc
	v_cvt_pk_bf16_f32 v25, v30, v31
	v_cvt_pk_bf16_f32 v26, v26, v27
	v_cvt_pk_bf16_f32 v27, v36, v37
	global_store_dwordx4 v[28:29], v[24:27], off
	v_pk_mul_f32 v[22:23], v[22:23], v[34:35] op_sel_hi:[1,0]
	v_pk_mul_f32 v[20:21], v[20:21], v[34:35] op_sel_hi:[1,0]
	v_pk_mul_f32 v[24:25], v[18:19], v[34:35] op_sel_hi:[1,0]
	v_pk_mul_f32 v[18:19], v[16:17], v[34:35] op_sel_hi:[1,0]
	v_cvt_pk_bf16_f32 v16, v20, v21
	v_cvt_pk_bf16_f32 v17, v22, v23
	v_cmp_gt_f32_e32 vcc, s58, v170
	v_cvt_pk_bf16_f32 v18, v18, v19
	v_mul_f32_e32 v19, 0x4b800000, v170
	v_lshl_add_u64 v[32:33], v[144:145], 0, s[22:23]
	v_cndmask_b32_e32 v19, v170, v19, vcc
	v_rsq_f32_e32 v20, v19
	v_cvt_pk_bf16_f32 v19, v24, v25
	global_store_dwordx4 v[32:33], v[16:19], off offset:256
	s_nop 1
	v_mul_f32_e32 v18, 0x45800000, v20
	v_cndmask_b32_e32 v18, v20, v18, vcc
	v_mul_f32_e32 v18, 0x3e0293ee, v18
	v_pk_mul_f32 v[12:13], v[12:13], v[18:19] op_sel_hi:[1,0]
	v_pk_mul_f32 v[20:21], v[10:11], v[18:19] op_sel_hi:[1,0]
	v_pk_mul_f32 v[10:11], v[8:9], v[18:19] op_sel_hi:[1,0]
	v_cvt_pk_bf16_f32 v8, v12, v13
	v_add_co_u32_e32 v12, vcc, s62, v144
	v_pk_mul_f32 v[14:15], v[14:15], v[18:19] op_sel_hi:[1,0]
	s_nop 0
	v_addc_co_u32_e32 v13, vcc, 0, v145, vcc
	v_cvt_pk_bf16_f32 v9, v14, v15
	v_lshl_add_u64 v[16:17], v[144:145], 0, s[24:25]
	v_cvt_pk_bf16_f32 v10, v10, v11
	v_cvt_pk_bf16_f32 v11, v20, v21
	global_store_dwordx4 v[12:13], v[8:11], off
	s_and_b64 vcc, exec, s[6:7]
	v_pk_mul_f32 v[6:7], v[6:7], v[18:19] op_sel_hi:[1,0]
	v_pk_mul_f32 v[8:9], v[2:3], v[18:19] op_sel_hi:[1,0]
	v_pk_mul_f32 v[2:3], v[0:1], v[18:19] op_sel_hi:[1,0]
	v_pk_mul_f32 v[4:5], v[4:5], v[18:19] op_sel_hi:[1,0]
	s_nop 0
	v_cvt_pk_bf16_f32 v0, v4, v5
	v_cvt_pk_bf16_f32 v1, v6, v7
	v_cvt_pk_bf16_f32 v2, v2, v3
	v_cvt_pk_bf16_f32 v3, v8, v9
	global_store_dwordx4 v[16:17], v[0:3], off offset:256
	s_cbranch_vccz .LBB0_1073
	s_waitcnt vmcnt(0)
	s_cmpk_gt_u32 s33, 0xff
	s_cbranch_scc1 .LBB0_1084
	s_barrier

.LBB0_1160:
	ds_read_b128 v[144:147], v178
	ds_read_b128 v[148:151], v178 offset:1024
	ds_read_b128 v[152:155], v178 offset:2048
	ds_read_b128 v[156:159], v178 offset:3072
	s_add_u32 s38, s36, 0xfffe0080
	s_addc_u32 s39, s37, -1
	s_cmp_eq_u32 s62, 4
	s_cselect_b32 s41, s25, s39
	s_cselect_b32 s40, s31, s38
	s_cselect_b32 s39, s23, s61
	s_cselect_b32 s38, s59, s60
	v_lshl_add_u64 v[172:173], s[36:37], 0, v[136:137]
	s_add_i32 m0, s35, 0xc000
	ds_read_b128 v[160:163], v179
	ds_read_b128 v[164:167], v179 offset:1024
	ds_read_b128 v[168:171], v179 offset:2048
	ds_read_b128 v[182:185], v179 offset:3072
	ds_read_b128 v[186:189], v179 offset:4096
	ds_read_b128 v[190:193], v179 offset:5120
	ds_read_b128 v[194:197], v179 offset:6144
	ds_read_b128 v[198:201], v179 offset:7168
	global_load_lds_dwordx4 v[172:173], off
	v_lshl_add_u64 v[172:173], s[36:37], 0, v[138:139]
	s_add_i32 m0, s35, 0xe000
	s_nop 0
	global_load_lds_dwordx4 v[172:173], off
	s_waitcnt lgkmcnt(8)
	s_setprio 1
	s_barrier
	s_waitcnt lgkmcnt(0)
	v_mfma_f32_16x16x32_bf16 v[124:127], v[144:147], v[160:163], v[124:127]
	v_mfma_f32_16x16x32_bf16 v[120:123], v[152:155], v[160:163], v[120:123]
	v_mfma_f32_16x16x32_bf16 v[108:111], v[144:147], v[168:171], v[108:111]
	v_mfma_f32_16x16x32_bf16 v[104:107], v[152:155], v[168:171], v[104:107]
	v_mfma_f32_16x16x32_bf16 v[96:99], v[144:147], v[186:189], v[96:99]
	v_mfma_f32_16x16x32_bf16 v[88:91], v[152:155], v[186:189], v[88:91]
	v_mfma_f32_16x16x32_bf16 v[80:83], v[144:147], v[194:197], v[80:83]
	v_mfma_f32_16x16x32_bf16 v[72:75], v[152:155], v[194:197], v[72:75]
	v_mfma_f32_16x16x32_bf16 v[124:127], v[148:151], v[164:167], v[124:127]
	v_mfma_f32_16x16x32_bf16 v[120:123], v[156:159], v[164:167], v[120:123]
	v_mfma_f32_16x16x32_bf16 v[108:111], v[148:151], v[182:185], v[108:111]
	v_mfma_f32_16x16x32_bf16 v[104:107], v[156:159], v[182:185], v[104:107]
	v_mfma_f32_16x16x32_bf16 v[96:99], v[148:151], v[190:193], v[96:99]
	v_mfma_f32_16x16x32_bf16 v[88:91], v[156:159], v[190:193], v[88:91]
	v_mfma_f32_16x16x32_bf16 v[80:83], v[148:151], v[198:201], v[80:83]
	v_mfma_f32_16x16x32_bf16 v[72:75], v[156:159], v[198:201], v[72:75]
	s_setprio 0
	s_barrier
	s_add_i32 s63, s57, s48
	v_lshl_add_u64 v[172:173], s[38:39], 0, v[130:131]
	s_mov_b32 m0, s63
	ds_read_b128 v[202:205], v180
	ds_read_b128 v[206:209], v180 offset:1024
	ds_read_b128 v[212:215], v180 offset:2048
	ds_read_b128 v[216:219], v180 offset:3072
	global_load_lds_dwordx4 v[172:173], off
	v_lshl_add_u64 v[220:221], s[38:39], 0, v[134:135]
	s_add_i32 m0, s63, 0x2000
	s_nop 0
	global_load_lds_dwordx4 v[220:221], off
	s_setprio 1
	s_barrier
	s_waitcnt lgkmcnt(0)
	v_mfma_f32_16x16x32_bf16 v[116:119], v[202:205], v[160:163], v[116:119]
	v_mfma_f32_16x16x32_bf16 v[112:115], v[212:215], v[160:163], v[112:115]
	v_mfma_f32_16x16x32_bf16 v[100:103], v[202:205], v[168:171], v[100:103]
	v_mfma_f32_16x16x32_bf16 v[92:95], v[212:215], v[168:171], v[92:95]
	v_mfma_f32_16x16x32_bf16 v[84:87], v[202:205], v[186:189], v[84:87]
	v_mfma_f32_16x16x32_bf16 v[76:79], v[212:215], v[186:189], v[76:79]
	v_mfma_f32_16x16x32_bf16 v[68:71], v[202:205], v[194:197], v[68:71]
	v_mfma_f32_16x16x32_bf16 v[64:67], v[212:215], v[194:197], v[64:67]
	v_mfma_f32_16x16x32_bf16 v[116:119], v[206:209], v[164:167], v[116:119]
	v_mfma_f32_16x16x32_bf16 v[112:115], v[216:219], v[164:167], v[112:115]
	v_mfma_f32_16x16x32_bf16 v[100:103], v[206:209], v[182:185], v[100:103]
	v_mfma_f32_16x16x32_bf16 v[92:95], v[216:219], v[182:185], v[92:95]
	v_mfma_f32_16x16x32_bf16 v[84:87], v[206:209], v[190:193], v[84:87]
	v_mfma_f32_16x16x32_bf16 v[76:79], v[216:219], v[190:193], v[76:79]
	v_mfma_f32_16x16x32_bf16 v[68:71], v[206:209], v[198:201], v[68:71]
	v_mfma_f32_16x16x32_bf16 v[64:67], v[216:219], v[198:201], v[64:67]
	s_setprio 0
	s_mov_b32 m0, s35
	v_lshl_add_u64 v[222:223], s[40:41], 0, v[128:129]
	s_barrier
	ds_read_b128 v[160:163], v179 offset:16384
	ds_read_b128 v[164:167], v179 offset:17408
	ds_read_b128 v[168:171], v179 offset:18432
	ds_read_b128 v[182:185], v179 offset:19456
	ds_read_b128 v[186:189], v179 offset:20480
	ds_read_b128 v[190:193], v179 offset:21504
	ds_read_b128 v[194:197], v179 offset:22528
	ds_read_b128 v[198:201], v179 offset:23552
	global_load_lds_dwordx4 v[222:223], off
	v_lshl_add_u64 v[224:225], s[40:41], 0, v[132:133]
	s_mov_b32 m0, s49
	s_nop 0
	global_load_lds_dwordx4 v[224:225], off
	s_setprio 1
	s_barrier
	s_waitcnt lgkmcnt(0)
	v_mfma_f32_16x16x32_bf16 v[60:63], v[144:147], v[160:163], v[60:63]
	v_mfma_f32_16x16x32_bf16 v[56:59], v[152:155], v[160:163], v[56:59]
	v_mfma_f32_16x16x32_bf16 v[44:47], v[144:147], v[168:171], v[44:47]
	v_mfma_f32_16x16x32_bf16 v[40:43], v[152:155], v[168:171], v[40:43]
	v_mfma_f32_16x16x32_bf16 v[32:35], v[144:147], v[186:189], v[32:35]
	v_mfma_f32_16x16x32_bf16 v[24:27], v[152:155], v[186:189], v[24:27]
	v_mfma_f32_16x16x32_bf16 v[16:19], v[144:147], v[194:197], v[16:19]
	v_mfma_f32_16x16x32_bf16 v[8:11], v[152:155], v[194:197], v[8:11]
	v_mfma_f32_16x16x32_bf16 v[60:63], v[148:151], v[164:167], v[60:63]
	v_mfma_f32_16x16x32_bf16 v[56:59], v[156:159], v[164:167], v[56:59]
	v_mfma_f32_16x16x32_bf16 v[44:47], v[148:151], v[182:185], v[44:47]
	v_mfma_f32_16x16x32_bf16 v[40:43], v[156:159], v[182:185], v[40:43]
	v_mfma_f32_16x16x32_bf16 v[32:35], v[148:151], v[190:193], v[32:35]
	v_mfma_f32_16x16x32_bf16 v[24:27], v[156:159], v[190:193], v[24:27]
	v_mfma_f32_16x16x32_bf16 v[16:19], v[148:151], v[198:201], v[16:19]
	v_mfma_f32_16x16x32_bf16 v[8:11], v[156:159], v[198:201], v[8:11]
	s_setprio 0
	s_barrier
	s_add_u32 s64, s38, 0x20000
	s_addc_u32 s65, s39, 0
	s_add_i32 s63, s58, s48
	v_lshl_add_u64 v[144:145], s[64:65], 0, v[130:131]
	s_mov_b32 m0, s63
	s_nop 0
	global_load_lds_dwordx4 v[144:145], off
	v_lshl_add_u64 v[144:145], s[64:65], 0, v[134:135]
	s_add_i32 m0, s63, 0x2000
	s_nop 0
	global_load_lds_dwordx4 v[144:145], off
	s_waitcnt vmcnt(6)
	s_setprio 1
	s_barrier
	v_mfma_f32_16x16x32_bf16 v[52:55], v[202:205], v[160:163], v[52:55]
	v_mfma_f32_16x16x32_bf16 v[48:51], v[212:215], v[160:163], v[48:51]
	v_mfma_f32_16x16x32_bf16 v[36:39], v[202:205], v[168:171], v[36:39]
	v_mfma_f32_16x16x32_bf16 v[28:31], v[212:215], v[168:171], v[28:31]
	v_mfma_f32_16x16x32_bf16 v[20:23], v[202:205], v[186:189], v[20:23]
	v_mfma_f32_16x16x32_bf16 v[12:15], v[212:215], v[186:189], v[12:15]
	v_mfma_f32_16x16x32_bf16 v[4:7], v[202:205], v[194:197], v[4:7]
	v_mfma_f32_16x16x32_bf16 v[0:3], v[212:215], v[194:197], v[0:3]
	v_mfma_f32_16x16x32_bf16 v[52:55], v[206:209], v[164:167], v[52:55]
	v_mfma_f32_16x16x32_bf16 v[48:51], v[216:219], v[164:167], v[48:51]
	v_mfma_f32_16x16x32_bf16 v[36:39], v[206:209], v[182:185], v[36:39]
	v_mfma_f32_16x16x32_bf16 v[28:31], v[216:219], v[182:185], v[28:31]
	v_mfma_f32_16x16x32_bf16 v[20:23], v[206:209], v[190:193], v[20:23]
	v_mfma_f32_16x16x32_bf16 v[12:15], v[216:219], v[190:193], v[12:15]
	v_mfma_f32_16x16x32_bf16 v[4:7], v[206:209], v[198:201], v[4:7]
	v_mfma_f32_16x16x32_bf16 v[0:3], v[216:219], v[198:201], v[0:3]
	s_setprio 0
	s_add_i32 s63, 0, 0x18000
	v_add_u32_e32 v156, s63, v176
	s_barrier
	ds_read_b128 v[144:147], v156
	ds_read_b128 v[148:151], v156 offset:1024
	ds_read_b128 v[152:155], v156 offset:2048
	ds_read_b128 v[156:159], v156 offset:3072
	s_add_u32 s40, s40, 0x20000
	s_addc_u32 s41, s41, 0
	s_mov_b32 m0, s50
	v_lshl_add_u64 v[202:203], s[40:41], 0, v[128:129]
	ds_read_b128 v[160:163], v179 offset:32768
	ds_read_b128 v[164:167], v179 offset:33792
	ds_read_b128 v[168:171], v179 offset:34816
	ds_read_b128 v[182:185], v179 offset:35840
	ds_read_b128 v[186:189], v179 offset:36864
	ds_read_b128 v[190:193], v179 offset:37888
	ds_read_b128 v[194:197], v179 offset:38912
	ds_read_b128 v[198:201], v179 offset:39936
	global_load_lds_dwordx4 v[202:203], off
	v_lshl_add_u64 v[202:203], s[40:41], 0, v[132:133]
	s_mov_b32 m0, s51
	s_nop 0
	global_load_lds_dwordx4 v[202:203], off
	s_waitcnt lgkmcnt(8)
	s_setprio 1
	s_barrier
	s_waitcnt lgkmcnt(0)
	v_mfma_f32_16x16x32_bf16 v[124:127], v[144:147], v[160:163], v[124:127]
	v_mfma_f32_16x16x32_bf16 v[120:123], v[152:155], v[160:163], v[120:123]
	v_mfma_f32_16x16x32_bf16 v[108:111], v[144:147], v[168:171], v[108:111]
	v_mfma_f32_16x16x32_bf16 v[104:107], v[152:155], v[168:171], v[104:107]
	v_mfma_f32_16x16x32_bf16 v[96:99], v[144:147], v[186:189], v[96:99]
	v_mfma_f32_16x16x32_bf16 v[88:91], v[152:155], v[186:189], v[88:91]
	v_mfma_f32_16x16x32_bf16 v[80:83], v[144:147], v[194:197], v[80:83]
	v_mfma_f32_16x16x32_bf16 v[72:75], v[152:155], v[194:197], v[72:75]
	v_mfma_f32_16x16x32_bf16 v[124:127], v[148:151], v[164:167], v[124:127]
	v_mfma_f32_16x16x32_bf16 v[120:123], v[156:159], v[164:167], v[120:123]
	v_mfma_f32_16x16x32_bf16 v[108:111], v[148:151], v[182:185], v[108:111]
	v_mfma_f32_16x16x32_bf16 v[104:107], v[156:159], v[182:185], v[104:107]
	v_mfma_f32_16x16x32_bf16 v[96:99], v[148:151], v[190:193], v[96:99]
	v_mfma_f32_16x16x32_bf16 v[88:91], v[156:159], v[190:193], v[88:91]
	v_mfma_f32_16x16x32_bf16 v[80:83], v[148:151], v[198:201], v[80:83]
	v_mfma_f32_16x16x32_bf16 v[72:75], v[156:159], v[198:201], v[72:75]
	s_setprio 0
	s_barrier
	s_add_i32 s40, 0, 0x1c000
	s_add_i32 s41, s63, s48
	v_add_u32_e32 v181, s40, v176
	v_lshl_add_u64 v[172:173], v[172:173], 0, s[0:1]
	s_mov_b32 m0, s41
	ds_read_b128 v[202:205], v181
	ds_read_b128 v[206:209], v181 offset:1024
	ds_read_b128 v[212:215], v181 offset:2048
	ds_read_b128 v[216:219], v181 offset:3072
	global_load_lds_dwordx4 v[172:173], off
	v_lshl_add_u64 v[172:173], v[220:221], 0, s[0:1]
	s_add_i32 m0, s41, 0x2000
	s_nop 0
	global_load_lds_dwordx4 v[172:173], off
	s_setprio 1
	s_barrier
	s_waitcnt lgkmcnt(0)
	v_mfma_f32_16x16x32_bf16 v[116:119], v[202:205], v[160:163], v[116:119]
	v_mfma_f32_16x16x32_bf16 v[112:115], v[212:215], v[160:163], v[112:115]
	v_mfma_f32_16x16x32_bf16 v[100:103], v[202:205], v[168:171], v[100:103]
	v_mfma_f32_16x16x32_bf16 v[92:95], v[212:215], v[168:171], v[92:95]
	v_mfma_f32_16x16x32_bf16 v[84:87], v[202:205], v[186:189], v[84:87]
	v_mfma_f32_16x16x32_bf16 v[76:79], v[212:215], v[186:189], v[76:79]
	v_mfma_f32_16x16x32_bf16 v[68:71], v[202:205], v[194:197], v[68:71]
	v_mfma_f32_16x16x32_bf16 v[64:67], v[212:215], v[194:197], v[64:67]
	v_mfma_f32_16x16x32_bf16 v[116:119], v[206:209], v[164:167], v[116:119]
	v_mfma_f32_16x16x32_bf16 v[112:115], v[216:219], v[164:167], v[112:115]
	v_mfma_f32_16x16x32_bf16 v[100:103], v[206:209], v[182:185], v[100:103]
	v_mfma_f32_16x16x32_bf16 v[92:95], v[216:219], v[182:185], v[92:95]
	v_mfma_f32_16x16x32_bf16 v[84:87], v[206:209], v[190:193], v[84:87]
	v_mfma_f32_16x16x32_bf16 v[76:79], v[216:219], v[190:193], v[76:79]
	v_mfma_f32_16x16x32_bf16 v[68:71], v[206:209], v[198:201], v[68:71]
	v_mfma_f32_16x16x32_bf16 v[64:67], v[216:219], v[198:201], v[64:67]
	s_setprio 0
	s_mov_b32 m0, s53
	v_lshl_add_u64 v[172:173], v[222:223], 0, s[0:1]
	s_barrier
	ds_read_b128 v[160:163], v179 offset:49152
	ds_read_b128 v[164:167], v179 offset:50176
	ds_read_b128 v[168:171], v179 offset:51200
	ds_read_b128 v[182:185], v179 offset:52224
	ds_read_b128 v[186:189], v179 offset:53248
	ds_read_b128 v[190:193], v179 offset:54272
	ds_read_b128 v[194:197], v179 offset:55296
	ds_read_b128 v[198:201], v179 offset:56320
	global_load_lds_dwordx4 v[172:173], off
	v_lshl_add_u64 v[172:173], v[224:225], 0, s[0:1]
	s_mov_b32 m0, s54
	s_nop 0
	global_load_lds_dwordx4 v[172:173], off
	s_setprio 1
	s_barrier
	s_waitcnt lgkmcnt(0)
	v_mfma_f32_16x16x32_bf16 v[60:63], v[144:147], v[160:163], v[60:63]
	v_mfma_f32_16x16x32_bf16 v[56:59], v[152:155], v[160:163], v[56:59]
	v_mfma_f32_16x16x32_bf16 v[44:47], v[144:147], v[168:171], v[44:47]
	v_mfma_f32_16x16x32_bf16 v[40:43], v[152:155], v[168:171], v[40:43]
	v_mfma_f32_16x16x32_bf16 v[32:35], v[144:147], v[186:189], v[32:35]
	v_mfma_f32_16x16x32_bf16 v[24:27], v[152:155], v[186:189], v[24:27]
	v_mfma_f32_16x16x32_bf16 v[16:19], v[144:147], v[194:197], v[16:19]
	v_mfma_f32_16x16x32_bf16 v[8:11], v[152:155], v[194:197], v[8:11]
	v_mfma_f32_16x16x32_bf16 v[60:63], v[148:151], v[164:167], v[60:63]
	v_mfma_f32_16x16x32_bf16 v[56:59], v[156:159], v[164:167], v[56:59]
	v_mfma_f32_16x16x32_bf16 v[44:47], v[148:151], v[182:185], v[44:47]
	v_mfma_f32_16x16x32_bf16 v[40:43], v[156:159], v[182:185], v[40:43]
	v_mfma_f32_16x16x32_bf16 v[32:35], v[148:151], v[190:193], v[32:35]
	v_mfma_f32_16x16x32_bf16 v[24:27], v[156:159], v[190:193], v[24:27]
	v_mfma_f32_16x16x32_bf16 v[16:19], v[148:151], v[198:201], v[16:19]
	v_mfma_f32_16x16x32_bf16 v[8:11], v[156:159], v[198:201], v[8:11]
	s_setprio 0
	s_barrier
	s_add_u32 s38, s38, 0x20080
	s_addc_u32 s39, s39, 0
	s_add_i32 s40, s40, s48
	v_lshl_add_u64 v[144:145], s[38:39], 0, v[130:131]
	s_mov_b32 m0, s40
	s_nop 0
	global_load_lds_dwordx4 v[144:145], off
	v_lshl_add_u64 v[144:145], s[38:39], 0, v[134:135]
	s_add_i32 m0, s40, 0x2000
	s_nop 0
	global_load_lds_dwordx4 v[144:145], off
	s_waitcnt vmcnt(6)
	s_setprio 1
	s_barrier
	v_mfma_f32_16x16x32_bf16 v[52:55], v[202:205], v[160:163], v[52:55]
	v_mfma_f32_16x16x32_bf16 v[48:51], v[212:215], v[160:163], v[48:51]
	v_mfma_f32_16x16x32_bf16 v[36:39], v[202:205], v[168:171], v[36:39]
	v_mfma_f32_16x16x32_bf16 v[28:31], v[212:215], v[168:171], v[28:31]
	v_mfma_f32_16x16x32_bf16 v[20:23], v[202:205], v[186:189], v[20:23]
	v_mfma_f32_16x16x32_bf16 v[12:15], v[212:215], v[186:189], v[12:15]
	v_mfma_f32_16x16x32_bf16 v[4:7], v[202:205], v[194:197], v[4:7]
	v_mfma_f32_16x16x32_bf16 v[0:3], v[212:215], v[194:197], v[0:3]
	v_mfma_f32_16x16x32_bf16 v[52:55], v[206:209], v[164:167], v[52:55]
	v_mfma_f32_16x16x32_bf16 v[48:51], v[216:219], v[164:167], v[48:51]
	v_mfma_f32_16x16x32_bf16 v[36:39], v[206:209], v[182:185], v[36:39]
	v_mfma_f32_16x16x32_bf16 v[28:31], v[216:219], v[182:185], v[28:31]
	v_mfma_f32_16x16x32_bf16 v[20:23], v[206:209], v[190:193], v[20:23]
	v_mfma_f32_16x16x32_bf16 v[12:15], v[216:219], v[190:193], v[12:15]
	v_mfma_f32_16x16x32_bf16 v[4:7], v[206:209], v[198:201], v[4:7]
	v_mfma_f32_16x16x32_bf16 v[0:3], v[216:219], v[198:201], v[0:3]
	s_setprio 0
	s_add_i32 s62, s62, 2
	s_add_u32 s36, s36, 0x100
	s_addc_u32 s37, s37, 0
	s_add_u32 s60, s60, 0x100
	s_addc_u32 s61, s61, 0
	s_cmp_gt_u32 s62, 5
	s_barrier
	s_cbranch_scc0 .LBB0_1160
	v_lshl_or_b32 v144, s34, 8, v177
	v_lshl_add_u32 v150, s30, 8, v175
	v_ashrrev_i32_e32 v145, 31, v144
	v_ashrrev_i32_e32 v151, 31, v150
	v_lshlrev_b64 v[144:145], 1, v[144:145]
	v_lshl_add_u64 v[146:147], s[10:11], 0, v[144:145]
	v_lshlrev_b64 v[148:149], 11, v[150:151]
	v_lshl_add_u64 v[152:153], v[146:147], 0, v[148:149]
	global_load_dwordx4 v[156:159], v[152:153], off
	global_load_dwordx4 v[160:163], v[152:153], off offset:256
	v_or_b32_e32 v152, 16, v150
	v_ashrrev_i32_e32 v153, 31, v152
	v_lshlrev_b64 v[170:171], 11, v[152:153]
	v_lshl_add_u64 v[152:153], v[146:147], 0, v[170:171]
	global_load_dwordx4 v[164:167], v[152:153], off
	global_load_dwordx4 v[182:185], v[152:153], off offset:256
	v_or_b32_e32 v152, 32, v150
	v_ashrrev_i32_e32 v153, 31, v152
	v_lshlrev_b64 v[154:155], 11, v[152:153]
	v_lshl_add_u64 v[152:153], v[146:147], 0, v[154:155]
	global_load_dwordx4 v[186:189], v[152:153], off
	global_load_dwordx4 v[190:193], v[152:153], off offset:256
	v_or_b32_e32 v152, 48, v150
	v_ashrrev_i32_e32 v153, 31, v152
	v_lshlrev_b64 v[152:153], 11, v[152:153]
	v_lshl_add_u64 v[168:169], v[146:147], 0, v[152:153]
	global_load_dwordx4 v[194:197], v[168:169], off
	global_load_dwordx4 v[198:201], v[168:169], off offset:256
	s_waitcnt vmcnt(0)
	v_lshlrev_b32_e32 v202, 16, v156
	v_and_b32_e32 v203, 0xffff0000, v156
	v_lshlrev_b32_e32 v204, 16, v157
	v_and_b32_e32 v205, 0xffff0000, v157
	v_lshlrev_b32_e32 v206, 16, v158
	v_and_b32_e32 v207, 0xffff0000, v158
	v_lshlrev_b32_e32 v208, 16, v159
	v_and_b32_e32 v209, 0xffff0000, v159
	v_pk_add_f32 v[126:127], v[126:127], v[204:205]
	v_pk_add_f32 v[124:125], v[124:125], v[202:203]
	v_lshlrev_b32_e32 v224, 16, v166
	v_and_b32_e32 v225, 0xffff0000, v166
	v_lshlrev_b32_e32 v226, 16, v167
	v_and_b32_e32 v227, 0xffff0000, v167
	v_lshlrev_b32_e32 v212, 16, v160
	v_lshlrev_b32_e32 v166, 16, v194
	v_and_b32_e32 v167, 0xffff0000, v194
	v_lshlrev_b32_e32 v172, 16, v195
	v_and_b32_e32 v173, 0xffff0000, v195
	v_pk_add_f32 v[194:195], v[122:123], v[208:209]
	v_pk_add_f32 v[122:123], v[120:121], v[206:207]
	v_mul_f32_e32 v120, v125, v125
	v_mul_f32_e32 v121, v127, v127
	v_fmac_f32_e32 v120, v124, v124
	v_fmac_f32_e32 v121, v126, v126
	v_add_f32_e32 v120, v120, v121
	v_mul_f32_e32 v121, v123, v123
	v_fmac_f32_e32 v121, v122, v122
	v_add_f32_e32 v120, v121, v120
	v_mul_f32_e32 v121, v195, v195
	v_fmac_f32_e32 v121, v194, v194
	v_and_b32_e32 v213, 0xffff0000, v160
	v_lshlrev_b32_e32 v214, 16, v161
	v_and_b32_e32 v215, 0xffff0000, v161
	v_add_f32_e32 v181, v121, v120
	v_cvt_pk_bf16_f32 v120, v124, v125
	v_lshl_add_u64 v[124:125], s[90:91], 0, v[148:149]
	v_lshlrev_b32_e32 v216, 16, v162
	v_and_b32_e32 v217, 0xffff0000, v162
	v_lshlrev_b32_e32 v218, 16, v163
	v_and_b32_e32 v219, 0xffff0000, v163
	v_cvt_pk_bf16_f32 v121, v126, v127
	v_lshl_add_u64 v[124:125], v[124:125], 0, v[144:145]
	v_pk_add_f32 v[118:119], v[118:119], v[214:215]
	v_pk_add_f32 v[116:117], v[116:117], v[212:213]
	v_cvt_pk_bf16_f32 v122, v122, v123
	v_cvt_pk_bf16_f32 v123, v194, v195
	global_store_dwordx4 v[124:125], v[120:123], off
	v_lshlrev_b32_e32 v220, 16, v164
	v_and_b32_e32 v221, 0xffff0000, v164
	v_pk_add_f32 v[120:121], v[114:115], v[218:219]
	v_pk_add_f32 v[114:115], v[112:113], v[216:217]
	v_mul_f32_e32 v112, v117, v117
	v_mul_f32_e32 v113, v119, v119
	v_fmac_f32_e32 v112, v116, v116
	v_fmac_f32_e32 v113, v118, v118
	v_add_f32_e32 v112, v112, v113
	v_mul_f32_e32 v113, v115, v115
	v_fmac_f32_e32 v113, v114, v114
	v_add_f32_e32 v112, v113, v112
	v_mul_f32_e32 v113, v121, v121
	v_fmac_f32_e32 v113, v120, v120
	v_add_f32_e32 v112, v113, v112
	v_lshlrev_b32_e32 v222, 16, v165
	v_and_b32_e32 v223, 0xffff0000, v165
	v_add_f32_e32 v126, v181, v112
	v_cvt_pk_bf16_f32 v112, v116, v117
	v_cvt_pk_bf16_f32 v113, v118, v119
	v_lshl_add_u64 v[116:117], s[90:91], 0, v[170:171]
	v_lshlrev_b32_e32 v230, 16, v184
	v_and_b32_e32 v231, 0xffff0000, v184
	v_lshlrev_b32_e32 v232, 16, v186
	v_and_b32_e32 v233, 0xffff0000, v186
	v_lshlrev_b32_e32 v186, 16, v187
	v_and_b32_e32 v187, 0xffff0000, v187
	v_cvt_pk_bf16_f32 v114, v114, v115
	v_cvt_pk_bf16_f32 v115, v120, v121
	global_store_dwordx4 v[124:125], v[112:115], off offset:256
	v_pk_add_f32 v[110:111], v[110:111], v[222:223]
	v_pk_add_f32 v[108:109], v[108:109], v[220:221]
	v_lshl_add_u64 v[118:119], v[116:117], 0, v[144:145]
	v_cvt_pk_bf16_f32 v112, v108, v109
	v_cvt_pk_bf16_f32 v113, v110, v111
	v_lshlrev_b32_e32 v228, 16, v182
	v_and_b32_e32 v229, 0xffff0000, v182
	v_lshlrev_b32_e32 v182, 16, v183
	v_and_b32_e32 v183, 0xffff0000, v183
	v_lshlrev_b32_e32 v184, 16, v185
	v_and_b32_e32 v185, 0xffff0000, v185
	v_lshlrev_b32_e32 v238, 16, v192
	v_and_b32_e32 v239, 0xffff0000, v192
	v_pk_add_f32 v[106:107], v[106:107], v[226:227]
	v_pk_add_f32 v[104:105], v[104:105], v[224:225]
	v_lshlrev_b32_e32 v156, 16, v200
	v_cvt_pk_bf16_f32 v114, v104, v105
	v_cvt_pk_bf16_f32 v115, v106, v107
	global_store_dwordx4 v[118:119], v[112:115], off
	v_and_b32_e32 v157, 0xffff0000, v200
	v_pk_add_f32 v[102:103], v[102:103], v[182:183]
	v_pk_add_f32 v[112:113], v[92:93], v[230:231]
	v_pk_add_f32 v[92:93], v[98:99], v[186:187]
	v_lshl_add_u64 v[98:99], s[90:91], 0, v[154:155]
	v_pk_add_f32 v[100:101], v[100:101], v[228:229]
	v_pk_add_f32 v[94:95], v[94:95], v[184:185]
	v_cvt_pk_bf16_f32 v114, v100, v101
	v_cvt_pk_bf16_f32 v115, v102, v103
	v_cvt_pk_bf16_f32 v116, v112, v113
	v_lshlrev_b32_e32 v234, 16, v188
	v_cvt_pk_bf16_f32 v117, v94, v95
	global_store_dwordx4 v[118:119], v[114:117], off offset:256
	v_lshl_add_u64 v[118:119], v[98:99], 0, v[144:145]
	v_pk_add_f32 v[98:99], v[76:77], v[238:239]
	v_pk_add_f32 v[76:77], v[82:83], v[172:173]
	v_lshl_add_u64 v[82:83], s[90:91], 0, v[152:153]
	v_lshl_add_u64 v[122:123], v[82:83], 0, v[144:145]
	v_pk_add_f32 v[82:83], v[64:65], v[156:157]
	v_and_b32_e32 v65, 64, v174
	v_and_b32_e32 v235, 0xffff0000, v188
	v_lshlrev_b32_e32 v188, 16, v189
	v_and_b32_e32 v189, 0xffff0000, v189
	v_lshlrev_b32_e32 v236, 16, v190
	v_and_b32_e32 v237, 0xffff0000, v190
	v_pk_add_f32 v[96:97], v[96:97], v[232:233]
	v_xor_b32_e32 v64, 16, v174
	v_cvt_pk_bf16_f32 v114, v96, v97
	v_add_u32_e32 v65, 64, v65
	v_lshlrev_b32_e32 v190, 16, v191
	v_and_b32_e32 v191, 0xffff0000, v191
	v_lshlrev_b32_e32 v192, 16, v193
	v_and_b32_e32 v193, 0xffff0000, v193
	v_pk_add_f32 v[90:91], v[90:91], v[188:189]
	v_pk_add_f32 v[88:89], v[88:89], v[234:235]
	v_cvt_pk_bf16_f32 v115, v92, v93
	v_pk_add_f32 v[84:85], v[84:85], v[236:237]
	v_cvt_pk_bf16_f32 v116, v88, v89
	v_cvt_pk_bf16_f32 v117, v90, v91
	global_store_dwordx4 v[118:119], v[114:117], off
	v_cmp_lt_i32_e32 vcc, v64, v65
	v_lshlrev_b32_e32 v164, 16, v196
	v_cvt_pk_bf16_f32 v114, v84, v85
	v_and_b32_e32 v165, 0xffff0000, v196
	v_lshlrev_b32_e32 v168, 16, v197
	v_and_b32_e32 v169, 0xffff0000, v197
	v_pk_add_f32 v[86:87], v[86:87], v[190:191]
	v_pk_add_f32 v[78:79], v[78:79], v[192:193]
	v_cvt_pk_bf16_f32 v115, v86, v87
	v_cvt_pk_bf16_f32 v116, v98, v99
	v_pk_add_f32 v[80:81], v[80:81], v[166:167]
	v_cvt_pk_bf16_f32 v117, v78, v79
	global_store_dwordx4 v[118:119], v[114:117], off offset:256
	v_cndmask_b32_e32 v64, v174, v64, vcc
	v_pk_add_f32 v[74:75], v[74:75], v[168:169]
	v_cvt_pk_bf16_f32 v114, v80, v81
	v_pk_add_f32 v[72:73], v[72:73], v[164:165]
	v_cvt_pk_bf16_f32 v115, v76, v77
	v_lshlrev_b32_e32 v158, 16, v198
	v_cvt_pk_bf16_f32 v116, v72, v73
	v_cvt_pk_bf16_f32 v117, v74, v75
	global_store_dwordx4 v[122:123], v[114:117], off
	v_and_b32_e32 v159, 0xffff0000, v198
	v_lshlrev_b32_e32 v162, 16, v199
	v_lshlrev_b32_e32 v114, 2, v64
	ds_bpermute_b32 v64, v114, v126
	v_xor_b32_e32 v115, 32, v174
	v_cmp_lt_i32_e32 vcc, v115, v65
	v_and_b32_e32 v163, 0xffff0000, v199
	v_lshlrev_b32_e32 v160, 16, v201
	v_cndmask_b32_e32 v65, v174, v115, vcc
	v_lshlrev_b32_e32 v115, 2, v65
	s_waitcnt lgkmcnt(0)
	v_add_f32_e32 v116, v126, v64
	ds_bpermute_b32 v117, v115, v116
	v_and_b32_e32 v161, 0xffff0000, v201
	v_pk_add_f32 v[70:71], v[70:71], v[162:163]
	v_pk_add_f32 v[68:69], v[68:69], v[158:159]
	v_pk_add_f32 v[66:67], v[66:67], v[160:161]
	v_lshl_add_u64 v[64:65], v[150:151], 2, s[8:9]
	v_cvt_pk_bf16_f32 v118, v68, v69
	v_cvt_pk_bf16_f32 v119, v70, v71
	v_cvt_pk_bf16_f32 v120, v82, v83
	v_cvt_pk_bf16_f32 v121, v66, v67
	global_store_dwordx4 v[122:123], v[118:121], off offset:256
	s_and_saveexec_b64 s[30:31], s[2:3]
	s_cbranch_execz .LBB0_1163
	s_waitcnt lgkmcnt(0)
	v_add_f32_e32 v116, v116, v117
	global_atomic_add_f32 v[64:65], v116, off

.LBB0_1218:
	ds_read_b128 v[144:147], v151
	ds_read_b128 v[156:159], v151 offset:1024
	ds_read_b128 v[160:163], v151 offset:2048
	ds_read_b128 v[164:167], v151 offset:3072
	s_add_u32 s30, s28, 0xfffc0080
	s_addc_u32 s31, s29, -1
	s_cmp_eq_u32 s63, 12
	s_cselect_b32 s35, s23, s31
	s_cselect_b32 s34, s59, s30
	s_cselect_b32 s31, s21, s62
	s_cselect_b32 s30, s60, s61
	v_lshl_add_u64 v[172:173], s[28:29], 0, v[136:137]
	s_add_i32 m0, s40, 0xc000
	ds_read_b128 v[168:171], v152
	ds_read_b128 v[176:179], v152 offset:1024
	ds_read_b128 v[180:183], v152 offset:2048
	ds_read_b128 v[184:187], v152 offset:3072
	ds_read_b128 v[188:191], v152 offset:4096
	ds_read_b128 v[192:195], v152 offset:5120
	ds_read_b128 v[196:199], v152 offset:6144
	ds_read_b128 v[200:203], v152 offset:7168
	global_load_lds_dwordx4 v[172:173], off
	v_lshl_add_u64 v[172:173], s[28:29], 0, v[138:139]
	s_add_i32 m0, s40, 0xe000
	s_nop 0
	global_load_lds_dwordx4 v[172:173], off
	s_waitcnt lgkmcnt(8)
	s_setprio 1
	s_barrier
	s_waitcnt lgkmcnt(0)
	v_mfma_f32_16x16x32_bf16 v[124:127], v[144:147], v[168:171], v[124:127]
	v_mfma_f32_16x16x32_bf16 v[120:123], v[160:163], v[168:171], v[120:123]
	v_mfma_f32_16x16x32_bf16 v[116:119], v[144:147], v[180:183], v[116:119]
	v_mfma_f32_16x16x32_bf16 v[112:115], v[160:163], v[180:183], v[112:115]
	v_mfma_f32_16x16x32_bf16 v[92:95], v[144:147], v[188:191], v[92:95]
	v_mfma_f32_16x16x32_bf16 v[88:91], v[160:163], v[188:191], v[88:91]
	v_mfma_f32_16x16x32_bf16 v[76:79], v[144:147], v[196:199], v[76:79]
	v_mfma_f32_16x16x32_bf16 v[72:75], v[160:163], v[196:199], v[72:75]
	v_mfma_f32_16x16x32_bf16 v[124:127], v[156:159], v[176:179], v[124:127]
	v_mfma_f32_16x16x32_bf16 v[120:123], v[164:167], v[176:179], v[120:123]
	v_mfma_f32_16x16x32_bf16 v[116:119], v[156:159], v[184:187], v[116:119]
	v_mfma_f32_16x16x32_bf16 v[112:115], v[164:167], v[184:187], v[112:115]
	v_mfma_f32_16x16x32_bf16 v[92:95], v[156:159], v[192:195], v[92:95]
	v_mfma_f32_16x16x32_bf16 v[88:91], v[164:167], v[192:195], v[88:91]
	v_mfma_f32_16x16x32_bf16 v[76:79], v[156:159], v[200:203], v[76:79]
	v_mfma_f32_16x16x32_bf16 v[72:75], v[164:167], v[200:203], v[72:75]
	s_setprio 0
	s_barrier
	s_add_i32 s64, s52, s39
	v_lshl_add_u64 v[172:173], s[30:31], 0, v[130:131]
	s_mov_b32 m0, s64
	ds_read_b128 v[204:207], v153
	ds_read_b128 v[212:215], v153 offset:1024
	ds_read_b128 v[216:219], v153 offset:2048
	ds_read_b128 v[220:223], v153 offset:3072
	global_load_lds_dwordx4 v[172:173], off
	v_lshl_add_u64 v[208:209], s[30:31], 0, v[134:135]
	s_add_i32 m0, s64, 0x2000
	s_nop 0
	global_load_lds_dwordx4 v[208:209], off
	s_setprio 1
	s_barrier
	s_waitcnt lgkmcnt(0)
	v_mfma_f32_16x16x32_bf16 v[108:111], v[204:207], v[168:171], v[108:111]
	v_mfma_f32_16x16x32_bf16 v[104:107], v[216:219], v[168:171], v[104:107]
	v_mfma_f32_16x16x32_bf16 v[100:103], v[204:207], v[180:183], v[100:103]
	v_mfma_f32_16x16x32_bf16 v[96:99], v[216:219], v[180:183], v[96:99]
	v_mfma_f32_16x16x32_bf16 v[84:87], v[204:207], v[188:191], v[84:87]
	v_mfma_f32_16x16x32_bf16 v[80:83], v[216:219], v[188:191], v[80:83]
	v_mfma_f32_16x16x32_bf16 v[68:71], v[204:207], v[196:199], v[68:71]
	v_mfma_f32_16x16x32_bf16 v[64:67], v[216:219], v[196:199], v[64:67]
	v_mfma_f32_16x16x32_bf16 v[108:111], v[212:215], v[176:179], v[108:111]
	v_mfma_f32_16x16x32_bf16 v[104:107], v[220:223], v[176:179], v[104:107]
	v_mfma_f32_16x16x32_bf16 v[100:103], v[212:215], v[184:187], v[100:103]
	v_mfma_f32_16x16x32_bf16 v[96:99], v[220:223], v[184:187], v[96:99]
	v_mfma_f32_16x16x32_bf16 v[84:87], v[212:215], v[192:195], v[84:87]
	v_mfma_f32_16x16x32_bf16 v[80:83], v[220:223], v[192:195], v[80:83]
	v_mfma_f32_16x16x32_bf16 v[68:71], v[212:215], v[200:203], v[68:71]
	v_mfma_f32_16x16x32_bf16 v[64:67], v[220:223], v[200:203], v[64:67]
	s_setprio 0
	s_mov_b32 m0, s40
	v_lshl_add_u64 v[224:225], s[34:35], 0, v[128:129]
	s_barrier
	ds_read_b128 v[168:171], v152 offset:16384
	ds_read_b128 v[176:179], v152 offset:17408
	ds_read_b128 v[180:183], v152 offset:18432
	ds_read_b128 v[184:187], v152 offset:19456
	ds_read_b128 v[188:191], v152 offset:20480
	ds_read_b128 v[192:195], v152 offset:21504
	ds_read_b128 v[196:199], v152 offset:22528
	ds_read_b128 v[200:203], v152 offset:23552
	global_load_lds_dwordx4 v[224:225], off
	v_lshl_add_u64 v[226:227], s[34:35], 0, v[132:133]
	s_mov_b32 m0, s41
	s_nop 0
	global_load_lds_dwordx4 v[226:227], off
	s_setprio 1
	s_barrier
	s_waitcnt lgkmcnt(0)
	v_mfma_f32_16x16x32_bf16 v[60:63], v[144:147], v[168:171], v[60:63]
	v_mfma_f32_16x16x32_bf16 v[56:59], v[160:163], v[168:171], v[56:59]
	v_mfma_f32_16x16x32_bf16 v[44:47], v[144:147], v[180:183], v[44:47]
	v_mfma_f32_16x16x32_bf16 v[40:43], v[160:163], v[180:183], v[40:43]
	v_mfma_f32_16x16x32_bf16 v[28:31], v[144:147], v[188:191], v[28:31]
	v_mfma_f32_16x16x32_bf16 v[24:27], v[160:163], v[188:191], v[24:27]
	v_mfma_f32_16x16x32_bf16 v[12:15], v[144:147], v[196:199], v[12:15]
	v_mfma_f32_16x16x32_bf16 v[8:11], v[160:163], v[196:199], v[8:11]
	v_mfma_f32_16x16x32_bf16 v[60:63], v[156:159], v[176:179], v[60:63]
	v_mfma_f32_16x16x32_bf16 v[56:59], v[164:167], v[176:179], v[56:59]
	v_mfma_f32_16x16x32_bf16 v[44:47], v[156:159], v[184:187], v[44:47]
	v_mfma_f32_16x16x32_bf16 v[40:43], v[164:167], v[184:187], v[40:43]
	v_mfma_f32_16x16x32_bf16 v[28:31], v[156:159], v[192:195], v[28:31]
	v_mfma_f32_16x16x32_bf16 v[24:27], v[164:167], v[192:195], v[24:27]
	v_mfma_f32_16x16x32_bf16 v[12:15], v[156:159], v[200:203], v[12:15]
	v_mfma_f32_16x16x32_bf16 v[8:11], v[164:167], v[200:203], v[8:11]
	s_setprio 0
	s_barrier
	s_add_u32 s64, s30, 0x40000
	s_addc_u32 s65, s31, 0
	s_add_i32 s66, s53, s39
	v_lshl_add_u64 v[144:145], s[64:65], 0, v[130:131]
	s_mov_b32 m0, s66
	s_nop 0
	global_load_lds_dwordx4 v[144:145], off
	v_lshl_add_u64 v[144:145], s[64:65], 0, v[134:135]
	s_add_i32 m0, s66, 0x2000
	s_nop 0
	global_load_lds_dwordx4 v[144:145], off
	s_waitcnt vmcnt(6)
	s_setprio 1
	s_barrier
	v_mfma_f32_16x16x32_bf16 v[52:55], v[204:207], v[168:171], v[52:55]
	v_mfma_f32_16x16x32_bf16 v[48:51], v[216:219], v[168:171], v[48:51]
	v_mfma_f32_16x16x32_bf16 v[36:39], v[204:207], v[180:183], v[36:39]
	v_mfma_f32_16x16x32_bf16 v[32:35], v[216:219], v[180:183], v[32:35]
	v_mfma_f32_16x16x32_bf16 v[20:23], v[204:207], v[188:191], v[20:23]
	v_mfma_f32_16x16x32_bf16 v[16:19], v[216:219], v[188:191], v[16:19]
	v_mfma_f32_16x16x32_bf16 v[4:7], v[204:207], v[196:199], v[4:7]
	v_mfma_f32_16x16x32_bf16 v[0:3], v[216:219], v[196:199], v[0:3]
	v_mfma_f32_16x16x32_bf16 v[52:55], v[212:215], v[176:179], v[52:55]
	v_mfma_f32_16x16x32_bf16 v[48:51], v[220:223], v[176:179], v[48:51]
	v_mfma_f32_16x16x32_bf16 v[36:39], v[212:215], v[184:187], v[36:39]
	v_mfma_f32_16x16x32_bf16 v[32:35], v[220:223], v[184:187], v[32:35]
	v_mfma_f32_16x16x32_bf16 v[20:23], v[212:215], v[192:195], v[20:23]
	v_mfma_f32_16x16x32_bf16 v[16:19], v[220:223], v[192:195], v[16:19]
	v_mfma_f32_16x16x32_bf16 v[4:7], v[212:215], v[200:203], v[4:7]
	v_mfma_f32_16x16x32_bf16 v[0:3], v[220:223], v[200:203], v[0:3]
	s_setprio 0
	s_add_i32 s64, 0, 0x18000
	v_add_u32_e32 v155, s64, v149
	s_barrier
	ds_read_b128 v[144:147], v155
	ds_read_b128 v[156:159], v155 offset:1024
	ds_read_b128 v[160:163], v155 offset:2048
	ds_read_b128 v[164:167], v155 offset:3072
	s_add_u32 s34, s34, 0x40000
	s_addc_u32 s35, s35, 0
	s_mov_b32 m0, s42
	v_lshl_add_u64 v[204:205], s[34:35], 0, v[128:129]
	ds_read_b128 v[168:171], v152 offset:32768
	ds_read_b128 v[176:179], v152 offset:33792
	ds_read_b128 v[180:183], v152 offset:34816
	ds_read_b128 v[184:187], v152 offset:35840
	ds_read_b128 v[188:191], v152 offset:36864
	ds_read_b128 v[192:195], v152 offset:37888
	ds_read_b128 v[196:199], v152 offset:38912
	ds_read_b128 v[200:203], v152 offset:39936
	global_load_lds_dwordx4 v[204:205], off
	v_lshl_add_u64 v[204:205], s[34:35], 0, v[132:133]
	s_mov_b32 m0, s43
	s_nop 0
	global_load_lds_dwordx4 v[204:205], off
	s_waitcnt lgkmcnt(8)
	s_setprio 1
	s_barrier
	s_waitcnt lgkmcnt(0)
	v_mfma_f32_16x16x32_bf16 v[124:127], v[144:147], v[168:171], v[124:127]
	v_mfma_f32_16x16x32_bf16 v[120:123], v[160:163], v[168:171], v[120:123]
	v_mfma_f32_16x16x32_bf16 v[116:119], v[144:147], v[180:183], v[116:119]
	v_mfma_f32_16x16x32_bf16 v[112:115], v[160:163], v[180:183], v[112:115]
	v_mfma_f32_16x16x32_bf16 v[92:95], v[144:147], v[188:191], v[92:95]
	v_mfma_f32_16x16x32_bf16 v[88:91], v[160:163], v[188:191], v[88:91]
	v_mfma_f32_16x16x32_bf16 v[76:79], v[144:147], v[196:199], v[76:79]
	v_mfma_f32_16x16x32_bf16 v[72:75], v[160:163], v[196:199], v[72:75]
	v_mfma_f32_16x16x32_bf16 v[124:127], v[156:159], v[176:179], v[124:127]
	v_mfma_f32_16x16x32_bf16 v[120:123], v[164:167], v[176:179], v[120:123]
	v_mfma_f32_16x16x32_bf16 v[116:119], v[156:159], v[184:187], v[116:119]
	v_mfma_f32_16x16x32_bf16 v[112:115], v[164:167], v[184:187], v[112:115]
	v_mfma_f32_16x16x32_bf16 v[92:95], v[156:159], v[192:195], v[92:95]
	v_mfma_f32_16x16x32_bf16 v[88:91], v[164:167], v[192:195], v[88:91]
	v_mfma_f32_16x16x32_bf16 v[76:79], v[156:159], v[200:203], v[76:79]
	v_mfma_f32_16x16x32_bf16 v[72:75], v[164:167], v[200:203], v[72:75]
	s_setprio 0
	s_barrier
	s_add_i32 s34, 0, 0x1c000
	s_add_i32 s35, s64, s39
	v_add_u32_e32 v155, s34, v149
	v_lshl_add_u64 v[172:173], v[172:173], 0, s[6:7]
	s_mov_b32 m0, s35
	ds_read_b128 v[204:207], v155
	ds_read_b128 v[212:215], v155 offset:1024
	ds_read_b128 v[216:219], v155 offset:2048
	ds_read_b128 v[220:223], v155 offset:3072
	global_load_lds_dwordx4 v[172:173], off
	v_lshl_add_u64 v[172:173], v[208:209], 0, s[6:7]
	s_add_i32 m0, s35, 0x2000
	s_nop 0
	global_load_lds_dwordx4 v[172:173], off
	s_setprio 1
	s_barrier
	s_waitcnt lgkmcnt(0)
	v_mfma_f32_16x16x32_bf16 v[108:111], v[204:207], v[168:171], v[108:111]
	v_mfma_f32_16x16x32_bf16 v[104:107], v[216:219], v[168:171], v[104:107]
	v_mfma_f32_16x16x32_bf16 v[100:103], v[204:207], v[180:183], v[100:103]
	v_mfma_f32_16x16x32_bf16 v[96:99], v[216:219], v[180:183], v[96:99]
	v_mfma_f32_16x16x32_bf16 v[84:87], v[204:207], v[188:191], v[84:87]
	v_mfma_f32_16x16x32_bf16 v[80:83], v[216:219], v[188:191], v[80:83]
	v_mfma_f32_16x16x32_bf16 v[68:71], v[204:207], v[196:199], v[68:71]
	v_mfma_f32_16x16x32_bf16 v[64:67], v[216:219], v[196:199], v[64:67]
	v_mfma_f32_16x16x32_bf16 v[108:111], v[212:215], v[176:179], v[108:111]
	v_mfma_f32_16x16x32_bf16 v[104:107], v[220:223], v[176:179], v[104:107]
	v_mfma_f32_16x16x32_bf16 v[100:103], v[212:215], v[184:187], v[100:103]
	v_mfma_f32_16x16x32_bf16 v[96:99], v[220:223], v[184:187], v[96:99]
	v_mfma_f32_16x16x32_bf16 v[84:87], v[212:215], v[192:195], v[84:87]
	v_mfma_f32_16x16x32_bf16 v[80:83], v[220:223], v[192:195], v[80:83]
	v_mfma_f32_16x16x32_bf16 v[68:71], v[212:215], v[200:203], v[68:71]
	v_mfma_f32_16x16x32_bf16 v[64:67], v[220:223], v[200:203], v[64:67]
	s_setprio 0
	s_mov_b32 m0, s49
	v_lshl_add_u64 v[172:173], v[224:225], 0, s[6:7]
	s_barrier
	ds_read_b128 v[168:171], v152 offset:49152
	ds_read_b128 v[176:179], v152 offset:50176
	ds_read_b128 v[180:183], v152 offset:51200
	ds_read_b128 v[184:187], v152 offset:52224
	ds_read_b128 v[188:191], v152 offset:53248
	ds_read_b128 v[192:195], v152 offset:54272
	ds_read_b128 v[196:199], v152 offset:55296
	ds_read_b128 v[200:203], v152 offset:56320
	global_load_lds_dwordx4 v[172:173], off
	v_lshl_add_u64 v[172:173], v[226:227], 0, s[6:7]
	s_mov_b32 m0, s50
	s_nop 0
	global_load_lds_dwordx4 v[172:173], off
	s_setprio 1
	s_barrier
	s_waitcnt lgkmcnt(0)
	v_mfma_f32_16x16x32_bf16 v[60:63], v[144:147], v[168:171], v[60:63]
	v_mfma_f32_16x16x32_bf16 v[56:59], v[160:163], v[168:171], v[56:59]
	v_mfma_f32_16x16x32_bf16 v[44:47], v[144:147], v[180:183], v[44:47]
	v_mfma_f32_16x16x32_bf16 v[40:43], v[160:163], v[180:183], v[40:43]
	v_mfma_f32_16x16x32_bf16 v[28:31], v[144:147], v[188:191], v[28:31]
	v_mfma_f32_16x16x32_bf16 v[24:27], v[160:163], v[188:191], v[24:27]
	v_mfma_f32_16x16x32_bf16 v[12:15], v[144:147], v[196:199], v[12:15]
	v_mfma_f32_16x16x32_bf16 v[8:11], v[160:163], v[196:199], v[8:11]
	v_mfma_f32_16x16x32_bf16 v[60:63], v[156:159], v[176:179], v[60:63]
	v_mfma_f32_16x16x32_bf16 v[56:59], v[164:167], v[176:179], v[56:59]
	v_mfma_f32_16x16x32_bf16 v[44:47], v[156:159], v[184:187], v[44:47]
	v_mfma_f32_16x16x32_bf16 v[40:43], v[164:167], v[184:187], v[40:43]
	v_mfma_f32_16x16x32_bf16 v[28:31], v[156:159], v[192:195], v[28:31]
	v_mfma_f32_16x16x32_bf16 v[24:27], v[164:167], v[192:195], v[24:27]
	v_mfma_f32_16x16x32_bf16 v[12:15], v[156:159], v[200:203], v[12:15]
	v_mfma_f32_16x16x32_bf16 v[8:11], v[164:167], v[200:203], v[8:11]
	s_setprio 0
	s_barrier
	s_add_u32 s30, s30, 0x40080
	s_addc_u32 s31, s31, 0
	s_add_i32 s34, s34, s39
	v_lshl_add_u64 v[144:145], s[30:31], 0, v[130:131]
	s_mov_b32 m0, s34
	s_nop 0
	global_load_lds_dwordx4 v[144:145], off
	v_lshl_add_u64 v[144:145], s[30:31], 0, v[134:135]
	s_add_i32 m0, s34, 0x2000
	s_nop 0
	global_load_lds_dwordx4 v[144:145], off
	s_waitcnt vmcnt(6)
	s_setprio 1
	s_barrier
	v_mfma_f32_16x16x32_bf16 v[52:55], v[204:207], v[168:171], v[52:55]
	v_mfma_f32_16x16x32_bf16 v[48:51], v[216:219], v[168:171], v[48:51]
	v_mfma_f32_16x16x32_bf16 v[36:39], v[204:207], v[180:183], v[36:39]
	v_mfma_f32_16x16x32_bf16 v[32:35], v[216:219], v[180:183], v[32:35]
	v_mfma_f32_16x16x32_bf16 v[20:23], v[204:207], v[188:191], v[20:23]
	v_mfma_f32_16x16x32_bf16 v[16:19], v[216:219], v[188:191], v[16:19]
	v_mfma_f32_16x16x32_bf16 v[4:7], v[204:207], v[196:199], v[4:7]
	v_mfma_f32_16x16x32_bf16 v[0:3], v[216:219], v[196:199], v[0:3]
	v_mfma_f32_16x16x32_bf16 v[52:55], v[212:215], v[176:179], v[52:55]
	v_mfma_f32_16x16x32_bf16 v[48:51], v[220:223], v[176:179], v[48:51]
	v_mfma_f32_16x16x32_bf16 v[36:39], v[212:215], v[184:187], v[36:39]
	v_mfma_f32_16x16x32_bf16 v[32:35], v[220:223], v[184:187], v[32:35]
	v_mfma_f32_16x16x32_bf16 v[20:23], v[212:215], v[192:195], v[20:23]
	v_mfma_f32_16x16x32_bf16 v[16:19], v[220:223], v[192:195], v[16:19]
	v_mfma_f32_16x16x32_bf16 v[4:7], v[212:215], v[200:203], v[4:7]
	v_mfma_f32_16x16x32_bf16 v[0:3], v[220:223], v[200:203], v[0:3]
	s_setprio 0
	s_add_i32 s63, s63, 2
	s_add_u32 s28, s28, 0x100
	s_addc_u32 s29, s29, 0
	s_add_u32 s61, s61, 0x100
	s_addc_u32 s62, s62, 0
	s_cmp_gt_u32 s63, 13
	s_barrier
	s_cbranch_scc0 .LBB0_1218
	v_lshl_add_u32 v146, s0, 8, v148
	v_ashrrev_i32_e32 v147, 31, v146
	v_lshl_add_u64 v[144:145], v[146:147], 2, s[8:9]
	global_load_dword v155, v[144:145], off
	global_load_dword v162, v[144:145], off offset:64
	global_load_dword v163, v[144:145], off offset:128
	global_load_dword v164, v[144:145], off offset:192
	global_load_dword v165, v[144:145], off offset:512
	global_load_dword v166, v[144:145], off offset:576
	global_load_dword v167, v[144:145], off offset:640
	global_load_dword v168, v[144:145], off offset:704
	v_lshl_or_b32 v144, s1, 8, v150
	v_ashrrev_i32_e32 v145, 31, v144
	v_lshlrev_b64 v[158:159], 13, v[146:147]
	v_lshlrev_b64 v[160:161], 1, v[144:145]
	v_lshl_add_u64 v[144:145], s[92:93], 0, v[158:159]
	v_lshl_add_u64 v[144:145], v[144:145], 0, v[160:161]
	v_or_b32_e32 v156, 16, v146
	v_ashrrev_i32_e32 v157, 31, v156
	v_lshlrev_b64 v[156:157], 13, v[156:157]
	v_lshl_add_u64 v[156:157], s[92:93], 0, v[156:157]
	v_lshl_add_u64 v[156:157], v[156:157], 0, v[160:161]
	s_mov_b64 s[30:31], s[26:27]
	s_mov_b64 s[28:29], s[24:25]
	s_waitcnt vmcnt(0)
	v_fmamk_f32 v147, v155, 0x3a800000, v154
	v_mul_f32_e32 v158, 0x4b800000, v147
	v_cmp_gt_f32_e32 vcc, s54, v147
	v_fmamk_f32 v155, v162, 0x3a800000, v154
	v_mul_f32_e32 v162, 0x4b800000, v155
	v_cndmask_b32_e32 v147, v147, v158, vcc
	v_rsq_f32_e32 v158, v147
	v_cmp_gt_f32_e64 s[0:1], s54, v155
	v_fmamk_f32 v159, v163, 0x3a800000, v154
	v_fmamk_f32 v163, v164, 0x3a800000, v154
	v_cndmask_b32_e64 v155, v155, v162, s[0:1]
	v_rsq_f32_e32 v155, v155
	v_mul_f32_e32 v162, 0x45800000, v158
	v_cndmask_b32_e32 v158, v158, v162, vcc
	v_pk_mul_f32 v[124:125], v[124:125], v[158:159] op_sel_hi:[1,0]
	v_pk_mul_f32 v[104:105], v[104:105], v[158:159] op_sel_hi:[1,0]
	v_fmamk_f32 v164, v165, 0x3a800000, v154
	v_fmamk_f32 v165, v166, 0x3a800000, v154
	v_fmamk_f32 v166, v167, 0x3a800000, v154
	v_mul_f32_e32 v167, 0x45800000, v155
	v_pk_mul_f32 v[126:127], v[126:127], v[158:159] op_sel_hi:[1,0]
	v_pk_mul_f32 v[122:123], v[122:123], v[158:159] op_sel_hi:[1,0]
	v_pk_mul_f32 v[120:121], v[120:121], v[158:159] op_sel_hi:[1,0]
	v_pk_mul_f32 v[108:109], v[108:109], v[158:159] op_sel_hi:[1,0]
	v_pk_mul_f32 v[106:107], v[106:107], v[158:159] op_sel_hi:[1,0]
	v_max_f32_e32 v124, 0, v124
	v_max_f32_e32 v125, 0, v125
	v_max_f32_e32 v104, 0, v104
	v_cndmask_b32_e64 v162, v155, v167, s[0:1]
	v_pk_mul_f32 v[110:111], v[110:111], v[158:159] op_sel_hi:[1,0]
	v_max_f32_e32 v120, 0, v120
	v_max_f32_e32 v121, 0, v121
	v_max_f32_e32 v126, 0, v126
	v_max_f32_e32 v122, 0, v122
	v_max_f32_e32 v127, 0, v127
	v_max_f32_e32 v123, 0, v123
	v_max_f32_e32 v108, 0, v108
	v_max_f32_e32 v109, 0, v109
	v_max_f32_e32 v105, 0, v105
	v_max_f32_e32 v106, 0, v106
	v_max_f32_e32 v107, 0, v107
	v_mul_f32_e32 v124, v124, v124
	v_mul_f32_e32 v125, v125, v125
	v_mul_f32_e32 v155, v104, v104
	v_cvt_pk_bf16_f32 v104, v124, v125
	v_fmamk_f32 v147, v168, 0x3a800000, v154
	v_pk_mul_f32 v[112:113], v[112:113], v[162:163] op_sel_hi:[1,0]
	v_max_f32_e32 v110, 0, v110
	v_max_f32_e32 v111, 0, v111
	v_mul_f32_e32 v120, v120, v120
	v_mul_f32_e32 v121, v121, v121
	v_mul_f32_e32 v126, v126, v126
	v_mul_f32_e32 v122, v122, v122
	v_mul_f32_e32 v127, v127, v127
	v_mul_f32_e32 v123, v123, v123
	v_mul_f32_e32 v108, v108, v108
	v_mul_f32_e32 v109, v109, v109
	v_mul_f32_e32 v158, v105, v105
	v_mul_f32_e32 v167, v106, v106
	v_mul_f32_e32 v168, v107, v107
	v_cvt_pk_bf16_f32 v105, v126, v127
	v_cvt_pk_bf16_f32 v106, v120, v121
	v_cvt_pk_bf16_f32 v107, v122, v123
	global_store_dwordx4 v[144:145], v[104:107], off nt
	v_pk_mul_f32 v[116:117], v[116:117], v[162:163] op_sel_hi:[1,0]
	v_mul_f32_e32 v110, v110, v110
	v_cvt_pk_bf16_f32 v104, v108, v109
	v_mul_f32_e32 v111, v111, v111
	v_cvt_pk_bf16_f32 v105, v110, v111
	v_cvt_pk_bf16_f32 v106, v155, v158
	v_cvt_pk_bf16_f32 v107, v167, v168
	global_store_dwordx4 v[144:145], v[104:107], off offset:256 nt
	v_pk_mul_f32 v[118:119], v[118:119], v[162:163] op_sel_hi:[1,0]
	v_pk_mul_f32 v[114:115], v[114:115], v[162:163] op_sel_hi:[1,0]
	v_max_f32_e32 v104, 0, v112
	v_mul_f32_e32 v106, v104, v104
	v_max_f32_e32 v104, 0, v117
	v_max_f32_e32 v116, 0, v116
	v_max_f32_e32 v107, 0, v113
	v_mul_f32_e32 v104, v104, v104
	v_pk_mul_f32 v[98:99], v[98:99], v[162:163] op_sel_hi:[1,0]
	v_pk_mul_f32 v[96:97], v[96:97], v[162:163] op_sel_hi:[1,0]
	v_mul_f32_e32 v105, v116, v116
	v_mul_f32_e32 v107, v107, v107
	v_max_f32_e32 v108, 0, v118
	v_max_f32_e32 v109, 0, v114
	v_max_f32_e32 v110, 0, v119
	v_max_f32_e32 v111, 0, v115
	v_cvt_pk_bf16_f32 v104, v105, v104
	v_pk_mul_f32 v[102:103], v[102:103], v[162:163] op_sel_hi:[1,0]
	v_pk_mul_f32 v[100:101], v[100:101], v[162:163] op_sel_hi:[1,0]
	v_max_f32_e32 v96, 0, v96
	v_max_f32_e32 v97, 0, v97
	v_max_f32_e32 v98, 0, v98
	v_mul_f32_e32 v108, v108, v108
	v_mul_f32_e32 v109, v109, v109
	v_mul_f32_e32 v110, v110, v110
	v_mul_f32_e32 v111, v111, v111
	v_cvt_pk_bf16_f32 v105, v108, v110
	v_cvt_pk_bf16_f32 v106, v106, v107
	v_cvt_pk_bf16_f32 v107, v109, v111
	global_store_dwordx4 v[156:157], v[104:107], off nt
	v_max_f32_e32 v100, 0, v100
	v_max_f32_e32 v99, 0, v99
	v_mul_f32_e32 v104, v96, v96
	v_max_f32_e32 v96, 0, v101
	v_mul_f32_e32 v101, v97, v97
	v_max_f32_e32 v97, 0, v102
	v_mul_f32_e32 v102, v98, v98
	v_max_f32_e32 v98, 0, v103
	v_mul_f32_e32 v96, v96, v96
	v_mul_f32_e32 v97, v97, v97
	v_mul_f32_e32 v98, v98, v98
	v_mul_f32_e32 v100, v100, v100
	v_mul_f32_e32 v99, v99, v99
	v_cvt_pk_bf16_f32 v96, v100, v96
	v_cvt_pk_bf16_f32 v97, v97, v98
	v_cvt_pk_bf16_f32 v98, v104, v101
	v_cvt_pk_bf16_f32 v99, v102, v99
	global_store_dwordx4 v[156:157], v[96:99], off offset:256 nt
	v_cmp_gt_f32_e32 vcc, s54, v159
	s_mov_b32 s1, s20
	v_mul_f32_e32 v98, 0x4b800000, v159
	v_cndmask_b32_e32 v98, v159, v98, vcc
	v_rsq_f32_e32 v98, v98
	v_or_b32_e32 v96, 32, v146
	v_ashrrev_i32_e32 v97, 31, v96
	v_lshlrev_b64 v[96:97], 13, v[96:97]
	v_mul_f32_e32 v99, 0x45800000, v98
	v_cndmask_b32_e32 v98, v98, v99, vcc
	v_pk_mul_f32 v[88:89], v[88:89], v[98:99] op_sel_hi:[1,0]
	v_pk_mul_f32 v[92:93], v[92:93], v[98:99] op_sel_hi:[1,0]
	v_pk_mul_f32 v[90:91], v[90:91], v[98:99] op_sel_hi:[1,0]
	v_max_f32_e32 v88, 0, v88
	v_pk_mul_f32 v[94:95], v[94:95], v[98:99] op_sel_hi:[1,0]
	v_mul_f32_e32 v99, v88, v88
	v_max_f32_e32 v88, 0, v93
	v_max_f32_e32 v89, 0, v89
	v_max_f32_e32 v90, 0, v90
	v_lshl_add_u64 v[96:97], s[92:93], 0, v[96:97]
	v_max_f32_e32 v92, 0, v92
	v_mul_f32_e32 v88, v88, v88
	v_mul_f32_e32 v93, v89, v89
	v_max_f32_e32 v89, 0, v94
	v_mul_f32_e32 v94, v90, v90
	v_max_f32_e32 v90, 0, v95
	v_max_f32_e32 v91, 0, v91
	v_pk_mul_f32 v[82:83], v[82:83], v[98:99] op_sel_hi:[1,0]
	v_pk_mul_f32 v[80:81], v[80:81], v[98:99] op_sel_hi:[1,0]
	v_lshl_add_u64 v[96:97], v[96:97], 0, v[160:161]
	v_mul_f32_e32 v92, v92, v92
	v_mul_f32_e32 v89, v89, v89
	v_mul_f32_e32 v90, v90, v90
	v_mul_f32_e32 v91, v91, v91
	v_cvt_pk_bf16_f32 v88, v92, v88
	v_pk_mul_f32 v[86:87], v[86:87], v[98:99] op_sel_hi:[1,0]
	v_pk_mul_f32 v[84:85], v[84:85], v[98:99] op_sel_hi:[1,0]
	v_max_f32_e32 v80, 0, v80
	v_max_f32_e32 v81, 0, v81
	v_max_f32_e32 v82, 0, v82
	v_cvt_pk_bf16_f32 v89, v89, v90
	v_cvt_pk_bf16_f32 v90, v99, v93
	v_cvt_pk_bf16_f32 v91, v94, v91
	global_store_dwordx4 v[96:97], v[88:91], off nt
	v_max_f32_e32 v84, 0, v84
	v_max_f32_e32 v83, 0, v83
	v_mul_f32_e32 v88, v80, v80
	v_max_f32_e32 v80, 0, v85
	v_mul_f32_e32 v85, v81, v81
	v_max_f32_e32 v81, 0, v86
	v_mul_f32_e32 v86, v82, v82
	v_max_f32_e32 v82, 0, v87
	v_mul_f32_e32 v80, v80, v80
	v_mul_f32_e32 v81, v81, v81
	v_mul_f32_e32 v82, v82, v82
	v_mul_f32_e32 v84, v84, v84
	v_mul_f32_e32 v83, v83, v83
	v_cvt_pk_bf16_f32 v80, v84, v80
	v_cvt_pk_bf16_f32 v81, v81, v82
	v_cvt_pk_bf16_f32 v82, v88, v85
	v_cvt_pk_bf16_f32 v83, v86, v83
	global_store_dwordx4 v[96:97], v[80:83], off offset:256 nt
	v_cmp_gt_f32_e32 vcc, s54, v163
	s_mov_b32 s0, s22
	v_mul_f32_e32 v82, 0x4b800000, v163
	v_cndmask_b32_e32 v82, v163, v82, vcc
	v_rsq_f32_e32 v82, v82
	v_or_b32_e32 v80, 48, v146
	v_ashrrev_i32_e32 v81, 31, v80
	v_lshlrev_b64 v[80:81], 13, v[80:81]
	v_mul_f32_e32 v83, 0x45800000, v82
	v_cndmask_b32_e32 v82, v82, v83, vcc
	v_pk_mul_f32 v[72:73], v[72:73], v[82:83] op_sel_hi:[1,0]
	v_pk_mul_f32 v[76:77], v[76:77], v[82:83] op_sel_hi:[1,0]
	v_pk_mul_f32 v[74:75], v[74:75], v[82:83] op_sel_hi:[1,0]
	v_max_f32_e32 v72, 0, v72
	v_pk_mul_f32 v[78:79], v[78:79], v[82:83] op_sel_hi:[1,0]
	v_mul_f32_e32 v83, v72, v72
	v_max_f32_e32 v72, 0, v77
	v_max_f32_e32 v73, 0, v73
	v_max_f32_e32 v74, 0, v74
	v_lshl_add_u64 v[80:81], s[92:93], 0, v[80:81]
	v_max_f32_e32 v76, 0, v76
	v_mul_f32_e32 v72, v72, v72
	v_mul_f32_e32 v77, v73, v73
	v_max_f32_e32 v73, 0, v78
	v_mul_f32_e32 v78, v74, v74
	v_max_f32_e32 v74, 0, v79
	v_max_f32_e32 v75, 0, v75
	v_pk_mul_f32 v[64:65], v[64:65], v[82:83] op_sel_hi:[1,0]
	v_lshl_add_u64 v[80:81], v[80:81], 0, v[160:161]
	v_mul_f32_e32 v76, v76, v76
	v_mul_f32_e32 v73, v73, v73
	v_mul_f32_e32 v74, v74, v74
	v_mul_f32_e32 v75, v75, v75
	v_cvt_pk_bf16_f32 v72, v76, v72
	v_pk_mul_f32 v[68:69], v[68:69], v[82:83] op_sel_hi:[1,0]
	v_max_f32_e32 v64, 0, v64
	v_cvt_pk_bf16_f32 v73, v73, v74
	v_cvt_pk_bf16_f32 v74, v83, v77
	v_cvt_pk_bf16_f32 v75, v78, v75
	global_store_dwordx4 v[80:81], v[72:75], off nt
	v_max_f32_e32 v68, 0, v68
	v_mul_f32_e32 v68, v68, v68
	v_mul_f32_e32 v72, v64, v64
	v_max_f32_e32 v64, 0, v69
	v_mul_f32_e32 v64, v64, v64
	v_cvt_pk_bf16_f32 v64, v68, v64
	v_mul_f32_e32 v68, 0x4b800000, v164
	v_cmp_gt_f32_e32 vcc, s54, v164
	v_pk_mul_f32 v[66:67], v[66:67], v[82:83] op_sel_hi:[1,0]
	v_pk_mul_f32 v[70:71], v[70:71], v[82:83] op_sel_hi:[1,0]
	v_cndmask_b32_e32 v68, v164, v68, vcc
	v_max_f32_e32 v65, 0, v65
	v_max_f32_e32 v66, 0, v66
	v_rsq_f32_e32 v68, v68
	v_mul_f32_e32 v69, v65, v65
	v_max_f32_e32 v65, 0, v70
	v_mul_f32_e32 v70, v66, v66
	v_max_f32_e32 v66, 0, v71
	v_mul_f32_e32 v65, v65, v65
	v_max_f32_e32 v67, 0, v67
	v_mul_f32_e32 v66, v66, v66
	v_mul_f32_e32 v67, v67, v67
	v_cvt_pk_bf16_f32 v65, v65, v66
	v_cvt_pk_bf16_f32 v66, v72, v69
	v_cvt_pk_bf16_f32 v67, v70, v67
	global_store_dwordx4 v[80:81], v[64:67], off offset:256 nt
	s_nop 1
	v_mul_f32_e32 v66, 0x45800000, v68
	v_cndmask_b32_e32 v66, v68, v66, vcc
	v_pk_mul_f32 v[56:57], v[56:57], v[66:67] op_sel_hi:[1,0]
	v_pk_mul_f32 v[60:61], v[60:61], v[66:67] op_sel_hi:[1,0]
	v_pk_mul_f32 v[58:59], v[58:59], v[66:67] op_sel_hi:[1,0]
	v_max_f32_e32 v56, 0, v56
	v_pk_mul_f32 v[62:63], v[62:63], v[66:67] op_sel_hi:[1,0]
	v_max_f32_e32 v60, 0, v60
	v_mul_f32_e32 v67, v56, v56
	v_max_f32_e32 v56, 0, v61
	v_max_f32_e32 v57, 0, v57
	v_max_f32_e32 v58, 0, v58
	v_mul_f32_e32 v60, v60, v60
	v_mul_f32_e32 v56, v56, v56
	v_mul_f32_e32 v61, v57, v57
	v_max_f32_e32 v57, 0, v62
	v_mul_f32_e32 v62, v58, v58
	v_max_f32_e32 v58, 0, v63
	v_mul_f32_e32 v57, v57, v57
	v_max_f32_e32 v59, 0, v59
	v_mul_f32_e32 v58, v58, v58
	v_cvt_pk_bf16_f32 v56, v60, v56
	v_add_co_u32_e32 v60, vcc, s55, v144
	v_pk_mul_f32 v[48:49], v[48:49], v[66:67] op_sel_hi:[1,0]
	v_mul_f32_e32 v59, v59, v59
	v_cvt_pk_bf16_f32 v57, v57, v58
	v_cvt_pk_bf16_f32 v58, v67, v61
	v_addc_co_u32_e32 v61, vcc, 0, v145, vcc
	v_pk_mul_f32 v[52:53], v[52:53], v[66:67] op_sel_hi:[1,0]
	v_max_f32_e32 v48, 0, v48
	v_cvt_pk_bf16_f32 v59, v62, v59
	global_store_dwordx4 v[60:61], v[56:59], off nt
	v_max_f32_e32 v52, 0, v52
	v_mul_f32_e32 v52, v52, v52
	v_mul_f32_e32 v56, v48, v48
	v_max_f32_e32 v48, 0, v53
	v_mul_f32_e32 v48, v48, v48
	v_cvt_pk_bf16_f32 v48, v52, v48
	v_mul_f32_e32 v52, 0x4b800000, v165
	v_cmp_gt_f32_e32 vcc, s54, v165
	v_pk_mul_f32 v[50:51], v[50:51], v[66:67] op_sel_hi:[1,0]
	v_pk_mul_f32 v[54:55], v[54:55], v[66:67] op_sel_hi:[1,0]
	v_cndmask_b32_e32 v52, v165, v52, vcc
	v_max_f32_e32 v49, 0, v49
	v_max_f32_e32 v50, 0, v50
	v_rsq_f32_e32 v52, v52
	v_mul_f32_e32 v53, v49, v49
	v_max_f32_e32 v49, 0, v54
	v_mul_f32_e32 v54, v50, v50
	v_max_f32_e32 v50, 0, v55
	v_mul_f32_e32 v49, v49, v49
	v_max_f32_e32 v51, 0, v51
	v_mul_f32_e32 v50, v50, v50
	v_lshl_add_u64 v[64:65], v[144:145], 0, s[12:13]
	v_mul_f32_e32 v51, v51, v51
	v_cvt_pk_bf16_f32 v49, v49, v50
	v_cvt_pk_bf16_f32 v50, v56, v53
	v_cvt_pk_bf16_f32 v51, v54, v51
	global_store_dwordx4 v[64:65], v[48:51], off offset:256 nt
	s_nop 1
	v_mul_f32_e32 v50, 0x45800000, v52
	v_cndmask_b32_e32 v50, v52, v50, vcc
	v_pk_mul_f32 v[40:41], v[40:41], v[50:51] op_sel_hi:[1,0]
	v_pk_mul_f32 v[44:45], v[44:45], v[50:51] op_sel_hi:[1,0]
	v_pk_mul_f32 v[42:43], v[42:43], v[50:51] op_sel_hi:[1,0]
	v_max_f32_e32 v40, 0, v40
	v_pk_mul_f32 v[46:47], v[46:47], v[50:51] op_sel_hi:[1,0]
	v_max_f32_e32 v44, 0, v44
	v_mul_f32_e32 v51, v40, v40
	v_max_f32_e32 v40, 0, v45
	v_max_f32_e32 v41, 0, v41
	v_max_f32_e32 v42, 0, v42
	v_mul_f32_e32 v44, v44, v44
	v_mul_f32_e32 v40, v40, v40
	v_mul_f32_e32 v45, v41, v41
	v_max_f32_e32 v41, 0, v46
	v_mul_f32_e32 v46, v42, v42
	v_max_f32_e32 v42, 0, v47
	v_mul_f32_e32 v41, v41, v41
	v_max_f32_e32 v43, 0, v43
	v_mul_f32_e32 v42, v42, v42
	v_cvt_pk_bf16_f32 v40, v44, v40
	v_add_co_u32_e32 v44, vcc, s56, v144
	v_pk_mul_f32 v[32:33], v[32:33], v[50:51] op_sel_hi:[1,0]
	v_mul_f32_e32 v43, v43, v43
	v_cvt_pk_bf16_f32 v41, v41, v42
	v_cvt_pk_bf16_f32 v42, v51, v45
	v_addc_co_u32_e32 v45, vcc, 0, v145, vcc
	v_pk_mul_f32 v[36:37], v[36:37], v[50:51] op_sel_hi:[1,0]
	v_max_f32_e32 v32, 0, v32
	v_cvt_pk_bf16_f32 v43, v46, v43
	global_store_dwordx4 v[44:45], v[40:43], off nt
	v_max_f32_e32 v36, 0, v36
	v_mul_f32_e32 v36, v36, v36
	v_mul_f32_e32 v40, v32, v32
	v_max_f32_e32 v32, 0, v37
	v_mul_f32_e32 v32, v32, v32
	v_cvt_pk_bf16_f32 v32, v36, v32
	v_mul_f32_e32 v36, 0x4b800000, v166
	v_cmp_gt_f32_e32 vcc, s54, v166
	v_pk_mul_f32 v[34:35], v[34:35], v[50:51] op_sel_hi:[1,0]
	v_pk_mul_f32 v[38:39], v[38:39], v[50:51] op_sel_hi:[1,0]
	v_cndmask_b32_e32 v36, v166, v36, vcc
	v_max_f32_e32 v33, 0, v33
	v_max_f32_e32 v34, 0, v34
	v_rsq_f32_e32 v36, v36
	v_mul_f32_e32 v37, v33, v33
	v_max_f32_e32 v33, 0, v38
	v_mul_f32_e32 v38, v34, v34
	v_max_f32_e32 v34, 0, v39
	v_mul_f32_e32 v33, v33, v33
	v_max_f32_e32 v35, 0, v35
	v_mul_f32_e32 v34, v34, v34
	v_lshl_add_u64 v[48:49], v[144:145], 0, s[14:15]
	v_mul_f32_e32 v35, v35, v35
	v_cvt_pk_bf16_f32 v33, v33, v34
	v_cvt_pk_bf16_f32 v34, v40, v37
	v_cvt_pk_bf16_f32 v35, v38, v35
	global_store_dwordx4 v[48:49], v[32:35], off offset:256 nt
	s_nop 1
	v_mul_f32_e32 v34, 0x45800000, v36
	v_cndmask_b32_e32 v34, v36, v34, vcc
	v_pk_mul_f32 v[24:25], v[24:25], v[34:35] op_sel_hi:[1,0]
	v_pk_mul_f32 v[28:29], v[28:29], v[34:35] op_sel_hi:[1,0]
	v_pk_mul_f32 v[26:27], v[26:27], v[34:35] op_sel_hi:[1,0]
	v_max_f32_e32 v24, 0, v24
	v_pk_mul_f32 v[30:31], v[30:31], v[34:35] op_sel_hi:[1,0]
	v_max_f32_e32 v28, 0, v28
	v_mul_f32_e32 v35, v24, v24
	v_max_f32_e32 v24, 0, v29
	v_max_f32_e32 v25, 0, v25
	v_max_f32_e32 v26, 0, v26
	v_mul_f32_e32 v28, v28, v28
	v_mul_f32_e32 v24, v24, v24
	v_mul_f32_e32 v29, v25, v25
	v_max_f32_e32 v25, 0, v30
	v_mul_f32_e32 v30, v26, v26
	v_max_f32_e32 v26, 0, v31
	v_mul_f32_e32 v25, v25, v25
	v_max_f32_e32 v27, 0, v27
	v_mul_f32_e32 v26, v26, v26
	v_cvt_pk_bf16_f32 v24, v28, v24
	v_add_co_u32_e32 v28, vcc, s57, v144
	v_pk_mul_f32 v[16:17], v[16:17], v[34:35] op_sel_hi:[1,0]
	v_mul_f32_e32 v27, v27, v27
	v_cvt_pk_bf16_f32 v25, v25, v26
	v_cvt_pk_bf16_f32 v26, v35, v29
	v_addc_co_u32_e32 v29, vcc, 0, v145, vcc
	v_pk_mul_f32 v[20:21], v[20:21], v[34:35] op_sel_hi:[1,0]
	v_max_f32_e32 v16, 0, v16
	v_cvt_pk_bf16_f32 v27, v30, v27
	global_store_dwordx4 v[28:29], v[24:27], off nt
	v_max_f32_e32 v20, 0, v20
	v_mul_f32_e32 v20, v20, v20
	v_mul_f32_e32 v24, v16, v16
	v_max_f32_e32 v16, 0, v21
	v_mul_f32_e32 v16, v16, v16
	v_cvt_pk_bf16_f32 v16, v20, v16
	v_mul_f32_e32 v20, 0x4b800000, v147
	v_cmp_gt_f32_e32 vcc, s54, v147
	v_pk_mul_f32 v[18:19], v[18:19], v[34:35] op_sel_hi:[1,0]
	v_pk_mul_f32 v[22:23], v[22:23], v[34:35] op_sel_hi:[1,0]
	v_cndmask_b32_e32 v20, v147, v20, vcc
	v_max_f32_e32 v17, 0, v17
	v_max_f32_e32 v18, 0, v18
	v_rsq_f32_e32 v20, v20
	v_mul_f32_e32 v21, v17, v17
	v_max_f32_e32 v17, 0, v22
	v_mul_f32_e32 v22, v18, v18
	v_max_f32_e32 v18, 0, v23
	v_mul_f32_e32 v17, v17, v17
	v_max_f32_e32 v19, 0, v19
	v_mul_f32_e32 v18, v18, v18
	v_lshl_add_u64 v[32:33], v[144:145], 0, s[16:17]
	v_mul_f32_e32 v19, v19, v19
	v_cvt_pk_bf16_f32 v17, v17, v18
	v_cvt_pk_bf16_f32 v18, v24, v21
	v_cvt_pk_bf16_f32 v19, v22, v19
	global_store_dwordx4 v[32:33], v[16:19], off offset:256 nt
	s_nop 1
	v_mul_f32_e32 v18, 0x45800000, v20
	v_cndmask_b32_e32 v18, v20, v18, vcc
	v_pk_mul_f32 v[8:9], v[8:9], v[18:19] op_sel_hi:[1,0]
	v_pk_mul_f32 v[12:13], v[12:13], v[18:19] op_sel_hi:[1,0]
	v_pk_mul_f32 v[10:11], v[10:11], v[18:19] op_sel_hi:[1,0]
	v_max_f32_e32 v8, 0, v8
	v_pk_mul_f32 v[14:15], v[14:15], v[18:19] op_sel_hi:[1,0]
	v_max_f32_e32 v12, 0, v12
	v_mul_f32_e32 v19, v8, v8
	v_max_f32_e32 v8, 0, v13
	v_max_f32_e32 v9, 0, v9
	v_max_f32_e32 v10, 0, v10
	v_mul_f32_e32 v12, v12, v12
	v_mul_f32_e32 v8, v8, v8
	v_mul_f32_e32 v13, v9, v9
	v_max_f32_e32 v9, 0, v14
	v_mul_f32_e32 v14, v10, v10
	v_max_f32_e32 v10, 0, v15
	v_mul_f32_e32 v9, v9, v9
	v_max_f32_e32 v11, 0, v11
	v_mul_f32_e32 v10, v10, v10
	v_cvt_pk_bf16_f32 v8, v12, v8
	v_add_co_u32_e32 v12, vcc, s58, v144
	v_pk_mul_f32 v[2:3], v[2:3], v[18:19] op_sel_hi:[1,0]
	v_pk_mul_f32 v[0:1], v[0:1], v[18:19] op_sel_hi:[1,0]
	v_mul_f32_e32 v11, v11, v11
	v_cvt_pk_bf16_f32 v9, v9, v10
	v_cvt_pk_bf16_f32 v10, v19, v13
	v_addc_co_u32_e32 v13, vcc, 0, v145, vcc
	v_pk_mul_f32 v[6:7], v[6:7], v[18:19] op_sel_hi:[1,0]
	v_pk_mul_f32 v[4:5], v[4:5], v[18:19] op_sel_hi:[1,0]
	v_max_f32_e32 v0, 0, v0
	v_max_f32_e32 v1, 0, v1
	v_max_f32_e32 v2, 0, v2
	v_cvt_pk_bf16_f32 v11, v14, v11
	global_store_dwordx4 v[12:13], v[8:11], off nt
	v_max_f32_e32 v3, 0, v3
	v_lshl_add_u64 v[16:17], v[144:145], 0, s[18:19]
	v_mul_f32_e32 v8, v0, v0
	v_max_f32_e32 v0, 0, v5
	v_mul_f32_e32 v5, v1, v1
	v_max_f32_e32 v1, 0, v6
	v_mul_f32_e32 v6, v2, v2
	v_max_f32_e32 v2, 0, v7
	v_max_f32_e32 v4, 0, v4
	v_mul_f32_e32 v0, v0, v0
	v_mul_f32_e32 v1, v1, v1
	v_mul_f32_e32 v2, v2, v2
	v_mul_f32_e32 v3, v3, v3
	s_and_b64 vcc, exec, s[2:3]
	v_mul_f32_e32 v4, v4, v4
	v_cvt_pk_bf16_f32 v0, v4, v0
	v_cvt_pk_bf16_f32 v1, v1, v2
	v_cvt_pk_bf16_f32 v2, v8, v5
	v_cvt_pk_bf16_f32 v3, v6, v3
	global_store_dwordx4 v[16:17], v[0:3], off offset:256 nt
	s_cbranch_vccz .LBB0_1211
	s_waitcnt vmcnt(0)
	s_cmpk_gt_u32 s33, 0xff
	s_cbranch_scc1 .LBB0_1222
	s_barrier

.LBB0_1264:
	ds_read_b128 v[144:147], v178
	ds_read_b128 v[148:151], v178 offset:1024
	ds_read_b128 v[152:155], v178 offset:2048
	ds_read_b128 v[156:159], v178 offset:3072
	s_add_u32 s34, s30, 0xfff00080
	s_addc_u32 s35, s31, -1
	s_cmp_eq_u32 s58, 60
	s_cselect_b32 s37, s21, s35
	s_cselect_b32 s36, s27, s34
	s_cselect_b32 s35, s19, s57
	s_cselect_b32 s34, s55, s56
	v_lshl_add_u64 v[172:173], s[30:31], 0, v[136:137]
	s_add_i32 m0, s29, 0xc000
	ds_read_b128 v[160:163], v179
	ds_read_b128 v[164:167], v179 offset:1024
	ds_read_b128 v[168:171], v179 offset:2048
	ds_read_b128 v[182:185], v179 offset:3072
	ds_read_b128 v[186:189], v179 offset:4096
	ds_read_b128 v[190:193], v179 offset:5120
	ds_read_b128 v[194:197], v179 offset:6144
	ds_read_b128 v[198:201], v179 offset:7168
	global_load_lds_dwordx4 v[172:173], off
	v_lshl_add_u64 v[172:173], s[30:31], 0, v[138:139]
	s_add_i32 m0, s29, 0xe000
	s_nop 0
	global_load_lds_dwordx4 v[172:173], off
	s_waitcnt lgkmcnt(8)
	s_setprio 1
	s_barrier
	s_waitcnt lgkmcnt(0)
	v_mfma_f32_16x16x32_bf16 v[124:127], v[144:147], v[160:163], v[124:127]
	v_mfma_f32_16x16x32_bf16 v[120:123], v[152:155], v[160:163], v[120:123]
	v_mfma_f32_16x16x32_bf16 v[108:111], v[144:147], v[168:171], v[108:111]
	v_mfma_f32_16x16x32_bf16 v[104:107], v[152:155], v[168:171], v[104:107]
	v_mfma_f32_16x16x32_bf16 v[96:99], v[144:147], v[186:189], v[96:99]
	v_mfma_f32_16x16x32_bf16 v[88:91], v[152:155], v[186:189], v[88:91]
	v_mfma_f32_16x16x32_bf16 v[80:83], v[144:147], v[194:197], v[80:83]
	v_mfma_f32_16x16x32_bf16 v[72:75], v[152:155], v[194:197], v[72:75]
	v_mfma_f32_16x16x32_bf16 v[124:127], v[148:151], v[164:167], v[124:127]
	v_mfma_f32_16x16x32_bf16 v[120:123], v[156:159], v[164:167], v[120:123]
	v_mfma_f32_16x16x32_bf16 v[108:111], v[148:151], v[182:185], v[108:111]
	v_mfma_f32_16x16x32_bf16 v[104:107], v[156:159], v[182:185], v[104:107]
	v_mfma_f32_16x16x32_bf16 v[96:99], v[148:151], v[190:193], v[96:99]
	v_mfma_f32_16x16x32_bf16 v[88:91], v[156:159], v[190:193], v[88:91]
	v_mfma_f32_16x16x32_bf16 v[80:83], v[148:151], v[198:201], v[80:83]
	v_mfma_f32_16x16x32_bf16 v[72:75], v[156:159], v[198:201], v[72:75]
	s_setprio 0
	s_barrier
	s_add_i32 s59, s53, s40
	v_lshl_add_u64 v[172:173], s[34:35], 0, v[130:131]
	s_mov_b32 m0, s59
	ds_read_b128 v[202:205], v180
	ds_read_b128 v[206:209], v180 offset:1024
	ds_read_b128 v[212:215], v180 offset:2048
	ds_read_b128 v[216:219], v180 offset:3072
	global_load_lds_dwordx4 v[172:173], off
	v_lshl_add_u64 v[220:221], s[34:35], 0, v[134:135]
	s_add_i32 m0, s59, 0x2000
	s_nop 0
	global_load_lds_dwordx4 v[220:221], off
	s_setprio 1
	s_barrier
	s_waitcnt lgkmcnt(0)
	v_mfma_f32_16x16x32_bf16 v[116:119], v[202:205], v[160:163], v[116:119]
	v_mfma_f32_16x16x32_bf16 v[112:115], v[212:215], v[160:163], v[112:115]
	v_mfma_f32_16x16x32_bf16 v[100:103], v[202:205], v[168:171], v[100:103]
	v_mfma_f32_16x16x32_bf16 v[92:95], v[212:215], v[168:171], v[92:95]
	v_mfma_f32_16x16x32_bf16 v[84:87], v[202:205], v[186:189], v[84:87]
	v_mfma_f32_16x16x32_bf16 v[76:79], v[212:215], v[186:189], v[76:79]
	v_mfma_f32_16x16x32_bf16 v[68:71], v[202:205], v[194:197], v[68:71]
	v_mfma_f32_16x16x32_bf16 v[64:67], v[212:215], v[194:197], v[64:67]
	v_mfma_f32_16x16x32_bf16 v[116:119], v[206:209], v[164:167], v[116:119]
	v_mfma_f32_16x16x32_bf16 v[112:115], v[216:219], v[164:167], v[112:115]
	v_mfma_f32_16x16x32_bf16 v[100:103], v[206:209], v[182:185], v[100:103]
	v_mfma_f32_16x16x32_bf16 v[92:95], v[216:219], v[182:185], v[92:95]
	v_mfma_f32_16x16x32_bf16 v[84:87], v[206:209], v[190:193], v[84:87]
	v_mfma_f32_16x16x32_bf16 v[76:79], v[216:219], v[190:193], v[76:79]
	v_mfma_f32_16x16x32_bf16 v[68:71], v[206:209], v[198:201], v[68:71]
	v_mfma_f32_16x16x32_bf16 v[64:67], v[216:219], v[198:201], v[64:67]
	s_setprio 0
	s_mov_b32 m0, s29
	v_lshl_add_u64 v[222:223], s[36:37], 0, v[128:129]
	s_barrier
	ds_read_b128 v[160:163], v179 offset:16384
	ds_read_b128 v[164:167], v179 offset:17408
	ds_read_b128 v[168:171], v179 offset:18432
	ds_read_b128 v[182:185], v179 offset:19456
	ds_read_b128 v[186:189], v179 offset:20480
	ds_read_b128 v[190:193], v179 offset:21504
	ds_read_b128 v[194:197], v179 offset:22528
	ds_read_b128 v[198:201], v179 offset:23552
	global_load_lds_dwordx4 v[222:223], off
	v_lshl_add_u64 v[224:225], s[36:37], 0, v[132:133]
	s_mov_b32 m0, s41
	s_nop 0
	global_load_lds_dwordx4 v[224:225], off
	s_setprio 1
	s_barrier
	s_waitcnt lgkmcnt(0)
	v_mfma_f32_16x16x32_bf16 v[60:63], v[144:147], v[160:163], v[60:63]
	v_mfma_f32_16x16x32_bf16 v[56:59], v[152:155], v[160:163], v[56:59]
	v_mfma_f32_16x16x32_bf16 v[44:47], v[144:147], v[168:171], v[44:47]
	v_mfma_f32_16x16x32_bf16 v[40:43], v[152:155], v[168:171], v[40:43]
	v_mfma_f32_16x16x32_bf16 v[32:35], v[144:147], v[186:189], v[32:35]
	v_mfma_f32_16x16x32_bf16 v[24:27], v[152:155], v[186:189], v[24:27]
	v_mfma_f32_16x16x32_bf16 v[16:19], v[144:147], v[194:197], v[16:19]
	v_mfma_f32_16x16x32_bf16 v[8:11], v[152:155], v[194:197], v[8:11]
	v_mfma_f32_16x16x32_bf16 v[60:63], v[148:151], v[164:167], v[60:63]
	v_mfma_f32_16x16x32_bf16 v[56:59], v[156:159], v[164:167], v[56:59]
	v_mfma_f32_16x16x32_bf16 v[44:47], v[148:151], v[182:185], v[44:47]
	v_mfma_f32_16x16x32_bf16 v[40:43], v[156:159], v[182:185], v[40:43]
	v_mfma_f32_16x16x32_bf16 v[32:35], v[148:151], v[190:193], v[32:35]
	v_mfma_f32_16x16x32_bf16 v[24:27], v[156:159], v[190:193], v[24:27]
	v_mfma_f32_16x16x32_bf16 v[16:19], v[148:151], v[198:201], v[16:19]
	v_mfma_f32_16x16x32_bf16 v[8:11], v[156:159], v[198:201], v[8:11]
	s_setprio 0
	s_barrier
	s_add_u32 s60, s34, 0x100000
	s_addc_u32 s61, s35, 0
	s_add_i32 s59, s54, s40
	v_lshl_add_u64 v[144:145], s[60:61], 0, v[130:131]
	s_mov_b32 m0, s59
	s_nop 0
	global_load_lds_dwordx4 v[144:145], off
	v_lshl_add_u64 v[144:145], s[60:61], 0, v[134:135]
	s_add_i32 m0, s59, 0x2000
	s_nop 0
	global_load_lds_dwordx4 v[144:145], off
	s_waitcnt vmcnt(6)
	s_setprio 1
	s_barrier
	v_mfma_f32_16x16x32_bf16 v[52:55], v[202:205], v[160:163], v[52:55]
	v_mfma_f32_16x16x32_bf16 v[48:51], v[212:215], v[160:163], v[48:51]
	v_mfma_f32_16x16x32_bf16 v[36:39], v[202:205], v[168:171], v[36:39]
	v_mfma_f32_16x16x32_bf16 v[28:31], v[212:215], v[168:171], v[28:31]
	v_mfma_f32_16x16x32_bf16 v[20:23], v[202:205], v[186:189], v[20:23]
	v_mfma_f32_16x16x32_bf16 v[12:15], v[212:215], v[186:189], v[12:15]
	v_mfma_f32_16x16x32_bf16 v[4:7], v[202:205], v[194:197], v[4:7]
	v_mfma_f32_16x16x32_bf16 v[0:3], v[212:215], v[194:197], v[0:3]
	v_mfma_f32_16x16x32_bf16 v[52:55], v[206:209], v[164:167], v[52:55]
	v_mfma_f32_16x16x32_bf16 v[48:51], v[216:219], v[164:167], v[48:51]
	v_mfma_f32_16x16x32_bf16 v[36:39], v[206:209], v[182:185], v[36:39]
	v_mfma_f32_16x16x32_bf16 v[28:31], v[216:219], v[182:185], v[28:31]
	v_mfma_f32_16x16x32_bf16 v[20:23], v[206:209], v[190:193], v[20:23]
	v_mfma_f32_16x16x32_bf16 v[12:15], v[216:219], v[190:193], v[12:15]
	v_mfma_f32_16x16x32_bf16 v[4:7], v[206:209], v[198:201], v[4:7]
	v_mfma_f32_16x16x32_bf16 v[0:3], v[216:219], v[198:201], v[0:3]
	s_setprio 0
	s_add_i32 s59, 0, 0x18000
	v_add_u32_e32 v156, s59, v176
	s_barrier
	ds_read_b128 v[144:147], v156
	ds_read_b128 v[148:151], v156 offset:1024
	ds_read_b128 v[152:155], v156 offset:2048
	ds_read_b128 v[156:159], v156 offset:3072
	s_add_u32 s36, s36, 0x100000
	s_addc_u32 s37, s37, 0
	s_mov_b32 m0, s42
	v_lshl_add_u64 v[202:203], s[36:37], 0, v[128:129]
	ds_read_b128 v[160:163], v179 offset:32768
	ds_read_b128 v[164:167], v179 offset:33792
	ds_read_b128 v[168:171], v179 offset:34816
	ds_read_b128 v[182:185], v179 offset:35840
	ds_read_b128 v[186:189], v179 offset:36864
	ds_read_b128 v[190:193], v179 offset:37888
	ds_read_b128 v[194:197], v179 offset:38912
	ds_read_b128 v[198:201], v179 offset:39936
	global_load_lds_dwordx4 v[202:203], off
	v_lshl_add_u64 v[202:203], s[36:37], 0, v[132:133]
	s_mov_b32 m0, s43
	s_nop 0
	global_load_lds_dwordx4 v[202:203], off
	s_waitcnt lgkmcnt(8)
	s_setprio 1
	s_barrier
	s_waitcnt lgkmcnt(0)
	v_mfma_f32_16x16x32_bf16 v[124:127], v[144:147], v[160:163], v[124:127]
	v_mfma_f32_16x16x32_bf16 v[120:123], v[152:155], v[160:163], v[120:123]
	v_mfma_f32_16x16x32_bf16 v[108:111], v[144:147], v[168:171], v[108:111]
	v_mfma_f32_16x16x32_bf16 v[104:107], v[152:155], v[168:171], v[104:107]
	v_mfma_f32_16x16x32_bf16 v[96:99], v[144:147], v[186:189], v[96:99]
	v_mfma_f32_16x16x32_bf16 v[88:91], v[152:155], v[186:189], v[88:91]
	v_mfma_f32_16x16x32_bf16 v[80:83], v[144:147], v[194:197], v[80:83]
	v_mfma_f32_16x16x32_bf16 v[72:75], v[152:155], v[194:197], v[72:75]
	v_mfma_f32_16x16x32_bf16 v[124:127], v[148:151], v[164:167], v[124:127]
	v_mfma_f32_16x16x32_bf16 v[120:123], v[156:159], v[164:167], v[120:123]
	v_mfma_f32_16x16x32_bf16 v[108:111], v[148:151], v[182:185], v[108:111]
	v_mfma_f32_16x16x32_bf16 v[104:107], v[156:159], v[182:185], v[104:107]
	v_mfma_f32_16x16x32_bf16 v[96:99], v[148:151], v[190:193], v[96:99]
	v_mfma_f32_16x16x32_bf16 v[88:91], v[156:159], v[190:193], v[88:91]
	v_mfma_f32_16x16x32_bf16 v[80:83], v[148:151], v[198:201], v[80:83]
	v_mfma_f32_16x16x32_bf16 v[72:75], v[156:159], v[198:201], v[72:75]
	s_setprio 0
	s_barrier
	s_add_i32 s36, 0, 0x1c000
	s_add_i32 s37, s59, s40
	v_add_u32_e32 v181, s36, v176
	v_lshl_add_u64 v[172:173], v[172:173], 0, s[0:1]
	s_mov_b32 m0, s37
	ds_read_b128 v[202:205], v181
	ds_read_b128 v[206:209], v181 offset:1024
	ds_read_b128 v[212:215], v181 offset:2048
	ds_read_b128 v[216:219], v181 offset:3072
	global_load_lds_dwordx4 v[172:173], off
	v_lshl_add_u64 v[172:173], v[220:221], 0, s[0:1]
	s_add_i32 m0, s37, 0x2000
	s_nop 0
	global_load_lds_dwordx4 v[172:173], off
	s_setprio 1
	s_barrier
	s_waitcnt lgkmcnt(0)
	v_mfma_f32_16x16x32_bf16 v[116:119], v[202:205], v[160:163], v[116:119]
	v_mfma_f32_16x16x32_bf16 v[112:115], v[212:215], v[160:163], v[112:115]
	v_mfma_f32_16x16x32_bf16 v[100:103], v[202:205], v[168:171], v[100:103]
	v_mfma_f32_16x16x32_bf16 v[92:95], v[212:215], v[168:171], v[92:95]
	v_mfma_f32_16x16x32_bf16 v[84:87], v[202:205], v[186:189], v[84:87]
	v_mfma_f32_16x16x32_bf16 v[76:79], v[212:215], v[186:189], v[76:79]
	v_mfma_f32_16x16x32_bf16 v[68:71], v[202:205], v[194:197], v[68:71]
	v_mfma_f32_16x16x32_bf16 v[64:67], v[212:215], v[194:197], v[64:67]
	v_mfma_f32_16x16x32_bf16 v[116:119], v[206:209], v[164:167], v[116:119]
	v_mfma_f32_16x16x32_bf16 v[112:115], v[216:219], v[164:167], v[112:115]
	v_mfma_f32_16x16x32_bf16 v[100:103], v[206:209], v[182:185], v[100:103]
	v_mfma_f32_16x16x32_bf16 v[92:95], v[216:219], v[182:185], v[92:95]
	v_mfma_f32_16x16x32_bf16 v[84:87], v[206:209], v[190:193], v[84:87]
	v_mfma_f32_16x16x32_bf16 v[76:79], v[216:219], v[190:193], v[76:79]
	v_mfma_f32_16x16x32_bf16 v[68:71], v[206:209], v[198:201], v[68:71]
	v_mfma_f32_16x16x32_bf16 v[64:67], v[216:219], v[198:201], v[64:67]
	s_setprio 0
	s_mov_b32 m0, s49
	v_lshl_add_u64 v[172:173], v[222:223], 0, s[0:1]
	s_barrier
	ds_read_b128 v[160:163], v179 offset:49152
	ds_read_b128 v[164:167], v179 offset:50176
	ds_read_b128 v[168:171], v179 offset:51200
	ds_read_b128 v[182:185], v179 offset:52224
	ds_read_b128 v[186:189], v179 offset:53248
	ds_read_b128 v[190:193], v179 offset:54272
	ds_read_b128 v[194:197], v179 offset:55296
	ds_read_b128 v[198:201], v179 offset:56320
	global_load_lds_dwordx4 v[172:173], off
	v_lshl_add_u64 v[172:173], v[224:225], 0, s[0:1]
	s_mov_b32 m0, s50
	s_nop 0
	global_load_lds_dwordx4 v[172:173], off
	s_setprio 1
	s_barrier
	s_waitcnt lgkmcnt(0)
	v_mfma_f32_16x16x32_bf16 v[60:63], v[144:147], v[160:163], v[60:63]
	v_mfma_f32_16x16x32_bf16 v[56:59], v[152:155], v[160:163], v[56:59]
	v_mfma_f32_16x16x32_bf16 v[44:47], v[144:147], v[168:171], v[44:47]
	v_mfma_f32_16x16x32_bf16 v[40:43], v[152:155], v[168:171], v[40:43]
	v_mfma_f32_16x16x32_bf16 v[32:35], v[144:147], v[186:189], v[32:35]
	v_mfma_f32_16x16x32_bf16 v[24:27], v[152:155], v[186:189], v[24:27]
	v_mfma_f32_16x16x32_bf16 v[16:19], v[144:147], v[194:197], v[16:19]
	v_mfma_f32_16x16x32_bf16 v[8:11], v[152:155], v[194:197], v[8:11]
	v_mfma_f32_16x16x32_bf16 v[60:63], v[148:151], v[164:167], v[60:63]
	v_mfma_f32_16x16x32_bf16 v[56:59], v[156:159], v[164:167], v[56:59]
	v_mfma_f32_16x16x32_bf16 v[44:47], v[148:151], v[182:185], v[44:47]
	v_mfma_f32_16x16x32_bf16 v[40:43], v[156:159], v[182:185], v[40:43]
	v_mfma_f32_16x16x32_bf16 v[32:35], v[148:151], v[190:193], v[32:35]
	v_mfma_f32_16x16x32_bf16 v[24:27], v[156:159], v[190:193], v[24:27]
	v_mfma_f32_16x16x32_bf16 v[16:19], v[148:151], v[198:201], v[16:19]
	v_mfma_f32_16x16x32_bf16 v[8:11], v[156:159], v[198:201], v[8:11]
	s_setprio 0
	s_barrier
	s_add_u32 s34, s34, 0x100080
	s_addc_u32 s35, s35, 0
	s_add_i32 s36, s36, s40
	v_lshl_add_u64 v[144:145], s[34:35], 0, v[130:131]
	s_mov_b32 m0, s36
	s_nop 0
	global_load_lds_dwordx4 v[144:145], off
	v_lshl_add_u64 v[144:145], s[34:35], 0, v[134:135]
	s_add_i32 m0, s36, 0x2000
	s_nop 0
	global_load_lds_dwordx4 v[144:145], off
	s_waitcnt vmcnt(6)
	s_setprio 1
	s_barrier
	v_mfma_f32_16x16x32_bf16 v[52:55], v[202:205], v[160:163], v[52:55]
	v_mfma_f32_16x16x32_bf16 v[48:51], v[212:215], v[160:163], v[48:51]
	v_mfma_f32_16x16x32_bf16 v[36:39], v[202:205], v[168:171], v[36:39]
	v_mfma_f32_16x16x32_bf16 v[28:31], v[212:215], v[168:171], v[28:31]
	v_mfma_f32_16x16x32_bf16 v[20:23], v[202:205], v[186:189], v[20:23]
	v_mfma_f32_16x16x32_bf16 v[12:15], v[212:215], v[186:189], v[12:15]
	v_mfma_f32_16x16x32_bf16 v[4:7], v[202:205], v[194:197], v[4:7]
	v_mfma_f32_16x16x32_bf16 v[0:3], v[212:215], v[194:197], v[0:3]
	v_mfma_f32_16x16x32_bf16 v[52:55], v[206:209], v[164:167], v[52:55]
	v_mfma_f32_16x16x32_bf16 v[48:51], v[216:219], v[164:167], v[48:51]
	v_mfma_f32_16x16x32_bf16 v[36:39], v[206:209], v[182:185], v[36:39]
	v_mfma_f32_16x16x32_bf16 v[28:31], v[216:219], v[182:185], v[28:31]
	v_mfma_f32_16x16x32_bf16 v[20:23], v[206:209], v[190:193], v[20:23]
	v_mfma_f32_16x16x32_bf16 v[12:15], v[216:219], v[190:193], v[12:15]
	v_mfma_f32_16x16x32_bf16 v[4:7], v[206:209], v[198:201], v[4:7]
	v_mfma_f32_16x16x32_bf16 v[0:3], v[216:219], v[198:201], v[0:3]
	s_setprio 0
	s_add_i32 s58, s58, 2
	s_add_u32 s30, s30, 0x100
	s_addc_u32 s31, s31, 0
	s_add_u32 s56, s56, 0x100
	s_addc_u32 s57, s57, 0
	s_cmp_gt_u32 s58, 61
	s_barrier
	s_cbranch_scc0 .LBB0_1264
	v_lshl_or_b32 v144, s28, 8, v177
	v_lshl_add_u32 v150, s26, 8, v175
	v_ashrrev_i32_e32 v145, 31, v144
	v_ashrrev_i32_e32 v151, 31, v150
	v_lshlrev_b64 v[144:145], 1, v[144:145]
	v_lshl_add_u64 v[146:147], s[90:91], 0, v[144:145]
	v_lshlrev_b64 v[148:149], 11, v[150:151]
	v_lshl_add_u64 v[152:153], v[146:147], 0, v[148:149]
	global_load_dwordx4 v[156:159], v[152:153], off
	global_load_dwordx4 v[160:163], v[152:153], off offset:256
	v_or_b32_e32 v152, 16, v150
	v_ashrrev_i32_e32 v153, 31, v152
	v_lshlrev_b64 v[170:171], 11, v[152:153]
	v_lshl_add_u64 v[152:153], v[146:147], 0, v[170:171]
	global_load_dwordx4 v[164:167], v[152:153], off
	global_load_dwordx4 v[182:185], v[152:153], off offset:256
	v_or_b32_e32 v152, 32, v150
	v_ashrrev_i32_e32 v153, 31, v152
	v_lshlrev_b64 v[154:155], 11, v[152:153]
	v_lshl_add_u64 v[152:153], v[146:147], 0, v[154:155]
	global_load_dwordx4 v[186:189], v[152:153], off
	global_load_dwordx4 v[190:193], v[152:153], off offset:256
	v_or_b32_e32 v152, 48, v150
	v_ashrrev_i32_e32 v153, 31, v152
	v_lshlrev_b64 v[152:153], 11, v[152:153]
	v_lshl_add_u64 v[168:169], v[146:147], 0, v[152:153]
	global_load_dwordx4 v[194:197], v[168:169], off
	global_load_dwordx4 v[198:201], v[168:169], off offset:256
	s_waitcnt vmcnt(0)
	v_lshlrev_b32_e32 v202, 16, v156
	v_and_b32_e32 v203, 0xffff0000, v156
	v_lshlrev_b32_e32 v204, 16, v157
	v_and_b32_e32 v205, 0xffff0000, v157
	v_lshlrev_b32_e32 v206, 16, v158
	v_and_b32_e32 v207, 0xffff0000, v158
	v_lshlrev_b32_e32 v208, 16, v159
	v_and_b32_e32 v209, 0xffff0000, v159
	v_pk_add_f32 v[126:127], v[126:127], v[204:205]
	v_pk_add_f32 v[124:125], v[124:125], v[202:203]
	v_lshlrev_b32_e32 v224, 16, v166
	v_and_b32_e32 v225, 0xffff0000, v166
	v_lshlrev_b32_e32 v226, 16, v167
	v_and_b32_e32 v227, 0xffff0000, v167
	v_lshlrev_b32_e32 v212, 16, v160
	v_lshlrev_b32_e32 v166, 16, v194
	v_and_b32_e32 v167, 0xffff0000, v194
	v_lshlrev_b32_e32 v172, 16, v195
	v_and_b32_e32 v173, 0xffff0000, v195
	v_pk_add_f32 v[194:195], v[122:123], v[208:209]
	v_pk_add_f32 v[122:123], v[120:121], v[206:207]
	v_mul_f32_e32 v120, v125, v125
	v_mul_f32_e32 v121, v127, v127
	v_fmac_f32_e32 v120, v124, v124
	v_fmac_f32_e32 v121, v126, v126
	v_add_f32_e32 v120, v120, v121
	v_mul_f32_e32 v121, v123, v123
	v_fmac_f32_e32 v121, v122, v122
	v_add_f32_e32 v120, v121, v120
	v_mul_f32_e32 v121, v195, v195
	v_fmac_f32_e32 v121, v194, v194
	v_and_b32_e32 v213, 0xffff0000, v160
	v_lshlrev_b32_e32 v214, 16, v161
	v_and_b32_e32 v215, 0xffff0000, v161
	v_add_f32_e32 v181, v121, v120
	v_cvt_pk_bf16_f32 v120, v124, v125
	v_lshl_add_u64 v[124:125], s[10:11], 0, v[148:149]
	v_lshlrev_b32_e32 v216, 16, v162
	v_and_b32_e32 v217, 0xffff0000, v162
	v_lshlrev_b32_e32 v218, 16, v163
	v_and_b32_e32 v219, 0xffff0000, v163
	v_cvt_pk_bf16_f32 v121, v126, v127
	v_lshl_add_u64 v[124:125], v[124:125], 0, v[144:145]
	v_pk_add_f32 v[118:119], v[118:119], v[214:215]
	v_pk_add_f32 v[116:117], v[116:117], v[212:213]
	v_cvt_pk_bf16_f32 v122, v122, v123
	v_cvt_pk_bf16_f32 v123, v194, v195
	global_store_dwordx4 v[124:125], v[120:123], off
	v_lshlrev_b32_e32 v220, 16, v164
	v_and_b32_e32 v221, 0xffff0000, v164
	v_pk_add_f32 v[120:121], v[114:115], v[218:219]
	v_pk_add_f32 v[114:115], v[112:113], v[216:217]
	v_mul_f32_e32 v112, v117, v117
	v_mul_f32_e32 v113, v119, v119
	v_fmac_f32_e32 v112, v116, v116
	v_fmac_f32_e32 v113, v118, v118
	v_add_f32_e32 v112, v112, v113
	v_mul_f32_e32 v113, v115, v115
	v_fmac_f32_e32 v113, v114, v114
	v_add_f32_e32 v112, v113, v112
	v_mul_f32_e32 v113, v121, v121
	v_fmac_f32_e32 v113, v120, v120
	v_add_f32_e32 v112, v113, v112
	v_lshlrev_b32_e32 v222, 16, v165
	v_and_b32_e32 v223, 0xffff0000, v165
	v_add_f32_e32 v126, v181, v112
	v_cvt_pk_bf16_f32 v112, v116, v117
	v_cvt_pk_bf16_f32 v113, v118, v119
	v_lshl_add_u64 v[116:117], s[10:11], 0, v[170:171]
	v_lshlrev_b32_e32 v230, 16, v184
	v_and_b32_e32 v231, 0xffff0000, v184
	v_lshlrev_b32_e32 v232, 16, v186
	v_and_b32_e32 v233, 0xffff0000, v186
	v_lshlrev_b32_e32 v186, 16, v187
	v_and_b32_e32 v187, 0xffff0000, v187
	v_cvt_pk_bf16_f32 v114, v114, v115
	v_cvt_pk_bf16_f32 v115, v120, v121
	global_store_dwordx4 v[124:125], v[112:115], off offset:256
	v_pk_add_f32 v[110:111], v[110:111], v[222:223]
	v_pk_add_f32 v[108:109], v[108:109], v[220:221]
	v_lshl_add_u64 v[118:119], v[116:117], 0, v[144:145]
	v_cvt_pk_bf16_f32 v112, v108, v109
	v_cvt_pk_bf16_f32 v113, v110, v111
	v_lshlrev_b32_e32 v228, 16, v182
	v_and_b32_e32 v229, 0xffff0000, v182
	v_lshlrev_b32_e32 v182, 16, v183
	v_and_b32_e32 v183, 0xffff0000, v183
	v_lshlrev_b32_e32 v184, 16, v185
	v_and_b32_e32 v185, 0xffff0000, v185
	v_lshlrev_b32_e32 v238, 16, v192
	v_and_b32_e32 v239, 0xffff0000, v192
	v_pk_add_f32 v[106:107], v[106:107], v[226:227]
	v_pk_add_f32 v[104:105], v[104:105], v[224:225]
	v_lshlrev_b32_e32 v156, 16, v200
	v_cvt_pk_bf16_f32 v114, v104, v105
	v_cvt_pk_bf16_f32 v115, v106, v107
	global_store_dwordx4 v[118:119], v[112:115], off
	v_and_b32_e32 v157, 0xffff0000, v200
	v_pk_add_f32 v[102:103], v[102:103], v[182:183]
	v_pk_add_f32 v[112:113], v[92:93], v[230:231]
	v_pk_add_f32 v[92:93], v[98:99], v[186:187]
	v_lshl_add_u64 v[98:99], s[10:11], 0, v[154:155]
	v_pk_add_f32 v[100:101], v[100:101], v[228:229]
	v_pk_add_f32 v[94:95], v[94:95], v[184:185]
	v_cvt_pk_bf16_f32 v114, v100, v101
	v_cvt_pk_bf16_f32 v115, v102, v103
	v_cvt_pk_bf16_f32 v116, v112, v113
	v_lshlrev_b32_e32 v234, 16, v188
	v_cvt_pk_bf16_f32 v117, v94, v95
	global_store_dwordx4 v[118:119], v[114:117], off offset:256
	v_lshl_add_u64 v[118:119], v[98:99], 0, v[144:145]
	v_pk_add_f32 v[98:99], v[76:77], v[238:239]
	v_pk_add_f32 v[76:77], v[82:83], v[172:173]
	v_lshl_add_u64 v[82:83], s[10:11], 0, v[152:153]
	v_lshl_add_u64 v[122:123], v[82:83], 0, v[144:145]
	v_pk_add_f32 v[82:83], v[64:65], v[156:157]
	v_and_b32_e32 v65, 64, v174
	v_and_b32_e32 v235, 0xffff0000, v188
	v_lshlrev_b32_e32 v188, 16, v189
	v_and_b32_e32 v189, 0xffff0000, v189
	v_lshlrev_b32_e32 v236, 16, v190
	v_and_b32_e32 v237, 0xffff0000, v190
	v_pk_add_f32 v[96:97], v[96:97], v[232:233]
	v_xor_b32_e32 v64, 16, v174
	v_cvt_pk_bf16_f32 v114, v96, v97
	v_add_u32_e32 v65, 64, v65
	v_lshlrev_b32_e32 v190, 16, v191
	v_and_b32_e32 v191, 0xffff0000, v191
	v_lshlrev_b32_e32 v192, 16, v193
	v_and_b32_e32 v193, 0xffff0000, v193
	v_pk_add_f32 v[90:91], v[90:91], v[188:189]
	v_pk_add_f32 v[88:89], v[88:89], v[234:235]
	v_cvt_pk_bf16_f32 v115, v92, v93
	v_pk_add_f32 v[84:85], v[84:85], v[236:237]
	v_cvt_pk_bf16_f32 v116, v88, v89
	v_cvt_pk_bf16_f32 v117, v90, v91
	global_store_dwordx4 v[118:119], v[114:117], off
	v_cmp_lt_i32_e32 vcc, v64, v65
	v_lshlrev_b32_e32 v164, 16, v196
	v_cvt_pk_bf16_f32 v114, v84, v85
	v_and_b32_e32 v165, 0xffff0000, v196
	v_lshlrev_b32_e32 v168, 16, v197
	v_and_b32_e32 v169, 0xffff0000, v197
	v_pk_add_f32 v[86:87], v[86:87], v[190:191]
	v_pk_add_f32 v[78:79], v[78:79], v[192:193]
	v_cvt_pk_bf16_f32 v115, v86, v87
	v_cvt_pk_bf16_f32 v116, v98, v99
	v_pk_add_f32 v[80:81], v[80:81], v[166:167]
	v_cvt_pk_bf16_f32 v117, v78, v79
	global_store_dwordx4 v[118:119], v[114:117], off offset:256
	v_cndmask_b32_e32 v64, v174, v64, vcc
	v_pk_add_f32 v[74:75], v[74:75], v[168:169]
	v_cvt_pk_bf16_f32 v114, v80, v81
	v_pk_add_f32 v[72:73], v[72:73], v[164:165]
	v_cvt_pk_bf16_f32 v115, v76, v77
	v_lshlrev_b32_e32 v158, 16, v198
	v_cvt_pk_bf16_f32 v116, v72, v73
	v_cvt_pk_bf16_f32 v117, v74, v75
	global_store_dwordx4 v[122:123], v[114:117], off
	v_and_b32_e32 v159, 0xffff0000, v198
	v_lshlrev_b32_e32 v162, 16, v199
	v_lshlrev_b32_e32 v114, 2, v64
	ds_bpermute_b32 v64, v114, v126
	v_xor_b32_e32 v115, 32, v174
	v_cmp_lt_i32_e32 vcc, v115, v65
	v_and_b32_e32 v163, 0xffff0000, v199
	v_lshlrev_b32_e32 v160, 16, v201
	v_cndmask_b32_e32 v65, v174, v115, vcc
	v_lshlrev_b32_e32 v115, 2, v65
	s_waitcnt lgkmcnt(0)
	v_add_f32_e32 v116, v126, v64
	ds_bpermute_b32 v117, v115, v116
	v_and_b32_e32 v161, 0xffff0000, v201
	v_pk_add_f32 v[70:71], v[70:71], v[162:163]
	v_pk_add_f32 v[68:69], v[68:69], v[158:159]
	v_pk_add_f32 v[66:67], v[66:67], v[160:161]
	v_lshl_add_u64 v[64:65], v[150:151], 2, s[6:7]
	v_cvt_pk_bf16_f32 v118, v68, v69
	v_cvt_pk_bf16_f32 v119, v70, v71
	v_cvt_pk_bf16_f32 v120, v82, v83
	v_cvt_pk_bf16_f32 v121, v66, v67
	global_store_dwordx4 v[122:123], v[118:121], off offset:256
	s_and_saveexec_b64 s[26:27], s[2:3]
	s_cbranch_execz .LBB0_1267
	s_waitcnt lgkmcnt(0)
	v_add_f32_e32 v116, v116, v117
	global_atomic_add_f32 v[64:65], v116, off
